# code placement: every MFMA cluster start on an 8-byte boundary (.p2align 3 ahead of the segment's closing waits) on top of 64-byte loop heads
# baseline (speedup 1.0000x reference)
.Lpeel_327:
	ds_read_b128 v[128:131], v177
	ds_read_b128 v[132:135], v177 offset:1024
	ds_read_b128 v[136:139], v177 offset:2048
	ds_read_b128 v[140:143], v177 offset:3072
	ds_read_b128 v[160:163], v178
	ds_read_b128 v[164:167], v178 offset:1024
	ds_read_b128 v[168:171], v178 offset:2048
	ds_read_b128 v[180:183], v178 offset:3072
	s_add_i32 s87, s40, 2
	s_add_u32 s41, s38, 0xfffc0080
	s_addc_u32 s42, s39, -1
	s_cmp_eq_u32 s57, s40
	s_cselect_b32 s40, s84, s85
	s_cselect_b32 s43, s81, s42
	s_cselect_b32 s42, s82, s41
	s_cselect_b32 s41, s83, s86
	s_add_i32 m0, s48, 0xc000
	ds_read_b128 v[184:187], v179
	ds_read_b128 v[188:191], v179 offset:1024
	ds_read_b128 v[192:195], v179 offset:2048
	ds_read_b128 v[196:199], v179 offset:3072
	ds_read_b128 v[202:205], v179 offset:4096
	ds_read_b128 v[206:209], v179 offset:5120
	ds_read_b128 v[210:213], v179 offset:6144
	ds_read_b128 v[214:217], v179 offset:7168
	global_load_lds_dwordx4 v152, s[38:39]
	s_add_i32 m0, s48, 0xe000
	s_nop 0
	global_load_lds_dwordx4 v154, s[38:39]
	.p2align	3
	s_waitcnt vmcnt(8)
	s_waitcnt lgkmcnt(0)
	s_setprio 1
	s_barrier
	v_mfma_f32_16x16x32_bf16 v[124:127], v[128:131], v[184:187], 0
	v_mfma_f32_16x16x32_bf16 v[120:123], v[136:139], v[184:187], 0
	v_mfma_f32_16x16x32_bf16 v[108:111], v[128:131], v[192:195], 0
	v_mfma_f32_16x16x32_bf16 v[104:107], v[136:139], v[192:195], 0
	v_mfma_f32_16x16x32_bf16 v[92:95], v[128:131], v[202:205], 0
	v_mfma_f32_16x16x32_bf16 v[88:91], v[136:139], v[202:205], 0
	v_mfma_f32_16x16x32_bf16 v[76:79], v[128:131], v[210:213], 0
	v_mfma_f32_16x16x32_bf16 v[72:75], v[136:139], v[210:213], 0
	v_mfma_f32_16x16x32_bf16 v[124:127], v[132:135], v[188:191], v[124:127]
	v_mfma_f32_16x16x32_bf16 v[120:123], v[140:143], v[188:191], v[120:123]
	v_mfma_f32_16x16x32_bf16 v[108:111], v[132:135], v[196:199], v[108:111]
	v_mfma_f32_16x16x32_bf16 v[104:107], v[140:143], v[196:199], v[104:107]
	v_mfma_f32_16x16x32_bf16 v[92:95], v[132:135], v[206:209], v[92:95]
	v_mfma_f32_16x16x32_bf16 v[88:91], v[140:143], v[206:209], v[88:91]
	v_mfma_f32_16x16x32_bf16 v[76:79], v[132:135], v[214:217], v[76:79]
	v_mfma_f32_16x16x32_bf16 v[72:75], v[140:143], v[214:217], v[72:75]
	v_mfma_f32_16x16x32_bf16 v[116:119], v[160:163], v[184:187], 0
	v_mfma_f32_16x16x32_bf16 v[112:115], v[168:171], v[184:187], 0
	v_mfma_f32_16x16x32_bf16 v[100:103], v[160:163], v[192:195], 0
	v_mfma_f32_16x16x32_bf16 v[96:99], v[168:171], v[192:195], 0
	v_mfma_f32_16x16x32_bf16 v[84:87], v[160:163], v[202:205], 0
	v_mfma_f32_16x16x32_bf16 v[80:83], v[168:171], v[202:205], 0
	v_mfma_f32_16x16x32_bf16 v[68:71], v[160:163], v[210:213], 0
	v_mfma_f32_16x16x32_bf16 v[64:67], v[168:171], v[210:213], 0
	v_mfma_f32_16x16x32_bf16 v[116:119], v[164:167], v[188:191], v[116:119]
	v_mfma_f32_16x16x32_bf16 v[112:115], v[180:183], v[188:191], v[112:115]
	v_mfma_f32_16x16x32_bf16 v[100:103], v[164:167], v[196:199], v[100:103]
	v_mfma_f32_16x16x32_bf16 v[96:99], v[180:183], v[196:199], v[96:99]
	v_mfma_f32_16x16x32_bf16 v[84:87], v[164:167], v[206:209], v[84:87]
	v_mfma_f32_16x16x32_bf16 v[80:83], v[180:183], v[206:209], v[80:83]
	v_mfma_f32_16x16x32_bf16 v[68:71], v[164:167], v[214:217], v[68:71]
	v_mfma_f32_16x16x32_bf16 v[64:67], v[180:183], v[214:217], v[64:67]
	s_barrier
	s_setprio 0
	s_add_i32 s88, s58, s33
	v_lshl_add_u64 v[172:173], s[40:41], 0, v[148:149]
	s_mov_b32 m0, s88
	ds_read_b128 v[184:187], v179 offset:16384
	ds_read_b128 v[188:191], v179 offset:17408
	ds_read_b128 v[192:195], v179 offset:18432
	ds_read_b128 v[196:199], v179 offset:19456
	ds_read_b128 v[202:205], v179 offset:20480
	ds_read_b128 v[206:209], v179 offset:21504
	ds_read_b128 v[210:213], v179 offset:22528
	ds_read_b128 v[214:217], v179 offset:23552
	global_load_lds_dwordx4 v[172:173], off
	s_add_i32 m0, s88, 0x2000
	s_add_u32 s88, s40, 0x40000
	v_lshl_add_u64 v[218:219], s[40:41], 0, v[144:145]
	s_addc_u32 s89, s41, 0
	s_add_i32 s90, s64, s33
	global_load_lds_dwordx4 v[218:219], off
	s_mov_b32 m0, s90
	v_lshl_add_u64 v[222:223], s[42:43], 0, v[146:147]
	global_load_lds_dwordx4 v148, s[88:89]
	s_add_i32 m0, s90, 0x2000
	s_nop 0
	global_load_lds_dwordx4 v144, s[88:89]
	v_lshl_add_u64 v[220:221], s[42:43], 0, v[150:151]
	s_mov_b32 m0, s48
	s_nop 0
	global_load_lds_dwordx4 v[220:221], off
	s_mov_b32 m0, s49
	s_nop 0
	global_load_lds_dwordx4 v[222:223], off
	.p2align	3
	s_waitcnt vmcnt(8)
	s_waitcnt lgkmcnt(0)
	s_setprio 1
	s_barrier
	v_mfma_f32_16x16x32_bf16 v[60:63], v[128:131], v[184:187], 0
	v_mfma_f32_16x16x32_bf16 v[56:59], v[136:139], v[184:187], 0
	v_mfma_f32_16x16x32_bf16 v[44:47], v[128:131], v[192:195], 0
	v_mfma_f32_16x16x32_bf16 v[40:43], v[136:139], v[192:195], 0
	v_mfma_f32_16x16x32_bf16 v[28:31], v[128:131], v[202:205], 0
	v_mfma_f32_16x16x32_bf16 v[24:27], v[136:139], v[202:205], 0
	v_mfma_f32_16x16x32_bf16 v[12:15], v[128:131], v[210:213], 0
	v_mfma_f32_16x16x32_bf16 v[8:11], v[136:139], v[210:213], 0
	v_mfma_f32_16x16x32_bf16 v[60:63], v[132:135], v[188:191], v[60:63]
	v_mfma_f32_16x16x32_bf16 v[56:59], v[140:143], v[188:191], v[56:59]
	v_mfma_f32_16x16x32_bf16 v[44:47], v[132:135], v[196:199], v[44:47]
	v_mfma_f32_16x16x32_bf16 v[40:43], v[140:143], v[196:199], v[40:43]
	v_mfma_f32_16x16x32_bf16 v[28:31], v[132:135], v[206:209], v[28:31]
	v_mfma_f32_16x16x32_bf16 v[24:27], v[140:143], v[206:209], v[24:27]
	v_mfma_f32_16x16x32_bf16 v[12:15], v[132:135], v[214:217], v[12:15]
	v_mfma_f32_16x16x32_bf16 v[8:11], v[140:143], v[214:217], v[8:11]
	v_mfma_f32_16x16x32_bf16 v[52:55], v[160:163], v[184:187], 0
	v_mfma_f32_16x16x32_bf16 v[48:51], v[168:171], v[184:187], 0
	v_mfma_f32_16x16x32_bf16 v[36:39], v[160:163], v[192:195], 0
	v_mfma_f32_16x16x32_bf16 v[32:35], v[168:171], v[192:195], 0
	v_mfma_f32_16x16x32_bf16 v[20:23], v[160:163], v[202:205], 0
	v_mfma_f32_16x16x32_bf16 v[16:19], v[168:171], v[202:205], 0
	v_mfma_f32_16x16x32_bf16 v[4:7], v[160:163], v[210:213], 0
	v_mfma_f32_16x16x32_bf16 v[0:3], v[168:171], v[210:213], 0
	v_mfma_f32_16x16x32_bf16 v[52:55], v[164:167], v[188:191], v[52:55]
	v_mfma_f32_16x16x32_bf16 v[48:51], v[180:183], v[188:191], v[48:51]
	v_mfma_f32_16x16x32_bf16 v[36:39], v[164:167], v[196:199], v[36:39]
	v_mfma_f32_16x16x32_bf16 v[32:35], v[180:183], v[196:199], v[32:35]
	v_mfma_f32_16x16x32_bf16 v[20:23], v[164:167], v[206:209], v[20:23]
	v_mfma_f32_16x16x32_bf16 v[16:19], v[180:183], v[206:209], v[16:19]
	v_mfma_f32_16x16x32_bf16 v[4:7], v[164:167], v[214:217], v[4:7]
	v_mfma_f32_16x16x32_bf16 v[0:3], v[180:183], v[214:217], v[0:3]
	s_barrier
	s_setprio 0
	s_add_i32 s88, 0, 0x18000
	s_add_i32 s89, 0, 0x1c000
	v_add_u32_e32 v140, s88, v175
	v_add_u32_e32 v180, s89, v175
	ds_read_b128 v[128:131], v140
	ds_read_b128 v[132:135], v140 offset:1024
	ds_read_b128 v[136:139], v140 offset:2048
	ds_read_b128 v[140:143], v140 offset:3072
	ds_read_b128 v[160:163], v180
	ds_read_b128 v[164:167], v180 offset:1024
	ds_read_b128 v[168:171], v180 offset:2048
	ds_read_b128 v[180:183], v180 offset:3072
	s_add_u32 s42, s42, 0x40000
	s_addc_u32 s43, s43, 0
	s_mov_b32 m0, s50
	ds_read_b128 v[184:187], v179 offset:32768
	ds_read_b128 v[188:191], v179 offset:33792
	ds_read_b128 v[192:195], v179 offset:34816
	ds_read_b128 v[196:199], v179 offset:35840
	ds_read_b128 v[202:205], v179 offset:36864
	ds_read_b128 v[206:209], v179 offset:37888
	ds_read_b128 v[210:213], v179 offset:38912
	ds_read_b128 v[214:217], v179 offset:39936
	global_load_lds_dwordx4 v150, s[42:43]
	s_mov_b32 m0, s51
	s_nop 0
	global_load_lds_dwordx4 v146, s[42:43]
	.p2align	3
	s_waitcnt vmcnt(8)
	s_waitcnt lgkmcnt(0)
	s_setprio 1
	s_barrier
	v_mfma_f32_16x16x32_bf16 v[124:127], v[128:131], v[184:187], v[124:127]
	v_mfma_f32_16x16x32_bf16 v[120:123], v[136:139], v[184:187], v[120:123]
	v_mfma_f32_16x16x32_bf16 v[108:111], v[128:131], v[192:195], v[108:111]
	v_mfma_f32_16x16x32_bf16 v[104:107], v[136:139], v[192:195], v[104:107]
	v_mfma_f32_16x16x32_bf16 v[92:95], v[128:131], v[202:205], v[92:95]
	v_mfma_f32_16x16x32_bf16 v[88:91], v[136:139], v[202:205], v[88:91]
	v_mfma_f32_16x16x32_bf16 v[76:79], v[128:131], v[210:213], v[76:79]
	v_mfma_f32_16x16x32_bf16 v[72:75], v[136:139], v[210:213], v[72:75]
	v_mfma_f32_16x16x32_bf16 v[124:127], v[132:135], v[188:191], v[124:127]
	v_mfma_f32_16x16x32_bf16 v[120:123], v[140:143], v[188:191], v[120:123]
	v_mfma_f32_16x16x32_bf16 v[108:111], v[132:135], v[196:199], v[108:111]
	v_mfma_f32_16x16x32_bf16 v[104:107], v[140:143], v[196:199], v[104:107]
	v_mfma_f32_16x16x32_bf16 v[92:95], v[132:135], v[206:209], v[92:95]
	v_mfma_f32_16x16x32_bf16 v[88:91], v[140:143], v[206:209], v[88:91]
	v_mfma_f32_16x16x32_bf16 v[76:79], v[132:135], v[214:217], v[76:79]
	v_mfma_f32_16x16x32_bf16 v[72:75], v[140:143], v[214:217], v[72:75]
	v_mfma_f32_16x16x32_bf16 v[116:119], v[160:163], v[184:187], v[116:119]
	v_mfma_f32_16x16x32_bf16 v[112:115], v[168:171], v[184:187], v[112:115]
	v_mfma_f32_16x16x32_bf16 v[100:103], v[160:163], v[192:195], v[100:103]
	v_mfma_f32_16x16x32_bf16 v[96:99], v[168:171], v[192:195], v[96:99]
	v_mfma_f32_16x16x32_bf16 v[84:87], v[160:163], v[202:205], v[84:87]
	v_mfma_f32_16x16x32_bf16 v[80:83], v[168:171], v[202:205], v[80:83]
	v_mfma_f32_16x16x32_bf16 v[68:71], v[160:163], v[210:213], v[68:71]
	v_mfma_f32_16x16x32_bf16 v[64:67], v[168:171], v[210:213], v[64:67]
	v_mfma_f32_16x16x32_bf16 v[116:119], v[164:167], v[188:191], v[116:119]
	v_mfma_f32_16x16x32_bf16 v[112:115], v[180:183], v[188:191], v[112:115]
	v_mfma_f32_16x16x32_bf16 v[100:103], v[164:167], v[196:199], v[100:103]
	v_mfma_f32_16x16x32_bf16 v[96:99], v[180:183], v[196:199], v[96:99]
	v_mfma_f32_16x16x32_bf16 v[84:87], v[164:167], v[206:209], v[84:87]
	v_mfma_f32_16x16x32_bf16 v[80:83], v[180:183], v[206:209], v[80:83]
	v_mfma_f32_16x16x32_bf16 v[68:71], v[164:167], v[214:217], v[68:71]
	v_mfma_f32_16x16x32_bf16 v[64:67], v[180:183], v[214:217], v[64:67]
	s_barrier
	s_setprio 0
	s_add_i32 s42, s88, s33
	v_lshl_add_u64 v[172:173], v[172:173], 0, s[10:11]
	s_mov_b32 m0, s42
	ds_read_b128 v[184:187], v179 offset:49152
	ds_read_b128 v[188:191], v179 offset:50176
	ds_read_b128 v[192:195], v179 offset:51200
	ds_read_b128 v[196:199], v179 offset:52224
	ds_read_b128 v[202:205], v179 offset:53248
	ds_read_b128 v[206:209], v179 offset:54272
	ds_read_b128 v[210:213], v179 offset:55296
	ds_read_b128 v[214:217], v179 offset:56320
	global_load_lds_dwordx4 v[172:173], off
	s_add_i32 m0, s42, 0x2000
	s_add_u32 s40, s40, 0x40080
	v_lshl_add_u64 v[172:173], v[218:219], 0, s[10:11]
	s_addc_u32 s41, s41, 0
	s_add_i32 s42, s89, s33
	global_load_lds_dwordx4 v[172:173], off
	s_mov_b32 m0, s42
	s_nop 0
	global_load_lds_dwordx4 v148, s[40:41]
	s_add_i32 m0, s42, 0x2000
	s_nop 0
	global_load_lds_dwordx4 v144, s[40:41]
	v_lshl_add_u64 v[172:173], v[220:221], 0, s[10:11]
	s_mov_b32 m0, s55
	s_nop 0
	global_load_lds_dwordx4 v[172:173], off
	v_lshl_add_u64 v[172:173], v[222:223], 0, s[10:11]
	s_mov_b32 m0, s56
	s_nop 0
	global_load_lds_dwordx4 v[172:173], off
	.p2align	3
	s_waitcnt vmcnt(8)
	s_waitcnt lgkmcnt(0)
	s_setprio 1
	s_barrier
	v_mfma_f32_16x16x32_bf16 v[60:63], v[128:131], v[184:187], v[60:63]
	v_mfma_f32_16x16x32_bf16 v[56:59], v[136:139], v[184:187], v[56:59]
	v_mfma_f32_16x16x32_bf16 v[44:47], v[128:131], v[192:195], v[44:47]
	v_mfma_f32_16x16x32_bf16 v[40:43], v[136:139], v[192:195], v[40:43]
	v_mfma_f32_16x16x32_bf16 v[28:31], v[128:131], v[202:205], v[28:31]
	v_mfma_f32_16x16x32_bf16 v[24:27], v[136:139], v[202:205], v[24:27]
	v_mfma_f32_16x16x32_bf16 v[12:15], v[128:131], v[210:213], v[12:15]
	v_mfma_f32_16x16x32_bf16 v[8:11], v[136:139], v[210:213], v[8:11]
	v_mfma_f32_16x16x32_bf16 v[60:63], v[132:135], v[188:191], v[60:63]
	v_mfma_f32_16x16x32_bf16 v[56:59], v[140:143], v[188:191], v[56:59]
	v_mfma_f32_16x16x32_bf16 v[44:47], v[132:135], v[196:199], v[44:47]
	v_mfma_f32_16x16x32_bf16 v[40:43], v[140:143], v[196:199], v[40:43]
	v_mfma_f32_16x16x32_bf16 v[28:31], v[132:135], v[206:209], v[28:31]
	v_mfma_f32_16x16x32_bf16 v[24:27], v[140:143], v[206:209], v[24:27]
	v_mfma_f32_16x16x32_bf16 v[12:15], v[132:135], v[214:217], v[12:15]
	v_mfma_f32_16x16x32_bf16 v[8:11], v[140:143], v[214:217], v[8:11]
	v_mfma_f32_16x16x32_bf16 v[52:55], v[160:163], v[184:187], v[52:55]
	v_mfma_f32_16x16x32_bf16 v[48:51], v[168:171], v[184:187], v[48:51]
	v_mfma_f32_16x16x32_bf16 v[36:39], v[160:163], v[192:195], v[36:39]
	v_mfma_f32_16x16x32_bf16 v[32:35], v[168:171], v[192:195], v[32:35]
	v_mfma_f32_16x16x32_bf16 v[20:23], v[160:163], v[202:205], v[20:23]
	v_mfma_f32_16x16x32_bf16 v[16:19], v[168:171], v[202:205], v[16:19]
	v_mfma_f32_16x16x32_bf16 v[4:7], v[160:163], v[210:213], v[4:7]
	v_mfma_f32_16x16x32_bf16 v[0:3], v[168:171], v[210:213], v[0:3]
	v_mfma_f32_16x16x32_bf16 v[52:55], v[164:167], v[188:191], v[52:55]
	v_mfma_f32_16x16x32_bf16 v[48:51], v[180:183], v[188:191], v[48:51]
	v_mfma_f32_16x16x32_bf16 v[36:39], v[164:167], v[196:199], v[36:39]
	v_mfma_f32_16x16x32_bf16 v[32:35], v[180:183], v[196:199], v[32:35]
	v_mfma_f32_16x16x32_bf16 v[20:23], v[164:167], v[206:209], v[20:23]
	v_mfma_f32_16x16x32_bf16 v[16:19], v[180:183], v[206:209], v[16:19]
	v_mfma_f32_16x16x32_bf16 v[4:7], v[164:167], v[214:217], v[4:7]
	v_mfma_f32_16x16x32_bf16 v[0:3], v[180:183], v[214:217], v[0:3]
	s_barrier
	s_setprio 0
	s_add_u32 s38, s38, 0x100
	s_addc_u32 s39, s39, 0
	s_add_u32 s85, s85, 0x100
	s_addc_u32 s86, s86, 0
	s_cmp_ge_i32 s87, s26
	s_mov_b32 s40, s87
	s_cbranch_scc0 .LBB7_327
	s_branch .Lpeelx_327
	.p2align	6
.LBB7_327:
	ds_read_b128 v[128:131], v177
	ds_read_b128 v[132:135], v177 offset:1024
	ds_read_b128 v[136:139], v177 offset:2048
	ds_read_b128 v[140:143], v177 offset:3072
	ds_read_b128 v[160:163], v178
	ds_read_b128 v[164:167], v178 offset:1024
	ds_read_b128 v[168:171], v178 offset:2048
	ds_read_b128 v[180:183], v178 offset:3072
	s_add_i32 s87, s40, 2
	s_add_u32 s41, s38, 0xfffc0080
	s_addc_u32 s42, s39, -1
	s_cmp_eq_u32 s57, s40
	s_cselect_b32 s40, s84, s85
	s_cselect_b32 s43, s81, s42
	s_cselect_b32 s42, s82, s41
	s_cselect_b32 s41, s83, s86
	s_add_i32 m0, s48, 0xc000
	ds_read_b128 v[184:187], v179
	ds_read_b128 v[188:191], v179 offset:1024
	ds_read_b128 v[192:195], v179 offset:2048
	ds_read_b128 v[196:199], v179 offset:3072
	ds_read_b128 v[202:205], v179 offset:4096
	ds_read_b128 v[206:209], v179 offset:5120
	ds_read_b128 v[210:213], v179 offset:6144
	ds_read_b128 v[214:217], v179 offset:7168
	global_load_lds_dwordx4 v152, s[38:39]
	s_add_i32 m0, s48, 0xe000
	s_nop 0
	global_load_lds_dwordx4 v154, s[38:39]
	.p2align	3
	s_waitcnt vmcnt(8)
	s_waitcnt lgkmcnt(0)
	s_setprio 1
	s_barrier
	v_mfma_f32_16x16x32_bf16 v[124:127], v[128:131], v[184:187], v[124:127]
	v_mfma_f32_16x16x32_bf16 v[120:123], v[136:139], v[184:187], v[120:123]
	v_mfma_f32_16x16x32_bf16 v[108:111], v[128:131], v[192:195], v[108:111]
	v_mfma_f32_16x16x32_bf16 v[104:107], v[136:139], v[192:195], v[104:107]
	v_mfma_f32_16x16x32_bf16 v[92:95], v[128:131], v[202:205], v[92:95]
	v_mfma_f32_16x16x32_bf16 v[88:91], v[136:139], v[202:205], v[88:91]
	v_mfma_f32_16x16x32_bf16 v[76:79], v[128:131], v[210:213], v[76:79]
	v_mfma_f32_16x16x32_bf16 v[72:75], v[136:139], v[210:213], v[72:75]
	v_mfma_f32_16x16x32_bf16 v[124:127], v[132:135], v[188:191], v[124:127]
	v_mfma_f32_16x16x32_bf16 v[120:123], v[140:143], v[188:191], v[120:123]
	v_mfma_f32_16x16x32_bf16 v[108:111], v[132:135], v[196:199], v[108:111]
	v_mfma_f32_16x16x32_bf16 v[104:107], v[140:143], v[196:199], v[104:107]
	v_mfma_f32_16x16x32_bf16 v[92:95], v[132:135], v[206:209], v[92:95]
	v_mfma_f32_16x16x32_bf16 v[88:91], v[140:143], v[206:209], v[88:91]
	v_mfma_f32_16x16x32_bf16 v[76:79], v[132:135], v[214:217], v[76:79]
	v_mfma_f32_16x16x32_bf16 v[72:75], v[140:143], v[214:217], v[72:75]
	v_mfma_f32_16x16x32_bf16 v[116:119], v[160:163], v[184:187], v[116:119]
	v_mfma_f32_16x16x32_bf16 v[112:115], v[168:171], v[184:187], v[112:115]
	v_mfma_f32_16x16x32_bf16 v[100:103], v[160:163], v[192:195], v[100:103]
	v_mfma_f32_16x16x32_bf16 v[96:99], v[168:171], v[192:195], v[96:99]
	v_mfma_f32_16x16x32_bf16 v[84:87], v[160:163], v[202:205], v[84:87]
	v_mfma_f32_16x16x32_bf16 v[80:83], v[168:171], v[202:205], v[80:83]
	v_mfma_f32_16x16x32_bf16 v[68:71], v[160:163], v[210:213], v[68:71]
	v_mfma_f32_16x16x32_bf16 v[64:67], v[168:171], v[210:213], v[64:67]
	v_mfma_f32_16x16x32_bf16 v[116:119], v[164:167], v[188:191], v[116:119]
	v_mfma_f32_16x16x32_bf16 v[112:115], v[180:183], v[188:191], v[112:115]
	v_mfma_f32_16x16x32_bf16 v[100:103], v[164:167], v[196:199], v[100:103]
	v_mfma_f32_16x16x32_bf16 v[96:99], v[180:183], v[196:199], v[96:99]
	v_mfma_f32_16x16x32_bf16 v[84:87], v[164:167], v[206:209], v[84:87]
	v_mfma_f32_16x16x32_bf16 v[80:83], v[180:183], v[206:209], v[80:83]
	v_mfma_f32_16x16x32_bf16 v[68:71], v[164:167], v[214:217], v[68:71]
	v_mfma_f32_16x16x32_bf16 v[64:67], v[180:183], v[214:217], v[64:67]
	s_barrier
	s_setprio 0
	s_add_i32 s88, s58, s33
	v_lshl_add_u64 v[172:173], s[40:41], 0, v[148:149]
	s_mov_b32 m0, s88
	ds_read_b128 v[184:187], v179 offset:16384
	ds_read_b128 v[188:191], v179 offset:17408
	ds_read_b128 v[192:195], v179 offset:18432
	ds_read_b128 v[196:199], v179 offset:19456
	ds_read_b128 v[202:205], v179 offset:20480
	ds_read_b128 v[206:209], v179 offset:21504
	ds_read_b128 v[210:213], v179 offset:22528
	ds_read_b128 v[214:217], v179 offset:23552
	global_load_lds_dwordx4 v[172:173], off
	s_add_i32 m0, s88, 0x2000
	s_add_u32 s88, s40, 0x40000
	v_lshl_add_u64 v[218:219], s[40:41], 0, v[144:145]
	s_addc_u32 s89, s41, 0
	s_add_i32 s90, s64, s33
	global_load_lds_dwordx4 v[218:219], off
	s_mov_b32 m0, s90
	v_lshl_add_u64 v[222:223], s[42:43], 0, v[146:147]
	global_load_lds_dwordx4 v148, s[88:89]
	s_add_i32 m0, s90, 0x2000
	s_nop 0
	global_load_lds_dwordx4 v144, s[88:89]
	v_lshl_add_u64 v[220:221], s[42:43], 0, v[150:151]
	s_mov_b32 m0, s48
	s_nop 0
	global_load_lds_dwordx4 v[220:221], off
	s_mov_b32 m0, s49
	s_nop 0
	global_load_lds_dwordx4 v[222:223], off
	.p2align	3
	s_waitcnt vmcnt(8)
	s_waitcnt lgkmcnt(0)
	s_setprio 1
	s_barrier
	v_mfma_f32_16x16x32_bf16 v[60:63], v[128:131], v[184:187], v[60:63]
	v_mfma_f32_16x16x32_bf16 v[56:59], v[136:139], v[184:187], v[56:59]
	v_mfma_f32_16x16x32_bf16 v[44:47], v[128:131], v[192:195], v[44:47]
	v_mfma_f32_16x16x32_bf16 v[40:43], v[136:139], v[192:195], v[40:43]
	v_mfma_f32_16x16x32_bf16 v[28:31], v[128:131], v[202:205], v[28:31]
	v_mfma_f32_16x16x32_bf16 v[24:27], v[136:139], v[202:205], v[24:27]
	v_mfma_f32_16x16x32_bf16 v[12:15], v[128:131], v[210:213], v[12:15]
	v_mfma_f32_16x16x32_bf16 v[8:11], v[136:139], v[210:213], v[8:11]
	v_mfma_f32_16x16x32_bf16 v[60:63], v[132:135], v[188:191], v[60:63]
	v_mfma_f32_16x16x32_bf16 v[56:59], v[140:143], v[188:191], v[56:59]
	v_mfma_f32_16x16x32_bf16 v[44:47], v[132:135], v[196:199], v[44:47]
	v_mfma_f32_16x16x32_bf16 v[40:43], v[140:143], v[196:199], v[40:43]
	v_mfma_f32_16x16x32_bf16 v[28:31], v[132:135], v[206:209], v[28:31]
	v_mfma_f32_16x16x32_bf16 v[24:27], v[140:143], v[206:209], v[24:27]
	v_mfma_f32_16x16x32_bf16 v[12:15], v[132:135], v[214:217], v[12:15]
	v_mfma_f32_16x16x32_bf16 v[8:11], v[140:143], v[214:217], v[8:11]
	v_mfma_f32_16x16x32_bf16 v[52:55], v[160:163], v[184:187], v[52:55]
	v_mfma_f32_16x16x32_bf16 v[48:51], v[168:171], v[184:187], v[48:51]
	v_mfma_f32_16x16x32_bf16 v[36:39], v[160:163], v[192:195], v[36:39]
	v_mfma_f32_16x16x32_bf16 v[32:35], v[168:171], v[192:195], v[32:35]
	v_mfma_f32_16x16x32_bf16 v[20:23], v[160:163], v[202:205], v[20:23]
	v_mfma_f32_16x16x32_bf16 v[16:19], v[168:171], v[202:205], v[16:19]
	v_mfma_f32_16x16x32_bf16 v[4:7], v[160:163], v[210:213], v[4:7]
	v_mfma_f32_16x16x32_bf16 v[0:3], v[168:171], v[210:213], v[0:3]
	v_mfma_f32_16x16x32_bf16 v[52:55], v[164:167], v[188:191], v[52:55]
	v_mfma_f32_16x16x32_bf16 v[48:51], v[180:183], v[188:191], v[48:51]
	v_mfma_f32_16x16x32_bf16 v[36:39], v[164:167], v[196:199], v[36:39]
	v_mfma_f32_16x16x32_bf16 v[32:35], v[180:183], v[196:199], v[32:35]
	v_mfma_f32_16x16x32_bf16 v[20:23], v[164:167], v[206:209], v[20:23]
	v_mfma_f32_16x16x32_bf16 v[16:19], v[180:183], v[206:209], v[16:19]
	v_mfma_f32_16x16x32_bf16 v[4:7], v[164:167], v[214:217], v[4:7]
	v_mfma_f32_16x16x32_bf16 v[0:3], v[180:183], v[214:217], v[0:3]
	s_barrier
	s_setprio 0
	s_add_i32 s88, 0, 0x18000
	s_add_i32 s89, 0, 0x1c000
	v_add_u32_e32 v140, s88, v175
	v_add_u32_e32 v180, s89, v175
	ds_read_b128 v[128:131], v140
	ds_read_b128 v[132:135], v140 offset:1024
	ds_read_b128 v[136:139], v140 offset:2048
	ds_read_b128 v[140:143], v140 offset:3072
	ds_read_b128 v[160:163], v180
	ds_read_b128 v[164:167], v180 offset:1024
	ds_read_b128 v[168:171], v180 offset:2048
	ds_read_b128 v[180:183], v180 offset:3072
	s_add_u32 s42, s42, 0x40000
	s_addc_u32 s43, s43, 0
	s_mov_b32 m0, s50
	ds_read_b128 v[184:187], v179 offset:32768
	ds_read_b128 v[188:191], v179 offset:33792
	ds_read_b128 v[192:195], v179 offset:34816
	ds_read_b128 v[196:199], v179 offset:35840
	ds_read_b128 v[202:205], v179 offset:36864
	ds_read_b128 v[206:209], v179 offset:37888
	ds_read_b128 v[210:213], v179 offset:38912
	ds_read_b128 v[214:217], v179 offset:39936
	global_load_lds_dwordx4 v150, s[42:43]
	s_mov_b32 m0, s51
	s_nop 0
	global_load_lds_dwordx4 v146, s[42:43]
	.p2align	3
	s_waitcnt vmcnt(8)
	s_waitcnt lgkmcnt(0)
	s_setprio 1
	s_barrier
	v_mfma_f32_16x16x32_bf16 v[124:127], v[128:131], v[184:187], v[124:127]
	v_mfma_f32_16x16x32_bf16 v[120:123], v[136:139], v[184:187], v[120:123]
	v_mfma_f32_16x16x32_bf16 v[108:111], v[128:131], v[192:195], v[108:111]
	v_mfma_f32_16x16x32_bf16 v[104:107], v[136:139], v[192:195], v[104:107]
	v_mfma_f32_16x16x32_bf16 v[92:95], v[128:131], v[202:205], v[92:95]
	v_mfma_f32_16x16x32_bf16 v[88:91], v[136:139], v[202:205], v[88:91]
	v_mfma_f32_16x16x32_bf16 v[76:79], v[128:131], v[210:213], v[76:79]
	v_mfma_f32_16x16x32_bf16 v[72:75], v[136:139], v[210:213], v[72:75]
	v_mfma_f32_16x16x32_bf16 v[124:127], v[132:135], v[188:191], v[124:127]
	v_mfma_f32_16x16x32_bf16 v[120:123], v[140:143], v[188:191], v[120:123]
	v_mfma_f32_16x16x32_bf16 v[108:111], v[132:135], v[196:199], v[108:111]
	v_mfma_f32_16x16x32_bf16 v[104:107], v[140:143], v[196:199], v[104:107]
	v_mfma_f32_16x16x32_bf16 v[92:95], v[132:135], v[206:209], v[92:95]
	v_mfma_f32_16x16x32_bf16 v[88:91], v[140:143], v[206:209], v[88:91]
	v_mfma_f32_16x16x32_bf16 v[76:79], v[132:135], v[214:217], v[76:79]
	v_mfma_f32_16x16x32_bf16 v[72:75], v[140:143], v[214:217], v[72:75]
	v_mfma_f32_16x16x32_bf16 v[116:119], v[160:163], v[184:187], v[116:119]
	v_mfma_f32_16x16x32_bf16 v[112:115], v[168:171], v[184:187], v[112:115]
	v_mfma_f32_16x16x32_bf16 v[100:103], v[160:163], v[192:195], v[100:103]
	v_mfma_f32_16x16x32_bf16 v[96:99], v[168:171], v[192:195], v[96:99]
	v_mfma_f32_16x16x32_bf16 v[84:87], v[160:163], v[202:205], v[84:87]
	v_mfma_f32_16x16x32_bf16 v[80:83], v[168:171], v[202:205], v[80:83]
	v_mfma_f32_16x16x32_bf16 v[68:71], v[160:163], v[210:213], v[68:71]
	v_mfma_f32_16x16x32_bf16 v[64:67], v[168:171], v[210:213], v[64:67]
	v_mfma_f32_16x16x32_bf16 v[116:119], v[164:167], v[188:191], v[116:119]
	v_mfma_f32_16x16x32_bf16 v[112:115], v[180:183], v[188:191], v[112:115]
	v_mfma_f32_16x16x32_bf16 v[100:103], v[164:167], v[196:199], v[100:103]
	v_mfma_f32_16x16x32_bf16 v[96:99], v[180:183], v[196:199], v[96:99]
	v_mfma_f32_16x16x32_bf16 v[84:87], v[164:167], v[206:209], v[84:87]
	v_mfma_f32_16x16x32_bf16 v[80:83], v[180:183], v[206:209], v[80:83]
	v_mfma_f32_16x16x32_bf16 v[68:71], v[164:167], v[214:217], v[68:71]
	v_mfma_f32_16x16x32_bf16 v[64:67], v[180:183], v[214:217], v[64:67]
	s_barrier
	s_setprio 0
	s_add_i32 s42, s88, s33
	v_lshl_add_u64 v[172:173], v[172:173], 0, s[10:11]
	s_mov_b32 m0, s42
	ds_read_b128 v[184:187], v179 offset:49152
	ds_read_b128 v[188:191], v179 offset:50176
	ds_read_b128 v[192:195], v179 offset:51200
	ds_read_b128 v[196:199], v179 offset:52224
	ds_read_b128 v[202:205], v179 offset:53248
	ds_read_b128 v[206:209], v179 offset:54272
	ds_read_b128 v[210:213], v179 offset:55296
	ds_read_b128 v[214:217], v179 offset:56320
	global_load_lds_dwordx4 v[172:173], off
	s_add_i32 m0, s42, 0x2000
	s_add_u32 s40, s40, 0x40080
	v_lshl_add_u64 v[172:173], v[218:219], 0, s[10:11]
	s_addc_u32 s41, s41, 0
	s_add_i32 s42, s89, s33
	global_load_lds_dwordx4 v[172:173], off
	s_mov_b32 m0, s42
	s_nop 0
	global_load_lds_dwordx4 v148, s[40:41]
	s_add_i32 m0, s42, 0x2000
	s_nop 0
	global_load_lds_dwordx4 v144, s[40:41]
	v_lshl_add_u64 v[172:173], v[220:221], 0, s[10:11]
	s_mov_b32 m0, s55
	s_nop 0
	global_load_lds_dwordx4 v[172:173], off
	v_lshl_add_u64 v[172:173], v[222:223], 0, s[10:11]
	s_mov_b32 m0, s56
	s_nop 0
	global_load_lds_dwordx4 v[172:173], off
	.p2align	3
	s_waitcnt vmcnt(8)
	s_waitcnt lgkmcnt(0)
	s_setprio 1
	s_barrier
	v_mfma_f32_16x16x32_bf16 v[60:63], v[128:131], v[184:187], v[60:63]
	v_mfma_f32_16x16x32_bf16 v[56:59], v[136:139], v[184:187], v[56:59]
	v_mfma_f32_16x16x32_bf16 v[44:47], v[128:131], v[192:195], v[44:47]
	v_mfma_f32_16x16x32_bf16 v[40:43], v[136:139], v[192:195], v[40:43]
	v_mfma_f32_16x16x32_bf16 v[28:31], v[128:131], v[202:205], v[28:31]
	v_mfma_f32_16x16x32_bf16 v[24:27], v[136:139], v[202:205], v[24:27]
	v_mfma_f32_16x16x32_bf16 v[12:15], v[128:131], v[210:213], v[12:15]
	v_mfma_f32_16x16x32_bf16 v[8:11], v[136:139], v[210:213], v[8:11]
	v_mfma_f32_16x16x32_bf16 v[60:63], v[132:135], v[188:191], v[60:63]
	v_mfma_f32_16x16x32_bf16 v[56:59], v[140:143], v[188:191], v[56:59]
	v_mfma_f32_16x16x32_bf16 v[44:47], v[132:135], v[196:199], v[44:47]
	v_mfma_f32_16x16x32_bf16 v[40:43], v[140:143], v[196:199], v[40:43]
	v_mfma_f32_16x16x32_bf16 v[28:31], v[132:135], v[206:209], v[28:31]
	v_mfma_f32_16x16x32_bf16 v[24:27], v[140:143], v[206:209], v[24:27]
	v_mfma_f32_16x16x32_bf16 v[12:15], v[132:135], v[214:217], v[12:15]
	v_mfma_f32_16x16x32_bf16 v[8:11], v[140:143], v[214:217], v[8:11]
	v_mfma_f32_16x16x32_bf16 v[52:55], v[160:163], v[184:187], v[52:55]
	v_mfma_f32_16x16x32_bf16 v[48:51], v[168:171], v[184:187], v[48:51]
	v_mfma_f32_16x16x32_bf16 v[36:39], v[160:163], v[192:195], v[36:39]
	v_mfma_f32_16x16x32_bf16 v[32:35], v[168:171], v[192:195], v[32:35]
	v_mfma_f32_16x16x32_bf16 v[20:23], v[160:163], v[202:205], v[20:23]
	v_mfma_f32_16x16x32_bf16 v[16:19], v[168:171], v[202:205], v[16:19]
	v_mfma_f32_16x16x32_bf16 v[4:7], v[160:163], v[210:213], v[4:7]
	v_mfma_f32_16x16x32_bf16 v[0:3], v[168:171], v[210:213], v[0:3]
	v_mfma_f32_16x16x32_bf16 v[52:55], v[164:167], v[188:191], v[52:55]
	v_mfma_f32_16x16x32_bf16 v[48:51], v[180:183], v[188:191], v[48:51]
	v_mfma_f32_16x16x32_bf16 v[36:39], v[164:167], v[196:199], v[36:39]
	v_mfma_f32_16x16x32_bf16 v[32:35], v[180:183], v[196:199], v[32:35]
	v_mfma_f32_16x16x32_bf16 v[20:23], v[164:167], v[206:209], v[20:23]
	v_mfma_f32_16x16x32_bf16 v[16:19], v[180:183], v[206:209], v[16:19]
	v_mfma_f32_16x16x32_bf16 v[4:7], v[164:167], v[214:217], v[4:7]
	v_mfma_f32_16x16x32_bf16 v[0:3], v[180:183], v[214:217], v[0:3]
	s_barrier
	s_setprio 0
	s_add_u32 s38, s38, 0x100
	s_addc_u32 s39, s39, 0
	s_add_u32 s85, s85, 0x100
	s_addc_u32 s86, s86, 0
	s_cmp_ge_i32 s87, s26
	s_mov_b32 s40, s87
	s_cbranch_scc0 .LBB7_327

.Lswi_nobar:
.Lpeel_357:
	s_add_i32 s86, s42, 2
	s_add_u32 s29, s16, 0xfffc0080
	s_addc_u32 s37, s17, -1
	s_add_i32 s74, 0, 0x10000
	s_cmp_eq_u32 s20, s42
	s_cselect_b32 s73, s9, s37
	s_cselect_b32 s72, s13, s29
	v_add_u32_e32 v170, s74, v179
	s_cselect_b32 s43, s28, s57
	s_cselect_b32 s42, s39, s56
	s_add_i32 s29, 0, 0x14000
	ds_read_b128 v[130:133], v170
	ds_read_b128 v[180:183], v170 offset:1024
	ds_read_b128 v[184:187], v170 offset:2048
	ds_read_b128 v[188:191], v170 offset:3072
	v_add_u32_e32 v170, s29, v179
	ds_read_b128 v[192:195], v170
	ds_read_b128 v[196:199], v170 offset:1024
	ds_read_b128 v[204:207], v170 offset:2048
	ds_read_b128 v[208:211], v170 offset:3072
	s_add_i32 m0, s4, 0xc000
	ds_read_b128 v[212:215], v143
	ds_read_b128 v[216:219], v143 offset:1024
	ds_read_b128 v[220:223], v143 offset:2048
	ds_read_b128 v[224:227], v143 offset:3072
	ds_read_b128 v[228:231], v143 offset:4096
	ds_read_b128 v[232:235], v143 offset:5120
	ds_read_b128 v[236:239], v143 offset:6144
	ds_read_b128 v[240:243], v143 offset:7168
	global_load_lds_dwordx4 v174, s[16:17]
	s_add_i32 m0, s4, 0xe000
	s_nop 0
	global_load_lds_dwordx4 v176, s[16:17]
	.p2align	3
	s_waitcnt vmcnt(8)
	s_waitcnt lgkmcnt(0)
	s_setprio 1
	s_barrier
	v_mfma_f32_16x16x32_bf16 v[126:129], v[130:133], v[212:215], 0
	v_mfma_f32_16x16x32_bf16 v[118:121], v[184:187], v[212:215], 0
	v_mfma_f32_16x16x32_bf16 v[110:113], v[130:133], v[220:223], 0
	v_mfma_f32_16x16x32_bf16 v[102:105], v[184:187], v[220:223], 0
	v_mfma_f32_16x16x32_bf16 v[94:97], v[130:133], v[228:231], 0
	v_mfma_f32_16x16x32_bf16 v[86:89], v[184:187], v[228:231], 0
	v_mfma_f32_16x16x32_bf16 v[78:81], v[130:133], v[236:239], 0
	v_mfma_f32_16x16x32_bf16 v[70:73], v[184:187], v[236:239], 0
	v_mfma_f32_16x16x32_bf16 v[126:129], v[180:183], v[216:219], v[126:129]
	v_mfma_f32_16x16x32_bf16 v[118:121], v[188:191], v[216:219], v[118:121]
	v_mfma_f32_16x16x32_bf16 v[110:113], v[180:183], v[224:227], v[110:113]
	v_mfma_f32_16x16x32_bf16 v[102:105], v[188:191], v[224:227], v[102:105]
	v_mfma_f32_16x16x32_bf16 v[94:97], v[180:183], v[232:235], v[94:97]
	v_mfma_f32_16x16x32_bf16 v[86:89], v[188:191], v[232:235], v[86:89]
	v_mfma_f32_16x16x32_bf16 v[78:81], v[180:183], v[240:243], v[78:81]
	v_mfma_f32_16x16x32_bf16 v[70:73], v[188:191], v[240:243], v[70:73]
	v_mfma_f32_16x16x32_bf16 v[122:125], v[192:195], v[212:215], 0
	v_mfma_f32_16x16x32_bf16 v[114:117], v[204:207], v[212:215], 0
	v_mfma_f32_16x16x32_bf16 v[106:109], v[192:195], v[220:223], 0
	v_mfma_f32_16x16x32_bf16 v[98:101], v[204:207], v[220:223], 0
	v_mfma_f32_16x16x32_bf16 v[90:93], v[192:195], v[228:231], 0
	v_mfma_f32_16x16x32_bf16 v[82:85], v[204:207], v[228:231], 0
	v_mfma_f32_16x16x32_bf16 v[74:77], v[192:195], v[236:239], 0
	v_mfma_f32_16x16x32_bf16 v[66:69], v[204:207], v[236:239], 0
	v_mfma_f32_16x16x32_bf16 v[122:125], v[196:199], v[216:219], v[122:125]
	v_mfma_f32_16x16x32_bf16 v[114:117], v[208:211], v[216:219], v[114:117]
	v_mfma_f32_16x16x32_bf16 v[106:109], v[196:199], v[224:227], v[106:109]
	v_mfma_f32_16x16x32_bf16 v[98:101], v[208:211], v[224:227], v[98:101]
	v_mfma_f32_16x16x32_bf16 v[90:93], v[196:199], v[232:235], v[90:93]
	v_mfma_f32_16x16x32_bf16 v[82:85], v[208:211], v[232:235], v[82:85]
	v_mfma_f32_16x16x32_bf16 v[74:77], v[196:199], v[240:243], v[74:77]
	v_mfma_f32_16x16x32_bf16 v[66:69], v[208:211], v[240:243], v[66:69]
	s_barrier
	s_setprio 0
	s_add_i32 s37, s74, s84
	v_lshl_add_u64 v[244:245], s[42:43], 0, v[138:139]
	s_mov_b32 m0, s37
	ds_read_b128 v[212:215], v143 offset:16384
	ds_read_b128 v[216:219], v143 offset:17408
	ds_read_b128 v[220:223], v143 offset:18432
	ds_read_b128 v[224:227], v143 offset:19456
	ds_read_b128 v[228:231], v143 offset:20480
	ds_read_b128 v[232:235], v143 offset:21504
	ds_read_b128 v[236:239], v143 offset:22528
	ds_read_b128 v[240:243], v143 offset:23552
	global_load_lds_dwordx4 v[244:245], off
	s_add_i32 m0, s37, 0x2000
	s_add_u32 s74, s42, 0x40000
	v_lshl_add_u64 v[246:247], s[42:43], 0, v[134:135]
	s_addc_u32 s75, s43, 0
	s_add_i32 s29, s29, s84
	global_load_lds_dwordx4 v[246:247], off
	s_mov_b32 m0, s29
	v_lshl_add_u64 v[170:171], s[72:73], 0, v[136:137]
	global_load_lds_dwordx4 v138, s[74:75]
	s_add_i32 m0, s29, 0x2000
	s_nop 0
	global_load_lds_dwordx4 v134, s[74:75]
	v_lshl_add_u64 v[248:249], s[72:73], 0, v[140:141]
	s_mov_b32 m0, s4
	s_nop 0
	global_load_lds_dwordx4 v[248:249], off
	s_mov_b32 m0, s5
	s_nop 0
	global_load_lds_dwordx4 v[170:171], off
	s_lshl_b32 s101, s38, 14
	s_add_i32 s101, s101, s84
	s_add_u32 s100, s66, s101
	s_addc_u32 s101, s67, 0
	v_lshlrev_b32_e32 v172, 4, v163
	v_add_u32_e32 v173, 0x2000, v172
	s_add_i32 m0, s84, 0x20000
	s_nop 0
	global_load_lds_dwordx4 v172, s[100:101]
	s_add_i32 m0, s84, 0x22000
	s_nop 0
	global_load_lds_dwordx4 v173, s[100:101]
	.p2align	3
	s_waitcnt vmcnt(8)
	s_waitcnt lgkmcnt(0)
	s_setprio 1
	s_barrier
	v_mfma_f32_16x16x32_bf16 v[62:65], v[130:133], v[212:215], 0
	v_mfma_f32_16x16x32_bf16 v[54:57], v[184:187], v[212:215], 0
	v_mfma_f32_16x16x32_bf16 v[46:49], v[130:133], v[220:223], 0
	v_mfma_f32_16x16x32_bf16 v[38:41], v[184:187], v[220:223], 0
	v_mfma_f32_16x16x32_bf16 v[30:33], v[130:133], v[228:231], 0
	v_mfma_f32_16x16x32_bf16 v[22:25], v[184:187], v[228:231], 0
	v_mfma_f32_16x16x32_bf16 v[14:17], v[130:133], v[236:239], 0
	v_mfma_f32_16x16x32_bf16 v[6:9], v[184:187], v[236:239], 0
	v_mfma_f32_16x16x32_bf16 v[62:65], v[180:183], v[216:219], v[62:65]
	v_mfma_f32_16x16x32_bf16 v[54:57], v[188:191], v[216:219], v[54:57]
	v_mfma_f32_16x16x32_bf16 v[46:49], v[180:183], v[224:227], v[46:49]
	v_mfma_f32_16x16x32_bf16 v[38:41], v[188:191], v[224:227], v[38:41]
	v_mfma_f32_16x16x32_bf16 v[30:33], v[180:183], v[232:235], v[30:33]
	v_mfma_f32_16x16x32_bf16 v[22:25], v[188:191], v[232:235], v[22:25]
	v_mfma_f32_16x16x32_bf16 v[14:17], v[180:183], v[240:243], v[14:17]
	v_mfma_f32_16x16x32_bf16 v[6:9], v[188:191], v[240:243], v[6:9]
	v_mfma_f32_16x16x32_bf16 v[58:61], v[192:195], v[212:215], 0
	v_mfma_f32_16x16x32_bf16 v[50:53], v[204:207], v[212:215], 0
	v_mfma_f32_16x16x32_bf16 v[42:45], v[192:195], v[220:223], 0
	v_mfma_f32_16x16x32_bf16 v[34:37], v[204:207], v[220:223], 0
	v_mfma_f32_16x16x32_bf16 v[26:29], v[192:195], v[228:231], 0
	v_mfma_f32_16x16x32_bf16 v[18:21], v[204:207], v[228:231], 0
	v_mfma_f32_16x16x32_bf16 v[10:13], v[192:195], v[236:239], 0
	v_mfma_f32_16x16x32_bf16 v[2:5], v[204:207], v[236:239], 0
	v_mfma_f32_16x16x32_bf16 v[58:61], v[196:199], v[216:219], v[58:61]
	v_mfma_f32_16x16x32_bf16 v[50:53], v[208:211], v[216:219], v[50:53]
	v_mfma_f32_16x16x32_bf16 v[42:45], v[196:199], v[224:227], v[42:45]
	v_mfma_f32_16x16x32_bf16 v[34:37], v[208:211], v[224:227], v[34:37]
	v_mfma_f32_16x16x32_bf16 v[26:29], v[196:199], v[232:235], v[26:29]
	v_mfma_f32_16x16x32_bf16 v[18:21], v[208:211], v[232:235], v[18:21]
	v_mfma_f32_16x16x32_bf16 v[10:13], v[196:199], v[240:243], v[10:13]
	v_mfma_f32_16x16x32_bf16 v[2:5], v[208:211], v[240:243], v[2:5]
	s_barrier
	s_setprio 0
	s_add_i32 s29, 0, 0x18000
	v_add_u32_e32 v172, s29, v179
	s_add_i32 s37, 0, 0x1c000
	ds_read_b128 v[130:133], v172
	ds_read_b128 v[180:183], v172 offset:1024
	ds_read_b128 v[184:187], v172 offset:2048
	ds_read_b128 v[188:191], v172 offset:3072
	v_add_u32_e32 v172, s37, v179
	ds_read_b128 v[192:195], v172
	ds_read_b128 v[196:199], v172 offset:1024
	ds_read_b128 v[204:207], v172 offset:2048
	ds_read_b128 v[208:211], v172 offset:3072
	s_add_u32 s72, s72, 0x40000
	s_addc_u32 s73, s73, 0
	s_mov_b32 m0, s93
	ds_read_b128 v[212:215], v143 offset:32768
	ds_read_b128 v[216:219], v143 offset:33792
	ds_read_b128 v[220:223], v143 offset:34816
	ds_read_b128 v[224:227], v143 offset:35840
	ds_read_b128 v[228:231], v143 offset:36864
	ds_read_b128 v[232:235], v143 offset:37888
	ds_read_b128 v[236:239], v143 offset:38912
	ds_read_b128 v[240:243], v143 offset:39936
	global_load_lds_dwordx4 v140, s[72:73]
	s_mov_b32 m0, s33
	s_nop 0
	global_load_lds_dwordx4 v136, s[72:73]
	.p2align	3
	s_waitcnt vmcnt(8)
	s_waitcnt lgkmcnt(0)
	s_setprio 1
	s_barrier
	v_mfma_f32_16x16x32_bf16 v[126:129], v[130:133], v[212:215], v[126:129]
	v_mfma_f32_16x16x32_bf16 v[118:121], v[184:187], v[212:215], v[118:121]
	v_mfma_f32_16x16x32_bf16 v[110:113], v[130:133], v[220:223], v[110:113]
	v_mfma_f32_16x16x32_bf16 v[102:105], v[184:187], v[220:223], v[102:105]
	v_mfma_f32_16x16x32_bf16 v[94:97], v[130:133], v[228:231], v[94:97]
	v_mfma_f32_16x16x32_bf16 v[86:89], v[184:187], v[228:231], v[86:89]
	v_mfma_f32_16x16x32_bf16 v[78:81], v[130:133], v[236:239], v[78:81]
	v_mfma_f32_16x16x32_bf16 v[70:73], v[184:187], v[236:239], v[70:73]
	v_mfma_f32_16x16x32_bf16 v[126:129], v[180:183], v[216:219], v[126:129]
	v_mfma_f32_16x16x32_bf16 v[118:121], v[188:191], v[216:219], v[118:121]
	v_mfma_f32_16x16x32_bf16 v[110:113], v[180:183], v[224:227], v[110:113]
	v_mfma_f32_16x16x32_bf16 v[102:105], v[188:191], v[224:227], v[102:105]
	v_mfma_f32_16x16x32_bf16 v[94:97], v[180:183], v[232:235], v[94:97]
	v_mfma_f32_16x16x32_bf16 v[86:89], v[188:191], v[232:235], v[86:89]
	v_mfma_f32_16x16x32_bf16 v[78:81], v[180:183], v[240:243], v[78:81]
	v_mfma_f32_16x16x32_bf16 v[70:73], v[188:191], v[240:243], v[70:73]
	v_mfma_f32_16x16x32_bf16 v[122:125], v[192:195], v[212:215], v[122:125]
	v_mfma_f32_16x16x32_bf16 v[114:117], v[204:207], v[212:215], v[114:117]
	v_mfma_f32_16x16x32_bf16 v[106:109], v[192:195], v[220:223], v[106:109]
	v_mfma_f32_16x16x32_bf16 v[98:101], v[204:207], v[220:223], v[98:101]
	v_mfma_f32_16x16x32_bf16 v[90:93], v[192:195], v[228:231], v[90:93]
	v_mfma_f32_16x16x32_bf16 v[82:85], v[204:207], v[228:231], v[82:85]
	v_mfma_f32_16x16x32_bf16 v[74:77], v[192:195], v[236:239], v[74:77]
	v_mfma_f32_16x16x32_bf16 v[66:69], v[204:207], v[236:239], v[66:69]
	v_mfma_f32_16x16x32_bf16 v[122:125], v[196:199], v[216:219], v[122:125]
	v_mfma_f32_16x16x32_bf16 v[114:117], v[208:211], v[216:219], v[114:117]
	v_mfma_f32_16x16x32_bf16 v[106:109], v[196:199], v[224:227], v[106:109]
	v_mfma_f32_16x16x32_bf16 v[98:101], v[208:211], v[224:227], v[98:101]
	v_mfma_f32_16x16x32_bf16 v[90:93], v[196:199], v[232:235], v[90:93]
	v_mfma_f32_16x16x32_bf16 v[82:85], v[208:211], v[232:235], v[82:85]
	v_mfma_f32_16x16x32_bf16 v[74:77], v[196:199], v[240:243], v[74:77]
	v_mfma_f32_16x16x32_bf16 v[66:69], v[208:211], v[240:243], v[66:69]
	s_barrier
	s_setprio 0
	s_add_i32 s29, s29, s84
	v_lshl_add_u64 v[172:173], v[244:245], 0, s[24:25]
	s_mov_b32 m0, s29
	ds_read_b128 v[212:215], v143 offset:49152
	ds_read_b128 v[216:219], v143 offset:50176
	ds_read_b128 v[220:223], v143 offset:51200
	ds_read_b128 v[224:227], v143 offset:52224
	ds_read_b128 v[228:231], v143 offset:53248
	ds_read_b128 v[232:235], v143 offset:54272
	ds_read_b128 v[236:239], v143 offset:55296
	ds_read_b128 v[240:243], v143 offset:56320
	global_load_lds_dwordx4 v[172:173], off
	s_add_i32 m0, s29, 0x2000
	s_add_u32 s42, s42, 0x40080
	v_lshl_add_u64 v[172:173], v[246:247], 0, s[24:25]
	s_addc_u32 s43, s43, 0
	s_add_i32 s29, s37, s84
	global_load_lds_dwordx4 v[172:173], off
	s_mov_b32 m0, s29
	v_lshl_add_u64 v[170:171], v[170:171], 0, s[24:25]
	global_load_lds_dwordx4 v138, s[42:43]
	s_add_i32 m0, s29, 0x2000
	s_nop 0
	global_load_lds_dwordx4 v134, s[42:43]
	v_lshl_add_u64 v[172:173], v[248:249], 0, s[24:25]
	s_mov_b32 m0, s97
	s_nop 0
	global_load_lds_dwordx4 v[172:173], off
	s_mov_b32 m0, s3
	s_nop 0
	global_load_lds_dwordx4 v[170:171], off
	.p2align	3
	s_waitcnt vmcnt(8)
	s_waitcnt lgkmcnt(0)
	s_setprio 1
	s_barrier
	v_mfma_f32_16x16x32_bf16 v[62:65], v[130:133], v[212:215], v[62:65]
	v_mfma_f32_16x16x32_bf16 v[54:57], v[184:187], v[212:215], v[54:57]
	v_mfma_f32_16x16x32_bf16 v[46:49], v[130:133], v[220:223], v[46:49]
	v_mfma_f32_16x16x32_bf16 v[38:41], v[184:187], v[220:223], v[38:41]
	v_mfma_f32_16x16x32_bf16 v[30:33], v[130:133], v[228:231], v[30:33]
	v_mfma_f32_16x16x32_bf16 v[22:25], v[184:187], v[228:231], v[22:25]
	v_mfma_f32_16x16x32_bf16 v[14:17], v[130:133], v[236:239], v[14:17]
	v_mfma_f32_16x16x32_bf16 v[6:9], v[184:187], v[236:239], v[6:9]
	v_mfma_f32_16x16x32_bf16 v[62:65], v[180:183], v[216:219], v[62:65]
	v_mfma_f32_16x16x32_bf16 v[54:57], v[188:191], v[216:219], v[54:57]
	v_mfma_f32_16x16x32_bf16 v[46:49], v[180:183], v[224:227], v[46:49]
	v_mfma_f32_16x16x32_bf16 v[38:41], v[188:191], v[224:227], v[38:41]
	v_mfma_f32_16x16x32_bf16 v[30:33], v[180:183], v[232:235], v[30:33]
	v_mfma_f32_16x16x32_bf16 v[22:25], v[188:191], v[232:235], v[22:25]
	v_mfma_f32_16x16x32_bf16 v[14:17], v[180:183], v[240:243], v[14:17]
	v_mfma_f32_16x16x32_bf16 v[6:9], v[188:191], v[240:243], v[6:9]
	v_mfma_f32_16x16x32_bf16 v[58:61], v[192:195], v[212:215], v[58:61]
	v_mfma_f32_16x16x32_bf16 v[50:53], v[204:207], v[212:215], v[50:53]
	v_mfma_f32_16x16x32_bf16 v[42:45], v[192:195], v[220:223], v[42:45]
	v_mfma_f32_16x16x32_bf16 v[34:37], v[204:207], v[220:223], v[34:37]
	v_mfma_f32_16x16x32_bf16 v[26:29], v[192:195], v[228:231], v[26:29]
	v_mfma_f32_16x16x32_bf16 v[18:21], v[204:207], v[228:231], v[18:21]
	v_mfma_f32_16x16x32_bf16 v[10:13], v[192:195], v[236:239], v[10:13]
	v_mfma_f32_16x16x32_bf16 v[2:5], v[204:207], v[236:239], v[2:5]
	v_mfma_f32_16x16x32_bf16 v[58:61], v[196:199], v[216:219], v[58:61]
	v_mfma_f32_16x16x32_bf16 v[50:53], v[208:211], v[216:219], v[50:53]
	v_mfma_f32_16x16x32_bf16 v[42:45], v[196:199], v[224:227], v[42:45]
	v_mfma_f32_16x16x32_bf16 v[34:37], v[208:211], v[224:227], v[34:37]
	v_mfma_f32_16x16x32_bf16 v[26:29], v[196:199], v[232:235], v[26:29]
	v_mfma_f32_16x16x32_bf16 v[18:21], v[208:211], v[232:235], v[18:21]
	v_mfma_f32_16x16x32_bf16 v[10:13], v[196:199], v[240:243], v[10:13]
	v_mfma_f32_16x16x32_bf16 v[2:5], v[208:211], v[240:243], v[2:5]
	s_barrier
	s_setprio 0
	s_lshl_b32 s100, s84, 1
	v_lshl_add_u32 v204, v163, 5, s100
	v_add_u32_e32 v204, 0x20000, v204
	ds_read_b128 v[208:211], v204
	ds_read_b128 v[212:215], v204 offset:16
	s_waitcnt lgkmcnt(0)
	v_add_f32_e32 v208, v208, v209
	v_add_f32_e32 v210, v210, v211
	v_add_f32_e32 v212, v212, v213
	v_add_f32_e32 v214, v214, v215
	v_add_f32_e32 v208, v208, v210
	v_add_f32_e32 v212, v212, v214
	v_add_f32_e32 v208, v208, v212
	v_mov_b32_e32 v209, 0x358637bd
	s_nop 0
	v_add_f32_dpp v208, v208, v208 quad_perm:[1,0,3,2] row_mask:0xf bank_mask:0xf
	v_fmamk_f32 v208, v208, 0x3a800000, v209
	v_rsq_f32_e32 v209, v208
	s_nop 0
	v_mul_f32_e32 v209, 0xbfb8aa3b, v209
	ds_write_b64 v204, v[208:209]
	s_add_u32 s16, s16, 0x100
	s_addc_u32 s17, s17, 0
	s_add_u32 s56, s56, 0x100
	s_addc_u32 s57, s57, 0
	s_cmp_ge_i32 s86, s23
	s_mov_b32 s42, s86
	s_cbranch_scc0 .LBB7_357
	s_branch .Lpeelx_357
	.p2align	6
.LBB7_357:
	s_add_i32 s86, s42, 2
	s_add_u32 s29, s16, 0xfffc0080
	s_addc_u32 s37, s17, -1
	s_add_i32 s74, 0, 0x10000
	s_cmp_eq_u32 s20, s42
	s_cselect_b32 s73, s9, s37
	s_cselect_b32 s72, s13, s29
	v_add_u32_e32 v170, s74, v179
	s_cselect_b32 s43, s28, s57
	s_cselect_b32 s42, s39, s56
	s_add_i32 s29, 0, 0x14000
	ds_read_b128 v[130:133], v170
	ds_read_b128 v[180:183], v170 offset:1024
	ds_read_b128 v[184:187], v170 offset:2048
	ds_read_b128 v[188:191], v170 offset:3072
	v_add_u32_e32 v170, s29, v179
	ds_read_b128 v[192:195], v170
	ds_read_b128 v[196:199], v170 offset:1024
	ds_read_b128 v[204:207], v170 offset:2048
	ds_read_b128 v[208:211], v170 offset:3072
	s_add_i32 m0, s4, 0xc000
	ds_read_b128 v[212:215], v143
	ds_read_b128 v[216:219], v143 offset:1024
	ds_read_b128 v[220:223], v143 offset:2048
	ds_read_b128 v[224:227], v143 offset:3072
	ds_read_b128 v[228:231], v143 offset:4096
	ds_read_b128 v[232:235], v143 offset:5120
	ds_read_b128 v[236:239], v143 offset:6144
	ds_read_b128 v[240:243], v143 offset:7168
	global_load_lds_dwordx4 v174, s[16:17]
	s_add_i32 m0, s4, 0xe000
	s_nop 0
	global_load_lds_dwordx4 v176, s[16:17]
	.p2align	3
	s_waitcnt vmcnt(8)
	s_waitcnt lgkmcnt(0)
	s_setprio 1
	s_barrier
	v_mfma_f32_16x16x32_bf16 v[126:129], v[130:133], v[212:215], v[126:129]
	v_mfma_f32_16x16x32_bf16 v[118:121], v[184:187], v[212:215], v[118:121]
	v_mfma_f32_16x16x32_bf16 v[110:113], v[130:133], v[220:223], v[110:113]
	v_mfma_f32_16x16x32_bf16 v[102:105], v[184:187], v[220:223], v[102:105]
	v_mfma_f32_16x16x32_bf16 v[94:97], v[130:133], v[228:231], v[94:97]
	v_mfma_f32_16x16x32_bf16 v[86:89], v[184:187], v[228:231], v[86:89]
	v_mfma_f32_16x16x32_bf16 v[78:81], v[130:133], v[236:239], v[78:81]
	v_mfma_f32_16x16x32_bf16 v[70:73], v[184:187], v[236:239], v[70:73]
	v_mfma_f32_16x16x32_bf16 v[126:129], v[180:183], v[216:219], v[126:129]
	v_mfma_f32_16x16x32_bf16 v[118:121], v[188:191], v[216:219], v[118:121]
	v_mfma_f32_16x16x32_bf16 v[110:113], v[180:183], v[224:227], v[110:113]
	v_mfma_f32_16x16x32_bf16 v[102:105], v[188:191], v[224:227], v[102:105]
	v_mfma_f32_16x16x32_bf16 v[94:97], v[180:183], v[232:235], v[94:97]
	v_mfma_f32_16x16x32_bf16 v[86:89], v[188:191], v[232:235], v[86:89]
	v_mfma_f32_16x16x32_bf16 v[78:81], v[180:183], v[240:243], v[78:81]
	v_mfma_f32_16x16x32_bf16 v[70:73], v[188:191], v[240:243], v[70:73]
	v_mfma_f32_16x16x32_bf16 v[122:125], v[192:195], v[212:215], v[122:125]
	v_mfma_f32_16x16x32_bf16 v[114:117], v[204:207], v[212:215], v[114:117]
	v_mfma_f32_16x16x32_bf16 v[106:109], v[192:195], v[220:223], v[106:109]
	v_mfma_f32_16x16x32_bf16 v[98:101], v[204:207], v[220:223], v[98:101]
	v_mfma_f32_16x16x32_bf16 v[90:93], v[192:195], v[228:231], v[90:93]
	v_mfma_f32_16x16x32_bf16 v[82:85], v[204:207], v[228:231], v[82:85]
	v_mfma_f32_16x16x32_bf16 v[74:77], v[192:195], v[236:239], v[74:77]
	v_mfma_f32_16x16x32_bf16 v[66:69], v[204:207], v[236:239], v[66:69]
	v_mfma_f32_16x16x32_bf16 v[122:125], v[196:199], v[216:219], v[122:125]
	v_mfma_f32_16x16x32_bf16 v[114:117], v[208:211], v[216:219], v[114:117]
	v_mfma_f32_16x16x32_bf16 v[106:109], v[196:199], v[224:227], v[106:109]
	v_mfma_f32_16x16x32_bf16 v[98:101], v[208:211], v[224:227], v[98:101]
	v_mfma_f32_16x16x32_bf16 v[90:93], v[196:199], v[232:235], v[90:93]
	v_mfma_f32_16x16x32_bf16 v[82:85], v[208:211], v[232:235], v[82:85]
	v_mfma_f32_16x16x32_bf16 v[74:77], v[196:199], v[240:243], v[74:77]
	v_mfma_f32_16x16x32_bf16 v[66:69], v[208:211], v[240:243], v[66:69]
	s_barrier
	s_setprio 0
	s_add_i32 s37, s74, s84
	v_lshl_add_u64 v[244:245], s[42:43], 0, v[138:139]
	s_mov_b32 m0, s37
	ds_read_b128 v[212:215], v143 offset:16384
	ds_read_b128 v[216:219], v143 offset:17408
	ds_read_b128 v[220:223], v143 offset:18432
	ds_read_b128 v[224:227], v143 offset:19456
	ds_read_b128 v[228:231], v143 offset:20480
	ds_read_b128 v[232:235], v143 offset:21504
	ds_read_b128 v[236:239], v143 offset:22528
	ds_read_b128 v[240:243], v143 offset:23552
	global_load_lds_dwordx4 v[244:245], off
	s_add_i32 m0, s37, 0x2000
	s_add_u32 s74, s42, 0x40000
	v_lshl_add_u64 v[246:247], s[42:43], 0, v[134:135]
	s_addc_u32 s75, s43, 0
	s_add_i32 s29, s29, s84
	global_load_lds_dwordx4 v[246:247], off
	s_mov_b32 m0, s29
	v_lshl_add_u64 v[170:171], s[72:73], 0, v[136:137]
	global_load_lds_dwordx4 v138, s[74:75]
	s_add_i32 m0, s29, 0x2000
	s_nop 0
	global_load_lds_dwordx4 v134, s[74:75]
	v_lshl_add_u64 v[248:249], s[72:73], 0, v[140:141]
	s_mov_b32 m0, s4
	s_nop 0
	global_load_lds_dwordx4 v[248:249], off
	s_mov_b32 m0, s5
	s_nop 0
	global_load_lds_dwordx4 v[170:171], off
	.p2align	3
	s_waitcnt vmcnt(8)
	s_waitcnt lgkmcnt(0)
	s_setprio 1
	s_barrier
	v_mfma_f32_16x16x32_bf16 v[62:65], v[130:133], v[212:215], v[62:65]
	v_mfma_f32_16x16x32_bf16 v[54:57], v[184:187], v[212:215], v[54:57]
	v_mfma_f32_16x16x32_bf16 v[46:49], v[130:133], v[220:223], v[46:49]
	v_mfma_f32_16x16x32_bf16 v[38:41], v[184:187], v[220:223], v[38:41]
	v_mfma_f32_16x16x32_bf16 v[30:33], v[130:133], v[228:231], v[30:33]
	v_mfma_f32_16x16x32_bf16 v[22:25], v[184:187], v[228:231], v[22:25]
	v_mfma_f32_16x16x32_bf16 v[14:17], v[130:133], v[236:239], v[14:17]
	v_mfma_f32_16x16x32_bf16 v[6:9], v[184:187], v[236:239], v[6:9]
	v_mfma_f32_16x16x32_bf16 v[62:65], v[180:183], v[216:219], v[62:65]
	v_mfma_f32_16x16x32_bf16 v[54:57], v[188:191], v[216:219], v[54:57]
	v_mfma_f32_16x16x32_bf16 v[46:49], v[180:183], v[224:227], v[46:49]
	v_mfma_f32_16x16x32_bf16 v[38:41], v[188:191], v[224:227], v[38:41]
	v_mfma_f32_16x16x32_bf16 v[30:33], v[180:183], v[232:235], v[30:33]
	v_mfma_f32_16x16x32_bf16 v[22:25], v[188:191], v[232:235], v[22:25]
	v_mfma_f32_16x16x32_bf16 v[14:17], v[180:183], v[240:243], v[14:17]
	v_mfma_f32_16x16x32_bf16 v[6:9], v[188:191], v[240:243], v[6:9]
	v_mfma_f32_16x16x32_bf16 v[58:61], v[192:195], v[212:215], v[58:61]
	v_mfma_f32_16x16x32_bf16 v[50:53], v[204:207], v[212:215], v[50:53]
	v_mfma_f32_16x16x32_bf16 v[42:45], v[192:195], v[220:223], v[42:45]
	v_mfma_f32_16x16x32_bf16 v[34:37], v[204:207], v[220:223], v[34:37]
	v_mfma_f32_16x16x32_bf16 v[26:29], v[192:195], v[228:231], v[26:29]
	v_mfma_f32_16x16x32_bf16 v[18:21], v[204:207], v[228:231], v[18:21]
	v_mfma_f32_16x16x32_bf16 v[10:13], v[192:195], v[236:239], v[10:13]
	v_mfma_f32_16x16x32_bf16 v[2:5], v[204:207], v[236:239], v[2:5]
	v_mfma_f32_16x16x32_bf16 v[58:61], v[196:199], v[216:219], v[58:61]
	v_mfma_f32_16x16x32_bf16 v[50:53], v[208:211], v[216:219], v[50:53]
	v_mfma_f32_16x16x32_bf16 v[42:45], v[196:199], v[224:227], v[42:45]
	v_mfma_f32_16x16x32_bf16 v[34:37], v[208:211], v[224:227], v[34:37]
	v_mfma_f32_16x16x32_bf16 v[26:29], v[196:199], v[232:235], v[26:29]
	v_mfma_f32_16x16x32_bf16 v[18:21], v[208:211], v[232:235], v[18:21]
	v_mfma_f32_16x16x32_bf16 v[10:13], v[196:199], v[240:243], v[10:13]
	v_mfma_f32_16x16x32_bf16 v[2:5], v[208:211], v[240:243], v[2:5]
	s_barrier
	s_setprio 0
	s_add_i32 s29, 0, 0x18000
	v_add_u32_e32 v172, s29, v179
	s_add_i32 s37, 0, 0x1c000
	ds_read_b128 v[130:133], v172
	ds_read_b128 v[180:183], v172 offset:1024
	ds_read_b128 v[184:187], v172 offset:2048
	ds_read_b128 v[188:191], v172 offset:3072
	v_add_u32_e32 v172, s37, v179
	ds_read_b128 v[192:195], v172
	ds_read_b128 v[196:199], v172 offset:1024
	ds_read_b128 v[204:207], v172 offset:2048
	ds_read_b128 v[208:211], v172 offset:3072
	s_add_u32 s72, s72, 0x40000
	s_addc_u32 s73, s73, 0
	s_mov_b32 m0, s93
	ds_read_b128 v[212:215], v143 offset:32768
	ds_read_b128 v[216:219], v143 offset:33792
	ds_read_b128 v[220:223], v143 offset:34816
	ds_read_b128 v[224:227], v143 offset:35840
	ds_read_b128 v[228:231], v143 offset:36864
	ds_read_b128 v[232:235], v143 offset:37888
	ds_read_b128 v[236:239], v143 offset:38912
	ds_read_b128 v[240:243], v143 offset:39936
	global_load_lds_dwordx4 v140, s[72:73]
	s_mov_b32 m0, s33
	s_nop 0
	global_load_lds_dwordx4 v136, s[72:73]
	.p2align	3
	s_waitcnt vmcnt(8)
	s_waitcnt lgkmcnt(0)
	s_setprio 1
	s_barrier
	v_mfma_f32_16x16x32_bf16 v[126:129], v[130:133], v[212:215], v[126:129]
	v_mfma_f32_16x16x32_bf16 v[118:121], v[184:187], v[212:215], v[118:121]
	v_mfma_f32_16x16x32_bf16 v[110:113], v[130:133], v[220:223], v[110:113]
	v_mfma_f32_16x16x32_bf16 v[102:105], v[184:187], v[220:223], v[102:105]
	v_mfma_f32_16x16x32_bf16 v[94:97], v[130:133], v[228:231], v[94:97]
	v_mfma_f32_16x16x32_bf16 v[86:89], v[184:187], v[228:231], v[86:89]
	v_mfma_f32_16x16x32_bf16 v[78:81], v[130:133], v[236:239], v[78:81]
	v_mfma_f32_16x16x32_bf16 v[70:73], v[184:187], v[236:239], v[70:73]
	v_mfma_f32_16x16x32_bf16 v[126:129], v[180:183], v[216:219], v[126:129]
	v_mfma_f32_16x16x32_bf16 v[118:121], v[188:191], v[216:219], v[118:121]
	v_mfma_f32_16x16x32_bf16 v[110:113], v[180:183], v[224:227], v[110:113]
	v_mfma_f32_16x16x32_bf16 v[102:105], v[188:191], v[224:227], v[102:105]
	v_mfma_f32_16x16x32_bf16 v[94:97], v[180:183], v[232:235], v[94:97]
	v_mfma_f32_16x16x32_bf16 v[86:89], v[188:191], v[232:235], v[86:89]
	v_mfma_f32_16x16x32_bf16 v[78:81], v[180:183], v[240:243], v[78:81]
	v_mfma_f32_16x16x32_bf16 v[70:73], v[188:191], v[240:243], v[70:73]
	v_mfma_f32_16x16x32_bf16 v[122:125], v[192:195], v[212:215], v[122:125]
	v_mfma_f32_16x16x32_bf16 v[114:117], v[204:207], v[212:215], v[114:117]
	v_mfma_f32_16x16x32_bf16 v[106:109], v[192:195], v[220:223], v[106:109]
	v_mfma_f32_16x16x32_bf16 v[98:101], v[204:207], v[220:223], v[98:101]
	v_mfma_f32_16x16x32_bf16 v[90:93], v[192:195], v[228:231], v[90:93]
	v_mfma_f32_16x16x32_bf16 v[82:85], v[204:207], v[228:231], v[82:85]
	v_mfma_f32_16x16x32_bf16 v[74:77], v[192:195], v[236:239], v[74:77]
	v_mfma_f32_16x16x32_bf16 v[66:69], v[204:207], v[236:239], v[66:69]
	v_mfma_f32_16x16x32_bf16 v[122:125], v[196:199], v[216:219], v[122:125]
	v_mfma_f32_16x16x32_bf16 v[114:117], v[208:211], v[216:219], v[114:117]
	v_mfma_f32_16x16x32_bf16 v[106:109], v[196:199], v[224:227], v[106:109]
	v_mfma_f32_16x16x32_bf16 v[98:101], v[208:211], v[224:227], v[98:101]
	v_mfma_f32_16x16x32_bf16 v[90:93], v[196:199], v[232:235], v[90:93]
	v_mfma_f32_16x16x32_bf16 v[82:85], v[208:211], v[232:235], v[82:85]
	v_mfma_f32_16x16x32_bf16 v[74:77], v[196:199], v[240:243], v[74:77]
	v_mfma_f32_16x16x32_bf16 v[66:69], v[208:211], v[240:243], v[66:69]
	s_barrier
	s_setprio 0
	s_add_i32 s29, s29, s84
	v_lshl_add_u64 v[172:173], v[244:245], 0, s[24:25]
	s_mov_b32 m0, s29
	ds_read_b128 v[212:215], v143 offset:49152
	ds_read_b128 v[216:219], v143 offset:50176
	ds_read_b128 v[220:223], v143 offset:51200
	ds_read_b128 v[224:227], v143 offset:52224
	ds_read_b128 v[228:231], v143 offset:53248
	ds_read_b128 v[232:235], v143 offset:54272
	ds_read_b128 v[236:239], v143 offset:55296
	ds_read_b128 v[240:243], v143 offset:56320
	global_load_lds_dwordx4 v[172:173], off
	s_add_i32 m0, s29, 0x2000
	s_add_u32 s42, s42, 0x40080
	v_lshl_add_u64 v[172:173], v[246:247], 0, s[24:25]
	s_addc_u32 s43, s43, 0
	s_add_i32 s29, s37, s84
	global_load_lds_dwordx4 v[172:173], off
	s_mov_b32 m0, s29
	v_lshl_add_u64 v[170:171], v[170:171], 0, s[24:25]
	global_load_lds_dwordx4 v138, s[42:43]
	s_add_i32 m0, s29, 0x2000
	s_nop 0
	global_load_lds_dwordx4 v134, s[42:43]
	v_lshl_add_u64 v[172:173], v[248:249], 0, s[24:25]
	s_mov_b32 m0, s97
	s_nop 0
	global_load_lds_dwordx4 v[172:173], off
	s_mov_b32 m0, s3
	s_nop 0
	global_load_lds_dwordx4 v[170:171], off
	.p2align	3
	s_waitcnt vmcnt(8)
	s_waitcnt lgkmcnt(0)
	s_setprio 1
	s_barrier
	v_mfma_f32_16x16x32_bf16 v[62:65], v[130:133], v[212:215], v[62:65]
	v_mfma_f32_16x16x32_bf16 v[54:57], v[184:187], v[212:215], v[54:57]
	v_mfma_f32_16x16x32_bf16 v[46:49], v[130:133], v[220:223], v[46:49]
	v_mfma_f32_16x16x32_bf16 v[38:41], v[184:187], v[220:223], v[38:41]
	v_mfma_f32_16x16x32_bf16 v[30:33], v[130:133], v[228:231], v[30:33]
	v_mfma_f32_16x16x32_bf16 v[22:25], v[184:187], v[228:231], v[22:25]
	v_mfma_f32_16x16x32_bf16 v[14:17], v[130:133], v[236:239], v[14:17]
	v_mfma_f32_16x16x32_bf16 v[6:9], v[184:187], v[236:239], v[6:9]
	v_mfma_f32_16x16x32_bf16 v[62:65], v[180:183], v[216:219], v[62:65]
	v_mfma_f32_16x16x32_bf16 v[54:57], v[188:191], v[216:219], v[54:57]
	v_mfma_f32_16x16x32_bf16 v[46:49], v[180:183], v[224:227], v[46:49]
	v_mfma_f32_16x16x32_bf16 v[38:41], v[188:191], v[224:227], v[38:41]
	v_mfma_f32_16x16x32_bf16 v[30:33], v[180:183], v[232:235], v[30:33]
	v_mfma_f32_16x16x32_bf16 v[22:25], v[188:191], v[232:235], v[22:25]
	v_mfma_f32_16x16x32_bf16 v[14:17], v[180:183], v[240:243], v[14:17]
	v_mfma_f32_16x16x32_bf16 v[6:9], v[188:191], v[240:243], v[6:9]
	v_mfma_f32_16x16x32_bf16 v[58:61], v[192:195], v[212:215], v[58:61]
	v_mfma_f32_16x16x32_bf16 v[50:53], v[204:207], v[212:215], v[50:53]
	v_mfma_f32_16x16x32_bf16 v[42:45], v[192:195], v[220:223], v[42:45]
	v_mfma_f32_16x16x32_bf16 v[34:37], v[204:207], v[220:223], v[34:37]
	v_mfma_f32_16x16x32_bf16 v[26:29], v[192:195], v[228:231], v[26:29]
	v_mfma_f32_16x16x32_bf16 v[18:21], v[204:207], v[228:231], v[18:21]
	v_mfma_f32_16x16x32_bf16 v[10:13], v[192:195], v[236:239], v[10:13]
	v_mfma_f32_16x16x32_bf16 v[2:5], v[204:207], v[236:239], v[2:5]
	v_mfma_f32_16x16x32_bf16 v[58:61], v[196:199], v[216:219], v[58:61]
	v_mfma_f32_16x16x32_bf16 v[50:53], v[208:211], v[216:219], v[50:53]
	v_mfma_f32_16x16x32_bf16 v[42:45], v[196:199], v[224:227], v[42:45]
	v_mfma_f32_16x16x32_bf16 v[34:37], v[208:211], v[224:227], v[34:37]
	v_mfma_f32_16x16x32_bf16 v[26:29], v[196:199], v[232:235], v[26:29]
	v_mfma_f32_16x16x32_bf16 v[18:21], v[208:211], v[232:235], v[18:21]
	v_mfma_f32_16x16x32_bf16 v[10:13], v[196:199], v[240:243], v[10:13]
	v_mfma_f32_16x16x32_bf16 v[2:5], v[208:211], v[240:243], v[2:5]
	s_barrier
	s_setprio 0
	s_add_u32 s16, s16, 0x100
	s_addc_u32 s17, s17, 0
	s_add_u32 s56, s56, 0x100
	s_addc_u32 s57, s57, 0
	s_cmp_ge_i32 s86, s23
	s_mov_b32 s42, s86
	s_cbranch_scc0 .LBB7_357

.Lpeel_434:
	s_add_i32 s75, s72, 2
	s_add_u32 s76, s16, 0x4000
	s_addc_u32 s73, s17, 0
	s_cmp_eq_u32 s3, s72
	s_cselect_b32 s72, s86, s76
	s_cselect_b32 s73, s20, s73
	s_cselect_b32 s84, s37, s29
	s_cselect_b32 s85, s87, s74
	s_add_u32 vcc_lo, s72, 0x8000
	s_addc_u32 vcc_hi, s73, 0
	s_add_i32 s76, 0, 0x10000
	v_add_u32_e32 v0, s76, v205
	s_add_i32 s91, 0, 0x14000
	ds_read_b128 v[132:135], v0
	ds_read_b128 v[136:139], v0 offset:1024
	ds_read_b128 v[140:143], v0 offset:2048
	ds_read_b128 v[144:147], v0 offset:3072
	v_add_u32_e32 v0, s91, v205
	ds_read_b128 v[148:151], v0
	ds_read_b128 v[152:155], v0 offset:1024
	ds_read_b128 v[156:159], v0 offset:2048
	ds_read_b128 v[184:187], v0 offset:3072
	s_waitcnt lgkmcnt(0)
	s_add_i32 m0, s23, 0xc000
	ds_read_b128 v[188:191], v207
	ds_read_b128 v[192:195], v207 offset:1024
	ds_read_b128 v[196:199], v207 offset:2048
	ds_read_b128 v[208:211], v207 offset:3072
	ds_read_b128 v[212:215], v207 offset:4096
	ds_read_b128 v[216:219], v207 offset:5120
	ds_read_b128 v[220:223], v207 offset:6144
	ds_read_b128 v[224:227], v207 offset:7168
	global_load_lds_dwordx4 v180, s[16:17]
	s_add_i32 m0, s23, 0xe000
	s_nop 0
	global_load_lds_dwordx4 v182, s[16:17]
	.p2align	3
	s_waitcnt vmcnt(8)
	s_waitcnt lgkmcnt(0)
	s_setprio 1
	s_barrier
	v_mfma_f32_16x16x32_bf16 v[128:131], v[132:135], v[188:191], 0
	v_mfma_f32_16x16x32_bf16 v[124:127], v[140:143], v[188:191], 0
	v_mfma_f32_16x16x32_bf16 v[120:123], v[132:135], v[196:199], 0
	v_mfma_f32_16x16x32_bf16 v[116:119], v[140:143], v[196:199], 0
	v_mfma_f32_16x16x32_bf16 v[112:115], v[132:135], v[212:215], 0
	v_mfma_f32_16x16x32_bf16 v[108:111], v[140:143], v[212:215], 0
	v_mfma_f32_16x16x32_bf16 v[104:107], v[132:135], v[220:223], 0
	v_mfma_f32_16x16x32_bf16 v[100:103], v[140:143], v[220:223], 0
	v_mfma_f32_16x16x32_bf16 v[128:131], v[136:139], v[192:195], v[128:131]
	v_mfma_f32_16x16x32_bf16 v[124:127], v[144:147], v[192:195], v[124:127]
	v_mfma_f32_16x16x32_bf16 v[120:123], v[136:139], v[208:211], v[120:123]
	v_mfma_f32_16x16x32_bf16 v[116:119], v[144:147], v[208:211], v[116:119]
	v_mfma_f32_16x16x32_bf16 v[112:115], v[136:139], v[216:219], v[112:115]
	v_mfma_f32_16x16x32_bf16 v[108:111], v[144:147], v[216:219], v[108:111]
	v_mfma_f32_16x16x32_bf16 v[104:107], v[136:139], v[224:227], v[104:107]
	v_mfma_f32_16x16x32_bf16 v[100:103], v[144:147], v[224:227], v[100:103]
	v_mfma_f32_16x16x32_bf16 v[96:99], v[148:151], v[188:191], 0
	v_mfma_f32_16x16x32_bf16 v[92:95], v[156:159], v[188:191], 0
	v_mfma_f32_16x16x32_bf16 v[88:91], v[148:151], v[196:199], 0
	v_mfma_f32_16x16x32_bf16 v[84:87], v[156:159], v[196:199], 0
	v_mfma_f32_16x16x32_bf16 v[80:83], v[148:151], v[212:215], 0
	v_mfma_f32_16x16x32_bf16 v[76:79], v[156:159], v[212:215], 0
	v_mfma_f32_16x16x32_bf16 v[72:75], v[148:151], v[220:223], 0
	v_mfma_f32_16x16x32_bf16 v[64:67], v[156:159], v[220:223], 0
	v_mfma_f32_16x16x32_bf16 v[96:99], v[152:155], v[192:195], v[96:99]
	v_mfma_f32_16x16x32_bf16 v[92:95], v[184:187], v[192:195], v[92:95]
	v_mfma_f32_16x16x32_bf16 v[88:91], v[152:155], v[208:211], v[88:91]
	v_mfma_f32_16x16x32_bf16 v[84:87], v[184:187], v[208:211], v[84:87]
	v_mfma_f32_16x16x32_bf16 v[80:83], v[152:155], v[216:219], v[80:83]
	v_mfma_f32_16x16x32_bf16 v[76:79], v[184:187], v[216:219], v[76:79]
	v_mfma_f32_16x16x32_bf16 v[72:75], v[152:155], v[224:227], v[72:75]
	v_mfma_f32_16x16x32_bf16 v[64:67], v[184:187], v[224:227], v[64:67]
	s_barrier
	s_setprio 0
	s_add_i32 s76, s76, s4
	s_mov_b32 m0, s76
	ds_read_b128 v[188:191], v207 offset:16384
	ds_read_b128 v[192:195], v207 offset:17408
	ds_read_b128 v[196:199], v207 offset:18432
	ds_read_b128 v[208:211], v207 offset:19456
	ds_read_b128 v[212:215], v207 offset:20480
	ds_read_b128 v[216:219], v207 offset:21504
	ds_read_b128 v[220:223], v207 offset:22528
	ds_read_b128 v[224:227], v207 offset:23552
	global_load_lds_dwordx4 v176, s[84:85]
	s_add_i32 m0, s76, 0x2000
	s_add_u32 s76, s84, 0x4000
	s_addc_u32 s77, s85, 0
	s_add_i32 s91, s91, s4
	global_load_lds_dwordx4 v160, s[84:85]
	s_mov_b32 m0, s91
	s_nop 0
	global_load_lds_dwordx4 v176, s[76:77]
	s_add_i32 m0, s91, 0x2000
	s_nop 0
	global_load_lds_dwordx4 v160, s[76:77]
	s_mov_b32 m0, s23
	s_nop 0
	global_load_lds_dwordx4 v178, s[72:73]
	s_mov_b32 m0, s31
	s_nop 0
	global_load_lds_dwordx4 v174, s[72:73]
	.p2align	3
	s_waitcnt vmcnt(8)
	s_waitcnt lgkmcnt(0)
	s_setprio 1
	s_barrier
	v_mfma_f32_16x16x32_bf16 v[68:71], v[132:135], v[188:191], 0
	v_mfma_f32_16x16x32_bf16 v[60:63], v[140:143], v[188:191], 0
	v_mfma_f32_16x16x32_bf16 v[56:59], v[132:135], v[196:199], 0
	v_mfma_f32_16x16x32_bf16 v[52:55], v[140:143], v[196:199], 0
	v_mfma_f32_16x16x32_bf16 v[48:51], v[132:135], v[212:215], 0
	v_mfma_f32_16x16x32_bf16 v[44:47], v[140:143], v[212:215], 0
	v_mfma_f32_16x16x32_bf16 v[40:43], v[132:135], v[220:223], 0
	v_mfma_f32_16x16x32_bf16 v[36:39], v[140:143], v[220:223], 0
	v_mfma_f32_16x16x32_bf16 v[68:71], v[136:139], v[192:195], v[68:71]
	v_mfma_f32_16x16x32_bf16 v[60:63], v[144:147], v[192:195], v[60:63]
	v_mfma_f32_16x16x32_bf16 v[56:59], v[136:139], v[208:211], v[56:59]
	v_mfma_f32_16x16x32_bf16 v[52:55], v[144:147], v[208:211], v[52:55]
	v_mfma_f32_16x16x32_bf16 v[48:51], v[136:139], v[216:219], v[48:51]
	v_mfma_f32_16x16x32_bf16 v[44:47], v[144:147], v[216:219], v[44:47]
	v_mfma_f32_16x16x32_bf16 v[40:43], v[136:139], v[224:227], v[40:43]
	v_mfma_f32_16x16x32_bf16 v[36:39], v[144:147], v[224:227], v[36:39]
	v_mfma_f32_16x16x32_bf16 v[32:35], v[148:151], v[188:191], 0
	v_mfma_f32_16x16x32_bf16 v[28:31], v[156:159], v[188:191], 0
	v_mfma_f32_16x16x32_bf16 v[24:27], v[148:151], v[196:199], 0
	v_mfma_f32_16x16x32_bf16 v[20:23], v[156:159], v[196:199], 0
	v_mfma_f32_16x16x32_bf16 v[16:19], v[148:151], v[212:215], 0
	v_mfma_f32_16x16x32_bf16 v[12:15], v[156:159], v[212:215], 0
	v_mfma_f32_16x16x32_bf16 v[8:11], v[148:151], v[220:223], 0
	v_mfma_f32_16x16x32_bf16 v[2:5], v[156:159], v[220:223], 0
	v_mfma_f32_16x16x32_bf16 v[32:35], v[152:155], v[192:195], v[32:35]
	v_mfma_f32_16x16x32_bf16 v[28:31], v[184:187], v[192:195], v[28:31]
	v_mfma_f32_16x16x32_bf16 v[24:27], v[152:155], v[208:211], v[24:27]
	v_mfma_f32_16x16x32_bf16 v[20:23], v[184:187], v[208:211], v[20:23]
	v_mfma_f32_16x16x32_bf16 v[16:19], v[152:155], v[216:219], v[16:19]
	v_mfma_f32_16x16x32_bf16 v[12:15], v[184:187], v[216:219], v[12:15]
	v_mfma_f32_16x16x32_bf16 v[8:11], v[152:155], v[224:227], v[8:11]
	v_mfma_f32_16x16x32_bf16 v[2:5], v[184:187], v[224:227], v[2:5]
	s_barrier
	s_setprio 0
	s_add_i32 s76, 0, 0x18000
	v_add_u32_e32 v0, s76, v205
	s_add_i32 s77, 0, 0x1c000
	ds_read_b128 v[132:135], v0
	ds_read_b128 v[136:139], v0 offset:1024
	ds_read_b128 v[140:143], v0 offset:2048
	ds_read_b128 v[144:147], v0 offset:3072
	v_add_u32_e32 v0, s77, v205
	ds_read_b128 v[148:151], v0
	ds_read_b128 v[152:155], v0 offset:1024
	ds_read_b128 v[156:159], v0 offset:2048
	ds_read_b128 v[184:187], v0 offset:3072
	s_add_u32 s72, s72, 0x4000
	s_addc_u32 s73, s73, 0
	s_mov_b32 m0, s33
	ds_read_b128 v[188:191], v207 offset:32768
	ds_read_b128 v[192:195], v207 offset:33792
	ds_read_b128 v[196:199], v207 offset:34816
	ds_read_b128 v[208:211], v207 offset:35840
	ds_read_b128 v[212:215], v207 offset:36864
	ds_read_b128 v[216:219], v207 offset:37888
	ds_read_b128 v[220:223], v207 offset:38912
	ds_read_b128 v[224:227], v207 offset:39936
	global_load_lds_dwordx4 v178, s[72:73]
	s_mov_b32 m0, s93
	s_nop 0
	global_load_lds_dwordx4 v174, s[72:73]
	.p2align	3
	s_waitcnt vmcnt(8)
	s_waitcnt lgkmcnt(0)
	s_setprio 1
	s_barrier
	v_mfma_f32_16x16x32_bf16 v[128:131], v[132:135], v[188:191], v[128:131]
	v_mfma_f32_16x16x32_bf16 v[124:127], v[140:143], v[188:191], v[124:127]
	v_mfma_f32_16x16x32_bf16 v[120:123], v[132:135], v[196:199], v[120:123]
	v_mfma_f32_16x16x32_bf16 v[116:119], v[140:143], v[196:199], v[116:119]
	v_mfma_f32_16x16x32_bf16 v[112:115], v[132:135], v[212:215], v[112:115]
	v_mfma_f32_16x16x32_bf16 v[108:111], v[140:143], v[212:215], v[108:111]
	v_mfma_f32_16x16x32_bf16 v[104:107], v[132:135], v[220:223], v[104:107]
	v_mfma_f32_16x16x32_bf16 v[100:103], v[140:143], v[220:223], v[100:103]
	v_mfma_f32_16x16x32_bf16 v[128:131], v[136:139], v[192:195], v[128:131]
	v_mfma_f32_16x16x32_bf16 v[124:127], v[144:147], v[192:195], v[124:127]
	v_mfma_f32_16x16x32_bf16 v[120:123], v[136:139], v[208:211], v[120:123]
	v_mfma_f32_16x16x32_bf16 v[116:119], v[144:147], v[208:211], v[116:119]
	v_mfma_f32_16x16x32_bf16 v[112:115], v[136:139], v[216:219], v[112:115]
	v_mfma_f32_16x16x32_bf16 v[108:111], v[144:147], v[216:219], v[108:111]
	v_mfma_f32_16x16x32_bf16 v[104:107], v[136:139], v[224:227], v[104:107]
	v_mfma_f32_16x16x32_bf16 v[100:103], v[144:147], v[224:227], v[100:103]
	v_mfma_f32_16x16x32_bf16 v[96:99], v[148:151], v[188:191], v[96:99]
	v_mfma_f32_16x16x32_bf16 v[92:95], v[156:159], v[188:191], v[92:95]
	v_mfma_f32_16x16x32_bf16 v[88:91], v[148:151], v[196:199], v[88:91]
	v_mfma_f32_16x16x32_bf16 v[84:87], v[156:159], v[196:199], v[84:87]
	v_mfma_f32_16x16x32_bf16 v[80:83], v[148:151], v[212:215], v[80:83]
	v_mfma_f32_16x16x32_bf16 v[76:79], v[156:159], v[212:215], v[76:79]
	v_mfma_f32_16x16x32_bf16 v[72:75], v[148:151], v[220:223], v[72:75]
	v_mfma_f32_16x16x32_bf16 v[64:67], v[156:159], v[220:223], v[64:67]
	v_mfma_f32_16x16x32_bf16 v[96:99], v[152:155], v[192:195], v[96:99]
	v_mfma_f32_16x16x32_bf16 v[92:95], v[184:187], v[192:195], v[92:95]
	v_mfma_f32_16x16x32_bf16 v[88:91], v[152:155], v[208:211], v[88:91]
	v_mfma_f32_16x16x32_bf16 v[84:87], v[184:187], v[208:211], v[84:87]
	v_mfma_f32_16x16x32_bf16 v[80:83], v[152:155], v[216:219], v[80:83]
	v_mfma_f32_16x16x32_bf16 v[76:79], v[184:187], v[216:219], v[76:79]
	v_mfma_f32_16x16x32_bf16 v[72:75], v[152:155], v[224:227], v[72:75]
	v_mfma_f32_16x16x32_bf16 v[64:67], v[184:187], v[224:227], v[64:67]
	s_barrier
	s_setprio 0
	s_add_u32 s72, s84, 0x8000
	s_addc_u32 s73, s85, 0
	s_add_i32 s76, s76, s4
	s_mov_b32 m0, s76
	ds_read_b128 v[188:191], v207 offset:49152
	ds_read_b128 v[192:195], v207 offset:50176
	ds_read_b128 v[196:199], v207 offset:51200
	ds_read_b128 v[208:211], v207 offset:52224
	ds_read_b128 v[212:215], v207 offset:53248
	ds_read_b128 v[216:219], v207 offset:54272
	ds_read_b128 v[220:223], v207 offset:55296
	ds_read_b128 v[224:227], v207 offset:56320
	global_load_lds_dwordx4 v176, s[72:73]
	s_add_i32 m0, s76, 0x2000
	v_lshl_add_u64 v[6:7], s[72:73], 0, v[160:161]
	s_add_u32 s72, s84, 0xc000
	s_addc_u32 s73, s85, 0
	s_add_i32 s76, s77, s4
	global_load_lds_dwordx4 v[6:7], off
	s_mov_b32 m0, s76
	s_nop 0
	global_load_lds_dwordx4 v176, s[72:73]
	s_add_i32 m0, s76, 0x2000
	s_nop 0
	global_load_lds_dwordx4 v160, s[72:73]
	s_mov_b32 m0, s97
	s_nop 0
	global_load_lds_dwordx4 v178, vcc
	s_mov_b32 m0, s38
	s_nop 0
	global_load_lds_dwordx4 v174, vcc
	.p2align	3
	s_waitcnt vmcnt(8)
	s_waitcnt lgkmcnt(0)
	s_setprio 1
	s_barrier
	v_mfma_f32_16x16x32_bf16 v[68:71], v[132:135], v[188:191], v[68:71]
	v_mfma_f32_16x16x32_bf16 v[60:63], v[140:143], v[188:191], v[60:63]
	v_mfma_f32_16x16x32_bf16 v[56:59], v[132:135], v[196:199], v[56:59]
	v_mfma_f32_16x16x32_bf16 v[52:55], v[140:143], v[196:199], v[52:55]
	v_mfma_f32_16x16x32_bf16 v[48:51], v[132:135], v[212:215], v[48:51]
	v_mfma_f32_16x16x32_bf16 v[44:47], v[140:143], v[212:215], v[44:47]
	v_mfma_f32_16x16x32_bf16 v[40:43], v[132:135], v[220:223], v[40:43]
	v_mfma_f32_16x16x32_bf16 v[36:39], v[140:143], v[220:223], v[36:39]
	v_mfma_f32_16x16x32_bf16 v[68:71], v[136:139], v[192:195], v[68:71]
	v_mfma_f32_16x16x32_bf16 v[60:63], v[144:147], v[192:195], v[60:63]
	v_mfma_f32_16x16x32_bf16 v[56:59], v[136:139], v[208:211], v[56:59]
	v_mfma_f32_16x16x32_bf16 v[52:55], v[144:147], v[208:211], v[52:55]
	v_mfma_f32_16x16x32_bf16 v[48:51], v[136:139], v[216:219], v[48:51]
	v_mfma_f32_16x16x32_bf16 v[44:47], v[144:147], v[216:219], v[44:47]
	v_mfma_f32_16x16x32_bf16 v[40:43], v[136:139], v[224:227], v[40:43]
	v_mfma_f32_16x16x32_bf16 v[36:39], v[144:147], v[224:227], v[36:39]
	v_mfma_f32_16x16x32_bf16 v[32:35], v[148:151], v[188:191], v[32:35]
	v_mfma_f32_16x16x32_bf16 v[28:31], v[156:159], v[188:191], v[28:31]
	v_mfma_f32_16x16x32_bf16 v[24:27], v[148:151], v[196:199], v[24:27]
	v_mfma_f32_16x16x32_bf16 v[20:23], v[156:159], v[196:199], v[20:23]
	v_mfma_f32_16x16x32_bf16 v[16:19], v[148:151], v[212:215], v[16:19]
	v_mfma_f32_16x16x32_bf16 v[12:15], v[156:159], v[212:215], v[12:15]
	v_mfma_f32_16x16x32_bf16 v[6:9], v[148:151], v[220:223], v[8:11]
	v_mfma_f32_16x16x32_bf16 v[2:5], v[156:159], v[220:223], v[2:5]
	v_mfma_f32_16x16x32_bf16 v[32:35], v[152:155], v[192:195], v[32:35]
	v_mfma_f32_16x16x32_bf16 v[28:31], v[184:187], v[192:195], v[28:31]
	v_mfma_f32_16x16x32_bf16 v[24:27], v[152:155], v[208:211], v[24:27]
	v_mfma_f32_16x16x32_bf16 v[20:23], v[184:187], v[208:211], v[20:23]
	v_mfma_f32_16x16x32_bf16 v[16:19], v[152:155], v[216:219], v[16:19]
	v_mfma_f32_16x16x32_bf16 v[12:15], v[184:187], v[216:219], v[12:15]
	v_mfma_f32_16x16x32_bf16 v[8:11], v[152:155], v[224:227], v[6:9]
	v_mfma_f32_16x16x32_bf16 v[4:7], v[184:187], v[224:227], v[2:5]
	s_barrier
	s_setprio 0
	s_add_u32 s29, s29, 0x10000
	s_addc_u32 s74, s74, 0
	s_add_u32 s16, s16, 0x10000
	s_addc_u32 s17, s17, 0
	s_cmp_ge_i32 s75, s39
	s_mov_b32 s72, s75
	s_cbranch_scc0 .LBB7_434
	s_branch .Lpeelx_434
	.p2align	6
.LBB7_434:
	s_add_i32 s75, s72, 2
	s_add_u32 s76, s16, 0x4000
	s_addc_u32 s73, s17, 0
	s_cmp_eq_u32 s3, s72
	s_cselect_b32 s72, s86, s76
	s_cselect_b32 s73, s20, s73
	s_cselect_b32 s84, s37, s29
	s_cselect_b32 s85, s87, s74
	s_add_u32 vcc_lo, s72, 0x8000
	s_addc_u32 vcc_hi, s73, 0
	s_add_i32 s76, 0, 0x10000
	v_add_u32_e32 v0, s76, v205
	s_add_i32 s91, 0, 0x14000
	ds_read_b128 v[132:135], v0
	ds_read_b128 v[136:139], v0 offset:1024
	ds_read_b128 v[140:143], v0 offset:2048
	ds_read_b128 v[144:147], v0 offset:3072
	v_add_u32_e32 v0, s91, v205
	ds_read_b128 v[148:151], v0
	ds_read_b128 v[152:155], v0 offset:1024
	ds_read_b128 v[156:159], v0 offset:2048
	ds_read_b128 v[184:187], v0 offset:3072
	s_waitcnt lgkmcnt(0)
	s_add_i32 m0, s23, 0xc000
	ds_read_b128 v[188:191], v207
	ds_read_b128 v[192:195], v207 offset:1024
	ds_read_b128 v[196:199], v207 offset:2048
	ds_read_b128 v[208:211], v207 offset:3072
	ds_read_b128 v[212:215], v207 offset:4096
	ds_read_b128 v[216:219], v207 offset:5120
	ds_read_b128 v[220:223], v207 offset:6144
	ds_read_b128 v[224:227], v207 offset:7168
	global_load_lds_dwordx4 v180, s[16:17]
	s_add_i32 m0, s23, 0xe000
	s_nop 0
	global_load_lds_dwordx4 v182, s[16:17]
	.p2align	3
	s_waitcnt vmcnt(8)
	s_waitcnt lgkmcnt(0)
	s_setprio 1
	s_barrier
	v_mfma_f32_16x16x32_bf16 v[128:131], v[132:135], v[188:191], v[128:131]
	v_mfma_f32_16x16x32_bf16 v[124:127], v[140:143], v[188:191], v[124:127]
	v_mfma_f32_16x16x32_bf16 v[120:123], v[132:135], v[196:199], v[120:123]
	v_mfma_f32_16x16x32_bf16 v[116:119], v[140:143], v[196:199], v[116:119]
	v_mfma_f32_16x16x32_bf16 v[112:115], v[132:135], v[212:215], v[112:115]
	v_mfma_f32_16x16x32_bf16 v[108:111], v[140:143], v[212:215], v[108:111]
	v_mfma_f32_16x16x32_bf16 v[104:107], v[132:135], v[220:223], v[104:107]
	v_mfma_f32_16x16x32_bf16 v[100:103], v[140:143], v[220:223], v[100:103]
	v_mfma_f32_16x16x32_bf16 v[128:131], v[136:139], v[192:195], v[128:131]
	v_mfma_f32_16x16x32_bf16 v[124:127], v[144:147], v[192:195], v[124:127]
	v_mfma_f32_16x16x32_bf16 v[120:123], v[136:139], v[208:211], v[120:123]
	v_mfma_f32_16x16x32_bf16 v[116:119], v[144:147], v[208:211], v[116:119]
	v_mfma_f32_16x16x32_bf16 v[112:115], v[136:139], v[216:219], v[112:115]
	v_mfma_f32_16x16x32_bf16 v[108:111], v[144:147], v[216:219], v[108:111]
	v_mfma_f32_16x16x32_bf16 v[104:107], v[136:139], v[224:227], v[104:107]
	v_mfma_f32_16x16x32_bf16 v[100:103], v[144:147], v[224:227], v[100:103]
	v_mfma_f32_16x16x32_bf16 v[96:99], v[148:151], v[188:191], v[96:99]
	v_mfma_f32_16x16x32_bf16 v[92:95], v[156:159], v[188:191], v[92:95]
	v_mfma_f32_16x16x32_bf16 v[88:91], v[148:151], v[196:199], v[88:91]
	v_mfma_f32_16x16x32_bf16 v[84:87], v[156:159], v[196:199], v[84:87]
	v_mfma_f32_16x16x32_bf16 v[80:83], v[148:151], v[212:215], v[80:83]
	v_mfma_f32_16x16x32_bf16 v[76:79], v[156:159], v[212:215], v[76:79]
	v_mfma_f32_16x16x32_bf16 v[72:75], v[148:151], v[220:223], v[72:75]
	v_mfma_f32_16x16x32_bf16 v[64:67], v[156:159], v[220:223], v[64:67]
	v_mfma_f32_16x16x32_bf16 v[96:99], v[152:155], v[192:195], v[96:99]
	v_mfma_f32_16x16x32_bf16 v[92:95], v[184:187], v[192:195], v[92:95]
	v_mfma_f32_16x16x32_bf16 v[88:91], v[152:155], v[208:211], v[88:91]
	v_mfma_f32_16x16x32_bf16 v[84:87], v[184:187], v[208:211], v[84:87]
	v_mfma_f32_16x16x32_bf16 v[80:83], v[152:155], v[216:219], v[80:83]
	v_mfma_f32_16x16x32_bf16 v[76:79], v[184:187], v[216:219], v[76:79]
	v_mfma_f32_16x16x32_bf16 v[72:75], v[152:155], v[224:227], v[72:75]
	v_mfma_f32_16x16x32_bf16 v[64:67], v[184:187], v[224:227], v[64:67]
	s_barrier
	s_setprio 0
	s_add_i32 s76, s76, s4
	s_mov_b32 m0, s76
	ds_read_b128 v[188:191], v207 offset:16384
	ds_read_b128 v[192:195], v207 offset:17408
	ds_read_b128 v[196:199], v207 offset:18432
	ds_read_b128 v[208:211], v207 offset:19456
	ds_read_b128 v[212:215], v207 offset:20480
	ds_read_b128 v[216:219], v207 offset:21504
	ds_read_b128 v[220:223], v207 offset:22528
	ds_read_b128 v[224:227], v207 offset:23552
	global_load_lds_dwordx4 v176, s[84:85]
	s_add_i32 m0, s76, 0x2000
	s_add_u32 s76, s84, 0x4000
	s_addc_u32 s77, s85, 0
	s_add_i32 s91, s91, s4
	global_load_lds_dwordx4 v160, s[84:85]
	s_mov_b32 m0, s91
	s_nop 0
	global_load_lds_dwordx4 v176, s[76:77]
	s_add_i32 m0, s91, 0x2000
	s_nop 0
	global_load_lds_dwordx4 v160, s[76:77]
	s_mov_b32 m0, s23
	s_nop 0
	global_load_lds_dwordx4 v178, s[72:73]
	s_mov_b32 m0, s31
	s_nop 0
	global_load_lds_dwordx4 v174, s[72:73]
	.p2align	3
	s_waitcnt vmcnt(8)
	s_waitcnt lgkmcnt(0)
	s_setprio 1
	s_barrier
	v_mfma_f32_16x16x32_bf16 v[68:71], v[132:135], v[188:191], v[68:71]
	v_mfma_f32_16x16x32_bf16 v[60:63], v[140:143], v[188:191], v[60:63]
	v_mfma_f32_16x16x32_bf16 v[56:59], v[132:135], v[196:199], v[56:59]
	v_mfma_f32_16x16x32_bf16 v[52:55], v[140:143], v[196:199], v[52:55]
	v_mfma_f32_16x16x32_bf16 v[48:51], v[132:135], v[212:215], v[48:51]
	v_mfma_f32_16x16x32_bf16 v[44:47], v[140:143], v[212:215], v[44:47]
	v_mfma_f32_16x16x32_bf16 v[40:43], v[132:135], v[220:223], v[40:43]
	v_mfma_f32_16x16x32_bf16 v[36:39], v[140:143], v[220:223], v[36:39]
	v_mfma_f32_16x16x32_bf16 v[68:71], v[136:139], v[192:195], v[68:71]
	v_mfma_f32_16x16x32_bf16 v[60:63], v[144:147], v[192:195], v[60:63]
	v_mfma_f32_16x16x32_bf16 v[56:59], v[136:139], v[208:211], v[56:59]
	v_mfma_f32_16x16x32_bf16 v[52:55], v[144:147], v[208:211], v[52:55]
	v_mfma_f32_16x16x32_bf16 v[48:51], v[136:139], v[216:219], v[48:51]
	v_mfma_f32_16x16x32_bf16 v[44:47], v[144:147], v[216:219], v[44:47]
	v_mfma_f32_16x16x32_bf16 v[40:43], v[136:139], v[224:227], v[40:43]
	v_mfma_f32_16x16x32_bf16 v[36:39], v[144:147], v[224:227], v[36:39]
	v_mfma_f32_16x16x32_bf16 v[32:35], v[148:151], v[188:191], v[32:35]
	v_mfma_f32_16x16x32_bf16 v[28:31], v[156:159], v[188:191], v[28:31]
	v_mfma_f32_16x16x32_bf16 v[24:27], v[148:151], v[196:199], v[24:27]
	v_mfma_f32_16x16x32_bf16 v[20:23], v[156:159], v[196:199], v[20:23]
	v_mfma_f32_16x16x32_bf16 v[16:19], v[148:151], v[212:215], v[16:19]
	v_mfma_f32_16x16x32_bf16 v[12:15], v[156:159], v[212:215], v[12:15]
	v_mfma_f32_16x16x32_bf16 v[8:11], v[148:151], v[220:223], v[8:11]
	v_mfma_f32_16x16x32_bf16 v[2:5], v[156:159], v[220:223], v[4:7]
	v_mfma_f32_16x16x32_bf16 v[32:35], v[152:155], v[192:195], v[32:35]
	v_mfma_f32_16x16x32_bf16 v[28:31], v[184:187], v[192:195], v[28:31]
	v_mfma_f32_16x16x32_bf16 v[24:27], v[152:155], v[208:211], v[24:27]
	v_mfma_f32_16x16x32_bf16 v[20:23], v[184:187], v[208:211], v[20:23]
	v_mfma_f32_16x16x32_bf16 v[16:19], v[152:155], v[216:219], v[16:19]
	v_mfma_f32_16x16x32_bf16 v[12:15], v[184:187], v[216:219], v[12:15]
	v_mfma_f32_16x16x32_bf16 v[8:11], v[152:155], v[224:227], v[8:11]
	v_mfma_f32_16x16x32_bf16 v[2:5], v[184:187], v[224:227], v[2:5]
	s_barrier
	s_setprio 0
	s_add_i32 s76, 0, 0x18000
	v_add_u32_e32 v0, s76, v205
	s_add_i32 s77, 0, 0x1c000
	ds_read_b128 v[132:135], v0
	ds_read_b128 v[136:139], v0 offset:1024
	ds_read_b128 v[140:143], v0 offset:2048
	ds_read_b128 v[144:147], v0 offset:3072
	v_add_u32_e32 v0, s77, v205
	ds_read_b128 v[148:151], v0
	ds_read_b128 v[152:155], v0 offset:1024
	ds_read_b128 v[156:159], v0 offset:2048
	ds_read_b128 v[184:187], v0 offset:3072
	s_add_u32 s72, s72, 0x4000
	s_addc_u32 s73, s73, 0
	s_mov_b32 m0, s33
	ds_read_b128 v[188:191], v207 offset:32768
	ds_read_b128 v[192:195], v207 offset:33792
	ds_read_b128 v[196:199], v207 offset:34816
	ds_read_b128 v[208:211], v207 offset:35840
	ds_read_b128 v[212:215], v207 offset:36864
	ds_read_b128 v[216:219], v207 offset:37888
	ds_read_b128 v[220:223], v207 offset:38912
	ds_read_b128 v[224:227], v207 offset:39936
	global_load_lds_dwordx4 v178, s[72:73]
	s_mov_b32 m0, s93
	s_nop 0
	global_load_lds_dwordx4 v174, s[72:73]
	.p2align	3
	s_waitcnt vmcnt(8)
	s_waitcnt lgkmcnt(0)
	s_setprio 1
	s_barrier
	v_mfma_f32_16x16x32_bf16 v[128:131], v[132:135], v[188:191], v[128:131]
	v_mfma_f32_16x16x32_bf16 v[124:127], v[140:143], v[188:191], v[124:127]
	v_mfma_f32_16x16x32_bf16 v[120:123], v[132:135], v[196:199], v[120:123]
	v_mfma_f32_16x16x32_bf16 v[116:119], v[140:143], v[196:199], v[116:119]
	v_mfma_f32_16x16x32_bf16 v[112:115], v[132:135], v[212:215], v[112:115]
	v_mfma_f32_16x16x32_bf16 v[108:111], v[140:143], v[212:215], v[108:111]
	v_mfma_f32_16x16x32_bf16 v[104:107], v[132:135], v[220:223], v[104:107]
	v_mfma_f32_16x16x32_bf16 v[100:103], v[140:143], v[220:223], v[100:103]
	v_mfma_f32_16x16x32_bf16 v[128:131], v[136:139], v[192:195], v[128:131]
	v_mfma_f32_16x16x32_bf16 v[124:127], v[144:147], v[192:195], v[124:127]
	v_mfma_f32_16x16x32_bf16 v[120:123], v[136:139], v[208:211], v[120:123]
	v_mfma_f32_16x16x32_bf16 v[116:119], v[144:147], v[208:211], v[116:119]
	v_mfma_f32_16x16x32_bf16 v[112:115], v[136:139], v[216:219], v[112:115]
	v_mfma_f32_16x16x32_bf16 v[108:111], v[144:147], v[216:219], v[108:111]
	v_mfma_f32_16x16x32_bf16 v[104:107], v[136:139], v[224:227], v[104:107]
	v_mfma_f32_16x16x32_bf16 v[100:103], v[144:147], v[224:227], v[100:103]
	v_mfma_f32_16x16x32_bf16 v[96:99], v[148:151], v[188:191], v[96:99]
	v_mfma_f32_16x16x32_bf16 v[92:95], v[156:159], v[188:191], v[92:95]
	v_mfma_f32_16x16x32_bf16 v[88:91], v[148:151], v[196:199], v[88:91]
	v_mfma_f32_16x16x32_bf16 v[84:87], v[156:159], v[196:199], v[84:87]
	v_mfma_f32_16x16x32_bf16 v[80:83], v[148:151], v[212:215], v[80:83]
	v_mfma_f32_16x16x32_bf16 v[76:79], v[156:159], v[212:215], v[76:79]
	v_mfma_f32_16x16x32_bf16 v[72:75], v[148:151], v[220:223], v[72:75]
	v_mfma_f32_16x16x32_bf16 v[64:67], v[156:159], v[220:223], v[64:67]
	v_mfma_f32_16x16x32_bf16 v[96:99], v[152:155], v[192:195], v[96:99]
	v_mfma_f32_16x16x32_bf16 v[92:95], v[184:187], v[192:195], v[92:95]
	v_mfma_f32_16x16x32_bf16 v[88:91], v[152:155], v[208:211], v[88:91]
	v_mfma_f32_16x16x32_bf16 v[84:87], v[184:187], v[208:211], v[84:87]
	v_mfma_f32_16x16x32_bf16 v[80:83], v[152:155], v[216:219], v[80:83]
	v_mfma_f32_16x16x32_bf16 v[76:79], v[184:187], v[216:219], v[76:79]
	v_mfma_f32_16x16x32_bf16 v[72:75], v[152:155], v[224:227], v[72:75]
	v_mfma_f32_16x16x32_bf16 v[64:67], v[184:187], v[224:227], v[64:67]
	s_barrier
	s_setprio 0
	s_add_u32 s72, s84, 0x8000
	s_addc_u32 s73, s85, 0
	s_add_i32 s76, s76, s4
	s_mov_b32 m0, s76
	ds_read_b128 v[188:191], v207 offset:49152
	ds_read_b128 v[192:195], v207 offset:50176
	ds_read_b128 v[196:199], v207 offset:51200
	ds_read_b128 v[208:211], v207 offset:52224
	ds_read_b128 v[212:215], v207 offset:53248
	ds_read_b128 v[216:219], v207 offset:54272
	ds_read_b128 v[220:223], v207 offset:55296
	ds_read_b128 v[224:227], v207 offset:56320
	global_load_lds_dwordx4 v176, s[72:73]
	s_add_i32 m0, s76, 0x2000
	v_lshl_add_u64 v[6:7], s[72:73], 0, v[160:161]
	s_add_u32 s72, s84, 0xc000
	s_addc_u32 s73, s85, 0
	s_add_i32 s76, s77, s4
	global_load_lds_dwordx4 v[6:7], off
	s_mov_b32 m0, s76
	s_nop 0
	global_load_lds_dwordx4 v176, s[72:73]
	s_add_i32 m0, s76, 0x2000
	s_nop 0
	global_load_lds_dwordx4 v160, s[72:73]
	s_mov_b32 m0, s97
	s_nop 0
	global_load_lds_dwordx4 v178, vcc
	s_mov_b32 m0, s38
	s_nop 0
	global_load_lds_dwordx4 v174, vcc
	.p2align	3
	s_waitcnt vmcnt(8)
	s_waitcnt lgkmcnt(0)
	s_setprio 1
	s_barrier
	v_mfma_f32_16x16x32_bf16 v[68:71], v[132:135], v[188:191], v[68:71]
	v_mfma_f32_16x16x32_bf16 v[60:63], v[140:143], v[188:191], v[60:63]
	v_mfma_f32_16x16x32_bf16 v[56:59], v[132:135], v[196:199], v[56:59]
	v_mfma_f32_16x16x32_bf16 v[52:55], v[140:143], v[196:199], v[52:55]
	v_mfma_f32_16x16x32_bf16 v[48:51], v[132:135], v[212:215], v[48:51]
	v_mfma_f32_16x16x32_bf16 v[44:47], v[140:143], v[212:215], v[44:47]
	v_mfma_f32_16x16x32_bf16 v[40:43], v[132:135], v[220:223], v[40:43]
	v_mfma_f32_16x16x32_bf16 v[36:39], v[140:143], v[220:223], v[36:39]
	v_mfma_f32_16x16x32_bf16 v[68:71], v[136:139], v[192:195], v[68:71]
	v_mfma_f32_16x16x32_bf16 v[60:63], v[144:147], v[192:195], v[60:63]
	v_mfma_f32_16x16x32_bf16 v[56:59], v[136:139], v[208:211], v[56:59]
	v_mfma_f32_16x16x32_bf16 v[52:55], v[144:147], v[208:211], v[52:55]
	v_mfma_f32_16x16x32_bf16 v[48:51], v[136:139], v[216:219], v[48:51]
	v_mfma_f32_16x16x32_bf16 v[44:47], v[144:147], v[216:219], v[44:47]
	v_mfma_f32_16x16x32_bf16 v[40:43], v[136:139], v[224:227], v[40:43]
	v_mfma_f32_16x16x32_bf16 v[36:39], v[144:147], v[224:227], v[36:39]
	v_mfma_f32_16x16x32_bf16 v[32:35], v[148:151], v[188:191], v[32:35]
	v_mfma_f32_16x16x32_bf16 v[28:31], v[156:159], v[188:191], v[28:31]
	v_mfma_f32_16x16x32_bf16 v[24:27], v[148:151], v[196:199], v[24:27]
	v_mfma_f32_16x16x32_bf16 v[20:23], v[156:159], v[196:199], v[20:23]
	v_mfma_f32_16x16x32_bf16 v[16:19], v[148:151], v[212:215], v[16:19]
	v_mfma_f32_16x16x32_bf16 v[12:15], v[156:159], v[212:215], v[12:15]
	v_mfma_f32_16x16x32_bf16 v[6:9], v[148:151], v[220:223], v[8:11]
	v_mfma_f32_16x16x32_bf16 v[2:5], v[156:159], v[220:223], v[2:5]
	v_mfma_f32_16x16x32_bf16 v[32:35], v[152:155], v[192:195], v[32:35]
	v_mfma_f32_16x16x32_bf16 v[28:31], v[184:187], v[192:195], v[28:31]
	v_mfma_f32_16x16x32_bf16 v[24:27], v[152:155], v[208:211], v[24:27]
	v_mfma_f32_16x16x32_bf16 v[20:23], v[184:187], v[208:211], v[20:23]
	v_mfma_f32_16x16x32_bf16 v[16:19], v[152:155], v[216:219], v[16:19]
	v_mfma_f32_16x16x32_bf16 v[12:15], v[184:187], v[216:219], v[12:15]
	v_mfma_f32_16x16x32_bf16 v[8:11], v[152:155], v[224:227], v[6:9]
	v_mfma_f32_16x16x32_bf16 v[4:7], v[184:187], v[224:227], v[2:5]
	s_barrier
	s_setprio 0
	s_add_u32 s29, s29, 0x10000
	s_addc_u32 s74, s74, 0
	s_add_u32 s16, s16, 0x10000
	s_addc_u32 s17, s17, 0
	s_cmp_ge_i32 s75, s39
	s_mov_b32 s72, s75
	s_cbranch_scc0 .LBB7_434

.Lpeel_523:
	s_add_i32 s56, s42, 2
	s_add_u32 s29, s16, 0xfffc0080
	s_addc_u32 s37, s17, -1
	s_add_i32 s57, 0, 0x10000
	s_cmp_eq_u32 s84, s42
	s_cselect_b32 s45, s13, s37
	s_cselect_b32 s44, s15, s29
	v_add_u32_e32 v0, s57, v195
	s_cselect_b32 s43, s38, s49
	s_cselect_b32 s42, s39, s48
	s_add_i32 s29, 0, 0x14000
	ds_read_b128 v[130:133], v0
	ds_read_b128 v[150:153], v0 offset:1024
	ds_read_b128 v[154:157], v0 offset:2048
	ds_read_b128 v[158:161], v0 offset:3072
	v_add_u32_e32 v0, s29, v195
	ds_read_b128 v[174:177], v0
	ds_read_b128 v[178:181], v0 offset:1024
	ds_read_b128 v[182:185], v0 offset:2048
	ds_read_b128 v[186:189], v0 offset:3072
	s_add_i32 m0, s5, 0xc000
	ds_read_b128 v[190:193], v196
	ds_read_b128 v[204:207], v196 offset:1024
	ds_read_b128 v[208:211], v196 offset:2048
	ds_read_b128 v[212:215], v196 offset:3072
	ds_read_b128 v[216:219], v196 offset:4096
	ds_read_b128 v[220:223], v196 offset:5120
	ds_read_b128 v[224:227], v196 offset:6144
	ds_read_b128 v[228:231], v196 offset:7168
	global_load_lds_dwordx4 v146, s[16:17]
	s_add_i32 m0, s5, 0xe000
	s_nop 0
	global_load_lds_dwordx4 v148, s[16:17]
	.p2align	3
	s_waitcnt vmcnt(8)
	s_waitcnt lgkmcnt(0)
	s_setprio 1
	s_barrier
	v_mfma_f32_16x16x32_bf16 v[126:129], v[130:133], v[190:193], 0
	v_mfma_f32_16x16x32_bf16 v[122:125], v[154:157], v[190:193], 0
	v_mfma_f32_16x16x32_bf16 v[110:113], v[130:133], v[208:211], 0
	v_mfma_f32_16x16x32_bf16 v[106:109], v[154:157], v[208:211], 0
	v_mfma_f32_16x16x32_bf16 v[94:97], v[130:133], v[216:219], 0
	v_mfma_f32_16x16x32_bf16 v[90:93], v[154:157], v[216:219], 0
	v_mfma_f32_16x16x32_bf16 v[78:81], v[130:133], v[224:227], 0
	v_mfma_f32_16x16x32_bf16 v[74:77], v[154:157], v[224:227], 0
	v_mfma_f32_16x16x32_bf16 v[126:129], v[150:153], v[204:207], v[126:129]
	v_mfma_f32_16x16x32_bf16 v[122:125], v[158:161], v[204:207], v[122:125]
	v_mfma_f32_16x16x32_bf16 v[110:113], v[150:153], v[212:215], v[110:113]
	v_mfma_f32_16x16x32_bf16 v[106:109], v[158:161], v[212:215], v[106:109]
	v_mfma_f32_16x16x32_bf16 v[94:97], v[150:153], v[220:223], v[94:97]
	v_mfma_f32_16x16x32_bf16 v[90:93], v[158:161], v[220:223], v[90:93]
	v_mfma_f32_16x16x32_bf16 v[78:81], v[150:153], v[228:231], v[78:81]
	v_mfma_f32_16x16x32_bf16 v[74:77], v[158:161], v[228:231], v[74:77]
	v_mfma_f32_16x16x32_bf16 v[118:121], v[174:177], v[190:193], 0
	v_mfma_f32_16x16x32_bf16 v[114:117], v[182:185], v[190:193], 0
	v_mfma_f32_16x16x32_bf16 v[102:105], v[174:177], v[208:211], 0
	v_mfma_f32_16x16x32_bf16 v[98:101], v[182:185], v[208:211], 0
	v_mfma_f32_16x16x32_bf16 v[86:89], v[174:177], v[216:219], 0
	v_mfma_f32_16x16x32_bf16 v[82:85], v[182:185], v[216:219], 0
	v_mfma_f32_16x16x32_bf16 v[70:73], v[174:177], v[224:227], 0
	v_mfma_f32_16x16x32_bf16 v[66:69], v[182:185], v[224:227], 0
	v_mfma_f32_16x16x32_bf16 v[118:121], v[178:181], v[204:207], v[118:121]
	v_mfma_f32_16x16x32_bf16 v[114:117], v[186:189], v[204:207], v[114:117]
	v_mfma_f32_16x16x32_bf16 v[102:105], v[178:181], v[212:215], v[102:105]
	v_mfma_f32_16x16x32_bf16 v[98:101], v[186:189], v[212:215], v[98:101]
	v_mfma_f32_16x16x32_bf16 v[86:89], v[178:181], v[220:223], v[86:89]
	v_mfma_f32_16x16x32_bf16 v[82:85], v[186:189], v[220:223], v[82:85]
	v_mfma_f32_16x16x32_bf16 v[70:73], v[178:181], v[228:231], v[70:73]
	v_mfma_f32_16x16x32_bf16 v[66:69], v[186:189], v[228:231], v[66:69]
	s_barrier
	s_setprio 0
	s_add_i32 s37, s57, s4
	v_lshl_add_u64 v[170:171], s[42:43], 0, v[138:139]
	s_mov_b32 m0, s37
	ds_read_b128 v[190:193], v196 offset:16384
	ds_read_b128 v[204:207], v196 offset:17408
	ds_read_b128 v[208:211], v196 offset:18432
	ds_read_b128 v[212:215], v196 offset:19456
	ds_read_b128 v[216:219], v196 offset:20480
	ds_read_b128 v[220:223], v196 offset:21504
	ds_read_b128 v[224:227], v196 offset:22528
	ds_read_b128 v[228:231], v196 offset:23552
	global_load_lds_dwordx4 v[170:171], off
	s_add_i32 m0, s37, 0x2000
	s_add_u32 s74, s42, 0x40000
	v_lshl_add_u64 v[172:173], s[42:43], 0, v[134:135]
	s_addc_u32 s75, s43, 0
	s_add_i32 s29, s29, s4
	global_load_lds_dwordx4 v[172:173], off
	s_mov_b32 m0, s29
	v_lshl_add_u64 v[232:233], s[44:45], 0, v[136:137]
	global_load_lds_dwordx4 v138, s[74:75]
	s_add_i32 m0, s29, 0x2000
	s_nop 0
	global_load_lds_dwordx4 v134, s[74:75]
	v_lshl_add_u64 v[198:199], s[44:45], 0, v[140:141]
	s_mov_b32 m0, s5
	s_nop 0
	global_load_lds_dwordx4 v[198:199], off
	s_mov_b32 m0, s20
	s_nop 0
	global_load_lds_dwordx4 v[232:233], off
	s_lshl_b32 s101, s28, 14
	s_add_i32 s101, s101, s5
	s_add_u32 s100, s66, s101
	s_addc_u32 s101, s67, 0
	v_lshlrev_b32_e32 v2, 4, v163
	v_add_u32_e32 v3, 0x2000, v2
	s_add_i32 m0, s5, 0x20000
	s_nop 0
	global_load_lds_dwordx4 v2, s[100:101]
	s_add_i32 m0, s5, 0x22000
	s_nop 0
	global_load_lds_dwordx4 v3, s[100:101]
	.p2align	3
	s_waitcnt vmcnt(8)
	s_waitcnt lgkmcnt(0)
	s_setprio 1
	s_barrier
	v_mfma_f32_16x16x32_bf16 v[62:65], v[130:133], v[190:193], 0
	v_mfma_f32_16x16x32_bf16 v[58:61], v[154:157], v[190:193], 0
	v_mfma_f32_16x16x32_bf16 v[46:49], v[130:133], v[208:211], 0
	v_mfma_f32_16x16x32_bf16 v[42:45], v[154:157], v[208:211], 0
	v_mfma_f32_16x16x32_bf16 v[30:33], v[130:133], v[216:219], 0
	v_mfma_f32_16x16x32_bf16 v[26:29], v[154:157], v[216:219], 0
	v_mfma_f32_16x16x32_bf16 v[14:17], v[130:133], v[224:227], 0
	v_mfma_f32_16x16x32_bf16 v[10:13], v[154:157], v[224:227], 0
	v_mfma_f32_16x16x32_bf16 v[62:65], v[150:153], v[204:207], v[62:65]
	v_mfma_f32_16x16x32_bf16 v[58:61], v[158:161], v[204:207], v[58:61]
	v_mfma_f32_16x16x32_bf16 v[46:49], v[150:153], v[212:215], v[46:49]
	v_mfma_f32_16x16x32_bf16 v[42:45], v[158:161], v[212:215], v[42:45]
	v_mfma_f32_16x16x32_bf16 v[30:33], v[150:153], v[220:223], v[30:33]
	v_mfma_f32_16x16x32_bf16 v[26:29], v[158:161], v[220:223], v[26:29]
	v_mfma_f32_16x16x32_bf16 v[14:17], v[150:153], v[228:231], v[14:17]
	v_mfma_f32_16x16x32_bf16 v[10:13], v[158:161], v[228:231], v[10:13]
	v_mfma_f32_16x16x32_bf16 v[54:57], v[174:177], v[190:193], 0
	v_mfma_f32_16x16x32_bf16 v[50:53], v[182:185], v[190:193], 0
	v_mfma_f32_16x16x32_bf16 v[38:41], v[174:177], v[208:211], 0
	v_mfma_f32_16x16x32_bf16 v[34:37], v[182:185], v[208:211], 0
	v_mfma_f32_16x16x32_bf16 v[22:25], v[174:177], v[216:219], 0
	v_mfma_f32_16x16x32_bf16 v[18:21], v[182:185], v[216:219], 0
	v_mfma_f32_16x16x32_bf16 v[6:9], v[174:177], v[224:227], 0
	v_mfma_f32_16x16x32_bf16 v[2:5], v[182:185], v[224:227], 0
	v_mfma_f32_16x16x32_bf16 v[54:57], v[178:181], v[204:207], v[54:57]
	v_mfma_f32_16x16x32_bf16 v[50:53], v[186:189], v[204:207], v[50:53]
	v_mfma_f32_16x16x32_bf16 v[38:41], v[178:181], v[212:215], v[38:41]
	v_mfma_f32_16x16x32_bf16 v[34:37], v[186:189], v[212:215], v[34:37]
	v_mfma_f32_16x16x32_bf16 v[22:25], v[178:181], v[220:223], v[22:25]
	v_mfma_f32_16x16x32_bf16 v[18:21], v[186:189], v[220:223], v[18:21]
	v_mfma_f32_16x16x32_bf16 v[6:9], v[178:181], v[228:231], v[6:9]
	v_mfma_f32_16x16x32_bf16 v[2:5], v[186:189], v[228:231], v[2:5]
	s_barrier
	s_setprio 0
	s_add_i32 s29, 0, 0x18000
	v_add_u32_e32 v0, s29, v195
	s_add_i32 s37, 0, 0x1c000
	ds_read_b128 v[130:133], v0
	ds_read_b128 v[150:153], v0 offset:1024
	ds_read_b128 v[154:157], v0 offset:2048
	ds_read_b128 v[158:161], v0 offset:3072
	v_add_u32_e32 v0, s37, v195
	ds_read_b128 v[174:177], v0
	ds_read_b128 v[178:181], v0 offset:1024
	ds_read_b128 v[182:185], v0 offset:2048
	ds_read_b128 v[186:189], v0 offset:3072
	s_add_u32 s44, s44, 0x40000
	s_addc_u32 s45, s45, 0
	s_mov_b32 m0, s22
	ds_read_b128 v[190:193], v196 offset:32768
	ds_read_b128 v[204:207], v196 offset:33792
	ds_read_b128 v[208:211], v196 offset:34816
	ds_read_b128 v[212:215], v196 offset:35840
	ds_read_b128 v[216:219], v196 offset:36864
	ds_read_b128 v[220:223], v196 offset:37888
	ds_read_b128 v[224:227], v196 offset:38912
	ds_read_b128 v[228:231], v196 offset:39936
	global_load_lds_dwordx4 v140, s[44:45]
	s_mov_b32 m0, s23
	s_nop 0
	global_load_lds_dwordx4 v136, s[44:45]
	.p2align	3
	s_waitcnt vmcnt(8)
	s_waitcnt lgkmcnt(0)
	s_setprio 1
	s_barrier
	v_mfma_f32_16x16x32_bf16 v[126:129], v[130:133], v[190:193], v[126:129]
	v_mfma_f32_16x16x32_bf16 v[122:125], v[154:157], v[190:193], v[122:125]
	v_mfma_f32_16x16x32_bf16 v[110:113], v[130:133], v[208:211], v[110:113]
	v_mfma_f32_16x16x32_bf16 v[106:109], v[154:157], v[208:211], v[106:109]
	v_mfma_f32_16x16x32_bf16 v[94:97], v[130:133], v[216:219], v[94:97]
	v_mfma_f32_16x16x32_bf16 v[90:93], v[154:157], v[216:219], v[90:93]
	v_mfma_f32_16x16x32_bf16 v[78:81], v[130:133], v[224:227], v[78:81]
	v_mfma_f32_16x16x32_bf16 v[74:77], v[154:157], v[224:227], v[74:77]
	v_mfma_f32_16x16x32_bf16 v[126:129], v[150:153], v[204:207], v[126:129]
	v_mfma_f32_16x16x32_bf16 v[122:125], v[158:161], v[204:207], v[122:125]
	v_mfma_f32_16x16x32_bf16 v[110:113], v[150:153], v[212:215], v[110:113]
	v_mfma_f32_16x16x32_bf16 v[106:109], v[158:161], v[212:215], v[106:109]
	v_mfma_f32_16x16x32_bf16 v[94:97], v[150:153], v[220:223], v[94:97]
	v_mfma_f32_16x16x32_bf16 v[90:93], v[158:161], v[220:223], v[90:93]
	v_mfma_f32_16x16x32_bf16 v[78:81], v[150:153], v[228:231], v[78:81]
	v_mfma_f32_16x16x32_bf16 v[74:77], v[158:161], v[228:231], v[74:77]
	v_mfma_f32_16x16x32_bf16 v[118:121], v[174:177], v[190:193], v[118:121]
	v_mfma_f32_16x16x32_bf16 v[114:117], v[182:185], v[190:193], v[114:117]
	v_mfma_f32_16x16x32_bf16 v[102:105], v[174:177], v[208:211], v[102:105]
	v_mfma_f32_16x16x32_bf16 v[98:101], v[182:185], v[208:211], v[98:101]
	v_mfma_f32_16x16x32_bf16 v[86:89], v[174:177], v[216:219], v[86:89]
	v_mfma_f32_16x16x32_bf16 v[82:85], v[182:185], v[216:219], v[82:85]
	v_mfma_f32_16x16x32_bf16 v[70:73], v[174:177], v[224:227], v[70:73]
	v_mfma_f32_16x16x32_bf16 v[66:69], v[182:185], v[224:227], v[66:69]
	v_mfma_f32_16x16x32_bf16 v[118:121], v[178:181], v[204:207], v[118:121]
	v_mfma_f32_16x16x32_bf16 v[114:117], v[186:189], v[204:207], v[114:117]
	v_mfma_f32_16x16x32_bf16 v[102:105], v[178:181], v[212:215], v[102:105]
	v_mfma_f32_16x16x32_bf16 v[98:101], v[186:189], v[212:215], v[98:101]
	v_mfma_f32_16x16x32_bf16 v[86:89], v[178:181], v[220:223], v[86:89]
	v_mfma_f32_16x16x32_bf16 v[82:85], v[186:189], v[220:223], v[82:85]
	v_mfma_f32_16x16x32_bf16 v[70:73], v[178:181], v[228:231], v[70:73]
	v_mfma_f32_16x16x32_bf16 v[66:69], v[186:189], v[228:231], v[66:69]
	s_barrier
	s_setprio 0
	s_add_i32 s29, s29, s4
	v_lshl_add_u64 v[170:171], v[170:171], 0, s[24:25]
	s_mov_b32 m0, s29
	ds_read_b128 v[190:193], v196 offset:49152
	ds_read_b128 v[204:207], v196 offset:50176
	ds_read_b128 v[208:211], v196 offset:51200
	ds_read_b128 v[212:215], v196 offset:52224
	ds_read_b128 v[216:219], v196 offset:53248
	ds_read_b128 v[220:223], v196 offset:54272
	ds_read_b128 v[224:227], v196 offset:55296
	ds_read_b128 v[228:231], v196 offset:56320
	global_load_lds_dwordx4 v[170:171], off
	s_add_i32 m0, s29, 0x2000
	s_add_u32 s42, s42, 0x40080
	v_lshl_add_u64 v[170:171], v[172:173], 0, s[24:25]
	s_addc_u32 s43, s43, 0
	s_add_i32 s29, s37, s4
	global_load_lds_dwordx4 v[170:171], off
	s_mov_b32 m0, s29
	s_nop 0
	global_load_lds_dwordx4 v138, s[42:43]
	s_add_i32 m0, s29, 0x2000
	s_nop 0
	global_load_lds_dwordx4 v134, s[42:43]
	v_lshl_add_u64 v[170:171], v[198:199], 0, s[24:25]
	s_mov_b32 m0, s33
	s_nop 0
	global_load_lds_dwordx4 v[170:171], off
	v_lshl_add_u64 v[170:171], v[232:233], 0, s[24:25]
	s_mov_b32 m0, s72
	s_nop 0
	global_load_lds_dwordx4 v[170:171], off
	.p2align	3
	s_waitcnt vmcnt(8)
	s_waitcnt lgkmcnt(0)
	s_setprio 1
	s_barrier
	v_mfma_f32_16x16x32_bf16 v[62:65], v[130:133], v[190:193], v[62:65]
	v_mfma_f32_16x16x32_bf16 v[58:61], v[154:157], v[190:193], v[58:61]
	v_mfma_f32_16x16x32_bf16 v[46:49], v[130:133], v[208:211], v[46:49]
	v_mfma_f32_16x16x32_bf16 v[42:45], v[154:157], v[208:211], v[42:45]
	v_mfma_f32_16x16x32_bf16 v[30:33], v[130:133], v[216:219], v[30:33]
	v_mfma_f32_16x16x32_bf16 v[26:29], v[154:157], v[216:219], v[26:29]
	v_mfma_f32_16x16x32_bf16 v[14:17], v[130:133], v[224:227], v[14:17]
	v_mfma_f32_16x16x32_bf16 v[10:13], v[154:157], v[224:227], v[10:13]
	v_mfma_f32_16x16x32_bf16 v[62:65], v[150:153], v[204:207], v[62:65]
	v_mfma_f32_16x16x32_bf16 v[58:61], v[158:161], v[204:207], v[58:61]
	v_mfma_f32_16x16x32_bf16 v[46:49], v[150:153], v[212:215], v[46:49]
	v_mfma_f32_16x16x32_bf16 v[42:45], v[158:161], v[212:215], v[42:45]
	v_mfma_f32_16x16x32_bf16 v[30:33], v[150:153], v[220:223], v[30:33]
	v_mfma_f32_16x16x32_bf16 v[26:29], v[158:161], v[220:223], v[26:29]
	v_mfma_f32_16x16x32_bf16 v[14:17], v[150:153], v[228:231], v[14:17]
	v_mfma_f32_16x16x32_bf16 v[10:13], v[158:161], v[228:231], v[10:13]
	v_mfma_f32_16x16x32_bf16 v[54:57], v[174:177], v[190:193], v[54:57]
	v_mfma_f32_16x16x32_bf16 v[50:53], v[182:185], v[190:193], v[50:53]
	v_mfma_f32_16x16x32_bf16 v[38:41], v[174:177], v[208:211], v[38:41]
	v_mfma_f32_16x16x32_bf16 v[34:37], v[182:185], v[208:211], v[34:37]
	v_mfma_f32_16x16x32_bf16 v[22:25], v[174:177], v[216:219], v[22:25]
	v_mfma_f32_16x16x32_bf16 v[18:21], v[182:185], v[216:219], v[18:21]
	v_mfma_f32_16x16x32_bf16 v[6:9], v[174:177], v[224:227], v[6:9]
	v_mfma_f32_16x16x32_bf16 v[2:5], v[182:185], v[224:227], v[2:5]
	v_mfma_f32_16x16x32_bf16 v[54:57], v[178:181], v[204:207], v[54:57]
	v_mfma_f32_16x16x32_bf16 v[50:53], v[186:189], v[204:207], v[50:53]
	v_mfma_f32_16x16x32_bf16 v[38:41], v[178:181], v[212:215], v[38:41]
	v_mfma_f32_16x16x32_bf16 v[34:37], v[186:189], v[212:215], v[34:37]
	v_mfma_f32_16x16x32_bf16 v[22:25], v[178:181], v[220:223], v[22:25]
	v_mfma_f32_16x16x32_bf16 v[18:21], v[186:189], v[220:223], v[18:21]
	v_mfma_f32_16x16x32_bf16 v[6:9], v[178:181], v[228:231], v[6:9]
	v_mfma_f32_16x16x32_bf16 v[2:5], v[186:189], v[228:231], v[2:5]
	s_barrier
	s_setprio 0
	s_add_u32 s16, s16, 0x100
	s_addc_u32 s17, s17, 0
	s_add_u32 s48, s48, 0x100
	s_addc_u32 s49, s49, 0
	s_cmp_ge_i32 s56, s3
	s_mov_b32 s42, s56
	s_cbranch_scc0 .LBB7_523
	s_branch .Lpeelx_523
	.p2align	6
.LBB7_523:
	s_add_i32 s56, s42, 2
	s_add_u32 s29, s16, 0xfffc0080
	s_addc_u32 s37, s17, -1
	s_add_i32 s57, 0, 0x10000
	s_cmp_eq_u32 s84, s42
	s_cselect_b32 s45, s13, s37
	s_cselect_b32 s44, s15, s29
	v_add_u32_e32 v0, s57, v195
	s_cselect_b32 s43, s38, s49
	s_cselect_b32 s42, s39, s48
	s_add_i32 s29, 0, 0x14000
	ds_read_b128 v[130:133], v0
	ds_read_b128 v[150:153], v0 offset:1024
	ds_read_b128 v[154:157], v0 offset:2048
	ds_read_b128 v[158:161], v0 offset:3072
	v_add_u32_e32 v0, s29, v195
	ds_read_b128 v[174:177], v0
	ds_read_b128 v[178:181], v0 offset:1024
	ds_read_b128 v[182:185], v0 offset:2048
	ds_read_b128 v[186:189], v0 offset:3072
	s_add_i32 m0, s5, 0xc000
	ds_read_b128 v[190:193], v196
	ds_read_b128 v[204:207], v196 offset:1024
	ds_read_b128 v[208:211], v196 offset:2048
	ds_read_b128 v[212:215], v196 offset:3072
	ds_read_b128 v[216:219], v196 offset:4096
	ds_read_b128 v[220:223], v196 offset:5120
	ds_read_b128 v[224:227], v196 offset:6144
	ds_read_b128 v[228:231], v196 offset:7168
	global_load_lds_dwordx4 v146, s[16:17]
	s_add_i32 m0, s5, 0xe000
	s_nop 0
	global_load_lds_dwordx4 v148, s[16:17]
	.p2align	3
	s_waitcnt vmcnt(8)
	s_waitcnt lgkmcnt(0)
	s_setprio 1
	s_barrier
	v_mfma_f32_16x16x32_bf16 v[126:129], v[130:133], v[190:193], v[126:129]
	v_mfma_f32_16x16x32_bf16 v[122:125], v[154:157], v[190:193], v[122:125]
	v_mfma_f32_16x16x32_bf16 v[110:113], v[130:133], v[208:211], v[110:113]
	v_mfma_f32_16x16x32_bf16 v[106:109], v[154:157], v[208:211], v[106:109]
	v_mfma_f32_16x16x32_bf16 v[94:97], v[130:133], v[216:219], v[94:97]
	v_mfma_f32_16x16x32_bf16 v[90:93], v[154:157], v[216:219], v[90:93]
	v_mfma_f32_16x16x32_bf16 v[78:81], v[130:133], v[224:227], v[78:81]
	v_mfma_f32_16x16x32_bf16 v[74:77], v[154:157], v[224:227], v[74:77]
	v_mfma_f32_16x16x32_bf16 v[126:129], v[150:153], v[204:207], v[126:129]
	v_mfma_f32_16x16x32_bf16 v[122:125], v[158:161], v[204:207], v[122:125]
	v_mfma_f32_16x16x32_bf16 v[110:113], v[150:153], v[212:215], v[110:113]
	v_mfma_f32_16x16x32_bf16 v[106:109], v[158:161], v[212:215], v[106:109]
	v_mfma_f32_16x16x32_bf16 v[94:97], v[150:153], v[220:223], v[94:97]
	v_mfma_f32_16x16x32_bf16 v[90:93], v[158:161], v[220:223], v[90:93]
	v_mfma_f32_16x16x32_bf16 v[78:81], v[150:153], v[228:231], v[78:81]
	v_mfma_f32_16x16x32_bf16 v[74:77], v[158:161], v[228:231], v[74:77]
	v_mfma_f32_16x16x32_bf16 v[118:121], v[174:177], v[190:193], v[118:121]
	v_mfma_f32_16x16x32_bf16 v[114:117], v[182:185], v[190:193], v[114:117]
	v_mfma_f32_16x16x32_bf16 v[102:105], v[174:177], v[208:211], v[102:105]
	v_mfma_f32_16x16x32_bf16 v[98:101], v[182:185], v[208:211], v[98:101]
	v_mfma_f32_16x16x32_bf16 v[86:89], v[174:177], v[216:219], v[86:89]
	v_mfma_f32_16x16x32_bf16 v[82:85], v[182:185], v[216:219], v[82:85]
	v_mfma_f32_16x16x32_bf16 v[70:73], v[174:177], v[224:227], v[70:73]
	v_mfma_f32_16x16x32_bf16 v[66:69], v[182:185], v[224:227], v[66:69]
	v_mfma_f32_16x16x32_bf16 v[118:121], v[178:181], v[204:207], v[118:121]
	v_mfma_f32_16x16x32_bf16 v[114:117], v[186:189], v[204:207], v[114:117]
	v_mfma_f32_16x16x32_bf16 v[102:105], v[178:181], v[212:215], v[102:105]
	v_mfma_f32_16x16x32_bf16 v[98:101], v[186:189], v[212:215], v[98:101]
	v_mfma_f32_16x16x32_bf16 v[86:89], v[178:181], v[220:223], v[86:89]
	v_mfma_f32_16x16x32_bf16 v[82:85], v[186:189], v[220:223], v[82:85]
	v_mfma_f32_16x16x32_bf16 v[70:73], v[178:181], v[228:231], v[70:73]
	v_mfma_f32_16x16x32_bf16 v[66:69], v[186:189], v[228:231], v[66:69]
	s_barrier
	s_setprio 0
	s_add_i32 s37, s57, s4
	v_lshl_add_u64 v[170:171], s[42:43], 0, v[138:139]
	s_mov_b32 m0, s37
	ds_read_b128 v[190:193], v196 offset:16384
	ds_read_b128 v[204:207], v196 offset:17408
	ds_read_b128 v[208:211], v196 offset:18432
	ds_read_b128 v[212:215], v196 offset:19456
	ds_read_b128 v[216:219], v196 offset:20480
	ds_read_b128 v[220:223], v196 offset:21504
	ds_read_b128 v[224:227], v196 offset:22528
	ds_read_b128 v[228:231], v196 offset:23552
	global_load_lds_dwordx4 v[170:171], off
	s_add_i32 m0, s37, 0x2000
	s_add_u32 s74, s42, 0x40000
	v_lshl_add_u64 v[172:173], s[42:43], 0, v[134:135]
	s_addc_u32 s75, s43, 0
	s_add_i32 s29, s29, s4
	global_load_lds_dwordx4 v[172:173], off
	s_mov_b32 m0, s29
	v_lshl_add_u64 v[232:233], s[44:45], 0, v[136:137]
	global_load_lds_dwordx4 v138, s[74:75]
	s_add_i32 m0, s29, 0x2000
	s_nop 0
	global_load_lds_dwordx4 v134, s[74:75]
	v_lshl_add_u64 v[198:199], s[44:45], 0, v[140:141]
	s_mov_b32 m0, s5
	s_nop 0
	global_load_lds_dwordx4 v[198:199], off
	s_mov_b32 m0, s20
	s_nop 0
	global_load_lds_dwordx4 v[232:233], off
	.p2align	3
	s_waitcnt vmcnt(8)
	s_waitcnt lgkmcnt(0)
	s_setprio 1
	s_barrier
	v_mfma_f32_16x16x32_bf16 v[62:65], v[130:133], v[190:193], v[62:65]
	v_mfma_f32_16x16x32_bf16 v[58:61], v[154:157], v[190:193], v[58:61]
	v_mfma_f32_16x16x32_bf16 v[46:49], v[130:133], v[208:211], v[46:49]
	v_mfma_f32_16x16x32_bf16 v[42:45], v[154:157], v[208:211], v[42:45]
	v_mfma_f32_16x16x32_bf16 v[30:33], v[130:133], v[216:219], v[30:33]
	v_mfma_f32_16x16x32_bf16 v[26:29], v[154:157], v[216:219], v[26:29]
	v_mfma_f32_16x16x32_bf16 v[14:17], v[130:133], v[224:227], v[14:17]
	v_mfma_f32_16x16x32_bf16 v[10:13], v[154:157], v[224:227], v[10:13]
	v_mfma_f32_16x16x32_bf16 v[62:65], v[150:153], v[204:207], v[62:65]
	v_mfma_f32_16x16x32_bf16 v[58:61], v[158:161], v[204:207], v[58:61]
	v_mfma_f32_16x16x32_bf16 v[46:49], v[150:153], v[212:215], v[46:49]
	v_mfma_f32_16x16x32_bf16 v[42:45], v[158:161], v[212:215], v[42:45]
	v_mfma_f32_16x16x32_bf16 v[30:33], v[150:153], v[220:223], v[30:33]
	v_mfma_f32_16x16x32_bf16 v[26:29], v[158:161], v[220:223], v[26:29]
	v_mfma_f32_16x16x32_bf16 v[14:17], v[150:153], v[228:231], v[14:17]
	v_mfma_f32_16x16x32_bf16 v[10:13], v[158:161], v[228:231], v[10:13]
	v_mfma_f32_16x16x32_bf16 v[54:57], v[174:177], v[190:193], v[54:57]
	v_mfma_f32_16x16x32_bf16 v[50:53], v[182:185], v[190:193], v[50:53]
	v_mfma_f32_16x16x32_bf16 v[38:41], v[174:177], v[208:211], v[38:41]
	v_mfma_f32_16x16x32_bf16 v[34:37], v[182:185], v[208:211], v[34:37]
	v_mfma_f32_16x16x32_bf16 v[22:25], v[174:177], v[216:219], v[22:25]
	v_mfma_f32_16x16x32_bf16 v[18:21], v[182:185], v[216:219], v[18:21]
	v_mfma_f32_16x16x32_bf16 v[6:9], v[174:177], v[224:227], v[6:9]
	v_mfma_f32_16x16x32_bf16 v[2:5], v[182:185], v[224:227], v[2:5]
	v_mfma_f32_16x16x32_bf16 v[54:57], v[178:181], v[204:207], v[54:57]
	v_mfma_f32_16x16x32_bf16 v[50:53], v[186:189], v[204:207], v[50:53]
	v_mfma_f32_16x16x32_bf16 v[38:41], v[178:181], v[212:215], v[38:41]
	v_mfma_f32_16x16x32_bf16 v[34:37], v[186:189], v[212:215], v[34:37]
	v_mfma_f32_16x16x32_bf16 v[22:25], v[178:181], v[220:223], v[22:25]
	v_mfma_f32_16x16x32_bf16 v[18:21], v[186:189], v[220:223], v[18:21]
	v_mfma_f32_16x16x32_bf16 v[6:9], v[178:181], v[228:231], v[6:9]
	v_mfma_f32_16x16x32_bf16 v[2:5], v[186:189], v[228:231], v[2:5]
	s_barrier
	s_setprio 0
	s_add_i32 s29, 0, 0x18000
	v_add_u32_e32 v0, s29, v195
	s_add_i32 s37, 0, 0x1c000
	ds_read_b128 v[130:133], v0
	ds_read_b128 v[150:153], v0 offset:1024
	ds_read_b128 v[154:157], v0 offset:2048
	ds_read_b128 v[158:161], v0 offset:3072
	v_add_u32_e32 v0, s37, v195
	ds_read_b128 v[174:177], v0
	ds_read_b128 v[178:181], v0 offset:1024
	ds_read_b128 v[182:185], v0 offset:2048
	ds_read_b128 v[186:189], v0 offset:3072
	s_add_u32 s44, s44, 0x40000
	s_addc_u32 s45, s45, 0
	s_mov_b32 m0, s22
	ds_read_b128 v[190:193], v196 offset:32768
	ds_read_b128 v[204:207], v196 offset:33792
	ds_read_b128 v[208:211], v196 offset:34816
	ds_read_b128 v[212:215], v196 offset:35840
	ds_read_b128 v[216:219], v196 offset:36864
	ds_read_b128 v[220:223], v196 offset:37888
	ds_read_b128 v[224:227], v196 offset:38912
	ds_read_b128 v[228:231], v196 offset:39936
	global_load_lds_dwordx4 v140, s[44:45]
	s_mov_b32 m0, s23
	s_nop 0
	global_load_lds_dwordx4 v136, s[44:45]
	.p2align	3
	s_waitcnt vmcnt(8)
	s_waitcnt lgkmcnt(0)
	s_setprio 1
	s_barrier
	v_mfma_f32_16x16x32_bf16 v[126:129], v[130:133], v[190:193], v[126:129]
	v_mfma_f32_16x16x32_bf16 v[122:125], v[154:157], v[190:193], v[122:125]
	v_mfma_f32_16x16x32_bf16 v[110:113], v[130:133], v[208:211], v[110:113]
	v_mfma_f32_16x16x32_bf16 v[106:109], v[154:157], v[208:211], v[106:109]
	v_mfma_f32_16x16x32_bf16 v[94:97], v[130:133], v[216:219], v[94:97]
	v_mfma_f32_16x16x32_bf16 v[90:93], v[154:157], v[216:219], v[90:93]
	v_mfma_f32_16x16x32_bf16 v[78:81], v[130:133], v[224:227], v[78:81]
	v_mfma_f32_16x16x32_bf16 v[74:77], v[154:157], v[224:227], v[74:77]
	v_mfma_f32_16x16x32_bf16 v[126:129], v[150:153], v[204:207], v[126:129]
	v_mfma_f32_16x16x32_bf16 v[122:125], v[158:161], v[204:207], v[122:125]
	v_mfma_f32_16x16x32_bf16 v[110:113], v[150:153], v[212:215], v[110:113]
	v_mfma_f32_16x16x32_bf16 v[106:109], v[158:161], v[212:215], v[106:109]
	v_mfma_f32_16x16x32_bf16 v[94:97], v[150:153], v[220:223], v[94:97]
	v_mfma_f32_16x16x32_bf16 v[90:93], v[158:161], v[220:223], v[90:93]
	v_mfma_f32_16x16x32_bf16 v[78:81], v[150:153], v[228:231], v[78:81]
	v_mfma_f32_16x16x32_bf16 v[74:77], v[158:161], v[228:231], v[74:77]
	v_mfma_f32_16x16x32_bf16 v[118:121], v[174:177], v[190:193], v[118:121]
	v_mfma_f32_16x16x32_bf16 v[114:117], v[182:185], v[190:193], v[114:117]
	v_mfma_f32_16x16x32_bf16 v[102:105], v[174:177], v[208:211], v[102:105]
	v_mfma_f32_16x16x32_bf16 v[98:101], v[182:185], v[208:211], v[98:101]
	v_mfma_f32_16x16x32_bf16 v[86:89], v[174:177], v[216:219], v[86:89]
	v_mfma_f32_16x16x32_bf16 v[82:85], v[182:185], v[216:219], v[82:85]
	v_mfma_f32_16x16x32_bf16 v[70:73], v[174:177], v[224:227], v[70:73]
	v_mfma_f32_16x16x32_bf16 v[66:69], v[182:185], v[224:227], v[66:69]
	v_mfma_f32_16x16x32_bf16 v[118:121], v[178:181], v[204:207], v[118:121]
	v_mfma_f32_16x16x32_bf16 v[114:117], v[186:189], v[204:207], v[114:117]
	v_mfma_f32_16x16x32_bf16 v[102:105], v[178:181], v[212:215], v[102:105]
	v_mfma_f32_16x16x32_bf16 v[98:101], v[186:189], v[212:215], v[98:101]
	v_mfma_f32_16x16x32_bf16 v[86:89], v[178:181], v[220:223], v[86:89]
	v_mfma_f32_16x16x32_bf16 v[82:85], v[186:189], v[220:223], v[82:85]
	v_mfma_f32_16x16x32_bf16 v[70:73], v[178:181], v[228:231], v[70:73]
	v_mfma_f32_16x16x32_bf16 v[66:69], v[186:189], v[228:231], v[66:69]
	s_barrier
	s_setprio 0
	s_add_i32 s29, s29, s4
	v_lshl_add_u64 v[170:171], v[170:171], 0, s[24:25]
	s_mov_b32 m0, s29
	ds_read_b128 v[190:193], v196 offset:49152
	ds_read_b128 v[204:207], v196 offset:50176
	ds_read_b128 v[208:211], v196 offset:51200
	ds_read_b128 v[212:215], v196 offset:52224
	ds_read_b128 v[216:219], v196 offset:53248
	ds_read_b128 v[220:223], v196 offset:54272
	ds_read_b128 v[224:227], v196 offset:55296
	ds_read_b128 v[228:231], v196 offset:56320
	global_load_lds_dwordx4 v[170:171], off
	s_add_i32 m0, s29, 0x2000
	s_add_u32 s42, s42, 0x40080
	v_lshl_add_u64 v[170:171], v[172:173], 0, s[24:25]
	s_addc_u32 s43, s43, 0
	s_add_i32 s29, s37, s4
	global_load_lds_dwordx4 v[170:171], off
	s_mov_b32 m0, s29
	s_nop 0
	global_load_lds_dwordx4 v138, s[42:43]
	s_add_i32 m0, s29, 0x2000
	s_nop 0
	global_load_lds_dwordx4 v134, s[42:43]
	v_lshl_add_u64 v[170:171], v[198:199], 0, s[24:25]
	s_mov_b32 m0, s33
	s_nop 0
	global_load_lds_dwordx4 v[170:171], off
	v_lshl_add_u64 v[170:171], v[232:233], 0, s[24:25]
	s_mov_b32 m0, s72
	s_nop 0
	global_load_lds_dwordx4 v[170:171], off
	.p2align	3
	s_waitcnt vmcnt(8)
	s_waitcnt lgkmcnt(0)
	s_setprio 1
	s_barrier
	v_mfma_f32_16x16x32_bf16 v[62:65], v[130:133], v[190:193], v[62:65]
	v_mfma_f32_16x16x32_bf16 v[58:61], v[154:157], v[190:193], v[58:61]
	v_mfma_f32_16x16x32_bf16 v[46:49], v[130:133], v[208:211], v[46:49]
	v_mfma_f32_16x16x32_bf16 v[42:45], v[154:157], v[208:211], v[42:45]
	v_mfma_f32_16x16x32_bf16 v[30:33], v[130:133], v[216:219], v[30:33]
	v_mfma_f32_16x16x32_bf16 v[26:29], v[154:157], v[216:219], v[26:29]
	v_mfma_f32_16x16x32_bf16 v[14:17], v[130:133], v[224:227], v[14:17]
	v_mfma_f32_16x16x32_bf16 v[10:13], v[154:157], v[224:227], v[10:13]
	v_mfma_f32_16x16x32_bf16 v[62:65], v[150:153], v[204:207], v[62:65]
	v_mfma_f32_16x16x32_bf16 v[58:61], v[158:161], v[204:207], v[58:61]
	v_mfma_f32_16x16x32_bf16 v[46:49], v[150:153], v[212:215], v[46:49]
	v_mfma_f32_16x16x32_bf16 v[42:45], v[158:161], v[212:215], v[42:45]
	v_mfma_f32_16x16x32_bf16 v[30:33], v[150:153], v[220:223], v[30:33]
	v_mfma_f32_16x16x32_bf16 v[26:29], v[158:161], v[220:223], v[26:29]
	v_mfma_f32_16x16x32_bf16 v[14:17], v[150:153], v[228:231], v[14:17]
	v_mfma_f32_16x16x32_bf16 v[10:13], v[158:161], v[228:231], v[10:13]
	v_mfma_f32_16x16x32_bf16 v[54:57], v[174:177], v[190:193], v[54:57]
	v_mfma_f32_16x16x32_bf16 v[50:53], v[182:185], v[190:193], v[50:53]
	v_mfma_f32_16x16x32_bf16 v[38:41], v[174:177], v[208:211], v[38:41]
	v_mfma_f32_16x16x32_bf16 v[34:37], v[182:185], v[208:211], v[34:37]
	v_mfma_f32_16x16x32_bf16 v[22:25], v[174:177], v[216:219], v[22:25]
	v_mfma_f32_16x16x32_bf16 v[18:21], v[182:185], v[216:219], v[18:21]
	v_mfma_f32_16x16x32_bf16 v[6:9], v[174:177], v[224:227], v[6:9]
	v_mfma_f32_16x16x32_bf16 v[2:5], v[182:185], v[224:227], v[2:5]
	v_mfma_f32_16x16x32_bf16 v[54:57], v[178:181], v[204:207], v[54:57]
	v_mfma_f32_16x16x32_bf16 v[50:53], v[186:189], v[204:207], v[50:53]
	v_mfma_f32_16x16x32_bf16 v[38:41], v[178:181], v[212:215], v[38:41]
	v_mfma_f32_16x16x32_bf16 v[34:37], v[186:189], v[212:215], v[34:37]
	v_mfma_f32_16x16x32_bf16 v[22:25], v[178:181], v[220:223], v[22:25]
	v_mfma_f32_16x16x32_bf16 v[18:21], v[186:189], v[220:223], v[18:21]
	v_mfma_f32_16x16x32_bf16 v[6:9], v[178:181], v[228:231], v[6:9]
	v_mfma_f32_16x16x32_bf16 v[2:5], v[186:189], v[228:231], v[2:5]
	s_barrier
	s_setprio 0
	s_add_u32 s16, s16, 0x100
	s_addc_u32 s17, s17, 0
	s_add_u32 s48, s48, 0x100
	s_addc_u32 s49, s49, 0
	s_cmp_ge_i32 s56, s3
	s_mov_b32 s42, s56
	s_cbranch_scc0 .LBB7_523

.Lpeel_676:
	s_add_i32 s29, s37, 2
	s_add_u32 s44, s42, 0x100
	s_addc_u32 s45, s43, 0
	s_add_i32 s74, 0, 0x10000
	v_add_u32_e32 v81, s74, v79
	ds_read_b128 v[82:85], v81
	ds_read_b128 v[86:89], v81 offset:1024
	ds_read_b128 v[90:93], v81 offset:2048
	ds_read_b128 v[94:97], v81 offset:3072
	s_cmp_eq_u32 s53, s37
	s_cselect_b32 s51, s56, s45
	s_cselect_b32 s50, s57, s44
	s_cselect_b32 s49, s72, s85
	s_cselect_b32 s48, s73, s84
	v_lshl_add_u64 v[130:131], s[42:43], 0, v[74:75]
	s_add_i32 m0, s5, 0xc000
	ds_read_b128 v[98:101], v80
	ds_read_b128 v[102:105], v80 offset:1024
	ds_read_b128 v[106:109], v80 offset:2048
	ds_read_b128 v[110:113], v80 offset:3072
	ds_read_b128 v[114:117], v80 offset:4096
	ds_read_b128 v[118:121], v80 offset:5120
	ds_read_b128 v[122:125], v80 offset:6144
	ds_read_b128 v[126:129], v80 offset:7168
	global_load_lds_dwordx4 v[130:131], off
	v_lshl_add_u64 v[130:131], s[42:43], 0, v[76:77]
	s_add_i32 m0, s5, 0xe000
	s_nop 0
	global_load_lds_dwordx4 v[130:131], off
	.p2align	3
	s_waitcnt vmcnt(8)
	s_waitcnt lgkmcnt(0)
	s_setprio 1
	s_barrier
	v_mfma_f32_16x16x32_bf16 v[62:65], v[82:85], v[98:101], 0
	v_mfma_f32_16x16x32_bf16 v[58:61], v[90:93], v[98:101], 0
	v_mfma_f32_16x16x32_bf16 v[54:57], v[82:85], v[106:109], 0
	v_mfma_f32_16x16x32_bf16 v[50:53], v[90:93], v[106:109], 0
	v_mfma_f32_16x16x32_bf16 v[46:49], v[82:85], v[114:117], 0
	v_mfma_f32_16x16x32_bf16 v[42:45], v[90:93], v[114:117], 0
	v_mfma_f32_16x16x32_bf16 v[38:41], v[82:85], v[122:125], 0
	v_mfma_f32_16x16x32_bf16 v[34:37], v[90:93], v[122:125], 0
	v_mfma_f32_16x16x32_bf16 v[62:65], v[86:89], v[102:105], v[62:65]
	v_mfma_f32_16x16x32_bf16 v[58:61], v[94:97], v[102:105], v[58:61]
	v_mfma_f32_16x16x32_bf16 v[54:57], v[86:89], v[110:113], v[54:57]
	v_mfma_f32_16x16x32_bf16 v[50:53], v[94:97], v[110:113], v[50:53]
	v_mfma_f32_16x16x32_bf16 v[46:49], v[86:89], v[118:121], v[46:49]
	v_mfma_f32_16x16x32_bf16 v[42:45], v[94:97], v[118:121], v[42:45]
	v_mfma_f32_16x16x32_bf16 v[38:41], v[86:89], v[126:129], v[38:41]
	v_mfma_f32_16x16x32_bf16 v[34:37], v[94:97], v[126:129], v[34:37]
	s_barrier
	s_setprio 0
	s_add_i32 s37, s74, s4
	v_lshl_add_u64 v[130:131], s[48:49], 0, v[70:71]
	s_mov_b32 m0, s37
	ds_read_b128 v[98:101], v80 offset:16384
	ds_read_b128 v[102:105], v80 offset:17408
	ds_read_b128 v[106:109], v80 offset:18432
	ds_read_b128 v[110:113], v80 offset:19456
	ds_read_b128 v[114:117], v80 offset:20480
	ds_read_b128 v[118:121], v80 offset:21504
	ds_read_b128 v[122:125], v80 offset:22528
	ds_read_b128 v[126:129], v80 offset:23552
	global_load_lds_dwordx4 v[130:131], off
	s_add_i32 m0, s37, 0x2000
	s_add_u32 s42, s48, 0x20000
	v_lshl_add_u64 v[132:133], s[48:49], 0, v[66:67]
	s_addc_u32 s43, s49, 0
	global_load_lds_dwordx4 v[132:133], off
	v_lshl_add_u64 v[134:135], s[42:43], 0, v[70:71]
	s_mov_b32 m0, s10
	v_lshl_add_u64 v[136:137], s[50:51], 0, v[68:69]
	global_load_lds_dwordx4 v[134:135], off
	v_lshl_add_u64 v[134:135], s[42:43], 0, v[66:67]
	s_mov_b32 m0, s20
	s_nop 0
	global_load_lds_dwordx4 v[134:135], off
	v_lshl_add_u64 v[134:135], s[50:51], 0, v[0:1]
	s_mov_b32 m0, s5
	s_nop 0
	global_load_lds_dwordx4 v[134:135], off
	s_mov_b32 m0, s22
	s_nop 0
	global_load_lds_dwordx4 v[136:137], off
	.p2align	3
	s_waitcnt vmcnt(8)
	s_waitcnt lgkmcnt(0)
	s_setprio 1
	s_barrier
	v_mfma_f32_16x16x32_bf16 v[30:33], v[82:85], v[98:101], 0
	v_mfma_f32_16x16x32_bf16 v[26:29], v[90:93], v[98:101], 0
	v_mfma_f32_16x16x32_bf16 v[22:25], v[82:85], v[106:109], 0
	v_mfma_f32_16x16x32_bf16 v[18:21], v[90:93], v[106:109], 0
	v_mfma_f32_16x16x32_bf16 v[14:17], v[82:85], v[114:117], 0
	v_mfma_f32_16x16x32_bf16 v[10:13], v[90:93], v[114:117], 0
	v_mfma_f32_16x16x32_bf16 v[6:9], v[82:85], v[122:125], 0
	v_mfma_f32_16x16x32_bf16 v[2:5], v[90:93], v[122:125], 0
	v_mfma_f32_16x16x32_bf16 v[30:33], v[86:89], v[102:105], v[30:33]
	v_mfma_f32_16x16x32_bf16 v[26:29], v[94:97], v[102:105], v[26:29]
	v_mfma_f32_16x16x32_bf16 v[22:25], v[86:89], v[110:113], v[22:25]
	v_mfma_f32_16x16x32_bf16 v[18:21], v[94:97], v[110:113], v[18:21]
	v_mfma_f32_16x16x32_bf16 v[14:17], v[86:89], v[118:121], v[14:17]
	v_mfma_f32_16x16x32_bf16 v[10:13], v[94:97], v[118:121], v[10:13]
	v_mfma_f32_16x16x32_bf16 v[6:9], v[86:89], v[126:129], v[6:9]
	v_mfma_f32_16x16x32_bf16 v[2:5], v[94:97], v[126:129], v[2:5]
	s_barrier
	s_setprio 0
	s_add_i32 s37, 0, 0x18000
	v_add_u32_e32 v81, s37, v79
	ds_read_b128 v[82:85], v81
	ds_read_b128 v[86:89], v81 offset:1024
	ds_read_b128 v[90:93], v81 offset:2048
	ds_read_b128 v[94:97], v81 offset:3072
	s_add_u32 s42, s50, 0x28000
	s_addc_u32 s43, s51, 0
	s_mov_b32 m0, s23
	v_lshl_add_u64 v[138:139], s[42:43], 0, v[0:1]
	ds_read_b128 v[98:101], v80 offset:32768
	ds_read_b128 v[102:105], v80 offset:33792
	ds_read_b128 v[106:109], v80 offset:34816
	ds_read_b128 v[110:113], v80 offset:35840
	ds_read_b128 v[114:117], v80 offset:36864
	ds_read_b128 v[118:121], v80 offset:37888
	ds_read_b128 v[122:125], v80 offset:38912
	ds_read_b128 v[126:129], v80 offset:39936
	global_load_lds_dwordx4 v[138:139], off
	v_lshl_add_u64 v[138:139], s[42:43], 0, v[68:69]
	s_mov_b32 m0, s28
	s_nop 0
	global_load_lds_dwordx4 v[138:139], off
	.p2align	3
	s_waitcnt vmcnt(8)
	s_waitcnt lgkmcnt(0)
	s_setprio 1
	s_barrier
	v_mfma_f32_16x16x32_bf16 v[62:65], v[82:85], v[98:101], v[62:65]
	v_mfma_f32_16x16x32_bf16 v[58:61], v[90:93], v[98:101], v[58:61]
	v_mfma_f32_16x16x32_bf16 v[54:57], v[82:85], v[106:109], v[54:57]
	v_mfma_f32_16x16x32_bf16 v[50:53], v[90:93], v[106:109], v[50:53]
	v_mfma_f32_16x16x32_bf16 v[46:49], v[82:85], v[114:117], v[46:49]
	v_mfma_f32_16x16x32_bf16 v[42:45], v[90:93], v[114:117], v[42:45]
	v_mfma_f32_16x16x32_bf16 v[38:41], v[82:85], v[122:125], v[38:41]
	v_mfma_f32_16x16x32_bf16 v[34:37], v[90:93], v[122:125], v[34:37]
	v_mfma_f32_16x16x32_bf16 v[62:65], v[86:89], v[102:105], v[62:65]
	v_mfma_f32_16x16x32_bf16 v[58:61], v[94:97], v[102:105], v[58:61]
	v_mfma_f32_16x16x32_bf16 v[54:57], v[86:89], v[110:113], v[54:57]
	v_mfma_f32_16x16x32_bf16 v[50:53], v[94:97], v[110:113], v[50:53]
	v_mfma_f32_16x16x32_bf16 v[46:49], v[86:89], v[118:121], v[46:49]
	v_mfma_f32_16x16x32_bf16 v[42:45], v[94:97], v[118:121], v[42:45]
	v_mfma_f32_16x16x32_bf16 v[38:41], v[86:89], v[126:129], v[38:41]
	v_mfma_f32_16x16x32_bf16 v[34:37], v[94:97], v[126:129], v[34:37]
	s_barrier
	s_setprio 0
	s_add_i32 s37, s37, s4
	v_lshl_add_u64 v[130:131], v[130:131], 0, s[24:25]
	s_mov_b32 m0, s37
	ds_read_b128 v[98:101], v80 offset:49152
	ds_read_b128 v[102:105], v80 offset:50176
	ds_read_b128 v[106:109], v80 offset:51200
	ds_read_b128 v[110:113], v80 offset:52224
	ds_read_b128 v[114:117], v80 offset:53248
	ds_read_b128 v[118:121], v80 offset:54272
	ds_read_b128 v[122:125], v80 offset:55296
	ds_read_b128 v[126:129], v80 offset:56320
	global_load_lds_dwordx4 v[130:131], off
	s_add_i32 m0, s37, 0x2000
	s_add_u32 s42, s48, 0x20080
	v_lshl_add_u64 v[130:131], v[132:133], 0, s[24:25]
	s_addc_u32 s43, s49, 0
	global_load_lds_dwordx4 v[130:131], off
	v_lshl_add_u64 v[130:131], s[42:43], 0, v[70:71]
	s_mov_b32 m0, s38
	s_nop 0
	global_load_lds_dwordx4 v[130:131], off
	v_lshl_add_u64 v[130:131], s[42:43], 0, v[66:67]
	s_mov_b32 m0, s39
	s_nop 0
	global_load_lds_dwordx4 v[130:131], off
	v_lshl_add_u64 v[130:131], v[134:135], 0, s[24:25]
	s_mov_b32 m0, s31
	s_nop 0
	global_load_lds_dwordx4 v[130:131], off
	v_lshl_add_u64 v[130:131], v[136:137], 0, s[24:25]
	s_mov_b32 m0, s33
	s_nop 0
	global_load_lds_dwordx4 v[130:131], off
	.p2align	3
	s_waitcnt vmcnt(8)
	s_waitcnt lgkmcnt(0)
	s_setprio 1
	s_barrier
	v_mfma_f32_16x16x32_bf16 v[30:33], v[82:85], v[98:101], v[30:33]
	v_mfma_f32_16x16x32_bf16 v[26:29], v[90:93], v[98:101], v[26:29]
	v_mfma_f32_16x16x32_bf16 v[22:25], v[82:85], v[106:109], v[22:25]
	v_mfma_f32_16x16x32_bf16 v[18:21], v[90:93], v[106:109], v[18:21]
	v_mfma_f32_16x16x32_bf16 v[14:17], v[82:85], v[114:117], v[14:17]
	v_mfma_f32_16x16x32_bf16 v[10:13], v[90:93], v[114:117], v[10:13]
	v_mfma_f32_16x16x32_bf16 v[6:9], v[82:85], v[122:125], v[6:9]
	v_mfma_f32_16x16x32_bf16 v[2:5], v[90:93], v[122:125], v[2:5]
	v_mfma_f32_16x16x32_bf16 v[30:33], v[86:89], v[102:105], v[30:33]
	v_mfma_f32_16x16x32_bf16 v[26:29], v[94:97], v[102:105], v[26:29]
	v_mfma_f32_16x16x32_bf16 v[22:25], v[86:89], v[110:113], v[22:25]
	v_mfma_f32_16x16x32_bf16 v[18:21], v[94:97], v[110:113], v[18:21]
	v_mfma_f32_16x16x32_bf16 v[14:17], v[86:89], v[118:121], v[14:17]
	v_mfma_f32_16x16x32_bf16 v[10:13], v[94:97], v[118:121], v[10:13]
	v_mfma_f32_16x16x32_bf16 v[6:9], v[86:89], v[126:129], v[6:9]
	v_mfma_f32_16x16x32_bf16 v[2:5], v[94:97], v[126:129], v[2:5]
	s_barrier
	s_setprio 0
	s_add_u32 s84, s84, 0x100
	s_addc_u32 s85, s85, 0
	s_cmp_ge_i32 s29, s3
	s_mov_b64 s[42:43], s[44:45]
	s_mov_b32 s37, s29
	s_cbranch_scc0 .LBB7_676
	s_branch .Lpeelx_676
	.p2align	6
.LBB7_676:
	s_add_i32 s29, s37, 2
	s_add_u32 s44, s42, 0x100
	s_addc_u32 s45, s43, 0
	s_add_i32 s74, 0, 0x10000
	v_add_u32_e32 v81, s74, v79
	ds_read_b128 v[82:85], v81
	ds_read_b128 v[86:89], v81 offset:1024
	ds_read_b128 v[90:93], v81 offset:2048
	ds_read_b128 v[94:97], v81 offset:3072
	s_cmp_eq_u32 s53, s37
	s_cselect_b32 s51, s56, s45
	s_cselect_b32 s50, s57, s44
	s_cselect_b32 s49, s72, s85
	s_cselect_b32 s48, s73, s84
	v_lshl_add_u64 v[130:131], s[42:43], 0, v[74:75]
	s_add_i32 m0, s5, 0xc000
	ds_read_b128 v[98:101], v80
	ds_read_b128 v[102:105], v80 offset:1024
	ds_read_b128 v[106:109], v80 offset:2048
	ds_read_b128 v[110:113], v80 offset:3072
	ds_read_b128 v[114:117], v80 offset:4096
	ds_read_b128 v[118:121], v80 offset:5120
	ds_read_b128 v[122:125], v80 offset:6144
	ds_read_b128 v[126:129], v80 offset:7168
	global_load_lds_dwordx4 v[130:131], off
	v_lshl_add_u64 v[130:131], s[42:43], 0, v[76:77]
	s_add_i32 m0, s5, 0xe000
	s_nop 0
	global_load_lds_dwordx4 v[130:131], off
	.p2align	3
	s_waitcnt vmcnt(8)
	s_waitcnt lgkmcnt(0)
	s_setprio 1
	s_barrier
	v_mfma_f32_16x16x32_bf16 v[62:65], v[82:85], v[98:101], v[62:65]
	v_mfma_f32_16x16x32_bf16 v[58:61], v[90:93], v[98:101], v[58:61]
	v_mfma_f32_16x16x32_bf16 v[54:57], v[82:85], v[106:109], v[54:57]
	v_mfma_f32_16x16x32_bf16 v[50:53], v[90:93], v[106:109], v[50:53]
	v_mfma_f32_16x16x32_bf16 v[46:49], v[82:85], v[114:117], v[46:49]
	v_mfma_f32_16x16x32_bf16 v[42:45], v[90:93], v[114:117], v[42:45]
	v_mfma_f32_16x16x32_bf16 v[38:41], v[82:85], v[122:125], v[38:41]
	v_mfma_f32_16x16x32_bf16 v[34:37], v[90:93], v[122:125], v[34:37]
	v_mfma_f32_16x16x32_bf16 v[62:65], v[86:89], v[102:105], v[62:65]
	v_mfma_f32_16x16x32_bf16 v[58:61], v[94:97], v[102:105], v[58:61]
	v_mfma_f32_16x16x32_bf16 v[54:57], v[86:89], v[110:113], v[54:57]
	v_mfma_f32_16x16x32_bf16 v[50:53], v[94:97], v[110:113], v[50:53]
	v_mfma_f32_16x16x32_bf16 v[46:49], v[86:89], v[118:121], v[46:49]
	v_mfma_f32_16x16x32_bf16 v[42:45], v[94:97], v[118:121], v[42:45]
	v_mfma_f32_16x16x32_bf16 v[38:41], v[86:89], v[126:129], v[38:41]
	v_mfma_f32_16x16x32_bf16 v[34:37], v[94:97], v[126:129], v[34:37]
	s_barrier
	s_setprio 0
	s_add_i32 s37, s74, s4
	v_lshl_add_u64 v[130:131], s[48:49], 0, v[70:71]
	s_mov_b32 m0, s37
	ds_read_b128 v[98:101], v80 offset:16384
	ds_read_b128 v[102:105], v80 offset:17408
	ds_read_b128 v[106:109], v80 offset:18432
	ds_read_b128 v[110:113], v80 offset:19456
	ds_read_b128 v[114:117], v80 offset:20480
	ds_read_b128 v[118:121], v80 offset:21504
	ds_read_b128 v[122:125], v80 offset:22528
	ds_read_b128 v[126:129], v80 offset:23552
	global_load_lds_dwordx4 v[130:131], off
	s_add_i32 m0, s37, 0x2000
	s_add_u32 s42, s48, 0x20000
	v_lshl_add_u64 v[132:133], s[48:49], 0, v[66:67]
	s_addc_u32 s43, s49, 0
	global_load_lds_dwordx4 v[132:133], off
	v_lshl_add_u64 v[134:135], s[42:43], 0, v[70:71]
	s_mov_b32 m0, s10
	v_lshl_add_u64 v[136:137], s[50:51], 0, v[68:69]
	global_load_lds_dwordx4 v[134:135], off
	v_lshl_add_u64 v[134:135], s[42:43], 0, v[66:67]
	s_mov_b32 m0, s20
	s_nop 0
	global_load_lds_dwordx4 v[134:135], off
	v_lshl_add_u64 v[134:135], s[50:51], 0, v[0:1]
	s_mov_b32 m0, s5
	s_nop 0
	global_load_lds_dwordx4 v[134:135], off
	s_mov_b32 m0, s22
	s_nop 0
	global_load_lds_dwordx4 v[136:137], off
	.p2align	3
	s_waitcnt vmcnt(8)
	s_waitcnt lgkmcnt(0)
	s_setprio 1
	s_barrier
	v_mfma_f32_16x16x32_bf16 v[30:33], v[82:85], v[98:101], v[30:33]
	v_mfma_f32_16x16x32_bf16 v[26:29], v[90:93], v[98:101], v[26:29]
	v_mfma_f32_16x16x32_bf16 v[22:25], v[82:85], v[106:109], v[22:25]
	v_mfma_f32_16x16x32_bf16 v[18:21], v[90:93], v[106:109], v[18:21]
	v_mfma_f32_16x16x32_bf16 v[14:17], v[82:85], v[114:117], v[14:17]
	v_mfma_f32_16x16x32_bf16 v[10:13], v[90:93], v[114:117], v[10:13]
	v_mfma_f32_16x16x32_bf16 v[6:9], v[82:85], v[122:125], v[6:9]
	v_mfma_f32_16x16x32_bf16 v[2:5], v[90:93], v[122:125], v[2:5]
	v_mfma_f32_16x16x32_bf16 v[30:33], v[86:89], v[102:105], v[30:33]
	v_mfma_f32_16x16x32_bf16 v[26:29], v[94:97], v[102:105], v[26:29]
	v_mfma_f32_16x16x32_bf16 v[22:25], v[86:89], v[110:113], v[22:25]
	v_mfma_f32_16x16x32_bf16 v[18:21], v[94:97], v[110:113], v[18:21]
	v_mfma_f32_16x16x32_bf16 v[14:17], v[86:89], v[118:121], v[14:17]
	v_mfma_f32_16x16x32_bf16 v[10:13], v[94:97], v[118:121], v[10:13]
	v_mfma_f32_16x16x32_bf16 v[6:9], v[86:89], v[126:129], v[6:9]
	v_mfma_f32_16x16x32_bf16 v[2:5], v[94:97], v[126:129], v[2:5]
	s_barrier
	s_setprio 0
	s_add_i32 s37, 0, 0x18000
	v_add_u32_e32 v81, s37, v79
	ds_read_b128 v[82:85], v81
	ds_read_b128 v[86:89], v81 offset:1024
	ds_read_b128 v[90:93], v81 offset:2048
	ds_read_b128 v[94:97], v81 offset:3072
	s_add_u32 s42, s50, 0x28000
	s_addc_u32 s43, s51, 0
	s_mov_b32 m0, s23
	v_lshl_add_u64 v[138:139], s[42:43], 0, v[0:1]
	ds_read_b128 v[98:101], v80 offset:32768
	ds_read_b128 v[102:105], v80 offset:33792
	ds_read_b128 v[106:109], v80 offset:34816
	ds_read_b128 v[110:113], v80 offset:35840
	ds_read_b128 v[114:117], v80 offset:36864
	ds_read_b128 v[118:121], v80 offset:37888
	ds_read_b128 v[122:125], v80 offset:38912
	ds_read_b128 v[126:129], v80 offset:39936
	global_load_lds_dwordx4 v[138:139], off
	v_lshl_add_u64 v[138:139], s[42:43], 0, v[68:69]
	s_mov_b32 m0, s28
	s_nop 0
	global_load_lds_dwordx4 v[138:139], off
	.p2align	3
	s_waitcnt vmcnt(8)
	s_waitcnt lgkmcnt(0)
	s_setprio 1
	s_barrier
	v_mfma_f32_16x16x32_bf16 v[62:65], v[82:85], v[98:101], v[62:65]
	v_mfma_f32_16x16x32_bf16 v[58:61], v[90:93], v[98:101], v[58:61]
	v_mfma_f32_16x16x32_bf16 v[54:57], v[82:85], v[106:109], v[54:57]
	v_mfma_f32_16x16x32_bf16 v[50:53], v[90:93], v[106:109], v[50:53]
	v_mfma_f32_16x16x32_bf16 v[46:49], v[82:85], v[114:117], v[46:49]
	v_mfma_f32_16x16x32_bf16 v[42:45], v[90:93], v[114:117], v[42:45]
	v_mfma_f32_16x16x32_bf16 v[38:41], v[82:85], v[122:125], v[38:41]
	v_mfma_f32_16x16x32_bf16 v[34:37], v[90:93], v[122:125], v[34:37]
	v_mfma_f32_16x16x32_bf16 v[62:65], v[86:89], v[102:105], v[62:65]
	v_mfma_f32_16x16x32_bf16 v[58:61], v[94:97], v[102:105], v[58:61]
	v_mfma_f32_16x16x32_bf16 v[54:57], v[86:89], v[110:113], v[54:57]
	v_mfma_f32_16x16x32_bf16 v[50:53], v[94:97], v[110:113], v[50:53]
	v_mfma_f32_16x16x32_bf16 v[46:49], v[86:89], v[118:121], v[46:49]
	v_mfma_f32_16x16x32_bf16 v[42:45], v[94:97], v[118:121], v[42:45]
	v_mfma_f32_16x16x32_bf16 v[38:41], v[86:89], v[126:129], v[38:41]
	v_mfma_f32_16x16x32_bf16 v[34:37], v[94:97], v[126:129], v[34:37]
	s_barrier
	s_setprio 0
	s_add_i32 s37, s37, s4
	v_lshl_add_u64 v[130:131], v[130:131], 0, s[24:25]
	s_mov_b32 m0, s37
	ds_read_b128 v[98:101], v80 offset:49152
	ds_read_b128 v[102:105], v80 offset:50176
	ds_read_b128 v[106:109], v80 offset:51200
	ds_read_b128 v[110:113], v80 offset:52224
	ds_read_b128 v[114:117], v80 offset:53248
	ds_read_b128 v[118:121], v80 offset:54272
	ds_read_b128 v[122:125], v80 offset:55296
	ds_read_b128 v[126:129], v80 offset:56320
	global_load_lds_dwordx4 v[130:131], off
	s_add_i32 m0, s37, 0x2000
	s_add_u32 s42, s48, 0x20080
	v_lshl_add_u64 v[130:131], v[132:133], 0, s[24:25]
	s_addc_u32 s43, s49, 0
	global_load_lds_dwordx4 v[130:131], off
	v_lshl_add_u64 v[130:131], s[42:43], 0, v[70:71]
	s_mov_b32 m0, s38
	s_nop 0
	global_load_lds_dwordx4 v[130:131], off
	v_lshl_add_u64 v[130:131], s[42:43], 0, v[66:67]
	s_mov_b32 m0, s39
	s_nop 0
	global_load_lds_dwordx4 v[130:131], off
	v_lshl_add_u64 v[130:131], v[134:135], 0, s[24:25]
	s_mov_b32 m0, s31
	s_nop 0
	global_load_lds_dwordx4 v[130:131], off
	v_lshl_add_u64 v[130:131], v[136:137], 0, s[24:25]
	s_mov_b32 m0, s33
	s_nop 0
	global_load_lds_dwordx4 v[130:131], off
	.p2align	3
	s_waitcnt vmcnt(8)
	s_waitcnt lgkmcnt(0)
	s_setprio 1
	s_barrier
	v_mfma_f32_16x16x32_bf16 v[30:33], v[82:85], v[98:101], v[30:33]
	v_mfma_f32_16x16x32_bf16 v[26:29], v[90:93], v[98:101], v[26:29]
	v_mfma_f32_16x16x32_bf16 v[22:25], v[82:85], v[106:109], v[22:25]
	v_mfma_f32_16x16x32_bf16 v[18:21], v[90:93], v[106:109], v[18:21]
	v_mfma_f32_16x16x32_bf16 v[14:17], v[82:85], v[114:117], v[14:17]
	v_mfma_f32_16x16x32_bf16 v[10:13], v[90:93], v[114:117], v[10:13]
	v_mfma_f32_16x16x32_bf16 v[6:9], v[82:85], v[122:125], v[6:9]
	v_mfma_f32_16x16x32_bf16 v[2:5], v[90:93], v[122:125], v[2:5]
	v_mfma_f32_16x16x32_bf16 v[30:33], v[86:89], v[102:105], v[30:33]
	v_mfma_f32_16x16x32_bf16 v[26:29], v[94:97], v[102:105], v[26:29]
	v_mfma_f32_16x16x32_bf16 v[22:25], v[86:89], v[110:113], v[22:25]
	v_mfma_f32_16x16x32_bf16 v[18:21], v[94:97], v[110:113], v[18:21]
	v_mfma_f32_16x16x32_bf16 v[14:17], v[86:89], v[118:121], v[14:17]
	v_mfma_f32_16x16x32_bf16 v[10:13], v[94:97], v[118:121], v[10:13]
	v_mfma_f32_16x16x32_bf16 v[6:9], v[86:89], v[126:129], v[6:9]
	v_mfma_f32_16x16x32_bf16 v[2:5], v[94:97], v[126:129], v[2:5]
	s_barrier
	s_setprio 0
	s_add_u32 s84, s84, 0x100
	s_addc_u32 s85, s85, 0
	s_cmp_ge_i32 s29, s3
	s_mov_b64 s[42:43], s[44:45]
	s_mov_b32 s37, s29
	s_cbranch_scc0 .LBB7_676

.Lpeel_886:
	s_add_i32 s37, s44, 2
	s_add_u32 s42, s16, 0x100
	s_addc_u32 s43, s17, 0
	s_add_i32 s29, 0, 0x10000
	s_cmp_eq_u32 s57, s44
	s_cselect_b32 s49, s39, s43
	s_cselect_b32 s48, s54, s42
	s_cselect_b32 s45, s55, s73
	s_cselect_b32 s44, s56, s72
	s_add_i32 s74, 0, 0x14000
	v_add_u32_e32 v142, s29, v193
	v_add_u32_e32 v158, s74, v193
	ds_read_b128 v[74:77], v142
	ds_read_b128 v[78:81], v142 offset:1024
	ds_read_b128 v[138:141], v142 offset:2048
	ds_read_b128 v[142:145], v142 offset:3072
	ds_read_b128 v[146:149], v158
	ds_read_b128 v[150:153], v158 offset:1024
	ds_read_b128 v[154:157], v158 offset:2048
	ds_read_b128 v[158:161], v158 offset:3072
	v_lshl_add_u64 v[170:171], s[16:17], 0, v[184:185]
	s_add_i32 m0, s5, 0xc000
	ds_read_b128 v[188:191], v195
	ds_read_b128 v[196:199], v195 offset:1024
	ds_read_b128 v[204:207], v195 offset:2048
	ds_read_b128 v[208:211], v195 offset:3072
	ds_read_b128 v[212:215], v195 offset:4096
	ds_read_b128 v[216:219], v195 offset:5120
	ds_read_b128 v[220:223], v195 offset:6144
	ds_read_b128 v[224:227], v195 offset:7168
	global_load_lds_dwordx4 v[170:171], off
	v_lshl_add_u64 v[170:171], s[16:17], 0, v[186:187]
	s_add_i32 m0, s5, 0xe000
	s_nop 0
	global_load_lds_dwordx4 v[170:171], off
	.p2align	3
	s_waitcnt vmcnt(8)
	s_waitcnt lgkmcnt(0)
	s_setprio 1
	s_barrier
	v_mfma_f32_16x16x32_bf16 v[134:137], v[74:77], v[188:191], 0
	v_mfma_f32_16x16x32_bf16 v[130:133], v[138:141], v[188:191], 0
	v_mfma_f32_16x16x32_bf16 v[118:121], v[74:77], v[204:207], 0
	v_mfma_f32_16x16x32_bf16 v[114:117], v[138:141], v[204:207], 0
	v_mfma_f32_16x16x32_bf16 v[102:105], v[74:77], v[212:215], 0
	v_mfma_f32_16x16x32_bf16 v[98:101], v[138:141], v[212:215], 0
	v_mfma_f32_16x16x32_bf16 v[86:89], v[74:77], v[220:223], 0
	v_mfma_f32_16x16x32_bf16 v[82:85], v[138:141], v[220:223], 0
	v_mfma_f32_16x16x32_bf16 v[134:137], v[78:81], v[196:199], v[134:137]
	v_mfma_f32_16x16x32_bf16 v[130:133], v[142:145], v[196:199], v[130:133]
	v_mfma_f32_16x16x32_bf16 v[118:121], v[78:81], v[208:211], v[118:121]
	v_mfma_f32_16x16x32_bf16 v[114:117], v[142:145], v[208:211], v[114:117]
	v_mfma_f32_16x16x32_bf16 v[102:105], v[78:81], v[216:219], v[102:105]
	v_mfma_f32_16x16x32_bf16 v[98:101], v[142:145], v[216:219], v[98:101]
	v_mfma_f32_16x16x32_bf16 v[86:89], v[78:81], v[224:227], v[86:89]
	v_mfma_f32_16x16x32_bf16 v[82:85], v[142:145], v[224:227], v[82:85]
	v_mfma_f32_16x16x32_bf16 v[126:129], v[146:149], v[188:191], 0
	v_mfma_f32_16x16x32_bf16 v[122:125], v[154:157], v[188:191], 0
	v_mfma_f32_16x16x32_bf16 v[110:113], v[146:149], v[204:207], 0
	v_mfma_f32_16x16x32_bf16 v[106:109], v[154:157], v[204:207], 0
	v_mfma_f32_16x16x32_bf16 v[94:97], v[146:149], v[212:215], 0
	v_mfma_f32_16x16x32_bf16 v[90:93], v[154:157], v[212:215], 0
	v_mfma_f32_16x16x32_bf16 v[70:73], v[146:149], v[220:223], 0
	v_mfma_f32_16x16x32_bf16 v[66:69], v[154:157], v[220:223], 0
	v_mfma_f32_16x16x32_bf16 v[126:129], v[150:153], v[196:199], v[126:129]
	v_mfma_f32_16x16x32_bf16 v[122:125], v[158:161], v[196:199], v[122:125]
	v_mfma_f32_16x16x32_bf16 v[110:113], v[150:153], v[208:211], v[110:113]
	v_mfma_f32_16x16x32_bf16 v[106:109], v[158:161], v[208:211], v[106:109]
	v_mfma_f32_16x16x32_bf16 v[94:97], v[150:153], v[216:219], v[94:97]
	v_mfma_f32_16x16x32_bf16 v[90:93], v[158:161], v[216:219], v[90:93]
	v_mfma_f32_16x16x32_bf16 v[70:73], v[150:153], v[224:227], v[70:73]
	v_mfma_f32_16x16x32_bf16 v[66:69], v[158:161], v[224:227], v[66:69]
	s_barrier
	s_setprio 0
	s_add_i32 s16, s29, s4
	v_lshl_add_u64 v[170:171], s[44:45], 0, v[178:179]
	s_mov_b32 m0, s16
	ds_read_b128 v[188:191], v195 offset:16384
	ds_read_b128 v[196:199], v195 offset:17408
	ds_read_b128 v[204:207], v195 offset:18432
	ds_read_b128 v[208:211], v195 offset:19456
	ds_read_b128 v[212:215], v195 offset:20480
	ds_read_b128 v[216:219], v195 offset:21504
	ds_read_b128 v[220:223], v195 offset:22528
	ds_read_b128 v[224:227], v195 offset:23552
	global_load_lds_dwordx4 v[170:171], off
	s_add_i32 m0, s16, 0x2000
	s_add_u32 s16, s44, 0x28000
	v_lshl_add_u64 v[172:173], s[44:45], 0, v[174:175]
	s_addc_u32 s17, s45, 0
	s_add_i32 s29, s74, s4
	global_load_lds_dwordx4 v[172:173], off
	v_lshl_add_u64 v[228:229], s[16:17], 0, v[178:179]
	s_mov_b32 m0, s29
	v_lshl_add_u64 v[230:231], s[48:49], 0, v[176:177]
	global_load_lds_dwordx4 v[228:229], off
	v_lshl_add_u64 v[228:229], s[16:17], 0, v[174:175]
	s_add_i32 m0, s29, 0x2000
	s_nop 0
	global_load_lds_dwordx4 v[228:229], off
	v_lshl_add_u64 v[228:229], s[48:49], 0, v[180:181]
	s_mov_b32 m0, s5
	s_nop 0
	global_load_lds_dwordx4 v[228:229], off
	s_mov_b32 m0, s20
	s_nop 0
	global_load_lds_dwordx4 v[230:231], off
	.p2align	3
	s_waitcnt vmcnt(8)
	s_waitcnt lgkmcnt(0)
	s_setprio 1
	s_barrier
	v_mfma_f32_16x16x32_bf16 v[62:65], v[74:77], v[188:191], 0
	v_mfma_f32_16x16x32_bf16 v[58:61], v[138:141], v[188:191], 0
	v_mfma_f32_16x16x32_bf16 v[46:49], v[74:77], v[204:207], 0
	v_mfma_f32_16x16x32_bf16 v[42:45], v[138:141], v[204:207], 0
	v_mfma_f32_16x16x32_bf16 v[30:33], v[74:77], v[212:215], 0
	v_mfma_f32_16x16x32_bf16 v[26:29], v[138:141], v[212:215], 0
	v_mfma_f32_16x16x32_bf16 v[14:17], v[74:77], v[220:223], 0
	v_mfma_f32_16x16x32_bf16 v[10:13], v[138:141], v[220:223], 0
	v_mfma_f32_16x16x32_bf16 v[62:65], v[78:81], v[196:199], v[62:65]
	v_mfma_f32_16x16x32_bf16 v[58:61], v[142:145], v[196:199], v[58:61]
	v_mfma_f32_16x16x32_bf16 v[46:49], v[78:81], v[208:211], v[46:49]
	v_mfma_f32_16x16x32_bf16 v[42:45], v[142:145], v[208:211], v[42:45]
	v_mfma_f32_16x16x32_bf16 v[30:33], v[78:81], v[216:219], v[30:33]
	v_mfma_f32_16x16x32_bf16 v[26:29], v[142:145], v[216:219], v[26:29]
	v_mfma_f32_16x16x32_bf16 v[14:17], v[78:81], v[224:227], v[14:17]
	v_mfma_f32_16x16x32_bf16 v[10:13], v[142:145], v[224:227], v[10:13]
	v_mfma_f32_16x16x32_bf16 v[54:57], v[146:149], v[188:191], 0
	v_mfma_f32_16x16x32_bf16 v[50:53], v[154:157], v[188:191], 0
	v_mfma_f32_16x16x32_bf16 v[38:41], v[146:149], v[204:207], 0
	v_mfma_f32_16x16x32_bf16 v[34:37], v[154:157], v[204:207], 0
	v_mfma_f32_16x16x32_bf16 v[22:25], v[146:149], v[212:215], 0
	v_mfma_f32_16x16x32_bf16 v[18:21], v[154:157], v[212:215], 0
	v_mfma_f32_16x16x32_bf16 v[6:9], v[146:149], v[220:223], 0
	v_mfma_f32_16x16x32_bf16 v[2:5], v[154:157], v[220:223], 0
	v_mfma_f32_16x16x32_bf16 v[54:57], v[150:153], v[196:199], v[54:57]
	v_mfma_f32_16x16x32_bf16 v[50:53], v[158:161], v[196:199], v[50:53]
	v_mfma_f32_16x16x32_bf16 v[38:41], v[150:153], v[208:211], v[38:41]
	v_mfma_f32_16x16x32_bf16 v[34:37], v[158:161], v[208:211], v[34:37]
	v_mfma_f32_16x16x32_bf16 v[22:25], v[150:153], v[216:219], v[22:25]
	v_mfma_f32_16x16x32_bf16 v[18:21], v[158:161], v[216:219], v[18:21]
	v_mfma_f32_16x16x32_bf16 v[6:9], v[150:153], v[224:227], v[6:9]
	v_mfma_f32_16x16x32_bf16 v[2:5], v[158:161], v[224:227], v[2:5]
	s_barrier
	s_setprio 0
	s_add_i32 s29, 0, 0x18000
	s_add_i32 s74, 0, 0x1c000
	v_add_u32_e32 v142, s29, v193
	v_add_u32_e32 v158, s74, v193
	ds_read_b128 v[74:77], v142
	ds_read_b128 v[78:81], v142 offset:1024
	ds_read_b128 v[138:141], v142 offset:2048
	ds_read_b128 v[142:145], v142 offset:3072
	ds_read_b128 v[146:149], v158
	ds_read_b128 v[150:153], v158 offset:1024
	ds_read_b128 v[154:157], v158 offset:2048
	ds_read_b128 v[158:161], v158 offset:3072
	s_add_u32 s16, s48, 0x28000
	s_addc_u32 s17, s49, 0
	s_mov_b32 m0, s22
	v_lshl_add_u64 v[232:233], s[16:17], 0, v[180:181]
	ds_read_b128 v[188:191], v195 offset:32768
	ds_read_b128 v[196:199], v195 offset:33792
	ds_read_b128 v[204:207], v195 offset:34816
	ds_read_b128 v[208:211], v195 offset:35840
	ds_read_b128 v[212:215], v195 offset:36864
	ds_read_b128 v[216:219], v195 offset:37888
	ds_read_b128 v[220:223], v195 offset:38912
	ds_read_b128 v[224:227], v195 offset:39936
	global_load_lds_dwordx4 v[232:233], off
	v_lshl_add_u64 v[232:233], s[16:17], 0, v[176:177]
	s_mov_b32 m0, s23
	s_nop 0
	global_load_lds_dwordx4 v[232:233], off
	.p2align	3
	s_waitcnt vmcnt(8)
	s_waitcnt lgkmcnt(0)
	s_setprio 1
	s_barrier
	v_mfma_f32_16x16x32_bf16 v[134:137], v[74:77], v[188:191], v[134:137]
	v_mfma_f32_16x16x32_bf16 v[130:133], v[138:141], v[188:191], v[130:133]
	v_mfma_f32_16x16x32_bf16 v[118:121], v[74:77], v[204:207], v[118:121]
	v_mfma_f32_16x16x32_bf16 v[114:117], v[138:141], v[204:207], v[114:117]
	v_mfma_f32_16x16x32_bf16 v[102:105], v[74:77], v[212:215], v[102:105]
	v_mfma_f32_16x16x32_bf16 v[98:101], v[138:141], v[212:215], v[98:101]
	v_mfma_f32_16x16x32_bf16 v[86:89], v[74:77], v[220:223], v[86:89]
	v_mfma_f32_16x16x32_bf16 v[82:85], v[138:141], v[220:223], v[82:85]
	v_mfma_f32_16x16x32_bf16 v[134:137], v[78:81], v[196:199], v[134:137]
	v_mfma_f32_16x16x32_bf16 v[130:133], v[142:145], v[196:199], v[130:133]
	v_mfma_f32_16x16x32_bf16 v[118:121], v[78:81], v[208:211], v[118:121]
	v_mfma_f32_16x16x32_bf16 v[114:117], v[142:145], v[208:211], v[114:117]
	v_mfma_f32_16x16x32_bf16 v[102:105], v[78:81], v[216:219], v[102:105]
	v_mfma_f32_16x16x32_bf16 v[98:101], v[142:145], v[216:219], v[98:101]
	v_mfma_f32_16x16x32_bf16 v[86:89], v[78:81], v[224:227], v[86:89]
	v_mfma_f32_16x16x32_bf16 v[82:85], v[142:145], v[224:227], v[82:85]
	v_mfma_f32_16x16x32_bf16 v[126:129], v[146:149], v[188:191], v[126:129]
	v_mfma_f32_16x16x32_bf16 v[122:125], v[154:157], v[188:191], v[122:125]
	v_mfma_f32_16x16x32_bf16 v[110:113], v[146:149], v[204:207], v[110:113]
	v_mfma_f32_16x16x32_bf16 v[106:109], v[154:157], v[204:207], v[106:109]
	v_mfma_f32_16x16x32_bf16 v[94:97], v[146:149], v[212:215], v[94:97]
	v_mfma_f32_16x16x32_bf16 v[90:93], v[154:157], v[212:215], v[90:93]
	v_mfma_f32_16x16x32_bf16 v[70:73], v[146:149], v[220:223], v[70:73]
	v_mfma_f32_16x16x32_bf16 v[66:69], v[154:157], v[220:223], v[66:69]
	v_mfma_f32_16x16x32_bf16 v[126:129], v[150:153], v[196:199], v[126:129]
	v_mfma_f32_16x16x32_bf16 v[122:125], v[158:161], v[196:199], v[122:125]
	v_mfma_f32_16x16x32_bf16 v[110:113], v[150:153], v[208:211], v[110:113]
	v_mfma_f32_16x16x32_bf16 v[106:109], v[158:161], v[208:211], v[106:109]
	v_mfma_f32_16x16x32_bf16 v[94:97], v[150:153], v[216:219], v[94:97]
	v_mfma_f32_16x16x32_bf16 v[90:93], v[158:161], v[216:219], v[90:93]
	v_mfma_f32_16x16x32_bf16 v[70:73], v[150:153], v[224:227], v[70:73]
	v_mfma_f32_16x16x32_bf16 v[66:69], v[158:161], v[224:227], v[66:69]
	s_barrier
	s_setprio 0
	s_add_i32 s16, s29, s4
	v_lshl_add_u64 v[170:171], v[170:171], 0, s[24:25]
	s_mov_b32 m0, s16
	ds_read_b128 v[188:191], v195 offset:49152
	ds_read_b128 v[196:199], v195 offset:50176
	ds_read_b128 v[204:207], v195 offset:51200
	ds_read_b128 v[208:211], v195 offset:52224
	ds_read_b128 v[212:215], v195 offset:53248
	ds_read_b128 v[216:219], v195 offset:54272
	ds_read_b128 v[220:223], v195 offset:55296
	ds_read_b128 v[224:227], v195 offset:56320
	global_load_lds_dwordx4 v[170:171], off
	s_add_i32 m0, s16, 0x2000
	s_add_u32 s16, s44, 0x28080
	v_lshl_add_u64 v[170:171], v[172:173], 0, s[24:25]
	s_addc_u32 s17, s45, 0
	s_add_i32 s29, s74, s4
	global_load_lds_dwordx4 v[170:171], off
	v_lshl_add_u64 v[170:171], s[16:17], 0, v[178:179]
	s_mov_b32 m0, s29
	s_nop 0
	global_load_lds_dwordx4 v[170:171], off
	v_lshl_add_u64 v[170:171], s[16:17], 0, v[174:175]
	s_add_i32 m0, s29, 0x2000
	s_nop 0
	global_load_lds_dwordx4 v[170:171], off
	v_lshl_add_u64 v[170:171], v[228:229], 0, s[24:25]
	s_mov_b32 m0, s31
	s_nop 0
	global_load_lds_dwordx4 v[170:171], off
	v_lshl_add_u64 v[170:171], v[230:231], 0, s[24:25]
	s_mov_b32 m0, s33
	s_nop 0
	global_load_lds_dwordx4 v[170:171], off
	.p2align	3
	s_waitcnt vmcnt(8)
	s_waitcnt lgkmcnt(0)
	s_setprio 1
	s_barrier
	v_mfma_f32_16x16x32_bf16 v[62:65], v[74:77], v[188:191], v[62:65]
	v_mfma_f32_16x16x32_bf16 v[58:61], v[138:141], v[188:191], v[58:61]
	v_mfma_f32_16x16x32_bf16 v[46:49], v[74:77], v[204:207], v[46:49]
	v_mfma_f32_16x16x32_bf16 v[42:45], v[138:141], v[204:207], v[42:45]
	v_mfma_f32_16x16x32_bf16 v[30:33], v[74:77], v[212:215], v[30:33]
	v_mfma_f32_16x16x32_bf16 v[26:29], v[138:141], v[212:215], v[26:29]
	v_mfma_f32_16x16x32_bf16 v[14:17], v[74:77], v[220:223], v[14:17]
	v_mfma_f32_16x16x32_bf16 v[10:13], v[138:141], v[220:223], v[10:13]
	v_mfma_f32_16x16x32_bf16 v[62:65], v[78:81], v[196:199], v[62:65]
	v_mfma_f32_16x16x32_bf16 v[58:61], v[142:145], v[196:199], v[58:61]
	v_mfma_f32_16x16x32_bf16 v[46:49], v[78:81], v[208:211], v[46:49]
	v_mfma_f32_16x16x32_bf16 v[42:45], v[142:145], v[208:211], v[42:45]
	v_mfma_f32_16x16x32_bf16 v[30:33], v[78:81], v[216:219], v[30:33]
	v_mfma_f32_16x16x32_bf16 v[26:29], v[142:145], v[216:219], v[26:29]
	v_mfma_f32_16x16x32_bf16 v[14:17], v[78:81], v[224:227], v[14:17]
	v_mfma_f32_16x16x32_bf16 v[10:13], v[142:145], v[224:227], v[10:13]
	v_mfma_f32_16x16x32_bf16 v[54:57], v[146:149], v[188:191], v[54:57]
	v_mfma_f32_16x16x32_bf16 v[50:53], v[154:157], v[188:191], v[50:53]
	v_mfma_f32_16x16x32_bf16 v[38:41], v[146:149], v[204:207], v[38:41]
	v_mfma_f32_16x16x32_bf16 v[34:37], v[154:157], v[204:207], v[34:37]
	v_mfma_f32_16x16x32_bf16 v[22:25], v[146:149], v[212:215], v[22:25]
	v_mfma_f32_16x16x32_bf16 v[18:21], v[154:157], v[212:215], v[18:21]
	v_mfma_f32_16x16x32_bf16 v[6:9], v[146:149], v[220:223], v[6:9]
	v_mfma_f32_16x16x32_bf16 v[2:5], v[154:157], v[220:223], v[2:5]
	v_mfma_f32_16x16x32_bf16 v[54:57], v[150:153], v[196:199], v[54:57]
	v_mfma_f32_16x16x32_bf16 v[50:53], v[158:161], v[196:199], v[50:53]
	v_mfma_f32_16x16x32_bf16 v[38:41], v[150:153], v[208:211], v[38:41]
	v_mfma_f32_16x16x32_bf16 v[34:37], v[158:161], v[208:211], v[34:37]
	v_mfma_f32_16x16x32_bf16 v[22:25], v[150:153], v[216:219], v[22:25]
	v_mfma_f32_16x16x32_bf16 v[18:21], v[158:161], v[216:219], v[18:21]
	v_mfma_f32_16x16x32_bf16 v[6:9], v[150:153], v[224:227], v[6:9]
	v_mfma_f32_16x16x32_bf16 v[2:5], v[158:161], v[224:227], v[2:5]
	s_barrier
	s_setprio 0
	s_add_u32 s72, s72, 0x100
	s_addc_u32 s73, s73, 0
	s_cmp_ge_i32 s37, s38
	s_mov_b64 s[16:17], s[42:43]
	s_mov_b32 s44, s37
	s_cbranch_scc0 .LBB7_886
	s_branch .Lpeelx_886
	.p2align	6
.LBB7_886:
	s_add_i32 s37, s44, 2
	s_add_u32 s42, s16, 0x100
	s_addc_u32 s43, s17, 0
	s_add_i32 s29, 0, 0x10000
	s_cmp_eq_u32 s57, s44
	s_cselect_b32 s49, s39, s43
	s_cselect_b32 s48, s54, s42
	s_cselect_b32 s45, s55, s73
	s_cselect_b32 s44, s56, s72
	s_add_i32 s74, 0, 0x14000
	v_add_u32_e32 v142, s29, v193
	v_add_u32_e32 v158, s74, v193
	ds_read_b128 v[74:77], v142
	ds_read_b128 v[78:81], v142 offset:1024
	ds_read_b128 v[138:141], v142 offset:2048
	ds_read_b128 v[142:145], v142 offset:3072
	ds_read_b128 v[146:149], v158
	ds_read_b128 v[150:153], v158 offset:1024
	ds_read_b128 v[154:157], v158 offset:2048
	ds_read_b128 v[158:161], v158 offset:3072
	v_lshl_add_u64 v[170:171], s[16:17], 0, v[184:185]
	s_add_i32 m0, s5, 0xc000
	ds_read_b128 v[188:191], v195
	ds_read_b128 v[196:199], v195 offset:1024
	ds_read_b128 v[204:207], v195 offset:2048
	ds_read_b128 v[208:211], v195 offset:3072
	ds_read_b128 v[212:215], v195 offset:4096
	ds_read_b128 v[216:219], v195 offset:5120
	ds_read_b128 v[220:223], v195 offset:6144
	ds_read_b128 v[224:227], v195 offset:7168
	global_load_lds_dwordx4 v[170:171], off
	v_lshl_add_u64 v[170:171], s[16:17], 0, v[186:187]
	s_add_i32 m0, s5, 0xe000
	s_nop 0
	global_load_lds_dwordx4 v[170:171], off
	.p2align	3
	s_waitcnt vmcnt(8)
	s_waitcnt lgkmcnt(0)
	s_setprio 1
	s_barrier
	v_mfma_f32_16x16x32_bf16 v[134:137], v[74:77], v[188:191], v[134:137]
	v_mfma_f32_16x16x32_bf16 v[130:133], v[138:141], v[188:191], v[130:133]
	v_mfma_f32_16x16x32_bf16 v[118:121], v[74:77], v[204:207], v[118:121]
	v_mfma_f32_16x16x32_bf16 v[114:117], v[138:141], v[204:207], v[114:117]
	v_mfma_f32_16x16x32_bf16 v[102:105], v[74:77], v[212:215], v[102:105]
	v_mfma_f32_16x16x32_bf16 v[98:101], v[138:141], v[212:215], v[98:101]
	v_mfma_f32_16x16x32_bf16 v[86:89], v[74:77], v[220:223], v[86:89]
	v_mfma_f32_16x16x32_bf16 v[82:85], v[138:141], v[220:223], v[82:85]
	v_mfma_f32_16x16x32_bf16 v[134:137], v[78:81], v[196:199], v[134:137]
	v_mfma_f32_16x16x32_bf16 v[130:133], v[142:145], v[196:199], v[130:133]
	v_mfma_f32_16x16x32_bf16 v[118:121], v[78:81], v[208:211], v[118:121]
	v_mfma_f32_16x16x32_bf16 v[114:117], v[142:145], v[208:211], v[114:117]
	v_mfma_f32_16x16x32_bf16 v[102:105], v[78:81], v[216:219], v[102:105]
	v_mfma_f32_16x16x32_bf16 v[98:101], v[142:145], v[216:219], v[98:101]
	v_mfma_f32_16x16x32_bf16 v[86:89], v[78:81], v[224:227], v[86:89]
	v_mfma_f32_16x16x32_bf16 v[82:85], v[142:145], v[224:227], v[82:85]
	v_mfma_f32_16x16x32_bf16 v[126:129], v[146:149], v[188:191], v[126:129]
	v_mfma_f32_16x16x32_bf16 v[122:125], v[154:157], v[188:191], v[122:125]
	v_mfma_f32_16x16x32_bf16 v[110:113], v[146:149], v[204:207], v[110:113]
	v_mfma_f32_16x16x32_bf16 v[106:109], v[154:157], v[204:207], v[106:109]
	v_mfma_f32_16x16x32_bf16 v[94:97], v[146:149], v[212:215], v[94:97]
	v_mfma_f32_16x16x32_bf16 v[90:93], v[154:157], v[212:215], v[90:93]
	v_mfma_f32_16x16x32_bf16 v[70:73], v[146:149], v[220:223], v[70:73]
	v_mfma_f32_16x16x32_bf16 v[66:69], v[154:157], v[220:223], v[66:69]
	v_mfma_f32_16x16x32_bf16 v[126:129], v[150:153], v[196:199], v[126:129]
	v_mfma_f32_16x16x32_bf16 v[122:125], v[158:161], v[196:199], v[122:125]
	v_mfma_f32_16x16x32_bf16 v[110:113], v[150:153], v[208:211], v[110:113]
	v_mfma_f32_16x16x32_bf16 v[106:109], v[158:161], v[208:211], v[106:109]
	v_mfma_f32_16x16x32_bf16 v[94:97], v[150:153], v[216:219], v[94:97]
	v_mfma_f32_16x16x32_bf16 v[90:93], v[158:161], v[216:219], v[90:93]
	v_mfma_f32_16x16x32_bf16 v[70:73], v[150:153], v[224:227], v[70:73]
	v_mfma_f32_16x16x32_bf16 v[66:69], v[158:161], v[224:227], v[66:69]
	s_barrier
	s_setprio 0
	s_add_i32 s16, s29, s4
	v_lshl_add_u64 v[170:171], s[44:45], 0, v[178:179]
	s_mov_b32 m0, s16
	ds_read_b128 v[188:191], v195 offset:16384
	ds_read_b128 v[196:199], v195 offset:17408
	ds_read_b128 v[204:207], v195 offset:18432
	ds_read_b128 v[208:211], v195 offset:19456
	ds_read_b128 v[212:215], v195 offset:20480
	ds_read_b128 v[216:219], v195 offset:21504
	ds_read_b128 v[220:223], v195 offset:22528
	ds_read_b128 v[224:227], v195 offset:23552
	global_load_lds_dwordx4 v[170:171], off
	s_add_i32 m0, s16, 0x2000
	s_add_u32 s16, s44, 0x28000
	v_lshl_add_u64 v[172:173], s[44:45], 0, v[174:175]
	s_addc_u32 s17, s45, 0
	s_add_i32 s29, s74, s4
	global_load_lds_dwordx4 v[172:173], off
	v_lshl_add_u64 v[228:229], s[16:17], 0, v[178:179]
	s_mov_b32 m0, s29
	v_lshl_add_u64 v[230:231], s[48:49], 0, v[176:177]
	global_load_lds_dwordx4 v[228:229], off
	v_lshl_add_u64 v[228:229], s[16:17], 0, v[174:175]
	s_add_i32 m0, s29, 0x2000
	s_nop 0
	global_load_lds_dwordx4 v[228:229], off
	v_lshl_add_u64 v[228:229], s[48:49], 0, v[180:181]
	s_mov_b32 m0, s5
	s_nop 0
	global_load_lds_dwordx4 v[228:229], off
	s_mov_b32 m0, s20
	s_nop 0
	global_load_lds_dwordx4 v[230:231], off
	.p2align	3
	s_waitcnt vmcnt(8)
	s_waitcnt lgkmcnt(0)
	s_setprio 1
	s_barrier
	v_mfma_f32_16x16x32_bf16 v[62:65], v[74:77], v[188:191], v[62:65]
	v_mfma_f32_16x16x32_bf16 v[58:61], v[138:141], v[188:191], v[58:61]
	v_mfma_f32_16x16x32_bf16 v[46:49], v[74:77], v[204:207], v[46:49]
	v_mfma_f32_16x16x32_bf16 v[42:45], v[138:141], v[204:207], v[42:45]
	v_mfma_f32_16x16x32_bf16 v[30:33], v[74:77], v[212:215], v[30:33]
	v_mfma_f32_16x16x32_bf16 v[26:29], v[138:141], v[212:215], v[26:29]
	v_mfma_f32_16x16x32_bf16 v[14:17], v[74:77], v[220:223], v[14:17]
	v_mfma_f32_16x16x32_bf16 v[10:13], v[138:141], v[220:223], v[10:13]
	v_mfma_f32_16x16x32_bf16 v[62:65], v[78:81], v[196:199], v[62:65]
	v_mfma_f32_16x16x32_bf16 v[58:61], v[142:145], v[196:199], v[58:61]
	v_mfma_f32_16x16x32_bf16 v[46:49], v[78:81], v[208:211], v[46:49]
	v_mfma_f32_16x16x32_bf16 v[42:45], v[142:145], v[208:211], v[42:45]
	v_mfma_f32_16x16x32_bf16 v[30:33], v[78:81], v[216:219], v[30:33]
	v_mfma_f32_16x16x32_bf16 v[26:29], v[142:145], v[216:219], v[26:29]
	v_mfma_f32_16x16x32_bf16 v[14:17], v[78:81], v[224:227], v[14:17]
	v_mfma_f32_16x16x32_bf16 v[10:13], v[142:145], v[224:227], v[10:13]
	v_mfma_f32_16x16x32_bf16 v[54:57], v[146:149], v[188:191], v[54:57]
	v_mfma_f32_16x16x32_bf16 v[50:53], v[154:157], v[188:191], v[50:53]
	v_mfma_f32_16x16x32_bf16 v[38:41], v[146:149], v[204:207], v[38:41]
	v_mfma_f32_16x16x32_bf16 v[34:37], v[154:157], v[204:207], v[34:37]
	v_mfma_f32_16x16x32_bf16 v[22:25], v[146:149], v[212:215], v[22:25]
	v_mfma_f32_16x16x32_bf16 v[18:21], v[154:157], v[212:215], v[18:21]
	v_mfma_f32_16x16x32_bf16 v[6:9], v[146:149], v[220:223], v[6:9]
	v_mfma_f32_16x16x32_bf16 v[2:5], v[154:157], v[220:223], v[2:5]
	v_mfma_f32_16x16x32_bf16 v[54:57], v[150:153], v[196:199], v[54:57]
	v_mfma_f32_16x16x32_bf16 v[50:53], v[158:161], v[196:199], v[50:53]
	v_mfma_f32_16x16x32_bf16 v[38:41], v[150:153], v[208:211], v[38:41]
	v_mfma_f32_16x16x32_bf16 v[34:37], v[158:161], v[208:211], v[34:37]
	v_mfma_f32_16x16x32_bf16 v[22:25], v[150:153], v[216:219], v[22:25]
	v_mfma_f32_16x16x32_bf16 v[18:21], v[158:161], v[216:219], v[18:21]
	v_mfma_f32_16x16x32_bf16 v[6:9], v[150:153], v[224:227], v[6:9]
	v_mfma_f32_16x16x32_bf16 v[2:5], v[158:161], v[224:227], v[2:5]
	s_barrier
	s_setprio 0
	s_add_i32 s29, 0, 0x18000
	s_add_i32 s74, 0, 0x1c000
	v_add_u32_e32 v142, s29, v193
	v_add_u32_e32 v158, s74, v193
	ds_read_b128 v[74:77], v142
	ds_read_b128 v[78:81], v142 offset:1024
	ds_read_b128 v[138:141], v142 offset:2048
	ds_read_b128 v[142:145], v142 offset:3072
	ds_read_b128 v[146:149], v158
	ds_read_b128 v[150:153], v158 offset:1024
	ds_read_b128 v[154:157], v158 offset:2048
	ds_read_b128 v[158:161], v158 offset:3072
	s_add_u32 s16, s48, 0x28000
	s_addc_u32 s17, s49, 0
	s_mov_b32 m0, s22
	v_lshl_add_u64 v[232:233], s[16:17], 0, v[180:181]
	ds_read_b128 v[188:191], v195 offset:32768
	ds_read_b128 v[196:199], v195 offset:33792
	ds_read_b128 v[204:207], v195 offset:34816
	ds_read_b128 v[208:211], v195 offset:35840
	ds_read_b128 v[212:215], v195 offset:36864
	ds_read_b128 v[216:219], v195 offset:37888
	ds_read_b128 v[220:223], v195 offset:38912
	ds_read_b128 v[224:227], v195 offset:39936
	global_load_lds_dwordx4 v[232:233], off
	v_lshl_add_u64 v[232:233], s[16:17], 0, v[176:177]
	s_mov_b32 m0, s23
	s_nop 0
	global_load_lds_dwordx4 v[232:233], off
	.p2align	3
	s_waitcnt vmcnt(8)
	s_waitcnt lgkmcnt(0)
	s_setprio 1
	s_barrier
	v_mfma_f32_16x16x32_bf16 v[134:137], v[74:77], v[188:191], v[134:137]
	v_mfma_f32_16x16x32_bf16 v[130:133], v[138:141], v[188:191], v[130:133]
	v_mfma_f32_16x16x32_bf16 v[118:121], v[74:77], v[204:207], v[118:121]
	v_mfma_f32_16x16x32_bf16 v[114:117], v[138:141], v[204:207], v[114:117]
	v_mfma_f32_16x16x32_bf16 v[102:105], v[74:77], v[212:215], v[102:105]
	v_mfma_f32_16x16x32_bf16 v[98:101], v[138:141], v[212:215], v[98:101]
	v_mfma_f32_16x16x32_bf16 v[86:89], v[74:77], v[220:223], v[86:89]
	v_mfma_f32_16x16x32_bf16 v[82:85], v[138:141], v[220:223], v[82:85]
	v_mfma_f32_16x16x32_bf16 v[134:137], v[78:81], v[196:199], v[134:137]
	v_mfma_f32_16x16x32_bf16 v[130:133], v[142:145], v[196:199], v[130:133]
	v_mfma_f32_16x16x32_bf16 v[118:121], v[78:81], v[208:211], v[118:121]
	v_mfma_f32_16x16x32_bf16 v[114:117], v[142:145], v[208:211], v[114:117]
	v_mfma_f32_16x16x32_bf16 v[102:105], v[78:81], v[216:219], v[102:105]
	v_mfma_f32_16x16x32_bf16 v[98:101], v[142:145], v[216:219], v[98:101]
	v_mfma_f32_16x16x32_bf16 v[86:89], v[78:81], v[224:227], v[86:89]
	v_mfma_f32_16x16x32_bf16 v[82:85], v[142:145], v[224:227], v[82:85]
	v_mfma_f32_16x16x32_bf16 v[126:129], v[146:149], v[188:191], v[126:129]
	v_mfma_f32_16x16x32_bf16 v[122:125], v[154:157], v[188:191], v[122:125]
	v_mfma_f32_16x16x32_bf16 v[110:113], v[146:149], v[204:207], v[110:113]
	v_mfma_f32_16x16x32_bf16 v[106:109], v[154:157], v[204:207], v[106:109]
	v_mfma_f32_16x16x32_bf16 v[94:97], v[146:149], v[212:215], v[94:97]
	v_mfma_f32_16x16x32_bf16 v[90:93], v[154:157], v[212:215], v[90:93]
	v_mfma_f32_16x16x32_bf16 v[70:73], v[146:149], v[220:223], v[70:73]
	v_mfma_f32_16x16x32_bf16 v[66:69], v[154:157], v[220:223], v[66:69]
	v_mfma_f32_16x16x32_bf16 v[126:129], v[150:153], v[196:199], v[126:129]
	v_mfma_f32_16x16x32_bf16 v[122:125], v[158:161], v[196:199], v[122:125]
	v_mfma_f32_16x16x32_bf16 v[110:113], v[150:153], v[208:211], v[110:113]
	v_mfma_f32_16x16x32_bf16 v[106:109], v[158:161], v[208:211], v[106:109]
	v_mfma_f32_16x16x32_bf16 v[94:97], v[150:153], v[216:219], v[94:97]
	v_mfma_f32_16x16x32_bf16 v[90:93], v[158:161], v[216:219], v[90:93]
	v_mfma_f32_16x16x32_bf16 v[70:73], v[150:153], v[224:227], v[70:73]
	v_mfma_f32_16x16x32_bf16 v[66:69], v[158:161], v[224:227], v[66:69]
	s_barrier
	s_setprio 0
	s_add_i32 s16, s29, s4
	v_lshl_add_u64 v[170:171], v[170:171], 0, s[24:25]
	s_mov_b32 m0, s16
	ds_read_b128 v[188:191], v195 offset:49152
	ds_read_b128 v[196:199], v195 offset:50176
	ds_read_b128 v[204:207], v195 offset:51200
	ds_read_b128 v[208:211], v195 offset:52224
	ds_read_b128 v[212:215], v195 offset:53248
	ds_read_b128 v[216:219], v195 offset:54272
	ds_read_b128 v[220:223], v195 offset:55296
	ds_read_b128 v[224:227], v195 offset:56320
	global_load_lds_dwordx4 v[170:171], off
	s_add_i32 m0, s16, 0x2000
	s_add_u32 s16, s44, 0x28080
	v_lshl_add_u64 v[170:171], v[172:173], 0, s[24:25]
	s_addc_u32 s17, s45, 0
	s_add_i32 s29, s74, s4
	global_load_lds_dwordx4 v[170:171], off
	v_lshl_add_u64 v[170:171], s[16:17], 0, v[178:179]
	s_mov_b32 m0, s29
	s_nop 0
	global_load_lds_dwordx4 v[170:171], off
	v_lshl_add_u64 v[170:171], s[16:17], 0, v[174:175]
	s_add_i32 m0, s29, 0x2000
	s_nop 0
	global_load_lds_dwordx4 v[170:171], off
	v_lshl_add_u64 v[170:171], v[228:229], 0, s[24:25]
	s_mov_b32 m0, s31
	s_nop 0
	global_load_lds_dwordx4 v[170:171], off
	v_lshl_add_u64 v[170:171], v[230:231], 0, s[24:25]
	s_mov_b32 m0, s33
	s_nop 0
	global_load_lds_dwordx4 v[170:171], off
	.p2align	3
	s_waitcnt vmcnt(8)
	s_waitcnt lgkmcnt(0)
	s_setprio 1
	s_barrier
	v_mfma_f32_16x16x32_bf16 v[62:65], v[74:77], v[188:191], v[62:65]
	v_mfma_f32_16x16x32_bf16 v[58:61], v[138:141], v[188:191], v[58:61]
	v_mfma_f32_16x16x32_bf16 v[46:49], v[74:77], v[204:207], v[46:49]
	v_mfma_f32_16x16x32_bf16 v[42:45], v[138:141], v[204:207], v[42:45]
	v_mfma_f32_16x16x32_bf16 v[30:33], v[74:77], v[212:215], v[30:33]
	v_mfma_f32_16x16x32_bf16 v[26:29], v[138:141], v[212:215], v[26:29]
	v_mfma_f32_16x16x32_bf16 v[14:17], v[74:77], v[220:223], v[14:17]
	v_mfma_f32_16x16x32_bf16 v[10:13], v[138:141], v[220:223], v[10:13]
	v_mfma_f32_16x16x32_bf16 v[62:65], v[78:81], v[196:199], v[62:65]
	v_mfma_f32_16x16x32_bf16 v[58:61], v[142:145], v[196:199], v[58:61]
	v_mfma_f32_16x16x32_bf16 v[46:49], v[78:81], v[208:211], v[46:49]
	v_mfma_f32_16x16x32_bf16 v[42:45], v[142:145], v[208:211], v[42:45]
	v_mfma_f32_16x16x32_bf16 v[30:33], v[78:81], v[216:219], v[30:33]
	v_mfma_f32_16x16x32_bf16 v[26:29], v[142:145], v[216:219], v[26:29]
	v_mfma_f32_16x16x32_bf16 v[14:17], v[78:81], v[224:227], v[14:17]
	v_mfma_f32_16x16x32_bf16 v[10:13], v[142:145], v[224:227], v[10:13]
	v_mfma_f32_16x16x32_bf16 v[54:57], v[146:149], v[188:191], v[54:57]
	v_mfma_f32_16x16x32_bf16 v[50:53], v[154:157], v[188:191], v[50:53]
	v_mfma_f32_16x16x32_bf16 v[38:41], v[146:149], v[204:207], v[38:41]
	v_mfma_f32_16x16x32_bf16 v[34:37], v[154:157], v[204:207], v[34:37]
	v_mfma_f32_16x16x32_bf16 v[22:25], v[146:149], v[212:215], v[22:25]
	v_mfma_f32_16x16x32_bf16 v[18:21], v[154:157], v[212:215], v[18:21]
	v_mfma_f32_16x16x32_bf16 v[6:9], v[146:149], v[220:223], v[6:9]
	v_mfma_f32_16x16x32_bf16 v[2:5], v[154:157], v[220:223], v[2:5]
	v_mfma_f32_16x16x32_bf16 v[54:57], v[150:153], v[196:199], v[54:57]
	v_mfma_f32_16x16x32_bf16 v[50:53], v[158:161], v[196:199], v[50:53]
	v_mfma_f32_16x16x32_bf16 v[38:41], v[150:153], v[208:211], v[38:41]
	v_mfma_f32_16x16x32_bf16 v[34:37], v[158:161], v[208:211], v[34:37]
	v_mfma_f32_16x16x32_bf16 v[22:25], v[150:153], v[216:219], v[22:25]
	v_mfma_f32_16x16x32_bf16 v[18:21], v[158:161], v[216:219], v[18:21]
	v_mfma_f32_16x16x32_bf16 v[6:9], v[150:153], v[224:227], v[6:9]
	v_mfma_f32_16x16x32_bf16 v[2:5], v[158:161], v[224:227], v[2:5]
	s_barrier
	s_setprio 0
	s_add_u32 s72, s72, 0x100
	s_addc_u32 s73, s73, 0
	s_cmp_ge_i32 s37, s38
	s_mov_b64 s[16:17], s[42:43]
	s_mov_b32 s44, s37
	s_cbranch_scc0 .LBB7_886

.Lpeel_963:
	s_add_i32 s37, s48, 2
	s_add_u32 s42, s16, 0x100
	s_addc_u32 s43, s17, 0
	s_add_i32 s29, 0, 0x10000
	s_cmp_eq_u32 s53, s48
	s_cselect_b32 s51, s38, s43
	s_cselect_b32 s50, s39, s42
	s_cselect_b32 s49, s56, s73
	s_cselect_b32 s48, s57, s72
	s_add_i32 s74, 0, 0x14000
	v_add_u32_e32 v142, s29, v197
	v_add_u32_e32 v158, s74, v197
	ds_read_b128 v[130:133], v142
	ds_read_b128 v[134:137], v142 offset:1024
	ds_read_b128 v[138:141], v142 offset:2048
	ds_read_b128 v[142:145], v142 offset:3072
	ds_read_b128 v[146:149], v158
	ds_read_b128 v[150:153], v158 offset:1024
	ds_read_b128 v[154:157], v158 offset:2048
	ds_read_b128 v[158:161], v158 offset:3072
	v_lshl_add_u64 v[170:171], s[16:17], 0, v[180:181]
	s_add_i32 m0, s5, 0xc000
	ds_read_b128 v[184:187], v199
	ds_read_b128 v[188:191], v199 offset:1024
	ds_read_b128 v[192:195], v199 offset:2048
	ds_read_b128 v[204:207], v199 offset:3072
	ds_read_b128 v[208:211], v199 offset:4096
	ds_read_b128 v[212:215], v199 offset:5120
	ds_read_b128 v[216:219], v199 offset:6144
	ds_read_b128 v[220:223], v199 offset:7168
	global_load_lds_dwordx4 v[170:171], off
	v_lshl_add_u64 v[170:171], s[16:17], 0, v[182:183]
	s_add_i32 m0, s5, 0xe000
	s_nop 0
	global_load_lds_dwordx4 v[170:171], off
	.p2align	3
	s_waitcnt vmcnt(8)
	s_waitcnt lgkmcnt(0)
	s_setprio 1
	s_barrier
	v_mfma_f32_16x16x32_bf16 v[126:129], v[130:133], v[184:187], 0
	v_mfma_f32_16x16x32_bf16 v[122:125], v[138:141], v[184:187], 0
	v_mfma_f32_16x16x32_bf16 v[110:113], v[130:133], v[192:195], 0
	v_mfma_f32_16x16x32_bf16 v[106:109], v[138:141], v[192:195], 0
	v_mfma_f32_16x16x32_bf16 v[94:97], v[130:133], v[208:211], 0
	v_mfma_f32_16x16x32_bf16 v[90:93], v[138:141], v[208:211], 0
	v_mfma_f32_16x16x32_bf16 v[78:81], v[130:133], v[216:219], 0
	v_mfma_f32_16x16x32_bf16 v[74:77], v[138:141], v[216:219], 0
	v_mfma_f32_16x16x32_bf16 v[126:129], v[134:137], v[188:191], v[126:129]
	v_mfma_f32_16x16x32_bf16 v[122:125], v[142:145], v[188:191], v[122:125]
	v_mfma_f32_16x16x32_bf16 v[110:113], v[134:137], v[204:207], v[110:113]
	v_mfma_f32_16x16x32_bf16 v[106:109], v[142:145], v[204:207], v[106:109]
	v_mfma_f32_16x16x32_bf16 v[94:97], v[134:137], v[212:215], v[94:97]
	v_mfma_f32_16x16x32_bf16 v[90:93], v[142:145], v[212:215], v[90:93]
	v_mfma_f32_16x16x32_bf16 v[78:81], v[134:137], v[220:223], v[78:81]
	v_mfma_f32_16x16x32_bf16 v[74:77], v[142:145], v[220:223], v[74:77]
	v_mfma_f32_16x16x32_bf16 v[118:121], v[146:149], v[184:187], 0
	v_mfma_f32_16x16x32_bf16 v[114:117], v[154:157], v[184:187], 0
	v_mfma_f32_16x16x32_bf16 v[102:105], v[146:149], v[192:195], 0
	v_mfma_f32_16x16x32_bf16 v[98:101], v[154:157], v[192:195], 0
	v_mfma_f32_16x16x32_bf16 v[86:89], v[146:149], v[208:211], 0
	v_mfma_f32_16x16x32_bf16 v[82:85], v[154:157], v[208:211], 0
	v_mfma_f32_16x16x32_bf16 v[70:73], v[146:149], v[216:219], 0
	v_mfma_f32_16x16x32_bf16 v[66:69], v[154:157], v[216:219], 0
	v_mfma_f32_16x16x32_bf16 v[118:121], v[150:153], v[188:191], v[118:121]
	v_mfma_f32_16x16x32_bf16 v[114:117], v[158:161], v[188:191], v[114:117]
	v_mfma_f32_16x16x32_bf16 v[102:105], v[150:153], v[204:207], v[102:105]
	v_mfma_f32_16x16x32_bf16 v[98:101], v[158:161], v[204:207], v[98:101]
	v_mfma_f32_16x16x32_bf16 v[86:89], v[150:153], v[212:215], v[86:89]
	v_mfma_f32_16x16x32_bf16 v[82:85], v[158:161], v[212:215], v[82:85]
	v_mfma_f32_16x16x32_bf16 v[70:73], v[150:153], v[220:223], v[70:73]
	v_mfma_f32_16x16x32_bf16 v[66:69], v[158:161], v[220:223], v[66:69]
	s_barrier
	s_setprio 0
	s_add_i32 s16, s29, s4
	v_lshl_add_u64 v[170:171], s[48:49], 0, v[0:1]
	s_mov_b32 m0, s16
	ds_read_b128 v[184:187], v199 offset:16384
	ds_read_b128 v[188:191], v199 offset:17408
	ds_read_b128 v[192:195], v199 offset:18432
	ds_read_b128 v[204:207], v199 offset:19456
	ds_read_b128 v[208:211], v199 offset:20480
	ds_read_b128 v[212:215], v199 offset:21504
	ds_read_b128 v[216:219], v199 offset:22528
	ds_read_b128 v[220:223], v199 offset:23552
	global_load_lds_dwordx4 v[170:171], off
	s_add_i32 m0, s16, 0x2000
	s_add_u32 s16, s48, 0x18000
	v_lshl_add_u64 v[172:173], s[48:49], 0, v[174:175]
	s_addc_u32 s17, s49, 0
	s_add_i32 s29, s74, s4
	global_load_lds_dwordx4 v[172:173], off
	v_lshl_add_u64 v[224:225], s[16:17], 0, v[0:1]
	s_mov_b32 m0, s29
	v_lshl_add_u64 v[226:227], s[50:51], 0, v[176:177]
	global_load_lds_dwordx4 v[224:225], off
	v_lshl_add_u64 v[224:225], s[16:17], 0, v[174:175]
	s_add_i32 m0, s29, 0x2000
	s_nop 0
	global_load_lds_dwordx4 v[224:225], off
	v_lshl_add_u64 v[224:225], s[50:51], 0, v[178:179]
	s_mov_b32 m0, s5
	s_nop 0
	global_load_lds_dwordx4 v[224:225], off
	s_mov_b32 m0, s20
	s_nop 0
	global_load_lds_dwordx4 v[226:227], off
	.p2align	3
	s_waitcnt vmcnt(8)
	s_waitcnt lgkmcnt(0)
	s_setprio 1
	s_barrier
	v_mfma_f32_16x16x32_bf16 v[62:65], v[130:133], v[184:187], 0
	v_mfma_f32_16x16x32_bf16 v[58:61], v[138:141], v[184:187], 0
	v_mfma_f32_16x16x32_bf16 v[46:49], v[130:133], v[192:195], 0
	v_mfma_f32_16x16x32_bf16 v[42:45], v[138:141], v[192:195], 0
	v_mfma_f32_16x16x32_bf16 v[30:33], v[130:133], v[208:211], 0
	v_mfma_f32_16x16x32_bf16 v[26:29], v[138:141], v[208:211], 0
	v_mfma_f32_16x16x32_bf16 v[14:17], v[130:133], v[216:219], 0
	v_mfma_f32_16x16x32_bf16 v[10:13], v[138:141], v[216:219], 0
	v_mfma_f32_16x16x32_bf16 v[62:65], v[134:137], v[188:191], v[62:65]
	v_mfma_f32_16x16x32_bf16 v[58:61], v[142:145], v[188:191], v[58:61]
	v_mfma_f32_16x16x32_bf16 v[46:49], v[134:137], v[204:207], v[46:49]
	v_mfma_f32_16x16x32_bf16 v[42:45], v[142:145], v[204:207], v[42:45]
	v_mfma_f32_16x16x32_bf16 v[30:33], v[134:137], v[212:215], v[30:33]
	v_mfma_f32_16x16x32_bf16 v[26:29], v[142:145], v[212:215], v[26:29]
	v_mfma_f32_16x16x32_bf16 v[14:17], v[134:137], v[220:223], v[14:17]
	v_mfma_f32_16x16x32_bf16 v[10:13], v[142:145], v[220:223], v[10:13]
	v_mfma_f32_16x16x32_bf16 v[54:57], v[146:149], v[184:187], 0
	v_mfma_f32_16x16x32_bf16 v[50:53], v[154:157], v[184:187], 0
	v_mfma_f32_16x16x32_bf16 v[38:41], v[146:149], v[192:195], 0
	v_mfma_f32_16x16x32_bf16 v[34:37], v[154:157], v[192:195], 0
	v_mfma_f32_16x16x32_bf16 v[22:25], v[146:149], v[208:211], 0
	v_mfma_f32_16x16x32_bf16 v[18:21], v[154:157], v[208:211], 0
	v_mfma_f32_16x16x32_bf16 v[6:9], v[146:149], v[216:219], 0
	v_mfma_f32_16x16x32_bf16 v[2:5], v[154:157], v[216:219], 0
	v_mfma_f32_16x16x32_bf16 v[54:57], v[150:153], v[188:191], v[54:57]
	v_mfma_f32_16x16x32_bf16 v[50:53], v[158:161], v[188:191], v[50:53]
	v_mfma_f32_16x16x32_bf16 v[38:41], v[150:153], v[204:207], v[38:41]
	v_mfma_f32_16x16x32_bf16 v[34:37], v[158:161], v[204:207], v[34:37]
	v_mfma_f32_16x16x32_bf16 v[22:25], v[150:153], v[212:215], v[22:25]
	v_mfma_f32_16x16x32_bf16 v[18:21], v[158:161], v[212:215], v[18:21]
	v_mfma_f32_16x16x32_bf16 v[6:9], v[150:153], v[220:223], v[6:9]
	v_mfma_f32_16x16x32_bf16 v[2:5], v[158:161], v[220:223], v[2:5]
	s_barrier
	s_setprio 0
	s_add_i32 s29, 0, 0x18000
	s_add_i32 s74, 0, 0x1c000
	v_add_u32_e32 v142, s29, v197
	v_add_u32_e32 v158, s74, v197
	ds_read_b128 v[130:133], v142
	ds_read_b128 v[134:137], v142 offset:1024
	ds_read_b128 v[138:141], v142 offset:2048
	ds_read_b128 v[142:145], v142 offset:3072
	ds_read_b128 v[146:149], v158
	ds_read_b128 v[150:153], v158 offset:1024
	ds_read_b128 v[154:157], v158 offset:2048
	ds_read_b128 v[158:161], v158 offset:3072
	s_add_u32 s16, s50, 0x18000
	s_addc_u32 s17, s51, 0
	s_mov_b32 m0, s22
	v_lshl_add_u64 v[228:229], s[16:17], 0, v[178:179]
	ds_read_b128 v[184:187], v199 offset:32768
	ds_read_b128 v[188:191], v199 offset:33792
	ds_read_b128 v[192:195], v199 offset:34816
	ds_read_b128 v[204:207], v199 offset:35840
	ds_read_b128 v[208:211], v199 offset:36864
	ds_read_b128 v[212:215], v199 offset:37888
	ds_read_b128 v[216:219], v199 offset:38912
	ds_read_b128 v[220:223], v199 offset:39936
	global_load_lds_dwordx4 v[228:229], off
	v_lshl_add_u64 v[228:229], s[16:17], 0, v[176:177]
	s_mov_b32 m0, s23
	s_nop 0
	global_load_lds_dwordx4 v[228:229], off
	.p2align	3
	s_waitcnt vmcnt(8)
	s_waitcnt lgkmcnt(0)
	s_setprio 1
	s_barrier
	v_mfma_f32_16x16x32_bf16 v[126:129], v[130:133], v[184:187], v[126:129]
	v_mfma_f32_16x16x32_bf16 v[122:125], v[138:141], v[184:187], v[122:125]
	v_mfma_f32_16x16x32_bf16 v[110:113], v[130:133], v[192:195], v[110:113]
	v_mfma_f32_16x16x32_bf16 v[106:109], v[138:141], v[192:195], v[106:109]
	v_mfma_f32_16x16x32_bf16 v[94:97], v[130:133], v[208:211], v[94:97]
	v_mfma_f32_16x16x32_bf16 v[90:93], v[138:141], v[208:211], v[90:93]
	v_mfma_f32_16x16x32_bf16 v[78:81], v[130:133], v[216:219], v[78:81]
	v_mfma_f32_16x16x32_bf16 v[74:77], v[138:141], v[216:219], v[74:77]
	v_mfma_f32_16x16x32_bf16 v[126:129], v[134:137], v[188:191], v[126:129]
	v_mfma_f32_16x16x32_bf16 v[122:125], v[142:145], v[188:191], v[122:125]
	v_mfma_f32_16x16x32_bf16 v[110:113], v[134:137], v[204:207], v[110:113]
	v_mfma_f32_16x16x32_bf16 v[106:109], v[142:145], v[204:207], v[106:109]
	v_mfma_f32_16x16x32_bf16 v[94:97], v[134:137], v[212:215], v[94:97]
	v_mfma_f32_16x16x32_bf16 v[90:93], v[142:145], v[212:215], v[90:93]
	v_mfma_f32_16x16x32_bf16 v[78:81], v[134:137], v[220:223], v[78:81]
	v_mfma_f32_16x16x32_bf16 v[74:77], v[142:145], v[220:223], v[74:77]
	v_mfma_f32_16x16x32_bf16 v[118:121], v[146:149], v[184:187], v[118:121]
	v_mfma_f32_16x16x32_bf16 v[114:117], v[154:157], v[184:187], v[114:117]
	v_mfma_f32_16x16x32_bf16 v[102:105], v[146:149], v[192:195], v[102:105]
	v_mfma_f32_16x16x32_bf16 v[98:101], v[154:157], v[192:195], v[98:101]
	v_mfma_f32_16x16x32_bf16 v[86:89], v[146:149], v[208:211], v[86:89]
	v_mfma_f32_16x16x32_bf16 v[82:85], v[154:157], v[208:211], v[82:85]
	v_mfma_f32_16x16x32_bf16 v[70:73], v[146:149], v[216:219], v[70:73]
	v_mfma_f32_16x16x32_bf16 v[66:69], v[154:157], v[216:219], v[66:69]
	v_mfma_f32_16x16x32_bf16 v[118:121], v[150:153], v[188:191], v[118:121]
	v_mfma_f32_16x16x32_bf16 v[114:117], v[158:161], v[188:191], v[114:117]
	v_mfma_f32_16x16x32_bf16 v[102:105], v[150:153], v[204:207], v[102:105]
	v_mfma_f32_16x16x32_bf16 v[98:101], v[158:161], v[204:207], v[98:101]
	v_mfma_f32_16x16x32_bf16 v[86:89], v[150:153], v[212:215], v[86:89]
	v_mfma_f32_16x16x32_bf16 v[82:85], v[158:161], v[212:215], v[82:85]
	v_mfma_f32_16x16x32_bf16 v[70:73], v[150:153], v[220:223], v[70:73]
	v_mfma_f32_16x16x32_bf16 v[66:69], v[158:161], v[220:223], v[66:69]
	s_barrier
	s_setprio 0
	s_add_i32 s16, s29, s4
	v_lshl_add_u64 v[170:171], v[170:171], 0, s[24:25]
	s_mov_b32 m0, s16
	ds_read_b128 v[184:187], v199 offset:49152
	ds_read_b128 v[188:191], v199 offset:50176
	ds_read_b128 v[192:195], v199 offset:51200
	ds_read_b128 v[204:207], v199 offset:52224
	ds_read_b128 v[208:211], v199 offset:53248
	ds_read_b128 v[212:215], v199 offset:54272
	ds_read_b128 v[216:219], v199 offset:55296
	ds_read_b128 v[220:223], v199 offset:56320
	global_load_lds_dwordx4 v[170:171], off
	s_add_i32 m0, s16, 0x2000
	s_add_u32 s16, s48, 0x18080
	v_lshl_add_u64 v[170:171], v[172:173], 0, s[24:25]
	s_addc_u32 s17, s49, 0
	s_add_i32 s29, s74, s4
	global_load_lds_dwordx4 v[170:171], off
	v_lshl_add_u64 v[170:171], s[16:17], 0, v[0:1]
	s_mov_b32 m0, s29
	s_nop 0
	global_load_lds_dwordx4 v[170:171], off
	v_lshl_add_u64 v[170:171], s[16:17], 0, v[174:175]
	s_add_i32 m0, s29, 0x2000
	s_nop 0
	global_load_lds_dwordx4 v[170:171], off
	v_lshl_add_u64 v[170:171], v[224:225], 0, s[24:25]
	s_mov_b32 m0, s31
	s_nop 0
	global_load_lds_dwordx4 v[170:171], off
	v_lshl_add_u64 v[170:171], v[226:227], 0, s[24:25]
	s_mov_b32 m0, s33
	s_nop 0
	global_load_lds_dwordx4 v[170:171], off
	.p2align	3
	s_waitcnt vmcnt(8)
	s_waitcnt lgkmcnt(0)
	s_setprio 1
	s_barrier
	v_mfma_f32_16x16x32_bf16 v[62:65], v[130:133], v[184:187], v[62:65]
	v_mfma_f32_16x16x32_bf16 v[58:61], v[138:141], v[184:187], v[58:61]
	v_mfma_f32_16x16x32_bf16 v[46:49], v[130:133], v[192:195], v[46:49]
	v_mfma_f32_16x16x32_bf16 v[42:45], v[138:141], v[192:195], v[42:45]
	v_mfma_f32_16x16x32_bf16 v[30:33], v[130:133], v[208:211], v[30:33]
	v_mfma_f32_16x16x32_bf16 v[26:29], v[138:141], v[208:211], v[26:29]
	v_mfma_f32_16x16x32_bf16 v[14:17], v[130:133], v[216:219], v[14:17]
	v_mfma_f32_16x16x32_bf16 v[10:13], v[138:141], v[216:219], v[10:13]
	v_mfma_f32_16x16x32_bf16 v[62:65], v[134:137], v[188:191], v[62:65]
	v_mfma_f32_16x16x32_bf16 v[58:61], v[142:145], v[188:191], v[58:61]
	v_mfma_f32_16x16x32_bf16 v[46:49], v[134:137], v[204:207], v[46:49]
	v_mfma_f32_16x16x32_bf16 v[42:45], v[142:145], v[204:207], v[42:45]
	v_mfma_f32_16x16x32_bf16 v[30:33], v[134:137], v[212:215], v[30:33]
	v_mfma_f32_16x16x32_bf16 v[26:29], v[142:145], v[212:215], v[26:29]
	v_mfma_f32_16x16x32_bf16 v[14:17], v[134:137], v[220:223], v[14:17]
	v_mfma_f32_16x16x32_bf16 v[10:13], v[142:145], v[220:223], v[10:13]
	v_mfma_f32_16x16x32_bf16 v[54:57], v[146:149], v[184:187], v[54:57]
	v_mfma_f32_16x16x32_bf16 v[50:53], v[154:157], v[184:187], v[50:53]
	v_mfma_f32_16x16x32_bf16 v[38:41], v[146:149], v[192:195], v[38:41]
	v_mfma_f32_16x16x32_bf16 v[34:37], v[154:157], v[192:195], v[34:37]
	v_mfma_f32_16x16x32_bf16 v[22:25], v[146:149], v[208:211], v[22:25]
	v_mfma_f32_16x16x32_bf16 v[18:21], v[154:157], v[208:211], v[18:21]
	v_mfma_f32_16x16x32_bf16 v[6:9], v[146:149], v[216:219], v[6:9]
	v_mfma_f32_16x16x32_bf16 v[2:5], v[154:157], v[216:219], v[2:5]
	v_mfma_f32_16x16x32_bf16 v[54:57], v[150:153], v[188:191], v[54:57]
	v_mfma_f32_16x16x32_bf16 v[50:53], v[158:161], v[188:191], v[50:53]
	v_mfma_f32_16x16x32_bf16 v[38:41], v[150:153], v[204:207], v[38:41]
	v_mfma_f32_16x16x32_bf16 v[34:37], v[158:161], v[204:207], v[34:37]
	v_mfma_f32_16x16x32_bf16 v[22:25], v[150:153], v[212:215], v[22:25]
	v_mfma_f32_16x16x32_bf16 v[18:21], v[158:161], v[212:215], v[18:21]
	v_mfma_f32_16x16x32_bf16 v[6:9], v[150:153], v[220:223], v[6:9]
	v_mfma_f32_16x16x32_bf16 v[2:5], v[158:161], v[220:223], v[2:5]
	s_barrier
	s_setprio 0
	s_add_u32 s72, s72, 0x100
	s_addc_u32 s73, s73, 0
	s_cmp_ge_i32 s37, s3
	s_mov_b64 s[16:17], s[42:43]
	s_mov_b32 s48, s37
	s_cbranch_scc0 .LBB7_963
	s_branch .Lpeelx_963
	.p2align	6
.LBB7_963:
	s_add_i32 s37, s48, 2
	s_add_u32 s42, s16, 0x100
	s_addc_u32 s43, s17, 0
	s_add_i32 s29, 0, 0x10000
	s_cmp_eq_u32 s53, s48
	s_cselect_b32 s51, s38, s43
	s_cselect_b32 s50, s39, s42
	s_cselect_b32 s49, s56, s73
	s_cselect_b32 s48, s57, s72
	s_add_i32 s74, 0, 0x14000
	v_add_u32_e32 v142, s29, v197
	v_add_u32_e32 v158, s74, v197
	ds_read_b128 v[130:133], v142
	ds_read_b128 v[134:137], v142 offset:1024
	ds_read_b128 v[138:141], v142 offset:2048
	ds_read_b128 v[142:145], v142 offset:3072
	ds_read_b128 v[146:149], v158
	ds_read_b128 v[150:153], v158 offset:1024
	ds_read_b128 v[154:157], v158 offset:2048
	ds_read_b128 v[158:161], v158 offset:3072
	v_lshl_add_u64 v[170:171], s[16:17], 0, v[180:181]
	s_add_i32 m0, s5, 0xc000
	ds_read_b128 v[184:187], v199
	ds_read_b128 v[188:191], v199 offset:1024
	ds_read_b128 v[192:195], v199 offset:2048
	ds_read_b128 v[204:207], v199 offset:3072
	ds_read_b128 v[208:211], v199 offset:4096
	ds_read_b128 v[212:215], v199 offset:5120
	ds_read_b128 v[216:219], v199 offset:6144
	ds_read_b128 v[220:223], v199 offset:7168
	global_load_lds_dwordx4 v[170:171], off
	v_lshl_add_u64 v[170:171], s[16:17], 0, v[182:183]
	s_add_i32 m0, s5, 0xe000
	s_nop 0
	global_load_lds_dwordx4 v[170:171], off
	.p2align	3
	s_waitcnt vmcnt(8)
	s_waitcnt lgkmcnt(0)
	s_setprio 1
	s_barrier
	v_mfma_f32_16x16x32_bf16 v[126:129], v[130:133], v[184:187], v[126:129]
	v_mfma_f32_16x16x32_bf16 v[122:125], v[138:141], v[184:187], v[122:125]
	v_mfma_f32_16x16x32_bf16 v[110:113], v[130:133], v[192:195], v[110:113]
	v_mfma_f32_16x16x32_bf16 v[106:109], v[138:141], v[192:195], v[106:109]
	v_mfma_f32_16x16x32_bf16 v[94:97], v[130:133], v[208:211], v[94:97]
	v_mfma_f32_16x16x32_bf16 v[90:93], v[138:141], v[208:211], v[90:93]
	v_mfma_f32_16x16x32_bf16 v[78:81], v[130:133], v[216:219], v[78:81]
	v_mfma_f32_16x16x32_bf16 v[74:77], v[138:141], v[216:219], v[74:77]
	v_mfma_f32_16x16x32_bf16 v[126:129], v[134:137], v[188:191], v[126:129]
	v_mfma_f32_16x16x32_bf16 v[122:125], v[142:145], v[188:191], v[122:125]
	v_mfma_f32_16x16x32_bf16 v[110:113], v[134:137], v[204:207], v[110:113]
	v_mfma_f32_16x16x32_bf16 v[106:109], v[142:145], v[204:207], v[106:109]
	v_mfma_f32_16x16x32_bf16 v[94:97], v[134:137], v[212:215], v[94:97]
	v_mfma_f32_16x16x32_bf16 v[90:93], v[142:145], v[212:215], v[90:93]
	v_mfma_f32_16x16x32_bf16 v[78:81], v[134:137], v[220:223], v[78:81]
	v_mfma_f32_16x16x32_bf16 v[74:77], v[142:145], v[220:223], v[74:77]
	v_mfma_f32_16x16x32_bf16 v[118:121], v[146:149], v[184:187], v[118:121]
	v_mfma_f32_16x16x32_bf16 v[114:117], v[154:157], v[184:187], v[114:117]
	v_mfma_f32_16x16x32_bf16 v[102:105], v[146:149], v[192:195], v[102:105]
	v_mfma_f32_16x16x32_bf16 v[98:101], v[154:157], v[192:195], v[98:101]
	v_mfma_f32_16x16x32_bf16 v[86:89], v[146:149], v[208:211], v[86:89]
	v_mfma_f32_16x16x32_bf16 v[82:85], v[154:157], v[208:211], v[82:85]
	v_mfma_f32_16x16x32_bf16 v[70:73], v[146:149], v[216:219], v[70:73]
	v_mfma_f32_16x16x32_bf16 v[66:69], v[154:157], v[216:219], v[66:69]
	v_mfma_f32_16x16x32_bf16 v[118:121], v[150:153], v[188:191], v[118:121]
	v_mfma_f32_16x16x32_bf16 v[114:117], v[158:161], v[188:191], v[114:117]
	v_mfma_f32_16x16x32_bf16 v[102:105], v[150:153], v[204:207], v[102:105]
	v_mfma_f32_16x16x32_bf16 v[98:101], v[158:161], v[204:207], v[98:101]
	v_mfma_f32_16x16x32_bf16 v[86:89], v[150:153], v[212:215], v[86:89]
	v_mfma_f32_16x16x32_bf16 v[82:85], v[158:161], v[212:215], v[82:85]
	v_mfma_f32_16x16x32_bf16 v[70:73], v[150:153], v[220:223], v[70:73]
	v_mfma_f32_16x16x32_bf16 v[66:69], v[158:161], v[220:223], v[66:69]
	s_barrier
	s_setprio 0
	s_add_i32 s16, s29, s4
	v_lshl_add_u64 v[170:171], s[48:49], 0, v[0:1]
	s_mov_b32 m0, s16
	ds_read_b128 v[184:187], v199 offset:16384
	ds_read_b128 v[188:191], v199 offset:17408
	ds_read_b128 v[192:195], v199 offset:18432
	ds_read_b128 v[204:207], v199 offset:19456
	ds_read_b128 v[208:211], v199 offset:20480
	ds_read_b128 v[212:215], v199 offset:21504
	ds_read_b128 v[216:219], v199 offset:22528
	ds_read_b128 v[220:223], v199 offset:23552
	global_load_lds_dwordx4 v[170:171], off
	s_add_i32 m0, s16, 0x2000
	s_add_u32 s16, s48, 0x18000
	v_lshl_add_u64 v[172:173], s[48:49], 0, v[174:175]
	s_addc_u32 s17, s49, 0
	s_add_i32 s29, s74, s4
	global_load_lds_dwordx4 v[172:173], off
	v_lshl_add_u64 v[224:225], s[16:17], 0, v[0:1]
	s_mov_b32 m0, s29
	v_lshl_add_u64 v[226:227], s[50:51], 0, v[176:177]
	global_load_lds_dwordx4 v[224:225], off
	v_lshl_add_u64 v[224:225], s[16:17], 0, v[174:175]
	s_add_i32 m0, s29, 0x2000
	s_nop 0
	global_load_lds_dwordx4 v[224:225], off
	v_lshl_add_u64 v[224:225], s[50:51], 0, v[178:179]
	s_mov_b32 m0, s5
	s_nop 0
	global_load_lds_dwordx4 v[224:225], off
	s_mov_b32 m0, s20
	s_nop 0
	global_load_lds_dwordx4 v[226:227], off
	.p2align	3
	s_waitcnt vmcnt(8)
	s_waitcnt lgkmcnt(0)
	s_setprio 1
	s_barrier
	v_mfma_f32_16x16x32_bf16 v[62:65], v[130:133], v[184:187], v[62:65]
	v_mfma_f32_16x16x32_bf16 v[58:61], v[138:141], v[184:187], v[58:61]
	v_mfma_f32_16x16x32_bf16 v[46:49], v[130:133], v[192:195], v[46:49]
	v_mfma_f32_16x16x32_bf16 v[42:45], v[138:141], v[192:195], v[42:45]
	v_mfma_f32_16x16x32_bf16 v[30:33], v[130:133], v[208:211], v[30:33]
	v_mfma_f32_16x16x32_bf16 v[26:29], v[138:141], v[208:211], v[26:29]
	v_mfma_f32_16x16x32_bf16 v[14:17], v[130:133], v[216:219], v[14:17]
	v_mfma_f32_16x16x32_bf16 v[10:13], v[138:141], v[216:219], v[10:13]
	v_mfma_f32_16x16x32_bf16 v[62:65], v[134:137], v[188:191], v[62:65]
	v_mfma_f32_16x16x32_bf16 v[58:61], v[142:145], v[188:191], v[58:61]
	v_mfma_f32_16x16x32_bf16 v[46:49], v[134:137], v[204:207], v[46:49]
	v_mfma_f32_16x16x32_bf16 v[42:45], v[142:145], v[204:207], v[42:45]
	v_mfma_f32_16x16x32_bf16 v[30:33], v[134:137], v[212:215], v[30:33]
	v_mfma_f32_16x16x32_bf16 v[26:29], v[142:145], v[212:215], v[26:29]
	v_mfma_f32_16x16x32_bf16 v[14:17], v[134:137], v[220:223], v[14:17]
	v_mfma_f32_16x16x32_bf16 v[10:13], v[142:145], v[220:223], v[10:13]
	v_mfma_f32_16x16x32_bf16 v[54:57], v[146:149], v[184:187], v[54:57]
	v_mfma_f32_16x16x32_bf16 v[50:53], v[154:157], v[184:187], v[50:53]
	v_mfma_f32_16x16x32_bf16 v[38:41], v[146:149], v[192:195], v[38:41]
	v_mfma_f32_16x16x32_bf16 v[34:37], v[154:157], v[192:195], v[34:37]
	v_mfma_f32_16x16x32_bf16 v[22:25], v[146:149], v[208:211], v[22:25]
	v_mfma_f32_16x16x32_bf16 v[18:21], v[154:157], v[208:211], v[18:21]
	v_mfma_f32_16x16x32_bf16 v[6:9], v[146:149], v[216:219], v[6:9]
	v_mfma_f32_16x16x32_bf16 v[2:5], v[154:157], v[216:219], v[2:5]
	v_mfma_f32_16x16x32_bf16 v[54:57], v[150:153], v[188:191], v[54:57]
	v_mfma_f32_16x16x32_bf16 v[50:53], v[158:161], v[188:191], v[50:53]
	v_mfma_f32_16x16x32_bf16 v[38:41], v[150:153], v[204:207], v[38:41]
	v_mfma_f32_16x16x32_bf16 v[34:37], v[158:161], v[204:207], v[34:37]
	v_mfma_f32_16x16x32_bf16 v[22:25], v[150:153], v[212:215], v[22:25]
	v_mfma_f32_16x16x32_bf16 v[18:21], v[158:161], v[212:215], v[18:21]
	v_mfma_f32_16x16x32_bf16 v[6:9], v[150:153], v[220:223], v[6:9]
	v_mfma_f32_16x16x32_bf16 v[2:5], v[158:161], v[220:223], v[2:5]
	s_barrier
	s_setprio 0
	s_add_i32 s29, 0, 0x18000
	s_add_i32 s74, 0, 0x1c000
	v_add_u32_e32 v142, s29, v197
	v_add_u32_e32 v158, s74, v197
	ds_read_b128 v[130:133], v142
	ds_read_b128 v[134:137], v142 offset:1024
	ds_read_b128 v[138:141], v142 offset:2048
	ds_read_b128 v[142:145], v142 offset:3072
	ds_read_b128 v[146:149], v158
	ds_read_b128 v[150:153], v158 offset:1024
	ds_read_b128 v[154:157], v158 offset:2048
	ds_read_b128 v[158:161], v158 offset:3072
	s_add_u32 s16, s50, 0x18000
	s_addc_u32 s17, s51, 0
	s_mov_b32 m0, s22
	v_lshl_add_u64 v[228:229], s[16:17], 0, v[178:179]
	ds_read_b128 v[184:187], v199 offset:32768
	ds_read_b128 v[188:191], v199 offset:33792
	ds_read_b128 v[192:195], v199 offset:34816
	ds_read_b128 v[204:207], v199 offset:35840
	ds_read_b128 v[208:211], v199 offset:36864
	ds_read_b128 v[212:215], v199 offset:37888
	ds_read_b128 v[216:219], v199 offset:38912
	ds_read_b128 v[220:223], v199 offset:39936
	global_load_lds_dwordx4 v[228:229], off
	v_lshl_add_u64 v[228:229], s[16:17], 0, v[176:177]
	s_mov_b32 m0, s23
	s_nop 0
	global_load_lds_dwordx4 v[228:229], off
	.p2align	3
	s_waitcnt vmcnt(8)
	s_waitcnt lgkmcnt(0)
	s_setprio 1
	s_barrier
	v_mfma_f32_16x16x32_bf16 v[126:129], v[130:133], v[184:187], v[126:129]
	v_mfma_f32_16x16x32_bf16 v[122:125], v[138:141], v[184:187], v[122:125]
	v_mfma_f32_16x16x32_bf16 v[110:113], v[130:133], v[192:195], v[110:113]
	v_mfma_f32_16x16x32_bf16 v[106:109], v[138:141], v[192:195], v[106:109]
	v_mfma_f32_16x16x32_bf16 v[94:97], v[130:133], v[208:211], v[94:97]
	v_mfma_f32_16x16x32_bf16 v[90:93], v[138:141], v[208:211], v[90:93]
	v_mfma_f32_16x16x32_bf16 v[78:81], v[130:133], v[216:219], v[78:81]
	v_mfma_f32_16x16x32_bf16 v[74:77], v[138:141], v[216:219], v[74:77]
	v_mfma_f32_16x16x32_bf16 v[126:129], v[134:137], v[188:191], v[126:129]
	v_mfma_f32_16x16x32_bf16 v[122:125], v[142:145], v[188:191], v[122:125]
	v_mfma_f32_16x16x32_bf16 v[110:113], v[134:137], v[204:207], v[110:113]
	v_mfma_f32_16x16x32_bf16 v[106:109], v[142:145], v[204:207], v[106:109]
	v_mfma_f32_16x16x32_bf16 v[94:97], v[134:137], v[212:215], v[94:97]
	v_mfma_f32_16x16x32_bf16 v[90:93], v[142:145], v[212:215], v[90:93]
	v_mfma_f32_16x16x32_bf16 v[78:81], v[134:137], v[220:223], v[78:81]
	v_mfma_f32_16x16x32_bf16 v[74:77], v[142:145], v[220:223], v[74:77]
	v_mfma_f32_16x16x32_bf16 v[118:121], v[146:149], v[184:187], v[118:121]
	v_mfma_f32_16x16x32_bf16 v[114:117], v[154:157], v[184:187], v[114:117]
	v_mfma_f32_16x16x32_bf16 v[102:105], v[146:149], v[192:195], v[102:105]
	v_mfma_f32_16x16x32_bf16 v[98:101], v[154:157], v[192:195], v[98:101]
	v_mfma_f32_16x16x32_bf16 v[86:89], v[146:149], v[208:211], v[86:89]
	v_mfma_f32_16x16x32_bf16 v[82:85], v[154:157], v[208:211], v[82:85]
	v_mfma_f32_16x16x32_bf16 v[70:73], v[146:149], v[216:219], v[70:73]
	v_mfma_f32_16x16x32_bf16 v[66:69], v[154:157], v[216:219], v[66:69]
	v_mfma_f32_16x16x32_bf16 v[118:121], v[150:153], v[188:191], v[118:121]
	v_mfma_f32_16x16x32_bf16 v[114:117], v[158:161], v[188:191], v[114:117]
	v_mfma_f32_16x16x32_bf16 v[102:105], v[150:153], v[204:207], v[102:105]
	v_mfma_f32_16x16x32_bf16 v[98:101], v[158:161], v[204:207], v[98:101]
	v_mfma_f32_16x16x32_bf16 v[86:89], v[150:153], v[212:215], v[86:89]
	v_mfma_f32_16x16x32_bf16 v[82:85], v[158:161], v[212:215], v[82:85]
	v_mfma_f32_16x16x32_bf16 v[70:73], v[150:153], v[220:223], v[70:73]
	v_mfma_f32_16x16x32_bf16 v[66:69], v[158:161], v[220:223], v[66:69]
	s_barrier
	s_setprio 0
	s_add_i32 s16, s29, s4
	v_lshl_add_u64 v[170:171], v[170:171], 0, s[24:25]
	s_mov_b32 m0, s16
	ds_read_b128 v[184:187], v199 offset:49152
	ds_read_b128 v[188:191], v199 offset:50176
	ds_read_b128 v[192:195], v199 offset:51200
	ds_read_b128 v[204:207], v199 offset:52224
	ds_read_b128 v[208:211], v199 offset:53248
	ds_read_b128 v[212:215], v199 offset:54272
	ds_read_b128 v[216:219], v199 offset:55296
	ds_read_b128 v[220:223], v199 offset:56320
	global_load_lds_dwordx4 v[170:171], off
	s_add_i32 m0, s16, 0x2000
	s_add_u32 s16, s48, 0x18080
	v_lshl_add_u64 v[170:171], v[172:173], 0, s[24:25]
	s_addc_u32 s17, s49, 0
	s_add_i32 s29, s74, s4
	global_load_lds_dwordx4 v[170:171], off
	v_lshl_add_u64 v[170:171], s[16:17], 0, v[0:1]
	s_mov_b32 m0, s29
	s_nop 0
	global_load_lds_dwordx4 v[170:171], off
	v_lshl_add_u64 v[170:171], s[16:17], 0, v[174:175]
	s_add_i32 m0, s29, 0x2000
	s_nop 0
	global_load_lds_dwordx4 v[170:171], off
	v_lshl_add_u64 v[170:171], v[224:225], 0, s[24:25]
	s_mov_b32 m0, s31
	s_nop 0
	global_load_lds_dwordx4 v[170:171], off
	v_lshl_add_u64 v[170:171], v[226:227], 0, s[24:25]
	s_mov_b32 m0, s33
	s_nop 0
	global_load_lds_dwordx4 v[170:171], off
	.p2align	3
	s_waitcnt vmcnt(8)
	s_waitcnt lgkmcnt(0)
	s_setprio 1
	s_barrier
	v_mfma_f32_16x16x32_bf16 v[62:65], v[130:133], v[184:187], v[62:65]
	v_mfma_f32_16x16x32_bf16 v[58:61], v[138:141], v[184:187], v[58:61]
	v_mfma_f32_16x16x32_bf16 v[46:49], v[130:133], v[192:195], v[46:49]
	v_mfma_f32_16x16x32_bf16 v[42:45], v[138:141], v[192:195], v[42:45]
	v_mfma_f32_16x16x32_bf16 v[30:33], v[130:133], v[208:211], v[30:33]
	v_mfma_f32_16x16x32_bf16 v[26:29], v[138:141], v[208:211], v[26:29]
	v_mfma_f32_16x16x32_bf16 v[14:17], v[130:133], v[216:219], v[14:17]
	v_mfma_f32_16x16x32_bf16 v[10:13], v[138:141], v[216:219], v[10:13]
	v_mfma_f32_16x16x32_bf16 v[62:65], v[134:137], v[188:191], v[62:65]
	v_mfma_f32_16x16x32_bf16 v[58:61], v[142:145], v[188:191], v[58:61]
	v_mfma_f32_16x16x32_bf16 v[46:49], v[134:137], v[204:207], v[46:49]
	v_mfma_f32_16x16x32_bf16 v[42:45], v[142:145], v[204:207], v[42:45]
	v_mfma_f32_16x16x32_bf16 v[30:33], v[134:137], v[212:215], v[30:33]
	v_mfma_f32_16x16x32_bf16 v[26:29], v[142:145], v[212:215], v[26:29]
	v_mfma_f32_16x16x32_bf16 v[14:17], v[134:137], v[220:223], v[14:17]
	v_mfma_f32_16x16x32_bf16 v[10:13], v[142:145], v[220:223], v[10:13]
	v_mfma_f32_16x16x32_bf16 v[54:57], v[146:149], v[184:187], v[54:57]
	v_mfma_f32_16x16x32_bf16 v[50:53], v[154:157], v[184:187], v[50:53]
	v_mfma_f32_16x16x32_bf16 v[38:41], v[146:149], v[192:195], v[38:41]
	v_mfma_f32_16x16x32_bf16 v[34:37], v[154:157], v[192:195], v[34:37]
	v_mfma_f32_16x16x32_bf16 v[22:25], v[146:149], v[208:211], v[22:25]
	v_mfma_f32_16x16x32_bf16 v[18:21], v[154:157], v[208:211], v[18:21]
	v_mfma_f32_16x16x32_bf16 v[6:9], v[146:149], v[216:219], v[6:9]
	v_mfma_f32_16x16x32_bf16 v[2:5], v[154:157], v[216:219], v[2:5]
	v_mfma_f32_16x16x32_bf16 v[54:57], v[150:153], v[188:191], v[54:57]
	v_mfma_f32_16x16x32_bf16 v[50:53], v[158:161], v[188:191], v[50:53]
	v_mfma_f32_16x16x32_bf16 v[38:41], v[150:153], v[204:207], v[38:41]
	v_mfma_f32_16x16x32_bf16 v[34:37], v[158:161], v[204:207], v[34:37]
	v_mfma_f32_16x16x32_bf16 v[22:25], v[150:153], v[212:215], v[22:25]
	v_mfma_f32_16x16x32_bf16 v[18:21], v[158:161], v[212:215], v[18:21]
	v_mfma_f32_16x16x32_bf16 v[6:9], v[150:153], v[220:223], v[6:9]
	v_mfma_f32_16x16x32_bf16 v[2:5], v[158:161], v[220:223], v[2:5]
	s_barrier
	s_setprio 0
	s_add_u32 s72, s72, 0x100
	s_addc_u32 s73, s73, 0
	s_cmp_ge_i32 s37, s3
	s_mov_b64 s[16:17], s[42:43]
	s_mov_b32 s48, s37
	s_cbranch_scc0 .LBB7_963

.Lpeel_1104:
	s_add_i32 s74, s72, 2
	s_add_u32 s75, vcc_lo, 0xfffc0080
	s_addc_u32 s73, vcc_hi, -1
	s_add_i32 s76, 0, 0x10000
	s_cmp_eq_u32 s39, s72
	s_cselect_b32 s73, s19, s73
	s_cselect_b32 s72, s20, s75
	v_add_u32_e32 v0, s76, v205
	s_cselect_b32 s85, s28, s49
	s_cselect_b32 s84, s29, s37
	s_add_i32 s75, 0, 0x14000
	ds_read_b128 v[132:135], v0
	ds_read_b128 v[136:139], v0 offset:1024
	ds_read_b128 v[140:143], v0 offset:2048
	ds_read_b128 v[144:147], v0 offset:3072
	v_add_u32_e32 v0, s75, v205
	ds_read_b128 v[148:151], v0
	ds_read_b128 v[152:155], v0 offset:1024
	ds_read_b128 v[156:159], v0 offset:2048
	ds_read_b128 v[184:187], v0 offset:3072
	s_waitcnt lgkmcnt(0)
	s_add_i32 m0, s5, 0xc000
	ds_read_b128 v[188:191], v207
	ds_read_b128 v[192:195], v207 offset:1024
	ds_read_b128 v[196:199], v207 offset:2048
	ds_read_b128 v[208:211], v207 offset:3072
	ds_read_b128 v[212:215], v207 offset:4096
	ds_read_b128 v[216:219], v207 offset:5120
	ds_read_b128 v[220:223], v207 offset:6144
	ds_read_b128 v[224:227], v207 offset:7168
	global_load_lds_dwordx4 v180, vcc
	s_add_i32 m0, s5, 0xe000
	s_nop 0
	global_load_lds_dwordx4 v182, vcc
	.p2align	3
	s_waitcnt vmcnt(8)
	s_waitcnt lgkmcnt(0)
	s_setprio 1
	s_barrier
	v_mfma_f32_16x16x32_bf16 v[128:131], v[132:135], v[188:191], 0
	v_mfma_f32_16x16x32_bf16 v[124:127], v[140:143], v[188:191], 0
	v_mfma_f32_16x16x32_bf16 v[120:123], v[132:135], v[196:199], 0
	v_mfma_f32_16x16x32_bf16 v[116:119], v[140:143], v[196:199], 0
	v_mfma_f32_16x16x32_bf16 v[112:115], v[132:135], v[212:215], 0
	v_mfma_f32_16x16x32_bf16 v[108:111], v[140:143], v[212:215], 0
	v_mfma_f32_16x16x32_bf16 v[104:107], v[132:135], v[220:223], 0
	v_mfma_f32_16x16x32_bf16 v[100:103], v[140:143], v[220:223], 0
	v_mfma_f32_16x16x32_bf16 v[128:131], v[136:139], v[192:195], v[128:131]
	v_mfma_f32_16x16x32_bf16 v[124:127], v[144:147], v[192:195], v[124:127]
	v_mfma_f32_16x16x32_bf16 v[120:123], v[136:139], v[208:211], v[120:123]
	v_mfma_f32_16x16x32_bf16 v[116:119], v[144:147], v[208:211], v[116:119]
	v_mfma_f32_16x16x32_bf16 v[112:115], v[136:139], v[216:219], v[112:115]
	v_mfma_f32_16x16x32_bf16 v[108:111], v[144:147], v[216:219], v[108:111]
	v_mfma_f32_16x16x32_bf16 v[104:107], v[136:139], v[224:227], v[104:107]
	v_mfma_f32_16x16x32_bf16 v[100:103], v[144:147], v[224:227], v[100:103]
	v_mfma_f32_16x16x32_bf16 v[96:99], v[148:151], v[188:191], 0
	v_mfma_f32_16x16x32_bf16 v[92:95], v[156:159], v[188:191], 0
	v_mfma_f32_16x16x32_bf16 v[88:91], v[148:151], v[196:199], 0
	v_mfma_f32_16x16x32_bf16 v[84:87], v[156:159], v[196:199], 0
	v_mfma_f32_16x16x32_bf16 v[80:83], v[148:151], v[212:215], 0
	v_mfma_f32_16x16x32_bf16 v[76:79], v[156:159], v[212:215], 0
	v_mfma_f32_16x16x32_bf16 v[72:75], v[148:151], v[220:223], 0
	v_mfma_f32_16x16x32_bf16 v[68:71], v[156:159], v[220:223], 0
	v_mfma_f32_16x16x32_bf16 v[96:99], v[152:155], v[192:195], v[96:99]
	v_mfma_f32_16x16x32_bf16 v[92:95], v[184:187], v[192:195], v[92:95]
	v_mfma_f32_16x16x32_bf16 v[88:91], v[152:155], v[208:211], v[88:91]
	v_mfma_f32_16x16x32_bf16 v[84:87], v[184:187], v[208:211], v[84:87]
	v_mfma_f32_16x16x32_bf16 v[80:83], v[152:155], v[216:219], v[80:83]
	v_mfma_f32_16x16x32_bf16 v[76:79], v[184:187], v[216:219], v[76:79]
	v_mfma_f32_16x16x32_bf16 v[72:75], v[152:155], v[224:227], v[72:75]
	v_mfma_f32_16x16x32_bf16 v[68:71], v[184:187], v[224:227], v[68:71]
	s_barrier
	s_setprio 0
	s_add_i32 s76, s76, s4
	v_lshl_add_u64 v[170:171], s[84:85], 0, v[176:177]
	s_mov_b32 m0, s76
	ds_read_b128 v[188:191], v207 offset:16384
	ds_read_b128 v[192:195], v207 offset:17408
	ds_read_b128 v[196:199], v207 offset:18432
	ds_read_b128 v[208:211], v207 offset:19456
	ds_read_b128 v[212:215], v207 offset:20480
	ds_read_b128 v[216:219], v207 offset:21504
	ds_read_b128 v[220:223], v207 offset:22528
	ds_read_b128 v[224:227], v207 offset:23552
	global_load_lds_dwordx4 v[170:171], off
	s_add_i32 m0, s76, 0x2000
	s_add_u32 s76, s84, 0x40000
	v_lshl_add_u64 v[172:173], s[84:85], 0, v[160:161]
	s_addc_u32 s77, s85, 0
	s_add_i32 s75, s75, s4
	global_load_lds_dwordx4 v[172:173], off
	s_mov_b32 m0, s75
	v_lshl_add_u64 v[228:229], s[72:73], 0, v[178:179]
	global_load_lds_dwordx4 v176, s[76:77]
	s_add_i32 m0, s75, 0x2000
	v_lshl_add_u64 v[230:231], s[72:73], 0, v[174:175]
	global_load_lds_dwordx4 v160, s[76:77]
	s_mov_b32 m0, s5
	s_nop 0
	global_load_lds_dwordx4 v[228:229], off
	s_mov_b32 m0, s22
	s_nop 0
	global_load_lds_dwordx4 v[230:231], off
	.p2align	3
	s_waitcnt vmcnt(8)
	s_waitcnt lgkmcnt(0)
	s_setprio 1
	s_barrier
	v_mfma_f32_16x16x32_bf16 v[64:67], v[132:135], v[188:191], 0
	v_mfma_f32_16x16x32_bf16 v[60:63], v[140:143], v[188:191], 0
	v_mfma_f32_16x16x32_bf16 v[56:59], v[132:135], v[196:199], 0
	v_mfma_f32_16x16x32_bf16 v[52:55], v[140:143], v[196:199], 0
	v_mfma_f32_16x16x32_bf16 v[48:51], v[132:135], v[212:215], 0
	v_mfma_f32_16x16x32_bf16 v[44:47], v[140:143], v[212:215], 0
	v_mfma_f32_16x16x32_bf16 v[40:43], v[132:135], v[220:223], 0
	v_mfma_f32_16x16x32_bf16 v[36:39], v[140:143], v[220:223], 0
	v_mfma_f32_16x16x32_bf16 v[64:67], v[136:139], v[192:195], v[64:67]
	v_mfma_f32_16x16x32_bf16 v[60:63], v[144:147], v[192:195], v[60:63]
	v_mfma_f32_16x16x32_bf16 v[56:59], v[136:139], v[208:211], v[56:59]
	v_mfma_f32_16x16x32_bf16 v[52:55], v[144:147], v[208:211], v[52:55]
	v_mfma_f32_16x16x32_bf16 v[48:51], v[136:139], v[216:219], v[48:51]
	v_mfma_f32_16x16x32_bf16 v[44:47], v[144:147], v[216:219], v[44:47]
	v_mfma_f32_16x16x32_bf16 v[40:43], v[136:139], v[224:227], v[40:43]
	v_mfma_f32_16x16x32_bf16 v[36:39], v[144:147], v[224:227], v[36:39]
	v_mfma_f32_16x16x32_bf16 v[32:35], v[148:151], v[188:191], 0
	v_mfma_f32_16x16x32_bf16 v[28:31], v[156:159], v[188:191], 0
	v_mfma_f32_16x16x32_bf16 v[24:27], v[148:151], v[196:199], 0
	v_mfma_f32_16x16x32_bf16 v[20:23], v[156:159], v[196:199], 0
	v_mfma_f32_16x16x32_bf16 v[16:19], v[148:151], v[212:215], 0
	v_mfma_f32_16x16x32_bf16 v[12:15], v[156:159], v[212:215], 0
	v_mfma_f32_16x16x32_bf16 v[8:11], v[148:151], v[220:223], 0
	v_mfma_f32_16x16x32_bf16 v[2:5], v[156:159], v[220:223], 0
	v_mfma_f32_16x16x32_bf16 v[32:35], v[152:155], v[192:195], v[32:35]
	v_mfma_f32_16x16x32_bf16 v[28:31], v[184:187], v[192:195], v[28:31]
	v_mfma_f32_16x16x32_bf16 v[24:27], v[152:155], v[208:211], v[24:27]
	v_mfma_f32_16x16x32_bf16 v[20:23], v[184:187], v[208:211], v[20:23]
	v_mfma_f32_16x16x32_bf16 v[16:19], v[152:155], v[216:219], v[16:19]
	v_mfma_f32_16x16x32_bf16 v[12:15], v[184:187], v[216:219], v[12:15]
	v_mfma_f32_16x16x32_bf16 v[8:11], v[152:155], v[224:227], v[8:11]
	v_mfma_f32_16x16x32_bf16 v[2:5], v[184:187], v[224:227], v[2:5]
	s_barrier
	s_setprio 0
	s_add_i32 s75, 0, 0x18000
	v_add_u32_e32 v0, s75, v205
	s_add_i32 s76, 0, 0x1c000
	ds_read_b128 v[132:135], v0
	ds_read_b128 v[136:139], v0 offset:1024
	ds_read_b128 v[140:143], v0 offset:2048
	ds_read_b128 v[144:147], v0 offset:3072
	v_add_u32_e32 v0, s76, v205
	ds_read_b128 v[148:151], v0
	ds_read_b128 v[152:155], v0 offset:1024
	ds_read_b128 v[156:159], v0 offset:2048
	ds_read_b128 v[184:187], v0 offset:3072
	s_add_u32 s72, s72, 0x40000
	s_addc_u32 s73, s73, 0
	s_mov_b32 m0, s23
	ds_read_b128 v[188:191], v207 offset:32768
	ds_read_b128 v[192:195], v207 offset:33792
	ds_read_b128 v[196:199], v207 offset:34816
	ds_read_b128 v[208:211], v207 offset:35840
	ds_read_b128 v[212:215], v207 offset:36864
	ds_read_b128 v[216:219], v207 offset:37888
	ds_read_b128 v[220:223], v207 offset:38912
	ds_read_b128 v[224:227], v207 offset:39936
	global_load_lds_dwordx4 v178, s[72:73]
	s_mov_b32 m0, s31
	s_nop 0
	global_load_lds_dwordx4 v174, s[72:73]
	.p2align	3
	s_waitcnt vmcnt(8)
	s_waitcnt lgkmcnt(0)
	s_setprio 1
	s_barrier
	v_mfma_f32_16x16x32_bf16 v[128:131], v[132:135], v[188:191], v[128:131]
	v_mfma_f32_16x16x32_bf16 v[124:127], v[140:143], v[188:191], v[124:127]
	v_mfma_f32_16x16x32_bf16 v[120:123], v[132:135], v[196:199], v[120:123]
	v_mfma_f32_16x16x32_bf16 v[116:119], v[140:143], v[196:199], v[116:119]
	v_mfma_f32_16x16x32_bf16 v[112:115], v[132:135], v[212:215], v[112:115]
	v_mfma_f32_16x16x32_bf16 v[108:111], v[140:143], v[212:215], v[108:111]
	v_mfma_f32_16x16x32_bf16 v[104:107], v[132:135], v[220:223], v[104:107]
	v_mfma_f32_16x16x32_bf16 v[100:103], v[140:143], v[220:223], v[100:103]
	v_mfma_f32_16x16x32_bf16 v[128:131], v[136:139], v[192:195], v[128:131]
	v_mfma_f32_16x16x32_bf16 v[124:127], v[144:147], v[192:195], v[124:127]
	v_mfma_f32_16x16x32_bf16 v[120:123], v[136:139], v[208:211], v[120:123]
	v_mfma_f32_16x16x32_bf16 v[116:119], v[144:147], v[208:211], v[116:119]
	v_mfma_f32_16x16x32_bf16 v[112:115], v[136:139], v[216:219], v[112:115]
	v_mfma_f32_16x16x32_bf16 v[108:111], v[144:147], v[216:219], v[108:111]
	v_mfma_f32_16x16x32_bf16 v[104:107], v[136:139], v[224:227], v[104:107]
	v_mfma_f32_16x16x32_bf16 v[100:103], v[144:147], v[224:227], v[100:103]
	v_mfma_f32_16x16x32_bf16 v[96:99], v[148:151], v[188:191], v[96:99]
	v_mfma_f32_16x16x32_bf16 v[92:95], v[156:159], v[188:191], v[92:95]
	v_mfma_f32_16x16x32_bf16 v[88:91], v[148:151], v[196:199], v[88:91]
	v_mfma_f32_16x16x32_bf16 v[84:87], v[156:159], v[196:199], v[84:87]
	v_mfma_f32_16x16x32_bf16 v[80:83], v[148:151], v[212:215], v[80:83]
	v_mfma_f32_16x16x32_bf16 v[76:79], v[156:159], v[212:215], v[76:79]
	v_mfma_f32_16x16x32_bf16 v[72:75], v[148:151], v[220:223], v[72:75]
	v_mfma_f32_16x16x32_bf16 v[68:71], v[156:159], v[220:223], v[68:71]
	v_mfma_f32_16x16x32_bf16 v[96:99], v[152:155], v[192:195], v[96:99]
	v_mfma_f32_16x16x32_bf16 v[92:95], v[184:187], v[192:195], v[92:95]
	v_mfma_f32_16x16x32_bf16 v[88:91], v[152:155], v[208:211], v[88:91]
	v_mfma_f32_16x16x32_bf16 v[84:87], v[184:187], v[208:211], v[84:87]
	v_mfma_f32_16x16x32_bf16 v[80:83], v[152:155], v[216:219], v[80:83]
	v_mfma_f32_16x16x32_bf16 v[76:79], v[184:187], v[216:219], v[76:79]
	v_mfma_f32_16x16x32_bf16 v[72:75], v[152:155], v[224:227], v[72:75]
	v_mfma_f32_16x16x32_bf16 v[68:71], v[184:187], v[224:227], v[68:71]
	s_barrier
	s_setprio 0
	s_add_i32 s72, s75, s4
	v_lshl_add_u64 v[6:7], v[170:171], 0, s[24:25]
	s_mov_b32 m0, s72
	ds_read_b128 v[188:191], v207 offset:49152
	ds_read_b128 v[192:195], v207 offset:50176
	ds_read_b128 v[196:199], v207 offset:51200
	ds_read_b128 v[208:211], v207 offset:52224
	ds_read_b128 v[212:215], v207 offset:53248
	ds_read_b128 v[216:219], v207 offset:54272
	ds_read_b128 v[220:223], v207 offset:55296
	ds_read_b128 v[224:227], v207 offset:56320
	global_load_lds_dwordx4 v[6:7], off
	s_add_i32 m0, s72, 0x2000
	s_add_u32 s72, s84, 0x40080
	v_lshl_add_u64 v[6:7], v[172:173], 0, s[24:25]
	s_addc_u32 s73, s85, 0
	s_add_i32 s75, s76, s4
	global_load_lds_dwordx4 v[6:7], off
	s_mov_b32 m0, s75
	s_nop 0
	global_load_lds_dwordx4 v176, s[72:73]
	s_add_i32 m0, s75, 0x2000
	s_nop 0
	global_load_lds_dwordx4 v160, s[72:73]
	v_lshl_add_u64 v[6:7], v[228:229], 0, s[24:25]
	s_mov_b32 m0, s33
	s_nop 0
	global_load_lds_dwordx4 v[6:7], off
	v_lshl_add_u64 v[6:7], v[230:231], 0, s[24:25]
	s_mov_b32 m0, s38
	s_nop 0
	global_load_lds_dwordx4 v[6:7], off
	.p2align	3
	s_waitcnt vmcnt(8)
	s_waitcnt lgkmcnt(0)
	s_setprio 1
	s_barrier
	v_mfma_f32_16x16x32_bf16 v[64:67], v[132:135], v[188:191], v[64:67]
	v_mfma_f32_16x16x32_bf16 v[60:63], v[140:143], v[188:191], v[60:63]
	v_mfma_f32_16x16x32_bf16 v[56:59], v[132:135], v[196:199], v[56:59]
	v_mfma_f32_16x16x32_bf16 v[52:55], v[140:143], v[196:199], v[52:55]
	v_mfma_f32_16x16x32_bf16 v[48:51], v[132:135], v[212:215], v[48:51]
	v_mfma_f32_16x16x32_bf16 v[44:47], v[140:143], v[212:215], v[44:47]
	v_mfma_f32_16x16x32_bf16 v[40:43], v[132:135], v[220:223], v[40:43]
	v_mfma_f32_16x16x32_bf16 v[36:39], v[140:143], v[220:223], v[36:39]
	v_mfma_f32_16x16x32_bf16 v[64:67], v[136:139], v[192:195], v[64:67]
	v_mfma_f32_16x16x32_bf16 v[60:63], v[144:147], v[192:195], v[60:63]
	v_mfma_f32_16x16x32_bf16 v[56:59], v[136:139], v[208:211], v[56:59]
	v_mfma_f32_16x16x32_bf16 v[52:55], v[144:147], v[208:211], v[52:55]
	v_mfma_f32_16x16x32_bf16 v[48:51], v[136:139], v[216:219], v[48:51]
	v_mfma_f32_16x16x32_bf16 v[44:47], v[144:147], v[216:219], v[44:47]
	v_mfma_f32_16x16x32_bf16 v[40:43], v[136:139], v[224:227], v[40:43]
	v_mfma_f32_16x16x32_bf16 v[36:39], v[144:147], v[224:227], v[36:39]
	v_mfma_f32_16x16x32_bf16 v[32:35], v[148:151], v[188:191], v[32:35]
	v_mfma_f32_16x16x32_bf16 v[28:31], v[156:159], v[188:191], v[28:31]
	v_mfma_f32_16x16x32_bf16 v[24:27], v[148:151], v[196:199], v[24:27]
	v_mfma_f32_16x16x32_bf16 v[20:23], v[156:159], v[196:199], v[20:23]
	v_mfma_f32_16x16x32_bf16 v[16:19], v[148:151], v[212:215], v[16:19]
	v_mfma_f32_16x16x32_bf16 v[12:15], v[156:159], v[212:215], v[12:15]
	v_mfma_f32_16x16x32_bf16 v[6:9], v[148:151], v[220:223], v[8:11]
	v_mfma_f32_16x16x32_bf16 v[2:5], v[156:159], v[220:223], v[2:5]
	v_mfma_f32_16x16x32_bf16 v[32:35], v[152:155], v[192:195], v[32:35]
	v_mfma_f32_16x16x32_bf16 v[28:31], v[184:187], v[192:195], v[28:31]
	v_mfma_f32_16x16x32_bf16 v[24:27], v[152:155], v[208:211], v[24:27]
	v_mfma_f32_16x16x32_bf16 v[20:23], v[184:187], v[208:211], v[20:23]
	v_mfma_f32_16x16x32_bf16 v[16:19], v[152:155], v[216:219], v[16:19]
	v_mfma_f32_16x16x32_bf16 v[12:15], v[184:187], v[216:219], v[12:15]
	v_mfma_f32_16x16x32_bf16 v[8:11], v[152:155], v[224:227], v[6:9]
	v_mfma_f32_16x16x32_bf16 v[4:7], v[184:187], v[224:227], v[2:5]
	s_barrier
	s_setprio 0
	s_add_u32 s37, s37, 0x100
	s_addc_u32 s49, s49, 0
	s_add_u32 vcc_lo, vcc_lo, 0x100
	s_addc_u32 vcc_hi, vcc_hi, 0
	s_cmp_ge_i32 s74, s3
	s_mov_b32 s72, s74
	s_cbranch_scc0 .LBB7_1104
	s_branch .Lpeelx_1104
	.p2align	6
.LBB7_1104:
	s_add_i32 s74, s72, 2
	s_add_u32 s75, vcc_lo, 0xfffc0080
	s_addc_u32 s73, vcc_hi, -1
	s_add_i32 s76, 0, 0x10000
	s_cmp_eq_u32 s39, s72
	s_cselect_b32 s73, s19, s73
	s_cselect_b32 s72, s20, s75
	v_add_u32_e32 v0, s76, v205
	s_cselect_b32 s85, s28, s49
	s_cselect_b32 s84, s29, s37
	s_add_i32 s75, 0, 0x14000
	ds_read_b128 v[132:135], v0
	ds_read_b128 v[136:139], v0 offset:1024
	ds_read_b128 v[140:143], v0 offset:2048
	ds_read_b128 v[144:147], v0 offset:3072
	v_add_u32_e32 v0, s75, v205
	ds_read_b128 v[148:151], v0
	ds_read_b128 v[152:155], v0 offset:1024
	ds_read_b128 v[156:159], v0 offset:2048
	ds_read_b128 v[184:187], v0 offset:3072
	s_waitcnt lgkmcnt(0)
	s_add_i32 m0, s5, 0xc000
	ds_read_b128 v[188:191], v207
	ds_read_b128 v[192:195], v207 offset:1024
	ds_read_b128 v[196:199], v207 offset:2048
	ds_read_b128 v[208:211], v207 offset:3072
	ds_read_b128 v[212:215], v207 offset:4096
	ds_read_b128 v[216:219], v207 offset:5120
	ds_read_b128 v[220:223], v207 offset:6144
	ds_read_b128 v[224:227], v207 offset:7168
	global_load_lds_dwordx4 v180, vcc
	s_add_i32 m0, s5, 0xe000
	s_nop 0
	global_load_lds_dwordx4 v182, vcc
	.p2align	3
	s_waitcnt vmcnt(8)
	s_waitcnt lgkmcnt(0)
	s_setprio 1
	s_barrier
	v_mfma_f32_16x16x32_bf16 v[128:131], v[132:135], v[188:191], v[128:131]
	v_mfma_f32_16x16x32_bf16 v[124:127], v[140:143], v[188:191], v[124:127]
	v_mfma_f32_16x16x32_bf16 v[120:123], v[132:135], v[196:199], v[120:123]
	v_mfma_f32_16x16x32_bf16 v[116:119], v[140:143], v[196:199], v[116:119]
	v_mfma_f32_16x16x32_bf16 v[112:115], v[132:135], v[212:215], v[112:115]
	v_mfma_f32_16x16x32_bf16 v[108:111], v[140:143], v[212:215], v[108:111]
	v_mfma_f32_16x16x32_bf16 v[104:107], v[132:135], v[220:223], v[104:107]
	v_mfma_f32_16x16x32_bf16 v[100:103], v[140:143], v[220:223], v[100:103]
	v_mfma_f32_16x16x32_bf16 v[128:131], v[136:139], v[192:195], v[128:131]
	v_mfma_f32_16x16x32_bf16 v[124:127], v[144:147], v[192:195], v[124:127]
	v_mfma_f32_16x16x32_bf16 v[120:123], v[136:139], v[208:211], v[120:123]
	v_mfma_f32_16x16x32_bf16 v[116:119], v[144:147], v[208:211], v[116:119]
	v_mfma_f32_16x16x32_bf16 v[112:115], v[136:139], v[216:219], v[112:115]
	v_mfma_f32_16x16x32_bf16 v[108:111], v[144:147], v[216:219], v[108:111]
	v_mfma_f32_16x16x32_bf16 v[104:107], v[136:139], v[224:227], v[104:107]
	v_mfma_f32_16x16x32_bf16 v[100:103], v[144:147], v[224:227], v[100:103]
	v_mfma_f32_16x16x32_bf16 v[96:99], v[148:151], v[188:191], v[96:99]
	v_mfma_f32_16x16x32_bf16 v[92:95], v[156:159], v[188:191], v[92:95]
	v_mfma_f32_16x16x32_bf16 v[88:91], v[148:151], v[196:199], v[88:91]
	v_mfma_f32_16x16x32_bf16 v[84:87], v[156:159], v[196:199], v[84:87]
	v_mfma_f32_16x16x32_bf16 v[80:83], v[148:151], v[212:215], v[80:83]
	v_mfma_f32_16x16x32_bf16 v[76:79], v[156:159], v[212:215], v[76:79]
	v_mfma_f32_16x16x32_bf16 v[72:75], v[148:151], v[220:223], v[72:75]
	v_mfma_f32_16x16x32_bf16 v[68:71], v[156:159], v[220:223], v[68:71]
	v_mfma_f32_16x16x32_bf16 v[96:99], v[152:155], v[192:195], v[96:99]
	v_mfma_f32_16x16x32_bf16 v[92:95], v[184:187], v[192:195], v[92:95]
	v_mfma_f32_16x16x32_bf16 v[88:91], v[152:155], v[208:211], v[88:91]
	v_mfma_f32_16x16x32_bf16 v[84:87], v[184:187], v[208:211], v[84:87]
	v_mfma_f32_16x16x32_bf16 v[80:83], v[152:155], v[216:219], v[80:83]
	v_mfma_f32_16x16x32_bf16 v[76:79], v[184:187], v[216:219], v[76:79]
	v_mfma_f32_16x16x32_bf16 v[72:75], v[152:155], v[224:227], v[72:75]
	v_mfma_f32_16x16x32_bf16 v[68:71], v[184:187], v[224:227], v[68:71]
	s_barrier
	s_setprio 0
	s_add_i32 s76, s76, s4
	v_lshl_add_u64 v[170:171], s[84:85], 0, v[176:177]
	s_mov_b32 m0, s76
	ds_read_b128 v[188:191], v207 offset:16384
	ds_read_b128 v[192:195], v207 offset:17408
	ds_read_b128 v[196:199], v207 offset:18432
	ds_read_b128 v[208:211], v207 offset:19456
	ds_read_b128 v[212:215], v207 offset:20480
	ds_read_b128 v[216:219], v207 offset:21504
	ds_read_b128 v[220:223], v207 offset:22528
	ds_read_b128 v[224:227], v207 offset:23552
	global_load_lds_dwordx4 v[170:171], off
	s_add_i32 m0, s76, 0x2000
	s_add_u32 s76, s84, 0x40000
	v_lshl_add_u64 v[172:173], s[84:85], 0, v[160:161]
	s_addc_u32 s77, s85, 0
	s_add_i32 s75, s75, s4
	global_load_lds_dwordx4 v[172:173], off
	s_mov_b32 m0, s75
	v_lshl_add_u64 v[228:229], s[72:73], 0, v[178:179]
	global_load_lds_dwordx4 v176, s[76:77]
	s_add_i32 m0, s75, 0x2000
	v_lshl_add_u64 v[230:231], s[72:73], 0, v[174:175]
	global_load_lds_dwordx4 v160, s[76:77]
	s_mov_b32 m0, s5
	s_nop 0
	global_load_lds_dwordx4 v[228:229], off
	s_mov_b32 m0, s22
	s_nop 0
	global_load_lds_dwordx4 v[230:231], off
	.p2align	3
	s_waitcnt vmcnt(8)
	s_waitcnt lgkmcnt(0)
	s_setprio 1
	s_barrier
	v_mfma_f32_16x16x32_bf16 v[64:67], v[132:135], v[188:191], v[64:67]
	v_mfma_f32_16x16x32_bf16 v[60:63], v[140:143], v[188:191], v[60:63]
	v_mfma_f32_16x16x32_bf16 v[56:59], v[132:135], v[196:199], v[56:59]
	v_mfma_f32_16x16x32_bf16 v[52:55], v[140:143], v[196:199], v[52:55]
	v_mfma_f32_16x16x32_bf16 v[48:51], v[132:135], v[212:215], v[48:51]
	v_mfma_f32_16x16x32_bf16 v[44:47], v[140:143], v[212:215], v[44:47]
	v_mfma_f32_16x16x32_bf16 v[40:43], v[132:135], v[220:223], v[40:43]
	v_mfma_f32_16x16x32_bf16 v[36:39], v[140:143], v[220:223], v[36:39]
	v_mfma_f32_16x16x32_bf16 v[64:67], v[136:139], v[192:195], v[64:67]
	v_mfma_f32_16x16x32_bf16 v[60:63], v[144:147], v[192:195], v[60:63]
	v_mfma_f32_16x16x32_bf16 v[56:59], v[136:139], v[208:211], v[56:59]
	v_mfma_f32_16x16x32_bf16 v[52:55], v[144:147], v[208:211], v[52:55]
	v_mfma_f32_16x16x32_bf16 v[48:51], v[136:139], v[216:219], v[48:51]
	v_mfma_f32_16x16x32_bf16 v[44:47], v[144:147], v[216:219], v[44:47]
	v_mfma_f32_16x16x32_bf16 v[40:43], v[136:139], v[224:227], v[40:43]
	v_mfma_f32_16x16x32_bf16 v[36:39], v[144:147], v[224:227], v[36:39]
	v_mfma_f32_16x16x32_bf16 v[32:35], v[148:151], v[188:191], v[32:35]
	v_mfma_f32_16x16x32_bf16 v[28:31], v[156:159], v[188:191], v[28:31]
	v_mfma_f32_16x16x32_bf16 v[24:27], v[148:151], v[196:199], v[24:27]
	v_mfma_f32_16x16x32_bf16 v[20:23], v[156:159], v[196:199], v[20:23]
	v_mfma_f32_16x16x32_bf16 v[16:19], v[148:151], v[212:215], v[16:19]
	v_mfma_f32_16x16x32_bf16 v[12:15], v[156:159], v[212:215], v[12:15]
	v_mfma_f32_16x16x32_bf16 v[8:11], v[148:151], v[220:223], v[8:11]
	v_mfma_f32_16x16x32_bf16 v[2:5], v[156:159], v[220:223], v[4:7]
	v_mfma_f32_16x16x32_bf16 v[32:35], v[152:155], v[192:195], v[32:35]
	v_mfma_f32_16x16x32_bf16 v[28:31], v[184:187], v[192:195], v[28:31]
	v_mfma_f32_16x16x32_bf16 v[24:27], v[152:155], v[208:211], v[24:27]
	v_mfma_f32_16x16x32_bf16 v[20:23], v[184:187], v[208:211], v[20:23]
	v_mfma_f32_16x16x32_bf16 v[16:19], v[152:155], v[216:219], v[16:19]
	v_mfma_f32_16x16x32_bf16 v[12:15], v[184:187], v[216:219], v[12:15]
	v_mfma_f32_16x16x32_bf16 v[8:11], v[152:155], v[224:227], v[8:11]
	v_mfma_f32_16x16x32_bf16 v[2:5], v[184:187], v[224:227], v[2:5]
	s_barrier
	s_setprio 0
	s_add_i32 s75, 0, 0x18000
	v_add_u32_e32 v0, s75, v205
	s_add_i32 s76, 0, 0x1c000
	ds_read_b128 v[132:135], v0
	ds_read_b128 v[136:139], v0 offset:1024
	ds_read_b128 v[140:143], v0 offset:2048
	ds_read_b128 v[144:147], v0 offset:3072
	v_add_u32_e32 v0, s76, v205
	ds_read_b128 v[148:151], v0
	ds_read_b128 v[152:155], v0 offset:1024
	ds_read_b128 v[156:159], v0 offset:2048
	ds_read_b128 v[184:187], v0 offset:3072
	s_add_u32 s72, s72, 0x40000
	s_addc_u32 s73, s73, 0
	s_mov_b32 m0, s23
	ds_read_b128 v[188:191], v207 offset:32768
	ds_read_b128 v[192:195], v207 offset:33792
	ds_read_b128 v[196:199], v207 offset:34816
	ds_read_b128 v[208:211], v207 offset:35840
	ds_read_b128 v[212:215], v207 offset:36864
	ds_read_b128 v[216:219], v207 offset:37888
	ds_read_b128 v[220:223], v207 offset:38912
	ds_read_b128 v[224:227], v207 offset:39936
	global_load_lds_dwordx4 v178, s[72:73]
	s_mov_b32 m0, s31
	s_nop 0
	global_load_lds_dwordx4 v174, s[72:73]
	.p2align	3
	s_waitcnt vmcnt(8)
	s_waitcnt lgkmcnt(0)
	s_setprio 1
	s_barrier
	v_mfma_f32_16x16x32_bf16 v[128:131], v[132:135], v[188:191], v[128:131]
	v_mfma_f32_16x16x32_bf16 v[124:127], v[140:143], v[188:191], v[124:127]
	v_mfma_f32_16x16x32_bf16 v[120:123], v[132:135], v[196:199], v[120:123]
	v_mfma_f32_16x16x32_bf16 v[116:119], v[140:143], v[196:199], v[116:119]
	v_mfma_f32_16x16x32_bf16 v[112:115], v[132:135], v[212:215], v[112:115]
	v_mfma_f32_16x16x32_bf16 v[108:111], v[140:143], v[212:215], v[108:111]
	v_mfma_f32_16x16x32_bf16 v[104:107], v[132:135], v[220:223], v[104:107]
	v_mfma_f32_16x16x32_bf16 v[100:103], v[140:143], v[220:223], v[100:103]
	v_mfma_f32_16x16x32_bf16 v[128:131], v[136:139], v[192:195], v[128:131]
	v_mfma_f32_16x16x32_bf16 v[124:127], v[144:147], v[192:195], v[124:127]
	v_mfma_f32_16x16x32_bf16 v[120:123], v[136:139], v[208:211], v[120:123]
	v_mfma_f32_16x16x32_bf16 v[116:119], v[144:147], v[208:211], v[116:119]
	v_mfma_f32_16x16x32_bf16 v[112:115], v[136:139], v[216:219], v[112:115]
	v_mfma_f32_16x16x32_bf16 v[108:111], v[144:147], v[216:219], v[108:111]
	v_mfma_f32_16x16x32_bf16 v[104:107], v[136:139], v[224:227], v[104:107]
	v_mfma_f32_16x16x32_bf16 v[100:103], v[144:147], v[224:227], v[100:103]
	v_mfma_f32_16x16x32_bf16 v[96:99], v[148:151], v[188:191], v[96:99]
	v_mfma_f32_16x16x32_bf16 v[92:95], v[156:159], v[188:191], v[92:95]
	v_mfma_f32_16x16x32_bf16 v[88:91], v[148:151], v[196:199], v[88:91]
	v_mfma_f32_16x16x32_bf16 v[84:87], v[156:159], v[196:199], v[84:87]
	v_mfma_f32_16x16x32_bf16 v[80:83], v[148:151], v[212:215], v[80:83]
	v_mfma_f32_16x16x32_bf16 v[76:79], v[156:159], v[212:215], v[76:79]
	v_mfma_f32_16x16x32_bf16 v[72:75], v[148:151], v[220:223], v[72:75]
	v_mfma_f32_16x16x32_bf16 v[68:71], v[156:159], v[220:223], v[68:71]
	v_mfma_f32_16x16x32_bf16 v[96:99], v[152:155], v[192:195], v[96:99]
	v_mfma_f32_16x16x32_bf16 v[92:95], v[184:187], v[192:195], v[92:95]
	v_mfma_f32_16x16x32_bf16 v[88:91], v[152:155], v[208:211], v[88:91]
	v_mfma_f32_16x16x32_bf16 v[84:87], v[184:187], v[208:211], v[84:87]
	v_mfma_f32_16x16x32_bf16 v[80:83], v[152:155], v[216:219], v[80:83]
	v_mfma_f32_16x16x32_bf16 v[76:79], v[184:187], v[216:219], v[76:79]
	v_mfma_f32_16x16x32_bf16 v[72:75], v[152:155], v[224:227], v[72:75]
	v_mfma_f32_16x16x32_bf16 v[68:71], v[184:187], v[224:227], v[68:71]
	s_barrier
	s_setprio 0
	s_add_i32 s72, s75, s4
	v_lshl_add_u64 v[6:7], v[170:171], 0, s[24:25]
	s_mov_b32 m0, s72
	ds_read_b128 v[188:191], v207 offset:49152
	ds_read_b128 v[192:195], v207 offset:50176
	ds_read_b128 v[196:199], v207 offset:51200
	ds_read_b128 v[208:211], v207 offset:52224
	ds_read_b128 v[212:215], v207 offset:53248
	ds_read_b128 v[216:219], v207 offset:54272
	ds_read_b128 v[220:223], v207 offset:55296
	ds_read_b128 v[224:227], v207 offset:56320
	global_load_lds_dwordx4 v[6:7], off
	s_add_i32 m0, s72, 0x2000
	s_add_u32 s72, s84, 0x40080
	v_lshl_add_u64 v[6:7], v[172:173], 0, s[24:25]
	s_addc_u32 s73, s85, 0
	s_add_i32 s75, s76, s4
	global_load_lds_dwordx4 v[6:7], off
	s_mov_b32 m0, s75
	s_nop 0
	global_load_lds_dwordx4 v176, s[72:73]
	s_add_i32 m0, s75, 0x2000
	s_nop 0
	global_load_lds_dwordx4 v160, s[72:73]
	v_lshl_add_u64 v[6:7], v[228:229], 0, s[24:25]
	s_mov_b32 m0, s33
	s_nop 0
	global_load_lds_dwordx4 v[6:7], off
	v_lshl_add_u64 v[6:7], v[230:231], 0, s[24:25]
	s_mov_b32 m0, s38
	s_nop 0
	global_load_lds_dwordx4 v[6:7], off
	.p2align	3
	s_waitcnt vmcnt(8)
	s_waitcnt lgkmcnt(0)
	s_setprio 1
	s_barrier
	v_mfma_f32_16x16x32_bf16 v[64:67], v[132:135], v[188:191], v[64:67]
	v_mfma_f32_16x16x32_bf16 v[60:63], v[140:143], v[188:191], v[60:63]
	v_mfma_f32_16x16x32_bf16 v[56:59], v[132:135], v[196:199], v[56:59]
	v_mfma_f32_16x16x32_bf16 v[52:55], v[140:143], v[196:199], v[52:55]
	v_mfma_f32_16x16x32_bf16 v[48:51], v[132:135], v[212:215], v[48:51]
	v_mfma_f32_16x16x32_bf16 v[44:47], v[140:143], v[212:215], v[44:47]
	v_mfma_f32_16x16x32_bf16 v[40:43], v[132:135], v[220:223], v[40:43]
	v_mfma_f32_16x16x32_bf16 v[36:39], v[140:143], v[220:223], v[36:39]
	v_mfma_f32_16x16x32_bf16 v[64:67], v[136:139], v[192:195], v[64:67]
	v_mfma_f32_16x16x32_bf16 v[60:63], v[144:147], v[192:195], v[60:63]
	v_mfma_f32_16x16x32_bf16 v[56:59], v[136:139], v[208:211], v[56:59]
	v_mfma_f32_16x16x32_bf16 v[52:55], v[144:147], v[208:211], v[52:55]
	v_mfma_f32_16x16x32_bf16 v[48:51], v[136:139], v[216:219], v[48:51]
	v_mfma_f32_16x16x32_bf16 v[44:47], v[144:147], v[216:219], v[44:47]
	v_mfma_f32_16x16x32_bf16 v[40:43], v[136:139], v[224:227], v[40:43]
	v_mfma_f32_16x16x32_bf16 v[36:39], v[144:147], v[224:227], v[36:39]
	v_mfma_f32_16x16x32_bf16 v[32:35], v[148:151], v[188:191], v[32:35]
	v_mfma_f32_16x16x32_bf16 v[28:31], v[156:159], v[188:191], v[28:31]
	v_mfma_f32_16x16x32_bf16 v[24:27], v[148:151], v[196:199], v[24:27]
	v_mfma_f32_16x16x32_bf16 v[20:23], v[156:159], v[196:199], v[20:23]
	v_mfma_f32_16x16x32_bf16 v[16:19], v[148:151], v[212:215], v[16:19]
	v_mfma_f32_16x16x32_bf16 v[12:15], v[156:159], v[212:215], v[12:15]
	v_mfma_f32_16x16x32_bf16 v[6:9], v[148:151], v[220:223], v[8:11]
	v_mfma_f32_16x16x32_bf16 v[2:5], v[156:159], v[220:223], v[2:5]
	v_mfma_f32_16x16x32_bf16 v[32:35], v[152:155], v[192:195], v[32:35]
	v_mfma_f32_16x16x32_bf16 v[28:31], v[184:187], v[192:195], v[28:31]
	v_mfma_f32_16x16x32_bf16 v[24:27], v[152:155], v[208:211], v[24:27]
	v_mfma_f32_16x16x32_bf16 v[20:23], v[184:187], v[208:211], v[20:23]
	v_mfma_f32_16x16x32_bf16 v[16:19], v[152:155], v[216:219], v[16:19]
	v_mfma_f32_16x16x32_bf16 v[12:15], v[184:187], v[216:219], v[12:15]
	v_mfma_f32_16x16x32_bf16 v[8:11], v[152:155], v[224:227], v[6:9]
	v_mfma_f32_16x16x32_bf16 v[4:7], v[184:187], v[224:227], v[2:5]
	s_barrier
	s_setprio 0
	s_add_u32 s37, s37, 0x100
	s_addc_u32 s49, s49, 0
	s_add_u32 vcc_lo, vcc_lo, 0x100
	s_addc_u32 vcc_hi, vcc_hi, 0
	s_cmp_ge_i32 s74, s3
	s_mov_b32 s72, s74
	s_cbranch_scc0 .LBB7_1104

.Lpeel_1196:
	s_add_i32 s72, s42, 2
	s_add_u32 s29, s16, 0xfffc0080
	s_addc_u32 s37, s17, -1
	s_add_i32 s73, 0, 0x10000
	s_cmp_eq_u32 s55, s42
	s_cselect_b32 s53, s13, s37
	s_cselect_b32 s52, s15, s29
	v_add_u32_e32 v146, s73, v153
	s_cselect_b32 s43, s28, s57
	s_cselect_b32 s42, s39, s56
	s_add_i32 s29, 0, 0x14000
	ds_read_b128 v[130:133], v146
	ds_read_b128 v[156:159], v146 offset:1024
	ds_read_b128 v[174:177], v146 offset:2048
	ds_read_b128 v[178:181], v146 offset:3072
	v_add_u32_e32 v146, s29, v153
	ds_read_b128 v[182:185], v146
	ds_read_b128 v[186:189], v146 offset:1024
	ds_read_b128 v[190:193], v146 offset:2048
	ds_read_b128 v[194:197], v146 offset:3072
	s_add_i32 m0, s5, 0xc000
	ds_read_b128 v[204:207], v161
	ds_read_b128 v[208:211], v161 offset:1024
	ds_read_b128 v[212:215], v161 offset:2048
	ds_read_b128 v[216:219], v161 offset:3072
	ds_read_b128 v[220:223], v161 offset:4096
	ds_read_b128 v[224:227], v161 offset:5120
	ds_read_b128 v[228:231], v161 offset:6144
	ds_read_b128 v[232:235], v161 offset:7168
	global_load_lds_dwordx4 v142, s[16:17]
	s_add_i32 m0, s5, 0xe000
	s_nop 0
	global_load_lds_dwordx4 v144, s[16:17]
	.p2align	3
	s_waitcnt vmcnt(8)
	s_waitcnt lgkmcnt(0)
	s_setprio 1
	s_barrier
	v_mfma_f32_16x16x32_bf16 v[126:129], v[130:133], v[204:207], 0
	v_mfma_f32_16x16x32_bf16 v[122:125], v[174:177], v[204:207], 0
	v_mfma_f32_16x16x32_bf16 v[110:113], v[130:133], v[212:215], 0
	v_mfma_f32_16x16x32_bf16 v[106:109], v[174:177], v[212:215], 0
	v_mfma_f32_16x16x32_bf16 v[94:97], v[130:133], v[220:223], 0
	v_mfma_f32_16x16x32_bf16 v[90:93], v[174:177], v[220:223], 0
	v_mfma_f32_16x16x32_bf16 v[78:81], v[130:133], v[228:231], 0
	v_mfma_f32_16x16x32_bf16 v[74:77], v[174:177], v[228:231], 0
	v_mfma_f32_16x16x32_bf16 v[126:129], v[156:159], v[208:211], v[126:129]
	v_mfma_f32_16x16x32_bf16 v[122:125], v[178:181], v[208:211], v[122:125]
	v_mfma_f32_16x16x32_bf16 v[110:113], v[156:159], v[216:219], v[110:113]
	v_mfma_f32_16x16x32_bf16 v[106:109], v[178:181], v[216:219], v[106:109]
	v_mfma_f32_16x16x32_bf16 v[94:97], v[156:159], v[224:227], v[94:97]
	v_mfma_f32_16x16x32_bf16 v[90:93], v[178:181], v[224:227], v[90:93]
	v_mfma_f32_16x16x32_bf16 v[78:81], v[156:159], v[232:235], v[78:81]
	v_mfma_f32_16x16x32_bf16 v[74:77], v[178:181], v[232:235], v[74:77]
	v_mfma_f32_16x16x32_bf16 v[118:121], v[182:185], v[204:207], 0
	v_mfma_f32_16x16x32_bf16 v[114:117], v[190:193], v[204:207], 0
	v_mfma_f32_16x16x32_bf16 v[102:105], v[182:185], v[212:215], 0
	v_mfma_f32_16x16x32_bf16 v[98:101], v[190:193], v[212:215], 0
	v_mfma_f32_16x16x32_bf16 v[86:89], v[182:185], v[220:223], 0
	v_mfma_f32_16x16x32_bf16 v[82:85], v[190:193], v[220:223], 0
	v_mfma_f32_16x16x32_bf16 v[70:73], v[182:185], v[228:231], 0
	v_mfma_f32_16x16x32_bf16 v[66:69], v[190:193], v[228:231], 0
	v_mfma_f32_16x16x32_bf16 v[118:121], v[186:189], v[208:211], v[118:121]
	v_mfma_f32_16x16x32_bf16 v[114:117], v[194:197], v[208:211], v[114:117]
	v_mfma_f32_16x16x32_bf16 v[102:105], v[186:189], v[216:219], v[102:105]
	v_mfma_f32_16x16x32_bf16 v[98:101], v[194:197], v[216:219], v[98:101]
	v_mfma_f32_16x16x32_bf16 v[86:89], v[186:189], v[224:227], v[86:89]
	v_mfma_f32_16x16x32_bf16 v[82:85], v[194:197], v[224:227], v[82:85]
	v_mfma_f32_16x16x32_bf16 v[70:73], v[186:189], v[232:235], v[70:73]
	v_mfma_f32_16x16x32_bf16 v[66:69], v[194:197], v[232:235], v[66:69]
	s_barrier
	s_setprio 0
	s_add_i32 s37, s73, s4
	v_lshl_add_u64 v[146:147], s[42:43], 0, v[0:1]
	s_mov_b32 m0, s37
	ds_read_b128 v[204:207], v161 offset:16384
	ds_read_b128 v[208:211], v161 offset:17408
	ds_read_b128 v[212:215], v161 offset:18432
	ds_read_b128 v[216:219], v161 offset:19456
	ds_read_b128 v[220:223], v161 offset:20480
	ds_read_b128 v[224:227], v161 offset:21504
	ds_read_b128 v[228:231], v161 offset:22528
	ds_read_b128 v[232:235], v161 offset:23552
	global_load_lds_dwordx4 v[146:147], off
	s_add_i32 m0, s37, 0x2000
	s_add_u32 s74, s42, 0x40000
	v_lshl_add_u64 v[150:151], s[42:43], 0, v[134:135]
	s_addc_u32 s75, s43, 0
	s_add_i32 s29, s29, s4
	global_load_lds_dwordx4 v[150:151], off
	s_mov_b32 m0, s29
	v_lshl_add_u64 v[172:173], s[52:53], 0, v[136:137]
	global_load_lds_dwordx4 v0, s[74:75]
	s_add_i32 m0, s29, 0x2000
	s_nop 0
	global_load_lds_dwordx4 v134, s[74:75]
	v_lshl_add_u64 v[170:171], s[52:53], 0, v[138:139]
	s_mov_b32 m0, s5
	s_nop 0
	global_load_lds_dwordx4 v[170:171], off
	s_mov_b32 m0, s20
	s_nop 0
	global_load_lds_dwordx4 v[172:173], off
	s_lshl_b32 s101, s10, 14
	s_add_i32 s101, s101, s5
	s_add_u32 s100, s66, s101
	s_addc_u32 s101, s67, 0
	v_lshlrev_b32_e32 v2, 4, v163
	v_add_u32_e32 v3, 0x2000, v2
	s_add_i32 m0, s5, 0x20000
	s_nop 0
	global_load_lds_dwordx4 v2, s[100:101]
	s_add_i32 m0, s5, 0x22000
	s_nop 0
	global_load_lds_dwordx4 v3, s[100:101]
	.p2align	3
	s_waitcnt vmcnt(8)
	s_waitcnt lgkmcnt(0)
	s_setprio 1
	s_barrier
	v_mfma_f32_16x16x32_bf16 v[62:65], v[130:133], v[204:207], 0
	v_mfma_f32_16x16x32_bf16 v[58:61], v[174:177], v[204:207], 0
	v_mfma_f32_16x16x32_bf16 v[46:49], v[130:133], v[212:215], 0
	v_mfma_f32_16x16x32_bf16 v[42:45], v[174:177], v[212:215], 0
	v_mfma_f32_16x16x32_bf16 v[30:33], v[130:133], v[220:223], 0
	v_mfma_f32_16x16x32_bf16 v[26:29], v[174:177], v[220:223], 0
	v_mfma_f32_16x16x32_bf16 v[14:17], v[130:133], v[228:231], 0
	v_mfma_f32_16x16x32_bf16 v[10:13], v[174:177], v[228:231], 0
	v_mfma_f32_16x16x32_bf16 v[62:65], v[156:159], v[208:211], v[62:65]
	v_mfma_f32_16x16x32_bf16 v[58:61], v[178:181], v[208:211], v[58:61]
	v_mfma_f32_16x16x32_bf16 v[46:49], v[156:159], v[216:219], v[46:49]
	v_mfma_f32_16x16x32_bf16 v[42:45], v[178:181], v[216:219], v[42:45]
	v_mfma_f32_16x16x32_bf16 v[30:33], v[156:159], v[224:227], v[30:33]
	v_mfma_f32_16x16x32_bf16 v[26:29], v[178:181], v[224:227], v[26:29]
	v_mfma_f32_16x16x32_bf16 v[14:17], v[156:159], v[232:235], v[14:17]
	v_mfma_f32_16x16x32_bf16 v[10:13], v[178:181], v[232:235], v[10:13]
	v_mfma_f32_16x16x32_bf16 v[54:57], v[182:185], v[204:207], 0
	v_mfma_f32_16x16x32_bf16 v[50:53], v[190:193], v[204:207], 0
	v_mfma_f32_16x16x32_bf16 v[38:41], v[182:185], v[212:215], 0
	v_mfma_f32_16x16x32_bf16 v[34:37], v[190:193], v[212:215], 0
	v_mfma_f32_16x16x32_bf16 v[22:25], v[182:185], v[220:223], 0
	v_mfma_f32_16x16x32_bf16 v[18:21], v[190:193], v[220:223], 0
	v_mfma_f32_16x16x32_bf16 v[6:9], v[182:185], v[228:231], 0
	v_mfma_f32_16x16x32_bf16 v[2:5], v[190:193], v[228:231], 0
	v_mfma_f32_16x16x32_bf16 v[54:57], v[186:189], v[208:211], v[54:57]
	v_mfma_f32_16x16x32_bf16 v[50:53], v[194:197], v[208:211], v[50:53]
	v_mfma_f32_16x16x32_bf16 v[38:41], v[186:189], v[216:219], v[38:41]
	v_mfma_f32_16x16x32_bf16 v[34:37], v[194:197], v[216:219], v[34:37]
	v_mfma_f32_16x16x32_bf16 v[22:25], v[186:189], v[224:227], v[22:25]
	v_mfma_f32_16x16x32_bf16 v[18:21], v[194:197], v[224:227], v[18:21]
	v_mfma_f32_16x16x32_bf16 v[6:9], v[186:189], v[232:235], v[6:9]
	v_mfma_f32_16x16x32_bf16 v[2:5], v[194:197], v[232:235], v[2:5]
	s_barrier
	s_setprio 0
	s_add_i32 s29, 0, 0x18000
	v_add_u32_e32 v148, s29, v153
	s_add_i32 s37, 0, 0x1c000
	ds_read_b128 v[130:133], v148
	ds_read_b128 v[156:159], v148 offset:1024
	ds_read_b128 v[174:177], v148 offset:2048
	ds_read_b128 v[178:181], v148 offset:3072
	v_add_u32_e32 v148, s37, v153
	ds_read_b128 v[182:185], v148
	ds_read_b128 v[186:189], v148 offset:1024
	ds_read_b128 v[190:193], v148 offset:2048
	ds_read_b128 v[194:197], v148 offset:3072
	s_add_u32 s52, s52, 0x40000
	s_addc_u32 s53, s53, 0
	s_mov_b32 m0, s22
	ds_read_b128 v[204:207], v161 offset:32768
	ds_read_b128 v[208:211], v161 offset:33792
	ds_read_b128 v[212:215], v161 offset:34816
	ds_read_b128 v[216:219], v161 offset:35840
	ds_read_b128 v[220:223], v161 offset:36864
	ds_read_b128 v[224:227], v161 offset:37888
	ds_read_b128 v[228:231], v161 offset:38912
	ds_read_b128 v[232:235], v161 offset:39936
	global_load_lds_dwordx4 v138, s[52:53]
	s_mov_b32 m0, s23
	s_nop 0
	global_load_lds_dwordx4 v136, s[52:53]
	.p2align	3
	s_waitcnt vmcnt(8)
	s_waitcnt lgkmcnt(0)
	s_setprio 1
	s_barrier
	v_mfma_f32_16x16x32_bf16 v[126:129], v[130:133], v[204:207], v[126:129]
	v_mfma_f32_16x16x32_bf16 v[122:125], v[174:177], v[204:207], v[122:125]
	v_mfma_f32_16x16x32_bf16 v[110:113], v[130:133], v[212:215], v[110:113]
	v_mfma_f32_16x16x32_bf16 v[106:109], v[174:177], v[212:215], v[106:109]
	v_mfma_f32_16x16x32_bf16 v[94:97], v[130:133], v[220:223], v[94:97]
	v_mfma_f32_16x16x32_bf16 v[90:93], v[174:177], v[220:223], v[90:93]
	v_mfma_f32_16x16x32_bf16 v[78:81], v[130:133], v[228:231], v[78:81]
	v_mfma_f32_16x16x32_bf16 v[74:77], v[174:177], v[228:231], v[74:77]
	v_mfma_f32_16x16x32_bf16 v[126:129], v[156:159], v[208:211], v[126:129]
	v_mfma_f32_16x16x32_bf16 v[122:125], v[178:181], v[208:211], v[122:125]
	v_mfma_f32_16x16x32_bf16 v[110:113], v[156:159], v[216:219], v[110:113]
	v_mfma_f32_16x16x32_bf16 v[106:109], v[178:181], v[216:219], v[106:109]
	v_mfma_f32_16x16x32_bf16 v[94:97], v[156:159], v[224:227], v[94:97]
	v_mfma_f32_16x16x32_bf16 v[90:93], v[178:181], v[224:227], v[90:93]
	v_mfma_f32_16x16x32_bf16 v[78:81], v[156:159], v[232:235], v[78:81]
	v_mfma_f32_16x16x32_bf16 v[74:77], v[178:181], v[232:235], v[74:77]
	v_mfma_f32_16x16x32_bf16 v[118:121], v[182:185], v[204:207], v[118:121]
	v_mfma_f32_16x16x32_bf16 v[114:117], v[190:193], v[204:207], v[114:117]
	v_mfma_f32_16x16x32_bf16 v[102:105], v[182:185], v[212:215], v[102:105]
	v_mfma_f32_16x16x32_bf16 v[98:101], v[190:193], v[212:215], v[98:101]
	v_mfma_f32_16x16x32_bf16 v[86:89], v[182:185], v[220:223], v[86:89]
	v_mfma_f32_16x16x32_bf16 v[82:85], v[190:193], v[220:223], v[82:85]
	v_mfma_f32_16x16x32_bf16 v[70:73], v[182:185], v[228:231], v[70:73]
	v_mfma_f32_16x16x32_bf16 v[66:69], v[190:193], v[228:231], v[66:69]
	v_mfma_f32_16x16x32_bf16 v[118:121], v[186:189], v[208:211], v[118:121]
	v_mfma_f32_16x16x32_bf16 v[114:117], v[194:197], v[208:211], v[114:117]
	v_mfma_f32_16x16x32_bf16 v[102:105], v[186:189], v[216:219], v[102:105]
	v_mfma_f32_16x16x32_bf16 v[98:101], v[194:197], v[216:219], v[98:101]
	v_mfma_f32_16x16x32_bf16 v[86:89], v[186:189], v[224:227], v[86:89]
	v_mfma_f32_16x16x32_bf16 v[82:85], v[194:197], v[224:227], v[82:85]
	v_mfma_f32_16x16x32_bf16 v[70:73], v[186:189], v[232:235], v[70:73]
	v_mfma_f32_16x16x32_bf16 v[66:69], v[194:197], v[232:235], v[66:69]
	s_barrier
	s_setprio 0
	s_add_i32 s29, s29, s4
	v_lshl_add_u64 v[146:147], v[146:147], 0, s[24:25]
	s_mov_b32 m0, s29
	ds_read_b128 v[204:207], v161 offset:49152
	ds_read_b128 v[208:211], v161 offset:50176
	ds_read_b128 v[212:215], v161 offset:51200
	ds_read_b128 v[216:219], v161 offset:52224
	ds_read_b128 v[220:223], v161 offset:53248
	ds_read_b128 v[224:227], v161 offset:54272
	ds_read_b128 v[228:231], v161 offset:55296
	ds_read_b128 v[232:235], v161 offset:56320
	global_load_lds_dwordx4 v[146:147], off
	s_add_i32 m0, s29, 0x2000
	s_add_u32 s42, s42, 0x40080
	v_lshl_add_u64 v[146:147], v[150:151], 0, s[24:25]
	s_addc_u32 s43, s43, 0
	s_add_i32 s29, s37, s4
	global_load_lds_dwordx4 v[146:147], off
	s_mov_b32 m0, s29
	s_nop 0
	global_load_lds_dwordx4 v0, s[42:43]
	s_add_i32 m0, s29, 0x2000
	s_nop 0
	global_load_lds_dwordx4 v134, s[42:43]
	v_lshl_add_u64 v[146:147], v[170:171], 0, s[24:25]
	s_mov_b32 m0, s31
	s_nop 0
	global_load_lds_dwordx4 v[146:147], off
	v_lshl_add_u64 v[146:147], v[172:173], 0, s[24:25]
	s_mov_b32 m0, s33
	s_nop 0
	global_load_lds_dwordx4 v[146:147], off
	.p2align	3
	s_waitcnt vmcnt(8)
	s_waitcnt lgkmcnt(0)
	s_setprio 1
	s_barrier
	v_mfma_f32_16x16x32_bf16 v[62:65], v[130:133], v[204:207], v[62:65]
	v_mfma_f32_16x16x32_bf16 v[58:61], v[174:177], v[204:207], v[58:61]
	v_mfma_f32_16x16x32_bf16 v[46:49], v[130:133], v[212:215], v[46:49]
	v_mfma_f32_16x16x32_bf16 v[42:45], v[174:177], v[212:215], v[42:45]
	v_mfma_f32_16x16x32_bf16 v[30:33], v[130:133], v[220:223], v[30:33]
	v_mfma_f32_16x16x32_bf16 v[26:29], v[174:177], v[220:223], v[26:29]
	v_mfma_f32_16x16x32_bf16 v[14:17], v[130:133], v[228:231], v[14:17]
	v_mfma_f32_16x16x32_bf16 v[10:13], v[174:177], v[228:231], v[10:13]
	v_mfma_f32_16x16x32_bf16 v[62:65], v[156:159], v[208:211], v[62:65]
	v_mfma_f32_16x16x32_bf16 v[58:61], v[178:181], v[208:211], v[58:61]
	v_mfma_f32_16x16x32_bf16 v[46:49], v[156:159], v[216:219], v[46:49]
	v_mfma_f32_16x16x32_bf16 v[42:45], v[178:181], v[216:219], v[42:45]
	v_mfma_f32_16x16x32_bf16 v[30:33], v[156:159], v[224:227], v[30:33]
	v_mfma_f32_16x16x32_bf16 v[26:29], v[178:181], v[224:227], v[26:29]
	v_mfma_f32_16x16x32_bf16 v[14:17], v[156:159], v[232:235], v[14:17]
	v_mfma_f32_16x16x32_bf16 v[10:13], v[178:181], v[232:235], v[10:13]
	v_mfma_f32_16x16x32_bf16 v[54:57], v[182:185], v[204:207], v[54:57]
	v_mfma_f32_16x16x32_bf16 v[50:53], v[190:193], v[204:207], v[50:53]
	v_mfma_f32_16x16x32_bf16 v[38:41], v[182:185], v[212:215], v[38:41]
	v_mfma_f32_16x16x32_bf16 v[34:37], v[190:193], v[212:215], v[34:37]
	v_mfma_f32_16x16x32_bf16 v[22:25], v[182:185], v[220:223], v[22:25]
	v_mfma_f32_16x16x32_bf16 v[18:21], v[190:193], v[220:223], v[18:21]
	v_mfma_f32_16x16x32_bf16 v[6:9], v[182:185], v[228:231], v[6:9]
	v_mfma_f32_16x16x32_bf16 v[2:5], v[190:193], v[228:231], v[2:5]
	v_mfma_f32_16x16x32_bf16 v[54:57], v[186:189], v[208:211], v[54:57]
	v_mfma_f32_16x16x32_bf16 v[50:53], v[194:197], v[208:211], v[50:53]
	v_mfma_f32_16x16x32_bf16 v[38:41], v[186:189], v[216:219], v[38:41]
	v_mfma_f32_16x16x32_bf16 v[34:37], v[194:197], v[216:219], v[34:37]
	v_mfma_f32_16x16x32_bf16 v[22:25], v[186:189], v[224:227], v[22:25]
	v_mfma_f32_16x16x32_bf16 v[18:21], v[194:197], v[224:227], v[18:21]
	v_mfma_f32_16x16x32_bf16 v[6:9], v[186:189], v[232:235], v[6:9]
	v_mfma_f32_16x16x32_bf16 v[2:5], v[194:197], v[232:235], v[2:5]
	s_barrier
	s_setprio 0
	s_add_u32 s16, s16, 0x100
	s_addc_u32 s17, s17, 0
	s_add_u32 s56, s56, 0x100
	s_addc_u32 s57, s57, 0
	s_cmp_ge_i32 s72, s3
	s_mov_b32 s42, s72
	s_cbranch_scc0 .LBB7_1196
	s_branch .Lpeelx_1196
	.p2align	6
.LBB7_1196:
	s_add_i32 s72, s42, 2
	s_add_u32 s29, s16, 0xfffc0080
	s_addc_u32 s37, s17, -1
	s_add_i32 s73, 0, 0x10000
	s_cmp_eq_u32 s55, s42
	s_cselect_b32 s53, s13, s37
	s_cselect_b32 s52, s15, s29
	v_add_u32_e32 v146, s73, v153
	s_cselect_b32 s43, s28, s57
	s_cselect_b32 s42, s39, s56
	s_add_i32 s29, 0, 0x14000
	ds_read_b128 v[130:133], v146
	ds_read_b128 v[156:159], v146 offset:1024
	ds_read_b128 v[174:177], v146 offset:2048
	ds_read_b128 v[178:181], v146 offset:3072
	v_add_u32_e32 v146, s29, v153
	ds_read_b128 v[182:185], v146
	ds_read_b128 v[186:189], v146 offset:1024
	ds_read_b128 v[190:193], v146 offset:2048
	ds_read_b128 v[194:197], v146 offset:3072
	s_add_i32 m0, s5, 0xc000
	ds_read_b128 v[204:207], v161
	ds_read_b128 v[208:211], v161 offset:1024
	ds_read_b128 v[212:215], v161 offset:2048
	ds_read_b128 v[216:219], v161 offset:3072
	ds_read_b128 v[220:223], v161 offset:4096
	ds_read_b128 v[224:227], v161 offset:5120
	ds_read_b128 v[228:231], v161 offset:6144
	ds_read_b128 v[232:235], v161 offset:7168
	global_load_lds_dwordx4 v142, s[16:17]
	s_add_i32 m0, s5, 0xe000
	s_nop 0
	global_load_lds_dwordx4 v144, s[16:17]
	.p2align	3
	s_waitcnt vmcnt(8)
	s_waitcnt lgkmcnt(0)
	s_setprio 1
	s_barrier
	v_mfma_f32_16x16x32_bf16 v[126:129], v[130:133], v[204:207], v[126:129]
	v_mfma_f32_16x16x32_bf16 v[122:125], v[174:177], v[204:207], v[122:125]
	v_mfma_f32_16x16x32_bf16 v[110:113], v[130:133], v[212:215], v[110:113]
	v_mfma_f32_16x16x32_bf16 v[106:109], v[174:177], v[212:215], v[106:109]
	v_mfma_f32_16x16x32_bf16 v[94:97], v[130:133], v[220:223], v[94:97]
	v_mfma_f32_16x16x32_bf16 v[90:93], v[174:177], v[220:223], v[90:93]
	v_mfma_f32_16x16x32_bf16 v[78:81], v[130:133], v[228:231], v[78:81]
	v_mfma_f32_16x16x32_bf16 v[74:77], v[174:177], v[228:231], v[74:77]
	v_mfma_f32_16x16x32_bf16 v[126:129], v[156:159], v[208:211], v[126:129]
	v_mfma_f32_16x16x32_bf16 v[122:125], v[178:181], v[208:211], v[122:125]
	v_mfma_f32_16x16x32_bf16 v[110:113], v[156:159], v[216:219], v[110:113]
	v_mfma_f32_16x16x32_bf16 v[106:109], v[178:181], v[216:219], v[106:109]
	v_mfma_f32_16x16x32_bf16 v[94:97], v[156:159], v[224:227], v[94:97]
	v_mfma_f32_16x16x32_bf16 v[90:93], v[178:181], v[224:227], v[90:93]
	v_mfma_f32_16x16x32_bf16 v[78:81], v[156:159], v[232:235], v[78:81]
	v_mfma_f32_16x16x32_bf16 v[74:77], v[178:181], v[232:235], v[74:77]
	v_mfma_f32_16x16x32_bf16 v[118:121], v[182:185], v[204:207], v[118:121]
	v_mfma_f32_16x16x32_bf16 v[114:117], v[190:193], v[204:207], v[114:117]
	v_mfma_f32_16x16x32_bf16 v[102:105], v[182:185], v[212:215], v[102:105]
	v_mfma_f32_16x16x32_bf16 v[98:101], v[190:193], v[212:215], v[98:101]
	v_mfma_f32_16x16x32_bf16 v[86:89], v[182:185], v[220:223], v[86:89]
	v_mfma_f32_16x16x32_bf16 v[82:85], v[190:193], v[220:223], v[82:85]
	v_mfma_f32_16x16x32_bf16 v[70:73], v[182:185], v[228:231], v[70:73]
	v_mfma_f32_16x16x32_bf16 v[66:69], v[190:193], v[228:231], v[66:69]
	v_mfma_f32_16x16x32_bf16 v[118:121], v[186:189], v[208:211], v[118:121]
	v_mfma_f32_16x16x32_bf16 v[114:117], v[194:197], v[208:211], v[114:117]
	v_mfma_f32_16x16x32_bf16 v[102:105], v[186:189], v[216:219], v[102:105]
	v_mfma_f32_16x16x32_bf16 v[98:101], v[194:197], v[216:219], v[98:101]
	v_mfma_f32_16x16x32_bf16 v[86:89], v[186:189], v[224:227], v[86:89]
	v_mfma_f32_16x16x32_bf16 v[82:85], v[194:197], v[224:227], v[82:85]
	v_mfma_f32_16x16x32_bf16 v[70:73], v[186:189], v[232:235], v[70:73]
	v_mfma_f32_16x16x32_bf16 v[66:69], v[194:197], v[232:235], v[66:69]
	s_barrier
	s_setprio 0
	s_add_i32 s37, s73, s4
	v_lshl_add_u64 v[146:147], s[42:43], 0, v[0:1]
	s_mov_b32 m0, s37
	ds_read_b128 v[204:207], v161 offset:16384
	ds_read_b128 v[208:211], v161 offset:17408
	ds_read_b128 v[212:215], v161 offset:18432
	ds_read_b128 v[216:219], v161 offset:19456
	ds_read_b128 v[220:223], v161 offset:20480
	ds_read_b128 v[224:227], v161 offset:21504
	ds_read_b128 v[228:231], v161 offset:22528
	ds_read_b128 v[232:235], v161 offset:23552
	global_load_lds_dwordx4 v[146:147], off
	s_add_i32 m0, s37, 0x2000
	s_add_u32 s74, s42, 0x40000
	v_lshl_add_u64 v[150:151], s[42:43], 0, v[134:135]
	s_addc_u32 s75, s43, 0
	s_add_i32 s29, s29, s4
	global_load_lds_dwordx4 v[150:151], off
	s_mov_b32 m0, s29
	v_lshl_add_u64 v[172:173], s[52:53], 0, v[136:137]
	global_load_lds_dwordx4 v0, s[74:75]
	s_add_i32 m0, s29, 0x2000
	s_nop 0
	global_load_lds_dwordx4 v134, s[74:75]
	v_lshl_add_u64 v[170:171], s[52:53], 0, v[138:139]
	s_mov_b32 m0, s5
	s_nop 0
	global_load_lds_dwordx4 v[170:171], off
	s_mov_b32 m0, s20
	s_nop 0
	global_load_lds_dwordx4 v[172:173], off
	.p2align	3
	s_waitcnt vmcnt(8)
	s_waitcnt lgkmcnt(0)
	s_setprio 1
	s_barrier
	v_mfma_f32_16x16x32_bf16 v[62:65], v[130:133], v[204:207], v[62:65]
	v_mfma_f32_16x16x32_bf16 v[58:61], v[174:177], v[204:207], v[58:61]
	v_mfma_f32_16x16x32_bf16 v[46:49], v[130:133], v[212:215], v[46:49]
	v_mfma_f32_16x16x32_bf16 v[42:45], v[174:177], v[212:215], v[42:45]
	v_mfma_f32_16x16x32_bf16 v[30:33], v[130:133], v[220:223], v[30:33]
	v_mfma_f32_16x16x32_bf16 v[26:29], v[174:177], v[220:223], v[26:29]
	v_mfma_f32_16x16x32_bf16 v[14:17], v[130:133], v[228:231], v[14:17]
	v_mfma_f32_16x16x32_bf16 v[10:13], v[174:177], v[228:231], v[10:13]
	v_mfma_f32_16x16x32_bf16 v[62:65], v[156:159], v[208:211], v[62:65]
	v_mfma_f32_16x16x32_bf16 v[58:61], v[178:181], v[208:211], v[58:61]
	v_mfma_f32_16x16x32_bf16 v[46:49], v[156:159], v[216:219], v[46:49]
	v_mfma_f32_16x16x32_bf16 v[42:45], v[178:181], v[216:219], v[42:45]
	v_mfma_f32_16x16x32_bf16 v[30:33], v[156:159], v[224:227], v[30:33]
	v_mfma_f32_16x16x32_bf16 v[26:29], v[178:181], v[224:227], v[26:29]
	v_mfma_f32_16x16x32_bf16 v[14:17], v[156:159], v[232:235], v[14:17]
	v_mfma_f32_16x16x32_bf16 v[10:13], v[178:181], v[232:235], v[10:13]
	v_mfma_f32_16x16x32_bf16 v[54:57], v[182:185], v[204:207], v[54:57]
	v_mfma_f32_16x16x32_bf16 v[50:53], v[190:193], v[204:207], v[50:53]
	v_mfma_f32_16x16x32_bf16 v[38:41], v[182:185], v[212:215], v[38:41]
	v_mfma_f32_16x16x32_bf16 v[34:37], v[190:193], v[212:215], v[34:37]
	v_mfma_f32_16x16x32_bf16 v[22:25], v[182:185], v[220:223], v[22:25]
	v_mfma_f32_16x16x32_bf16 v[18:21], v[190:193], v[220:223], v[18:21]
	v_mfma_f32_16x16x32_bf16 v[6:9], v[182:185], v[228:231], v[6:9]
	v_mfma_f32_16x16x32_bf16 v[2:5], v[190:193], v[228:231], v[2:5]
	v_mfma_f32_16x16x32_bf16 v[54:57], v[186:189], v[208:211], v[54:57]
	v_mfma_f32_16x16x32_bf16 v[50:53], v[194:197], v[208:211], v[50:53]
	v_mfma_f32_16x16x32_bf16 v[38:41], v[186:189], v[216:219], v[38:41]
	v_mfma_f32_16x16x32_bf16 v[34:37], v[194:197], v[216:219], v[34:37]
	v_mfma_f32_16x16x32_bf16 v[22:25], v[186:189], v[224:227], v[22:25]
	v_mfma_f32_16x16x32_bf16 v[18:21], v[194:197], v[224:227], v[18:21]
	v_mfma_f32_16x16x32_bf16 v[6:9], v[186:189], v[232:235], v[6:9]
	v_mfma_f32_16x16x32_bf16 v[2:5], v[194:197], v[232:235], v[2:5]
	s_barrier
	s_setprio 0
	s_add_i32 s29, 0, 0x18000
	v_add_u32_e32 v148, s29, v153
	s_add_i32 s37, 0, 0x1c000
	ds_read_b128 v[130:133], v148
	ds_read_b128 v[156:159], v148 offset:1024
	ds_read_b128 v[174:177], v148 offset:2048
	ds_read_b128 v[178:181], v148 offset:3072
	v_add_u32_e32 v148, s37, v153
	ds_read_b128 v[182:185], v148
	ds_read_b128 v[186:189], v148 offset:1024
	ds_read_b128 v[190:193], v148 offset:2048
	ds_read_b128 v[194:197], v148 offset:3072
	s_add_u32 s52, s52, 0x40000
	s_addc_u32 s53, s53, 0
	s_mov_b32 m0, s22
	ds_read_b128 v[204:207], v161 offset:32768
	ds_read_b128 v[208:211], v161 offset:33792
	ds_read_b128 v[212:215], v161 offset:34816
	ds_read_b128 v[216:219], v161 offset:35840
	ds_read_b128 v[220:223], v161 offset:36864
	ds_read_b128 v[224:227], v161 offset:37888
	ds_read_b128 v[228:231], v161 offset:38912
	ds_read_b128 v[232:235], v161 offset:39936
	global_load_lds_dwordx4 v138, s[52:53]
	s_mov_b32 m0, s23
	s_nop 0
	global_load_lds_dwordx4 v136, s[52:53]
	.p2align	3
	s_waitcnt vmcnt(8)
	s_waitcnt lgkmcnt(0)
	s_setprio 1
	s_barrier
	v_mfma_f32_16x16x32_bf16 v[126:129], v[130:133], v[204:207], v[126:129]
	v_mfma_f32_16x16x32_bf16 v[122:125], v[174:177], v[204:207], v[122:125]
	v_mfma_f32_16x16x32_bf16 v[110:113], v[130:133], v[212:215], v[110:113]
	v_mfma_f32_16x16x32_bf16 v[106:109], v[174:177], v[212:215], v[106:109]
	v_mfma_f32_16x16x32_bf16 v[94:97], v[130:133], v[220:223], v[94:97]
	v_mfma_f32_16x16x32_bf16 v[90:93], v[174:177], v[220:223], v[90:93]
	v_mfma_f32_16x16x32_bf16 v[78:81], v[130:133], v[228:231], v[78:81]
	v_mfma_f32_16x16x32_bf16 v[74:77], v[174:177], v[228:231], v[74:77]
	v_mfma_f32_16x16x32_bf16 v[126:129], v[156:159], v[208:211], v[126:129]
	v_mfma_f32_16x16x32_bf16 v[122:125], v[178:181], v[208:211], v[122:125]
	v_mfma_f32_16x16x32_bf16 v[110:113], v[156:159], v[216:219], v[110:113]
	v_mfma_f32_16x16x32_bf16 v[106:109], v[178:181], v[216:219], v[106:109]
	v_mfma_f32_16x16x32_bf16 v[94:97], v[156:159], v[224:227], v[94:97]
	v_mfma_f32_16x16x32_bf16 v[90:93], v[178:181], v[224:227], v[90:93]
	v_mfma_f32_16x16x32_bf16 v[78:81], v[156:159], v[232:235], v[78:81]
	v_mfma_f32_16x16x32_bf16 v[74:77], v[178:181], v[232:235], v[74:77]
	v_mfma_f32_16x16x32_bf16 v[118:121], v[182:185], v[204:207], v[118:121]
	v_mfma_f32_16x16x32_bf16 v[114:117], v[190:193], v[204:207], v[114:117]
	v_mfma_f32_16x16x32_bf16 v[102:105], v[182:185], v[212:215], v[102:105]
	v_mfma_f32_16x16x32_bf16 v[98:101], v[190:193], v[212:215], v[98:101]
	v_mfma_f32_16x16x32_bf16 v[86:89], v[182:185], v[220:223], v[86:89]
	v_mfma_f32_16x16x32_bf16 v[82:85], v[190:193], v[220:223], v[82:85]
	v_mfma_f32_16x16x32_bf16 v[70:73], v[182:185], v[228:231], v[70:73]
	v_mfma_f32_16x16x32_bf16 v[66:69], v[190:193], v[228:231], v[66:69]
	v_mfma_f32_16x16x32_bf16 v[118:121], v[186:189], v[208:211], v[118:121]
	v_mfma_f32_16x16x32_bf16 v[114:117], v[194:197], v[208:211], v[114:117]
	v_mfma_f32_16x16x32_bf16 v[102:105], v[186:189], v[216:219], v[102:105]
	v_mfma_f32_16x16x32_bf16 v[98:101], v[194:197], v[216:219], v[98:101]
	v_mfma_f32_16x16x32_bf16 v[86:89], v[186:189], v[224:227], v[86:89]
	v_mfma_f32_16x16x32_bf16 v[82:85], v[194:197], v[224:227], v[82:85]
	v_mfma_f32_16x16x32_bf16 v[70:73], v[186:189], v[232:235], v[70:73]
	v_mfma_f32_16x16x32_bf16 v[66:69], v[194:197], v[232:235], v[66:69]
	s_barrier
	s_setprio 0
	s_add_i32 s29, s29, s4
	v_lshl_add_u64 v[146:147], v[146:147], 0, s[24:25]
	s_mov_b32 m0, s29
	ds_read_b128 v[204:207], v161 offset:49152
	ds_read_b128 v[208:211], v161 offset:50176
	ds_read_b128 v[212:215], v161 offset:51200
	ds_read_b128 v[216:219], v161 offset:52224
	ds_read_b128 v[220:223], v161 offset:53248
	ds_read_b128 v[224:227], v161 offset:54272
	ds_read_b128 v[228:231], v161 offset:55296
	ds_read_b128 v[232:235], v161 offset:56320
	global_load_lds_dwordx4 v[146:147], off
	s_add_i32 m0, s29, 0x2000
	s_add_u32 s42, s42, 0x40080
	v_lshl_add_u64 v[146:147], v[150:151], 0, s[24:25]
	s_addc_u32 s43, s43, 0
	s_add_i32 s29, s37, s4
	global_load_lds_dwordx4 v[146:147], off
	s_mov_b32 m0, s29
	s_nop 0
	global_load_lds_dwordx4 v0, s[42:43]
	s_add_i32 m0, s29, 0x2000
	s_nop 0
	global_load_lds_dwordx4 v134, s[42:43]
	v_lshl_add_u64 v[146:147], v[170:171], 0, s[24:25]
	s_mov_b32 m0, s31
	s_nop 0
	global_load_lds_dwordx4 v[146:147], off
	v_lshl_add_u64 v[146:147], v[172:173], 0, s[24:25]
	s_mov_b32 m0, s33
	s_nop 0
	global_load_lds_dwordx4 v[146:147], off
	.p2align	3
	s_waitcnt vmcnt(8)
	s_waitcnt lgkmcnt(0)
	s_setprio 1
	s_barrier
	v_mfma_f32_16x16x32_bf16 v[62:65], v[130:133], v[204:207], v[62:65]
	v_mfma_f32_16x16x32_bf16 v[58:61], v[174:177], v[204:207], v[58:61]
	v_mfma_f32_16x16x32_bf16 v[46:49], v[130:133], v[212:215], v[46:49]
	v_mfma_f32_16x16x32_bf16 v[42:45], v[174:177], v[212:215], v[42:45]
	v_mfma_f32_16x16x32_bf16 v[30:33], v[130:133], v[220:223], v[30:33]
	v_mfma_f32_16x16x32_bf16 v[26:29], v[174:177], v[220:223], v[26:29]
	v_mfma_f32_16x16x32_bf16 v[14:17], v[130:133], v[228:231], v[14:17]
	v_mfma_f32_16x16x32_bf16 v[10:13], v[174:177], v[228:231], v[10:13]
	v_mfma_f32_16x16x32_bf16 v[62:65], v[156:159], v[208:211], v[62:65]
	v_mfma_f32_16x16x32_bf16 v[58:61], v[178:181], v[208:211], v[58:61]
	v_mfma_f32_16x16x32_bf16 v[46:49], v[156:159], v[216:219], v[46:49]
	v_mfma_f32_16x16x32_bf16 v[42:45], v[178:181], v[216:219], v[42:45]
	v_mfma_f32_16x16x32_bf16 v[30:33], v[156:159], v[224:227], v[30:33]
	v_mfma_f32_16x16x32_bf16 v[26:29], v[178:181], v[224:227], v[26:29]
	v_mfma_f32_16x16x32_bf16 v[14:17], v[156:159], v[232:235], v[14:17]
	v_mfma_f32_16x16x32_bf16 v[10:13], v[178:181], v[232:235], v[10:13]
	v_mfma_f32_16x16x32_bf16 v[54:57], v[182:185], v[204:207], v[54:57]
	v_mfma_f32_16x16x32_bf16 v[50:53], v[190:193], v[204:207], v[50:53]
	v_mfma_f32_16x16x32_bf16 v[38:41], v[182:185], v[212:215], v[38:41]
	v_mfma_f32_16x16x32_bf16 v[34:37], v[190:193], v[212:215], v[34:37]
	v_mfma_f32_16x16x32_bf16 v[22:25], v[182:185], v[220:223], v[22:25]
	v_mfma_f32_16x16x32_bf16 v[18:21], v[190:193], v[220:223], v[18:21]
	v_mfma_f32_16x16x32_bf16 v[6:9], v[182:185], v[228:231], v[6:9]
	v_mfma_f32_16x16x32_bf16 v[2:5], v[190:193], v[228:231], v[2:5]
	v_mfma_f32_16x16x32_bf16 v[54:57], v[186:189], v[208:211], v[54:57]
	v_mfma_f32_16x16x32_bf16 v[50:53], v[194:197], v[208:211], v[50:53]
	v_mfma_f32_16x16x32_bf16 v[38:41], v[186:189], v[216:219], v[38:41]
	v_mfma_f32_16x16x32_bf16 v[34:37], v[194:197], v[216:219], v[34:37]
	v_mfma_f32_16x16x32_bf16 v[22:25], v[186:189], v[224:227], v[22:25]
	v_mfma_f32_16x16x32_bf16 v[18:21], v[194:197], v[224:227], v[18:21]
	v_mfma_f32_16x16x32_bf16 v[6:9], v[186:189], v[232:235], v[6:9]
	v_mfma_f32_16x16x32_bf16 v[2:5], v[194:197], v[232:235], v[2:5]
	s_barrier
	s_setprio 0
	s_add_u32 s16, s16, 0x100
	s_addc_u32 s17, s17, 0
	s_add_u32 s56, s56, 0x100
	s_addc_u32 s57, s57, 0
	s_cmp_ge_i32 s72, s3
	s_mov_b32 s42, s72
	s_cbranch_scc0 .LBB7_1196

.Lpeel_1219:
	s_add_i32 s56, s52, 2
	s_add_u32 s29, s16, 0xfffc0080
	s_addc_u32 s37, s17, -1
	s_add_i32 s57, 0, 0x10000
	s_cmp_eq_u32 s84, s52
	s_cselect_b32 s55, s10, s37
	s_cselect_b32 s54, s13, s29
	s_cselect_b32 s53, s15, s39
	s_cselect_b32 s52, s28, s38
	s_add_i32 s29, 0, 0x14000
	v_add_u32_e32 v152, s57, v157
	v_add_u32_e32 v170, s29, v157
	ds_read_b128 v[140:143], v152
	ds_read_b128 v[144:147], v152 offset:1024
	ds_read_b128 v[148:151], v152 offset:2048
	ds_read_b128 v[152:155], v152 offset:3072
	ds_read_b128 v[184:187], v170
	ds_read_b128 v[188:191], v170 offset:1024
	ds_read_b128 v[192:195], v170 offset:2048
	ds_read_b128 v[196:199], v170 offset:3072
	s_add_i32 m0, s5, 0xc000
	ds_read_b128 v[204:207], v181
	ds_read_b128 v[208:211], v181 offset:1024
	ds_read_b128 v[212:215], v181 offset:2048
	ds_read_b128 v[216:219], v181 offset:3072
	ds_read_b128 v[220:223], v181 offset:4096
	ds_read_b128 v[224:227], v181 offset:5120
	ds_read_b128 v[228:231], v181 offset:6144
	ds_read_b128 v[232:235], v181 offset:7168
	global_load_lds_dwordx4 v136, s[16:17]
	s_add_i32 m0, s5, 0xe000
	s_nop 0
	global_load_lds_dwordx4 v138, s[16:17]
	.p2align	3
	s_waitcnt vmcnt(8)
	s_waitcnt lgkmcnt(0)
	s_setprio 1
	s_barrier
	v_mfma_f32_16x16x32_bf16 v[126:129], v[140:143], v[204:207], 0
	v_mfma_f32_16x16x32_bf16 v[122:125], v[148:151], v[204:207], 0
	v_mfma_f32_16x16x32_bf16 v[118:121], v[140:143], v[212:215], 0
	v_mfma_f32_16x16x32_bf16 v[114:117], v[148:151], v[212:215], 0
	v_mfma_f32_16x16x32_bf16 v[106:109], v[140:143], v[220:223], 0
	v_mfma_f32_16x16x32_bf16 v[98:101], v[148:151], v[220:223], 0
	v_mfma_f32_16x16x32_bf16 v[90:93], v[140:143], v[228:231], 0
	v_mfma_f32_16x16x32_bf16 v[82:85], v[148:151], v[228:231], 0
	v_mfma_f32_16x16x32_bf16 v[126:129], v[144:147], v[208:211], v[126:129]
	v_mfma_f32_16x16x32_bf16 v[122:125], v[152:155], v[208:211], v[122:125]
	v_mfma_f32_16x16x32_bf16 v[118:121], v[144:147], v[216:219], v[118:121]
	v_mfma_f32_16x16x32_bf16 v[114:117], v[152:155], v[216:219], v[114:117]
	v_mfma_f32_16x16x32_bf16 v[106:109], v[144:147], v[224:227], v[106:109]
	v_mfma_f32_16x16x32_bf16 v[98:101], v[152:155], v[224:227], v[98:101]
	v_mfma_f32_16x16x32_bf16 v[90:93], v[144:147], v[232:235], v[90:93]
	v_mfma_f32_16x16x32_bf16 v[82:85], v[152:155], v[232:235], v[82:85]
	v_mfma_f32_16x16x32_bf16 v[110:113], v[184:187], v[204:207], 0
	v_mfma_f32_16x16x32_bf16 v[102:105], v[192:195], v[204:207], 0
	v_mfma_f32_16x16x32_bf16 v[94:97], v[184:187], v[212:215], 0
	v_mfma_f32_16x16x32_bf16 v[86:89], v[192:195], v[212:215], 0
	v_mfma_f32_16x16x32_bf16 v[78:81], v[184:187], v[220:223], 0
	v_mfma_f32_16x16x32_bf16 v[74:77], v[192:195], v[220:223], 0
	v_mfma_f32_16x16x32_bf16 v[70:73], v[184:187], v[228:231], 0
	v_mfma_f32_16x16x32_bf16 v[66:69], v[192:195], v[228:231], 0
	v_mfma_f32_16x16x32_bf16 v[110:113], v[188:191], v[208:211], v[110:113]
	v_mfma_f32_16x16x32_bf16 v[102:105], v[196:199], v[208:211], v[102:105]
	v_mfma_f32_16x16x32_bf16 v[94:97], v[188:191], v[216:219], v[94:97]
	v_mfma_f32_16x16x32_bf16 v[86:89], v[196:199], v[216:219], v[86:89]
	v_mfma_f32_16x16x32_bf16 v[78:81], v[188:191], v[224:227], v[78:81]
	v_mfma_f32_16x16x32_bf16 v[74:77], v[196:199], v[224:227], v[74:77]
	v_mfma_f32_16x16x32_bf16 v[70:73], v[188:191], v[232:235], v[70:73]
	v_mfma_f32_16x16x32_bf16 v[66:69], v[196:199], v[232:235], v[66:69]
	s_barrier
	s_setprio 0
	s_add_i32 s37, s57, s4
	v_lshl_add_u64 v[170:171], s[52:53], 0, v[0:1]
	s_mov_b32 m0, s37
	ds_read_b128 v[204:207], v181 offset:16384
	ds_read_b128 v[208:211], v181 offset:17408
	ds_read_b128 v[212:215], v181 offset:18432
	ds_read_b128 v[216:219], v181 offset:19456
	ds_read_b128 v[220:223], v181 offset:20480
	ds_read_b128 v[224:227], v181 offset:21504
	ds_read_b128 v[228:231], v181 offset:22528
	ds_read_b128 v[232:235], v181 offset:23552
	global_load_lds_dwordx4 v[170:171], off
	s_add_i32 m0, s37, 0x2000
	s_add_u32 s74, s52, 0x40000
	v_lshl_add_u64 v[172:173], s[52:53], 0, v[130:131]
	s_addc_u32 s75, s53, 0
	s_add_i32 s29, s29, s4
	global_load_lds_dwordx4 v[172:173], off
	s_mov_b32 m0, s29
	v_lshl_add_u64 v[238:239], s[54:55], 0, v[132:133]
	global_load_lds_dwordx4 v0, s[74:75]
	s_add_i32 m0, s29, 0x2000
	s_nop 0
	global_load_lds_dwordx4 v130, s[74:75]
	v_lshl_add_u64 v[236:237], s[54:55], 0, v[134:135]
	s_mov_b32 m0, s5
	s_nop 0
	global_load_lds_dwordx4 v[236:237], off
	s_mov_b32 m0, s20
	s_nop 0
	global_load_lds_dwordx4 v[238:239], off
	.p2align	3
	s_waitcnt vmcnt(8)
	s_waitcnt lgkmcnt(0)
	s_setprio 1
	s_barrier
	v_mfma_f32_16x16x32_bf16 v[62:65], v[140:143], v[204:207], 0
	v_mfma_f32_16x16x32_bf16 v[58:61], v[148:151], v[204:207], 0
	v_mfma_f32_16x16x32_bf16 v[54:57], v[140:143], v[212:215], 0
	v_mfma_f32_16x16x32_bf16 v[50:53], v[148:151], v[212:215], 0
	v_mfma_f32_16x16x32_bf16 v[42:45], v[140:143], v[220:223], 0
	v_mfma_f32_16x16x32_bf16 v[34:37], v[148:151], v[220:223], 0
	v_mfma_f32_16x16x32_bf16 v[26:29], v[140:143], v[228:231], 0
	v_mfma_f32_16x16x32_bf16 v[18:21], v[148:151], v[228:231], 0
	v_mfma_f32_16x16x32_bf16 v[62:65], v[144:147], v[208:211], v[62:65]
	v_mfma_f32_16x16x32_bf16 v[58:61], v[152:155], v[208:211], v[58:61]
	v_mfma_f32_16x16x32_bf16 v[54:57], v[144:147], v[216:219], v[54:57]
	v_mfma_f32_16x16x32_bf16 v[50:53], v[152:155], v[216:219], v[50:53]
	v_mfma_f32_16x16x32_bf16 v[42:45], v[144:147], v[224:227], v[42:45]
	v_mfma_f32_16x16x32_bf16 v[34:37], v[152:155], v[224:227], v[34:37]
	v_mfma_f32_16x16x32_bf16 v[26:29], v[144:147], v[232:235], v[26:29]
	v_mfma_f32_16x16x32_bf16 v[18:21], v[152:155], v[232:235], v[18:21]
	v_mfma_f32_16x16x32_bf16 v[46:49], v[184:187], v[204:207], 0
	v_mfma_f32_16x16x32_bf16 v[38:41], v[192:195], v[204:207], 0
	v_mfma_f32_16x16x32_bf16 v[30:33], v[184:187], v[212:215], 0
	v_mfma_f32_16x16x32_bf16 v[22:25], v[192:195], v[212:215], 0
	v_mfma_f32_16x16x32_bf16 v[14:17], v[184:187], v[220:223], 0
	v_mfma_f32_16x16x32_bf16 v[10:13], v[192:195], v[220:223], 0
	v_mfma_f32_16x16x32_bf16 v[6:9], v[184:187], v[228:231], 0
	v_mfma_f32_16x16x32_bf16 v[2:5], v[192:195], v[228:231], 0
	v_mfma_f32_16x16x32_bf16 v[46:49], v[188:191], v[208:211], v[46:49]
	v_mfma_f32_16x16x32_bf16 v[38:41], v[196:199], v[208:211], v[38:41]
	v_mfma_f32_16x16x32_bf16 v[30:33], v[188:191], v[216:219], v[30:33]
	v_mfma_f32_16x16x32_bf16 v[22:25], v[196:199], v[216:219], v[22:25]
	v_mfma_f32_16x16x32_bf16 v[14:17], v[188:191], v[224:227], v[14:17]
	v_mfma_f32_16x16x32_bf16 v[10:13], v[196:199], v[224:227], v[10:13]
	v_mfma_f32_16x16x32_bf16 v[6:9], v[188:191], v[232:235], v[6:9]
	v_mfma_f32_16x16x32_bf16 v[2:5], v[196:199], v[232:235], v[2:5]
	s_barrier
	s_setprio 0
	s_add_i32 s29, 0, 0x18000
	s_add_i32 s37, 0, 0x1c000
	v_add_u32_e32 v152, s29, v157
	v_add_u32_e32 v183, s37, v157
	ds_read_b128 v[140:143], v152
	ds_read_b128 v[144:147], v152 offset:1024
	ds_read_b128 v[148:151], v152 offset:2048
	ds_read_b128 v[152:155], v152 offset:3072
	ds_read_b128 v[184:187], v183
	ds_read_b128 v[188:191], v183 offset:1024
	ds_read_b128 v[192:195], v183 offset:2048
	ds_read_b128 v[196:199], v183 offset:3072
	s_add_u32 s54, s54, 0x40000
	s_addc_u32 s55, s55, 0
	s_mov_b32 m0, s22
	ds_read_b128 v[204:207], v181 offset:32768
	ds_read_b128 v[208:211], v181 offset:33792
	ds_read_b128 v[212:215], v181 offset:34816
	ds_read_b128 v[216:219], v181 offset:35840
	ds_read_b128 v[220:223], v181 offset:36864
	ds_read_b128 v[224:227], v181 offset:37888
	ds_read_b128 v[228:231], v181 offset:38912
	ds_read_b128 v[232:235], v181 offset:39936
	global_load_lds_dwordx4 v134, s[54:55]
	s_mov_b32 m0, s23
	s_nop 0
	global_load_lds_dwordx4 v132, s[54:55]
	.p2align	3
	s_waitcnt vmcnt(8)
	s_waitcnt lgkmcnt(0)
	s_setprio 1
	s_barrier
	v_mfma_f32_16x16x32_bf16 v[126:129], v[140:143], v[204:207], v[126:129]
	v_mfma_f32_16x16x32_bf16 v[122:125], v[148:151], v[204:207], v[122:125]
	v_mfma_f32_16x16x32_bf16 v[118:121], v[140:143], v[212:215], v[118:121]
	v_mfma_f32_16x16x32_bf16 v[114:117], v[148:151], v[212:215], v[114:117]
	v_mfma_f32_16x16x32_bf16 v[106:109], v[140:143], v[220:223], v[106:109]
	v_mfma_f32_16x16x32_bf16 v[98:101], v[148:151], v[220:223], v[98:101]
	v_mfma_f32_16x16x32_bf16 v[90:93], v[140:143], v[228:231], v[90:93]
	v_mfma_f32_16x16x32_bf16 v[82:85], v[148:151], v[228:231], v[82:85]
	v_mfma_f32_16x16x32_bf16 v[126:129], v[144:147], v[208:211], v[126:129]
	v_mfma_f32_16x16x32_bf16 v[122:125], v[152:155], v[208:211], v[122:125]
	v_mfma_f32_16x16x32_bf16 v[118:121], v[144:147], v[216:219], v[118:121]
	v_mfma_f32_16x16x32_bf16 v[114:117], v[152:155], v[216:219], v[114:117]
	v_mfma_f32_16x16x32_bf16 v[106:109], v[144:147], v[224:227], v[106:109]
	v_mfma_f32_16x16x32_bf16 v[98:101], v[152:155], v[224:227], v[98:101]
	v_mfma_f32_16x16x32_bf16 v[90:93], v[144:147], v[232:235], v[90:93]
	v_mfma_f32_16x16x32_bf16 v[82:85], v[152:155], v[232:235], v[82:85]
	v_mfma_f32_16x16x32_bf16 v[110:113], v[184:187], v[204:207], v[110:113]
	v_mfma_f32_16x16x32_bf16 v[102:105], v[192:195], v[204:207], v[102:105]
	v_mfma_f32_16x16x32_bf16 v[94:97], v[184:187], v[212:215], v[94:97]
	v_mfma_f32_16x16x32_bf16 v[86:89], v[192:195], v[212:215], v[86:89]
	v_mfma_f32_16x16x32_bf16 v[78:81], v[184:187], v[220:223], v[78:81]
	v_mfma_f32_16x16x32_bf16 v[74:77], v[192:195], v[220:223], v[74:77]
	v_mfma_f32_16x16x32_bf16 v[70:73], v[184:187], v[228:231], v[70:73]
	v_mfma_f32_16x16x32_bf16 v[66:69], v[192:195], v[228:231], v[66:69]
	v_mfma_f32_16x16x32_bf16 v[110:113], v[188:191], v[208:211], v[110:113]
	v_mfma_f32_16x16x32_bf16 v[102:105], v[196:199], v[208:211], v[102:105]
	v_mfma_f32_16x16x32_bf16 v[94:97], v[188:191], v[216:219], v[94:97]
	v_mfma_f32_16x16x32_bf16 v[86:89], v[196:199], v[216:219], v[86:89]
	v_mfma_f32_16x16x32_bf16 v[78:81], v[188:191], v[224:227], v[78:81]
	v_mfma_f32_16x16x32_bf16 v[74:77], v[196:199], v[224:227], v[74:77]
	v_mfma_f32_16x16x32_bf16 v[70:73], v[188:191], v[232:235], v[70:73]
	v_mfma_f32_16x16x32_bf16 v[66:69], v[196:199], v[232:235], v[66:69]
	s_barrier
	s_setprio 0
	s_add_i32 s29, s29, s4
	v_lshl_add_u64 v[170:171], v[170:171], 0, s[24:25]
	s_mov_b32 m0, s29
	ds_read_b128 v[204:207], v181 offset:49152
	ds_read_b128 v[208:211], v181 offset:50176
	ds_read_b128 v[212:215], v181 offset:51200
	ds_read_b128 v[216:219], v181 offset:52224
	ds_read_b128 v[220:223], v181 offset:53248
	ds_read_b128 v[224:227], v181 offset:54272
	ds_read_b128 v[228:231], v181 offset:55296
	ds_read_b128 v[232:235], v181 offset:56320
	global_load_lds_dwordx4 v[170:171], off
	s_add_i32 m0, s29, 0x2000
	s_add_u32 s52, s52, 0x40080
	v_lshl_add_u64 v[170:171], v[172:173], 0, s[24:25]
	s_addc_u32 s53, s53, 0
	s_add_i32 s29, s37, s4
	global_load_lds_dwordx4 v[170:171], off
	s_mov_b32 m0, s29
	s_nop 0
	global_load_lds_dwordx4 v0, s[52:53]
	s_add_i32 m0, s29, 0x2000
	s_nop 0
	global_load_lds_dwordx4 v130, s[52:53]
	v_lshl_add_u64 v[170:171], v[236:237], 0, s[24:25]
	s_mov_b32 m0, s31
	s_nop 0
	global_load_lds_dwordx4 v[170:171], off
	v_lshl_add_u64 v[170:171], v[238:239], 0, s[24:25]
	s_mov_b32 m0, s33
	s_nop 0
	global_load_lds_dwordx4 v[170:171], off
	.p2align	3
	s_waitcnt vmcnt(8)
	s_waitcnt lgkmcnt(0)
	s_setprio 1
	s_barrier
	v_mfma_f32_16x16x32_bf16 v[62:65], v[140:143], v[204:207], v[62:65]
	v_mfma_f32_16x16x32_bf16 v[58:61], v[148:151], v[204:207], v[58:61]
	v_mfma_f32_16x16x32_bf16 v[54:57], v[140:143], v[212:215], v[54:57]
	v_mfma_f32_16x16x32_bf16 v[50:53], v[148:151], v[212:215], v[50:53]
	v_mfma_f32_16x16x32_bf16 v[42:45], v[140:143], v[220:223], v[42:45]
	v_mfma_f32_16x16x32_bf16 v[34:37], v[148:151], v[220:223], v[34:37]
	v_mfma_f32_16x16x32_bf16 v[26:29], v[140:143], v[228:231], v[26:29]
	v_mfma_f32_16x16x32_bf16 v[18:21], v[148:151], v[228:231], v[18:21]
	v_mfma_f32_16x16x32_bf16 v[62:65], v[144:147], v[208:211], v[62:65]
	v_mfma_f32_16x16x32_bf16 v[58:61], v[152:155], v[208:211], v[58:61]
	v_mfma_f32_16x16x32_bf16 v[54:57], v[144:147], v[216:219], v[54:57]
	v_mfma_f32_16x16x32_bf16 v[50:53], v[152:155], v[216:219], v[50:53]
	v_mfma_f32_16x16x32_bf16 v[42:45], v[144:147], v[224:227], v[42:45]
	v_mfma_f32_16x16x32_bf16 v[34:37], v[152:155], v[224:227], v[34:37]
	v_mfma_f32_16x16x32_bf16 v[26:29], v[144:147], v[232:235], v[26:29]
	v_mfma_f32_16x16x32_bf16 v[18:21], v[152:155], v[232:235], v[18:21]
	v_mfma_f32_16x16x32_bf16 v[46:49], v[184:187], v[204:207], v[46:49]
	v_mfma_f32_16x16x32_bf16 v[38:41], v[192:195], v[204:207], v[38:41]
	v_mfma_f32_16x16x32_bf16 v[30:33], v[184:187], v[212:215], v[30:33]
	v_mfma_f32_16x16x32_bf16 v[22:25], v[192:195], v[212:215], v[22:25]
	v_mfma_f32_16x16x32_bf16 v[14:17], v[184:187], v[220:223], v[14:17]
	v_mfma_f32_16x16x32_bf16 v[10:13], v[192:195], v[220:223], v[10:13]
	v_mfma_f32_16x16x32_bf16 v[6:9], v[184:187], v[228:231], v[6:9]
	v_mfma_f32_16x16x32_bf16 v[2:5], v[192:195], v[228:231], v[2:5]
	v_mfma_f32_16x16x32_bf16 v[46:49], v[188:191], v[208:211], v[46:49]
	v_mfma_f32_16x16x32_bf16 v[38:41], v[196:199], v[208:211], v[38:41]
	v_mfma_f32_16x16x32_bf16 v[30:33], v[188:191], v[216:219], v[30:33]
	v_mfma_f32_16x16x32_bf16 v[22:25], v[196:199], v[216:219], v[22:25]
	v_mfma_f32_16x16x32_bf16 v[14:17], v[188:191], v[224:227], v[14:17]
	v_mfma_f32_16x16x32_bf16 v[10:13], v[196:199], v[224:227], v[10:13]
	v_mfma_f32_16x16x32_bf16 v[6:9], v[188:191], v[232:235], v[6:9]
	v_mfma_f32_16x16x32_bf16 v[2:5], v[196:199], v[232:235], v[2:5]
	s_barrier
	s_setprio 0
	s_add_u32 s16, s16, 0x100
	s_addc_u32 s17, s17, 0
	s_add_u32 s38, s38, 0x100
	s_addc_u32 s39, s39, 0
	s_cmp_ge_i32 s56, s3
	s_mov_b32 s52, s56
	s_cbranch_scc0 .LBB7_1219
	s_branch .Lpeelx_1219
	.p2align	6
.LBB7_1219:
	s_add_i32 s56, s52, 2
	s_add_u32 s29, s16, 0xfffc0080
	s_addc_u32 s37, s17, -1
	s_add_i32 s57, 0, 0x10000
	s_cmp_eq_u32 s84, s52
	s_cselect_b32 s55, s10, s37
	s_cselect_b32 s54, s13, s29
	s_cselect_b32 s53, s15, s39
	s_cselect_b32 s52, s28, s38
	s_add_i32 s29, 0, 0x14000
	v_add_u32_e32 v152, s57, v157
	v_add_u32_e32 v170, s29, v157
	ds_read_b128 v[140:143], v152
	ds_read_b128 v[144:147], v152 offset:1024
	ds_read_b128 v[148:151], v152 offset:2048
	ds_read_b128 v[152:155], v152 offset:3072
	ds_read_b128 v[184:187], v170
	ds_read_b128 v[188:191], v170 offset:1024
	ds_read_b128 v[192:195], v170 offset:2048
	ds_read_b128 v[196:199], v170 offset:3072
	s_add_i32 m0, s5, 0xc000
	ds_read_b128 v[204:207], v181
	ds_read_b128 v[208:211], v181 offset:1024
	ds_read_b128 v[212:215], v181 offset:2048
	ds_read_b128 v[216:219], v181 offset:3072
	ds_read_b128 v[220:223], v181 offset:4096
	ds_read_b128 v[224:227], v181 offset:5120
	ds_read_b128 v[228:231], v181 offset:6144
	ds_read_b128 v[232:235], v181 offset:7168
	global_load_lds_dwordx4 v136, s[16:17]
	s_add_i32 m0, s5, 0xe000
	s_nop 0
	global_load_lds_dwordx4 v138, s[16:17]
	.p2align	3
	s_waitcnt vmcnt(8)
	s_waitcnt lgkmcnt(0)
	s_setprio 1
	s_barrier
	v_mfma_f32_16x16x32_bf16 v[126:129], v[140:143], v[204:207], v[126:129]
	v_mfma_f32_16x16x32_bf16 v[122:125], v[148:151], v[204:207], v[122:125]
	v_mfma_f32_16x16x32_bf16 v[118:121], v[140:143], v[212:215], v[118:121]
	v_mfma_f32_16x16x32_bf16 v[114:117], v[148:151], v[212:215], v[114:117]
	v_mfma_f32_16x16x32_bf16 v[106:109], v[140:143], v[220:223], v[106:109]
	v_mfma_f32_16x16x32_bf16 v[98:101], v[148:151], v[220:223], v[98:101]
	v_mfma_f32_16x16x32_bf16 v[90:93], v[140:143], v[228:231], v[90:93]
	v_mfma_f32_16x16x32_bf16 v[82:85], v[148:151], v[228:231], v[82:85]
	v_mfma_f32_16x16x32_bf16 v[126:129], v[144:147], v[208:211], v[126:129]
	v_mfma_f32_16x16x32_bf16 v[122:125], v[152:155], v[208:211], v[122:125]
	v_mfma_f32_16x16x32_bf16 v[118:121], v[144:147], v[216:219], v[118:121]
	v_mfma_f32_16x16x32_bf16 v[114:117], v[152:155], v[216:219], v[114:117]
	v_mfma_f32_16x16x32_bf16 v[106:109], v[144:147], v[224:227], v[106:109]
	v_mfma_f32_16x16x32_bf16 v[98:101], v[152:155], v[224:227], v[98:101]
	v_mfma_f32_16x16x32_bf16 v[90:93], v[144:147], v[232:235], v[90:93]
	v_mfma_f32_16x16x32_bf16 v[82:85], v[152:155], v[232:235], v[82:85]
	v_mfma_f32_16x16x32_bf16 v[110:113], v[184:187], v[204:207], v[110:113]
	v_mfma_f32_16x16x32_bf16 v[102:105], v[192:195], v[204:207], v[102:105]
	v_mfma_f32_16x16x32_bf16 v[94:97], v[184:187], v[212:215], v[94:97]
	v_mfma_f32_16x16x32_bf16 v[86:89], v[192:195], v[212:215], v[86:89]
	v_mfma_f32_16x16x32_bf16 v[78:81], v[184:187], v[220:223], v[78:81]
	v_mfma_f32_16x16x32_bf16 v[74:77], v[192:195], v[220:223], v[74:77]
	v_mfma_f32_16x16x32_bf16 v[70:73], v[184:187], v[228:231], v[70:73]
	v_mfma_f32_16x16x32_bf16 v[66:69], v[192:195], v[228:231], v[66:69]
	v_mfma_f32_16x16x32_bf16 v[110:113], v[188:191], v[208:211], v[110:113]
	v_mfma_f32_16x16x32_bf16 v[102:105], v[196:199], v[208:211], v[102:105]
	v_mfma_f32_16x16x32_bf16 v[94:97], v[188:191], v[216:219], v[94:97]
	v_mfma_f32_16x16x32_bf16 v[86:89], v[196:199], v[216:219], v[86:89]
	v_mfma_f32_16x16x32_bf16 v[78:81], v[188:191], v[224:227], v[78:81]
	v_mfma_f32_16x16x32_bf16 v[74:77], v[196:199], v[224:227], v[74:77]
	v_mfma_f32_16x16x32_bf16 v[70:73], v[188:191], v[232:235], v[70:73]
	v_mfma_f32_16x16x32_bf16 v[66:69], v[196:199], v[232:235], v[66:69]
	s_barrier
	s_setprio 0
	s_add_i32 s37, s57, s4
	v_lshl_add_u64 v[170:171], s[52:53], 0, v[0:1]
	s_mov_b32 m0, s37
	ds_read_b128 v[204:207], v181 offset:16384
	ds_read_b128 v[208:211], v181 offset:17408
	ds_read_b128 v[212:215], v181 offset:18432
	ds_read_b128 v[216:219], v181 offset:19456
	ds_read_b128 v[220:223], v181 offset:20480
	ds_read_b128 v[224:227], v181 offset:21504
	ds_read_b128 v[228:231], v181 offset:22528
	ds_read_b128 v[232:235], v181 offset:23552
	global_load_lds_dwordx4 v[170:171], off
	s_add_i32 m0, s37, 0x2000
	s_add_u32 s74, s52, 0x40000
	v_lshl_add_u64 v[172:173], s[52:53], 0, v[130:131]
	s_addc_u32 s75, s53, 0
	s_add_i32 s29, s29, s4
	global_load_lds_dwordx4 v[172:173], off
	s_mov_b32 m0, s29
	v_lshl_add_u64 v[238:239], s[54:55], 0, v[132:133]
	global_load_lds_dwordx4 v0, s[74:75]
	s_add_i32 m0, s29, 0x2000
	s_nop 0
	global_load_lds_dwordx4 v130, s[74:75]
	v_lshl_add_u64 v[236:237], s[54:55], 0, v[134:135]
	s_mov_b32 m0, s5
	s_nop 0
	global_load_lds_dwordx4 v[236:237], off
	s_mov_b32 m0, s20
	s_nop 0
	global_load_lds_dwordx4 v[238:239], off
	.p2align	3
	s_waitcnt vmcnt(8)
	s_waitcnt lgkmcnt(0)
	s_setprio 1
	s_barrier
	v_mfma_f32_16x16x32_bf16 v[62:65], v[140:143], v[204:207], v[62:65]
	v_mfma_f32_16x16x32_bf16 v[58:61], v[148:151], v[204:207], v[58:61]
	v_mfma_f32_16x16x32_bf16 v[54:57], v[140:143], v[212:215], v[54:57]
	v_mfma_f32_16x16x32_bf16 v[50:53], v[148:151], v[212:215], v[50:53]
	v_mfma_f32_16x16x32_bf16 v[42:45], v[140:143], v[220:223], v[42:45]
	v_mfma_f32_16x16x32_bf16 v[34:37], v[148:151], v[220:223], v[34:37]
	v_mfma_f32_16x16x32_bf16 v[26:29], v[140:143], v[228:231], v[26:29]
	v_mfma_f32_16x16x32_bf16 v[18:21], v[148:151], v[228:231], v[18:21]
	v_mfma_f32_16x16x32_bf16 v[62:65], v[144:147], v[208:211], v[62:65]
	v_mfma_f32_16x16x32_bf16 v[58:61], v[152:155], v[208:211], v[58:61]
	v_mfma_f32_16x16x32_bf16 v[54:57], v[144:147], v[216:219], v[54:57]
	v_mfma_f32_16x16x32_bf16 v[50:53], v[152:155], v[216:219], v[50:53]
	v_mfma_f32_16x16x32_bf16 v[42:45], v[144:147], v[224:227], v[42:45]
	v_mfma_f32_16x16x32_bf16 v[34:37], v[152:155], v[224:227], v[34:37]
	v_mfma_f32_16x16x32_bf16 v[26:29], v[144:147], v[232:235], v[26:29]
	v_mfma_f32_16x16x32_bf16 v[18:21], v[152:155], v[232:235], v[18:21]
	v_mfma_f32_16x16x32_bf16 v[46:49], v[184:187], v[204:207], v[46:49]
	v_mfma_f32_16x16x32_bf16 v[38:41], v[192:195], v[204:207], v[38:41]
	v_mfma_f32_16x16x32_bf16 v[30:33], v[184:187], v[212:215], v[30:33]
	v_mfma_f32_16x16x32_bf16 v[22:25], v[192:195], v[212:215], v[22:25]
	v_mfma_f32_16x16x32_bf16 v[14:17], v[184:187], v[220:223], v[14:17]
	v_mfma_f32_16x16x32_bf16 v[10:13], v[192:195], v[220:223], v[10:13]
	v_mfma_f32_16x16x32_bf16 v[6:9], v[184:187], v[228:231], v[6:9]
	v_mfma_f32_16x16x32_bf16 v[2:5], v[192:195], v[228:231], v[2:5]
	v_mfma_f32_16x16x32_bf16 v[46:49], v[188:191], v[208:211], v[46:49]
	v_mfma_f32_16x16x32_bf16 v[38:41], v[196:199], v[208:211], v[38:41]
	v_mfma_f32_16x16x32_bf16 v[30:33], v[188:191], v[216:219], v[30:33]
	v_mfma_f32_16x16x32_bf16 v[22:25], v[196:199], v[216:219], v[22:25]
	v_mfma_f32_16x16x32_bf16 v[14:17], v[188:191], v[224:227], v[14:17]
	v_mfma_f32_16x16x32_bf16 v[10:13], v[196:199], v[224:227], v[10:13]
	v_mfma_f32_16x16x32_bf16 v[6:9], v[188:191], v[232:235], v[6:9]
	v_mfma_f32_16x16x32_bf16 v[2:5], v[196:199], v[232:235], v[2:5]
	s_barrier
	s_setprio 0
	s_add_i32 s29, 0, 0x18000
	s_add_i32 s37, 0, 0x1c000
	v_add_u32_e32 v152, s29, v157
	v_add_u32_e32 v183, s37, v157
	ds_read_b128 v[140:143], v152
	ds_read_b128 v[144:147], v152 offset:1024
	ds_read_b128 v[148:151], v152 offset:2048
	ds_read_b128 v[152:155], v152 offset:3072
	ds_read_b128 v[184:187], v183
	ds_read_b128 v[188:191], v183 offset:1024
	ds_read_b128 v[192:195], v183 offset:2048
	ds_read_b128 v[196:199], v183 offset:3072
	s_add_u32 s54, s54, 0x40000
	s_addc_u32 s55, s55, 0
	s_mov_b32 m0, s22
	ds_read_b128 v[204:207], v181 offset:32768
	ds_read_b128 v[208:211], v181 offset:33792
	ds_read_b128 v[212:215], v181 offset:34816
	ds_read_b128 v[216:219], v181 offset:35840
	ds_read_b128 v[220:223], v181 offset:36864
	ds_read_b128 v[224:227], v181 offset:37888
	ds_read_b128 v[228:231], v181 offset:38912
	ds_read_b128 v[232:235], v181 offset:39936
	global_load_lds_dwordx4 v134, s[54:55]
	s_mov_b32 m0, s23
	s_nop 0
	global_load_lds_dwordx4 v132, s[54:55]
	.p2align	3
	s_waitcnt vmcnt(8)
	s_waitcnt lgkmcnt(0)
	s_setprio 1
	s_barrier
	v_mfma_f32_16x16x32_bf16 v[126:129], v[140:143], v[204:207], v[126:129]
	v_mfma_f32_16x16x32_bf16 v[122:125], v[148:151], v[204:207], v[122:125]
	v_mfma_f32_16x16x32_bf16 v[118:121], v[140:143], v[212:215], v[118:121]
	v_mfma_f32_16x16x32_bf16 v[114:117], v[148:151], v[212:215], v[114:117]
	v_mfma_f32_16x16x32_bf16 v[106:109], v[140:143], v[220:223], v[106:109]
	v_mfma_f32_16x16x32_bf16 v[98:101], v[148:151], v[220:223], v[98:101]
	v_mfma_f32_16x16x32_bf16 v[90:93], v[140:143], v[228:231], v[90:93]
	v_mfma_f32_16x16x32_bf16 v[82:85], v[148:151], v[228:231], v[82:85]
	v_mfma_f32_16x16x32_bf16 v[126:129], v[144:147], v[208:211], v[126:129]
	v_mfma_f32_16x16x32_bf16 v[122:125], v[152:155], v[208:211], v[122:125]
	v_mfma_f32_16x16x32_bf16 v[118:121], v[144:147], v[216:219], v[118:121]
	v_mfma_f32_16x16x32_bf16 v[114:117], v[152:155], v[216:219], v[114:117]
	v_mfma_f32_16x16x32_bf16 v[106:109], v[144:147], v[224:227], v[106:109]
	v_mfma_f32_16x16x32_bf16 v[98:101], v[152:155], v[224:227], v[98:101]
	v_mfma_f32_16x16x32_bf16 v[90:93], v[144:147], v[232:235], v[90:93]
	v_mfma_f32_16x16x32_bf16 v[82:85], v[152:155], v[232:235], v[82:85]
	v_mfma_f32_16x16x32_bf16 v[110:113], v[184:187], v[204:207], v[110:113]
	v_mfma_f32_16x16x32_bf16 v[102:105], v[192:195], v[204:207], v[102:105]
	v_mfma_f32_16x16x32_bf16 v[94:97], v[184:187], v[212:215], v[94:97]
	v_mfma_f32_16x16x32_bf16 v[86:89], v[192:195], v[212:215], v[86:89]
	v_mfma_f32_16x16x32_bf16 v[78:81], v[184:187], v[220:223], v[78:81]
	v_mfma_f32_16x16x32_bf16 v[74:77], v[192:195], v[220:223], v[74:77]
	v_mfma_f32_16x16x32_bf16 v[70:73], v[184:187], v[228:231], v[70:73]
	v_mfma_f32_16x16x32_bf16 v[66:69], v[192:195], v[228:231], v[66:69]
	v_mfma_f32_16x16x32_bf16 v[110:113], v[188:191], v[208:211], v[110:113]
	v_mfma_f32_16x16x32_bf16 v[102:105], v[196:199], v[208:211], v[102:105]
	v_mfma_f32_16x16x32_bf16 v[94:97], v[188:191], v[216:219], v[94:97]
	v_mfma_f32_16x16x32_bf16 v[86:89], v[196:199], v[216:219], v[86:89]
	v_mfma_f32_16x16x32_bf16 v[78:81], v[188:191], v[224:227], v[78:81]
	v_mfma_f32_16x16x32_bf16 v[74:77], v[196:199], v[224:227], v[74:77]
	v_mfma_f32_16x16x32_bf16 v[70:73], v[188:191], v[232:235], v[70:73]
	v_mfma_f32_16x16x32_bf16 v[66:69], v[196:199], v[232:235], v[66:69]
	s_barrier
	s_setprio 0
	s_add_i32 s29, s29, s4
	v_lshl_add_u64 v[170:171], v[170:171], 0, s[24:25]
	s_mov_b32 m0, s29
	ds_read_b128 v[204:207], v181 offset:49152
	ds_read_b128 v[208:211], v181 offset:50176
	ds_read_b128 v[212:215], v181 offset:51200
	ds_read_b128 v[216:219], v181 offset:52224
	ds_read_b128 v[220:223], v181 offset:53248
	ds_read_b128 v[224:227], v181 offset:54272
	ds_read_b128 v[228:231], v181 offset:55296
	ds_read_b128 v[232:235], v181 offset:56320
	global_load_lds_dwordx4 v[170:171], off
	s_add_i32 m0, s29, 0x2000
	s_add_u32 s52, s52, 0x40080
	v_lshl_add_u64 v[170:171], v[172:173], 0, s[24:25]
	s_addc_u32 s53, s53, 0
	s_add_i32 s29, s37, s4
	global_load_lds_dwordx4 v[170:171], off
	s_mov_b32 m0, s29
	s_nop 0
	global_load_lds_dwordx4 v0, s[52:53]
	s_add_i32 m0, s29, 0x2000
	s_nop 0
	global_load_lds_dwordx4 v130, s[52:53]
	v_lshl_add_u64 v[170:171], v[236:237], 0, s[24:25]
	s_mov_b32 m0, s31
	s_nop 0
	global_load_lds_dwordx4 v[170:171], off
	v_lshl_add_u64 v[170:171], v[238:239], 0, s[24:25]
	s_mov_b32 m0, s33
	s_nop 0
	global_load_lds_dwordx4 v[170:171], off
	.p2align	3
	s_waitcnt vmcnt(8)
	s_waitcnt lgkmcnt(0)
	s_setprio 1
	s_barrier
	v_mfma_f32_16x16x32_bf16 v[62:65], v[140:143], v[204:207], v[62:65]
	v_mfma_f32_16x16x32_bf16 v[58:61], v[148:151], v[204:207], v[58:61]
	v_mfma_f32_16x16x32_bf16 v[54:57], v[140:143], v[212:215], v[54:57]
	v_mfma_f32_16x16x32_bf16 v[50:53], v[148:151], v[212:215], v[50:53]
	v_mfma_f32_16x16x32_bf16 v[42:45], v[140:143], v[220:223], v[42:45]
	v_mfma_f32_16x16x32_bf16 v[34:37], v[148:151], v[220:223], v[34:37]
	v_mfma_f32_16x16x32_bf16 v[26:29], v[140:143], v[228:231], v[26:29]
	v_mfma_f32_16x16x32_bf16 v[18:21], v[148:151], v[228:231], v[18:21]
	v_mfma_f32_16x16x32_bf16 v[62:65], v[144:147], v[208:211], v[62:65]
	v_mfma_f32_16x16x32_bf16 v[58:61], v[152:155], v[208:211], v[58:61]
	v_mfma_f32_16x16x32_bf16 v[54:57], v[144:147], v[216:219], v[54:57]
	v_mfma_f32_16x16x32_bf16 v[50:53], v[152:155], v[216:219], v[50:53]
	v_mfma_f32_16x16x32_bf16 v[42:45], v[144:147], v[224:227], v[42:45]
	v_mfma_f32_16x16x32_bf16 v[34:37], v[152:155], v[224:227], v[34:37]
	v_mfma_f32_16x16x32_bf16 v[26:29], v[144:147], v[232:235], v[26:29]
	v_mfma_f32_16x16x32_bf16 v[18:21], v[152:155], v[232:235], v[18:21]
	v_mfma_f32_16x16x32_bf16 v[46:49], v[184:187], v[204:207], v[46:49]
	v_mfma_f32_16x16x32_bf16 v[38:41], v[192:195], v[204:207], v[38:41]
	v_mfma_f32_16x16x32_bf16 v[30:33], v[184:187], v[212:215], v[30:33]
	v_mfma_f32_16x16x32_bf16 v[22:25], v[192:195], v[212:215], v[22:25]
	v_mfma_f32_16x16x32_bf16 v[14:17], v[184:187], v[220:223], v[14:17]
	v_mfma_f32_16x16x32_bf16 v[10:13], v[192:195], v[220:223], v[10:13]
	v_mfma_f32_16x16x32_bf16 v[6:9], v[184:187], v[228:231], v[6:9]
	v_mfma_f32_16x16x32_bf16 v[2:5], v[192:195], v[228:231], v[2:5]
	v_mfma_f32_16x16x32_bf16 v[46:49], v[188:191], v[208:211], v[46:49]
	v_mfma_f32_16x16x32_bf16 v[38:41], v[196:199], v[208:211], v[38:41]
	v_mfma_f32_16x16x32_bf16 v[30:33], v[188:191], v[216:219], v[30:33]
	v_mfma_f32_16x16x32_bf16 v[22:25], v[196:199], v[216:219], v[22:25]
	v_mfma_f32_16x16x32_bf16 v[14:17], v[188:191], v[224:227], v[14:17]
	v_mfma_f32_16x16x32_bf16 v[10:13], v[196:199], v[224:227], v[10:13]
	v_mfma_f32_16x16x32_bf16 v[6:9], v[188:191], v[232:235], v[6:9]
	v_mfma_f32_16x16x32_bf16 v[2:5], v[196:199], v[232:235], v[2:5]
	s_barrier
	s_setprio 0
	s_add_u32 s16, s16, 0x100
	s_addc_u32 s17, s17, 0
	s_add_u32 s38, s38, 0x100
	s_addc_u32 s39, s39, 0
	s_cmp_ge_i32 s56, s3
	s_mov_b32 s52, s56
	s_cbranch_scc0 .LBB7_1219

.Lpeel_1274:
	s_add_i32 s72, s50, 2
	s_add_u32 s29, s48, 0xfffc0080
	s_addc_u32 s37, s49, -1
	s_add_i32 s73, 0, 0x10000
	s_cmp_eq_u32 s33, s50
	s_cselect_b32 s53, s13, s37
	s_cselect_b32 s52, s15, s29
	s_cselect_b32 s51, s54, s57
	s_cselect_b32 s50, s55, s56
	s_add_i32 s29, 0, 0x14000
	v_add_u32_e32 v156, s73, v141
	v_add_u32_e32 v160, s29, v141
	ds_read_b128 v[144:147], v156
	ds_read_b128 v[148:151], v156 offset:1024
	ds_read_b128 v[152:155], v156 offset:2048
	ds_read_b128 v[156:159], v156 offset:3072
	ds_read_b128 v[174:177], v160
	ds_read_b128 v[178:181], v160 offset:1024
	ds_read_b128 v[182:185], v160 offset:2048
	ds_read_b128 v[186:189], v160 offset:3072
	s_add_i32 m0, s5, 0xc000
	ds_read_b128 v[190:193], v143
	ds_read_b128 v[194:197], v143 offset:1024
	ds_read_b128 v[204:207], v143 offset:2048
	ds_read_b128 v[208:211], v143 offset:3072
	ds_read_b128 v[212:215], v143 offset:4096
	ds_read_b128 v[216:219], v143 offset:5120
	ds_read_b128 v[220:223], v143 offset:6144
	ds_read_b128 v[224:227], v143 offset:7168
	global_load_lds_dwordx4 v136, s[48:49]
	s_add_i32 m0, s5, 0xe000
	s_nop 0
	global_load_lds_dwordx4 v138, s[48:49]
	.p2align	3
	s_waitcnt vmcnt(8)
	s_waitcnt lgkmcnt(0)
	s_setprio 1
	s_barrier
	v_mfma_f32_16x16x32_bf16 v[126:129], v[144:147], v[190:193], 0
	v_mfma_f32_16x16x32_bf16 v[122:125], v[152:155], v[190:193], 0
	v_mfma_f32_16x16x32_bf16 v[110:113], v[144:147], v[204:207], 0
	v_mfma_f32_16x16x32_bf16 v[106:109], v[152:155], v[204:207], 0
	v_mfma_f32_16x16x32_bf16 v[94:97], v[144:147], v[212:215], 0
	v_mfma_f32_16x16x32_bf16 v[90:93], v[152:155], v[212:215], 0
	v_mfma_f32_16x16x32_bf16 v[78:81], v[144:147], v[220:223], 0
	v_mfma_f32_16x16x32_bf16 v[74:77], v[152:155], v[220:223], 0
	v_mfma_f32_16x16x32_bf16 v[126:129], v[148:151], v[194:197], v[126:129]
	v_mfma_f32_16x16x32_bf16 v[122:125], v[156:159], v[194:197], v[122:125]
	v_mfma_f32_16x16x32_bf16 v[110:113], v[148:151], v[208:211], v[110:113]
	v_mfma_f32_16x16x32_bf16 v[106:109], v[156:159], v[208:211], v[106:109]
	v_mfma_f32_16x16x32_bf16 v[94:97], v[148:151], v[216:219], v[94:97]
	v_mfma_f32_16x16x32_bf16 v[90:93], v[156:159], v[216:219], v[90:93]
	v_mfma_f32_16x16x32_bf16 v[78:81], v[148:151], v[224:227], v[78:81]
	v_mfma_f32_16x16x32_bf16 v[74:77], v[156:159], v[224:227], v[74:77]
	v_mfma_f32_16x16x32_bf16 v[118:121], v[174:177], v[190:193], 0
	v_mfma_f32_16x16x32_bf16 v[114:117], v[182:185], v[190:193], 0
	v_mfma_f32_16x16x32_bf16 v[102:105], v[174:177], v[204:207], 0
	v_mfma_f32_16x16x32_bf16 v[98:101], v[182:185], v[204:207], 0
	v_mfma_f32_16x16x32_bf16 v[86:89], v[174:177], v[212:215], 0
	v_mfma_f32_16x16x32_bf16 v[82:85], v[182:185], v[212:215], 0
	v_mfma_f32_16x16x32_bf16 v[70:73], v[174:177], v[220:223], 0
	v_mfma_f32_16x16x32_bf16 v[66:69], v[182:185], v[220:223], 0
	v_mfma_f32_16x16x32_bf16 v[118:121], v[178:181], v[194:197], v[118:121]
	v_mfma_f32_16x16x32_bf16 v[114:117], v[186:189], v[194:197], v[114:117]
	v_mfma_f32_16x16x32_bf16 v[102:105], v[178:181], v[208:211], v[102:105]
	v_mfma_f32_16x16x32_bf16 v[98:101], v[186:189], v[208:211], v[98:101]
	v_mfma_f32_16x16x32_bf16 v[86:89], v[178:181], v[216:219], v[86:89]
	v_mfma_f32_16x16x32_bf16 v[82:85], v[186:189], v[216:219], v[82:85]
	v_mfma_f32_16x16x32_bf16 v[70:73], v[178:181], v[224:227], v[70:73]
	v_mfma_f32_16x16x32_bf16 v[66:69], v[186:189], v[224:227], v[66:69]
	s_barrier
	s_setprio 0
	s_add_i32 s37, s73, s4
	v_lshl_add_u64 v[160:161], s[50:51], 0, v[0:1]
	s_mov_b32 m0, s37
	ds_read_b128 v[190:193], v143 offset:16384
	ds_read_b128 v[194:197], v143 offset:17408
	ds_read_b128 v[204:207], v143 offset:18432
	ds_read_b128 v[208:211], v143 offset:19456
	ds_read_b128 v[212:215], v143 offset:20480
	ds_read_b128 v[216:219], v143 offset:21504
	ds_read_b128 v[220:223], v143 offset:22528
	ds_read_b128 v[224:227], v143 offset:23552
	global_load_lds_dwordx4 v[160:161], off
	s_add_i32 m0, s37, 0x2000
	s_add_u32 s74, s50, 0x100000
	v_lshl_add_u64 v[170:171], s[50:51], 0, v[130:131]
	s_addc_u32 s75, s51, 0
	s_add_i32 s29, s29, s4
	global_load_lds_dwordx4 v[170:171], off
	s_mov_b32 m0, s29
	v_lshl_add_u64 v[198:199], s[52:53], 0, v[132:133]
	global_load_lds_dwordx4 v0, s[74:75]
	s_add_i32 m0, s29, 0x2000
	s_nop 0
	global_load_lds_dwordx4 v130, s[74:75]
	v_lshl_add_u64 v[172:173], s[52:53], 0, v[134:135]
	s_mov_b32 m0, s5
	s_nop 0
	global_load_lds_dwordx4 v[172:173], off
	s_mov_b32 m0, s10
	s_nop 0
	global_load_lds_dwordx4 v[198:199], off
	.p2align	3
	s_waitcnt vmcnt(8)
	s_waitcnt lgkmcnt(0)
	s_setprio 1
	s_barrier
	v_mfma_f32_16x16x32_bf16 v[62:65], v[144:147], v[190:193], 0
	v_mfma_f32_16x16x32_bf16 v[58:61], v[152:155], v[190:193], 0
	v_mfma_f32_16x16x32_bf16 v[46:49], v[144:147], v[204:207], 0
	v_mfma_f32_16x16x32_bf16 v[42:45], v[152:155], v[204:207], 0
	v_mfma_f32_16x16x32_bf16 v[30:33], v[144:147], v[212:215], 0
	v_mfma_f32_16x16x32_bf16 v[26:29], v[152:155], v[212:215], 0
	v_mfma_f32_16x16x32_bf16 v[14:17], v[144:147], v[220:223], 0
	v_mfma_f32_16x16x32_bf16 v[10:13], v[152:155], v[220:223], 0
	v_mfma_f32_16x16x32_bf16 v[62:65], v[148:151], v[194:197], v[62:65]
	v_mfma_f32_16x16x32_bf16 v[58:61], v[156:159], v[194:197], v[58:61]
	v_mfma_f32_16x16x32_bf16 v[46:49], v[148:151], v[208:211], v[46:49]
	v_mfma_f32_16x16x32_bf16 v[42:45], v[156:159], v[208:211], v[42:45]
	v_mfma_f32_16x16x32_bf16 v[30:33], v[148:151], v[216:219], v[30:33]
	v_mfma_f32_16x16x32_bf16 v[26:29], v[156:159], v[216:219], v[26:29]
	v_mfma_f32_16x16x32_bf16 v[14:17], v[148:151], v[224:227], v[14:17]
	v_mfma_f32_16x16x32_bf16 v[10:13], v[156:159], v[224:227], v[10:13]
	v_mfma_f32_16x16x32_bf16 v[54:57], v[174:177], v[190:193], 0
	v_mfma_f32_16x16x32_bf16 v[50:53], v[182:185], v[190:193], 0
	v_mfma_f32_16x16x32_bf16 v[38:41], v[174:177], v[204:207], 0
	v_mfma_f32_16x16x32_bf16 v[34:37], v[182:185], v[204:207], 0
	v_mfma_f32_16x16x32_bf16 v[22:25], v[174:177], v[212:215], 0
	v_mfma_f32_16x16x32_bf16 v[18:21], v[182:185], v[212:215], 0
	v_mfma_f32_16x16x32_bf16 v[6:9], v[174:177], v[220:223], 0
	v_mfma_f32_16x16x32_bf16 v[2:5], v[182:185], v[220:223], 0
	v_mfma_f32_16x16x32_bf16 v[54:57], v[178:181], v[194:197], v[54:57]
	v_mfma_f32_16x16x32_bf16 v[50:53], v[186:189], v[194:197], v[50:53]
	v_mfma_f32_16x16x32_bf16 v[38:41], v[178:181], v[208:211], v[38:41]
	v_mfma_f32_16x16x32_bf16 v[34:37], v[186:189], v[208:211], v[34:37]
	v_mfma_f32_16x16x32_bf16 v[22:25], v[178:181], v[216:219], v[22:25]
	v_mfma_f32_16x16x32_bf16 v[18:21], v[186:189], v[216:219], v[18:21]
	v_mfma_f32_16x16x32_bf16 v[6:9], v[178:181], v[224:227], v[6:9]
	v_mfma_f32_16x16x32_bf16 v[2:5], v[186:189], v[224:227], v[2:5]
	s_barrier
	s_setprio 0
	s_add_i32 s29, 0, 0x18000
	s_add_i32 s37, 0, 0x1c000
	v_add_u32_e32 v156, s29, v141
	v_add_u32_e32 v186, s37, v141
	ds_read_b128 v[144:147], v156
	ds_read_b128 v[148:151], v156 offset:1024
	ds_read_b128 v[152:155], v156 offset:2048
	ds_read_b128 v[156:159], v156 offset:3072
	ds_read_b128 v[174:177], v186
	ds_read_b128 v[178:181], v186 offset:1024
	ds_read_b128 v[182:185], v186 offset:2048
	ds_read_b128 v[186:189], v186 offset:3072
	s_add_u32 s52, s52, 0x40000
	s_addc_u32 s53, s53, 0
	s_mov_b32 m0, s20
	ds_read_b128 v[190:193], v143 offset:32768
	ds_read_b128 v[194:197], v143 offset:33792
	ds_read_b128 v[204:207], v143 offset:34816
	ds_read_b128 v[208:211], v143 offset:35840
	ds_read_b128 v[212:215], v143 offset:36864
	ds_read_b128 v[216:219], v143 offset:37888
	ds_read_b128 v[220:223], v143 offset:38912
	ds_read_b128 v[224:227], v143 offset:39936
	global_load_lds_dwordx4 v134, s[52:53]
	s_mov_b32 m0, s22
	s_nop 0
	global_load_lds_dwordx4 v132, s[52:53]
	.p2align	3
	s_waitcnt vmcnt(8)
	s_waitcnt lgkmcnt(0)
	s_setprio 1
	s_barrier
	v_mfma_f32_16x16x32_bf16 v[126:129], v[144:147], v[190:193], v[126:129]
	v_mfma_f32_16x16x32_bf16 v[122:125], v[152:155], v[190:193], v[122:125]
	v_mfma_f32_16x16x32_bf16 v[110:113], v[144:147], v[204:207], v[110:113]
	v_mfma_f32_16x16x32_bf16 v[106:109], v[152:155], v[204:207], v[106:109]
	v_mfma_f32_16x16x32_bf16 v[94:97], v[144:147], v[212:215], v[94:97]
	v_mfma_f32_16x16x32_bf16 v[90:93], v[152:155], v[212:215], v[90:93]
	v_mfma_f32_16x16x32_bf16 v[78:81], v[144:147], v[220:223], v[78:81]
	v_mfma_f32_16x16x32_bf16 v[74:77], v[152:155], v[220:223], v[74:77]
	v_mfma_f32_16x16x32_bf16 v[126:129], v[148:151], v[194:197], v[126:129]
	v_mfma_f32_16x16x32_bf16 v[122:125], v[156:159], v[194:197], v[122:125]
	v_mfma_f32_16x16x32_bf16 v[110:113], v[148:151], v[208:211], v[110:113]
	v_mfma_f32_16x16x32_bf16 v[106:109], v[156:159], v[208:211], v[106:109]
	v_mfma_f32_16x16x32_bf16 v[94:97], v[148:151], v[216:219], v[94:97]
	v_mfma_f32_16x16x32_bf16 v[90:93], v[156:159], v[216:219], v[90:93]
	v_mfma_f32_16x16x32_bf16 v[78:81], v[148:151], v[224:227], v[78:81]
	v_mfma_f32_16x16x32_bf16 v[74:77], v[156:159], v[224:227], v[74:77]
	v_mfma_f32_16x16x32_bf16 v[118:121], v[174:177], v[190:193], v[118:121]
	v_mfma_f32_16x16x32_bf16 v[114:117], v[182:185], v[190:193], v[114:117]
	v_mfma_f32_16x16x32_bf16 v[102:105], v[174:177], v[204:207], v[102:105]
	v_mfma_f32_16x16x32_bf16 v[98:101], v[182:185], v[204:207], v[98:101]
	v_mfma_f32_16x16x32_bf16 v[86:89], v[174:177], v[212:215], v[86:89]
	v_mfma_f32_16x16x32_bf16 v[82:85], v[182:185], v[212:215], v[82:85]
	v_mfma_f32_16x16x32_bf16 v[70:73], v[174:177], v[220:223], v[70:73]
	v_mfma_f32_16x16x32_bf16 v[66:69], v[182:185], v[220:223], v[66:69]
	v_mfma_f32_16x16x32_bf16 v[118:121], v[178:181], v[194:197], v[118:121]
	v_mfma_f32_16x16x32_bf16 v[114:117], v[186:189], v[194:197], v[114:117]
	v_mfma_f32_16x16x32_bf16 v[102:105], v[178:181], v[208:211], v[102:105]
	v_mfma_f32_16x16x32_bf16 v[98:101], v[186:189], v[208:211], v[98:101]
	v_mfma_f32_16x16x32_bf16 v[86:89], v[178:181], v[216:219], v[86:89]
	v_mfma_f32_16x16x32_bf16 v[82:85], v[186:189], v[216:219], v[82:85]
	v_mfma_f32_16x16x32_bf16 v[70:73], v[178:181], v[224:227], v[70:73]
	v_mfma_f32_16x16x32_bf16 v[66:69], v[186:189], v[224:227], v[66:69]
	s_barrier
	s_setprio 0
	s_add_i32 s29, s29, s4
	v_lshl_add_u64 v[160:161], v[160:161], 0, s[24:25]
	s_mov_b32 m0, s29
	ds_read_b128 v[190:193], v143 offset:49152
	ds_read_b128 v[194:197], v143 offset:50176
	ds_read_b128 v[204:207], v143 offset:51200
	ds_read_b128 v[208:211], v143 offset:52224
	ds_read_b128 v[212:215], v143 offset:53248
	ds_read_b128 v[216:219], v143 offset:54272
	ds_read_b128 v[220:223], v143 offset:55296
	ds_read_b128 v[224:227], v143 offset:56320
	global_load_lds_dwordx4 v[160:161], off
	s_add_i32 m0, s29, 0x2000
	s_add_u32 s50, s50, 0x100080
	v_lshl_add_u64 v[160:161], v[170:171], 0, s[24:25]
	s_addc_u32 s51, s51, 0
	s_add_i32 s29, s37, s4
	global_load_lds_dwordx4 v[160:161], off
	s_mov_b32 m0, s29
	s_nop 0
	global_load_lds_dwordx4 v0, s[50:51]
	s_add_i32 m0, s29, 0x2000
	s_nop 0
	global_load_lds_dwordx4 v130, s[50:51]
	v_lshl_add_u64 v[160:161], v[172:173], 0, s[24:25]
	s_mov_b32 m0, s23
	s_nop 0
	global_load_lds_dwordx4 v[160:161], off
	v_lshl_add_u64 v[160:161], v[198:199], 0, s[24:25]
	s_mov_b32 m0, s28
	s_nop 0
	global_load_lds_dwordx4 v[160:161], off
	.p2align	3
	s_waitcnt vmcnt(8)
	s_waitcnt lgkmcnt(0)
	s_setprio 1
	s_barrier
	v_mfma_f32_16x16x32_bf16 v[62:65], v[144:147], v[190:193], v[62:65]
	v_mfma_f32_16x16x32_bf16 v[58:61], v[152:155], v[190:193], v[58:61]
	v_mfma_f32_16x16x32_bf16 v[46:49], v[144:147], v[204:207], v[46:49]
	v_mfma_f32_16x16x32_bf16 v[42:45], v[152:155], v[204:207], v[42:45]
	v_mfma_f32_16x16x32_bf16 v[30:33], v[144:147], v[212:215], v[30:33]
	v_mfma_f32_16x16x32_bf16 v[26:29], v[152:155], v[212:215], v[26:29]
	v_mfma_f32_16x16x32_bf16 v[14:17], v[144:147], v[220:223], v[14:17]
	v_mfma_f32_16x16x32_bf16 v[10:13], v[152:155], v[220:223], v[10:13]
	v_mfma_f32_16x16x32_bf16 v[62:65], v[148:151], v[194:197], v[62:65]
	v_mfma_f32_16x16x32_bf16 v[58:61], v[156:159], v[194:197], v[58:61]
	v_mfma_f32_16x16x32_bf16 v[46:49], v[148:151], v[208:211], v[46:49]
	v_mfma_f32_16x16x32_bf16 v[42:45], v[156:159], v[208:211], v[42:45]
	v_mfma_f32_16x16x32_bf16 v[30:33], v[148:151], v[216:219], v[30:33]
	v_mfma_f32_16x16x32_bf16 v[26:29], v[156:159], v[216:219], v[26:29]
	v_mfma_f32_16x16x32_bf16 v[14:17], v[148:151], v[224:227], v[14:17]
	v_mfma_f32_16x16x32_bf16 v[10:13], v[156:159], v[224:227], v[10:13]
	v_mfma_f32_16x16x32_bf16 v[54:57], v[174:177], v[190:193], v[54:57]
	v_mfma_f32_16x16x32_bf16 v[50:53], v[182:185], v[190:193], v[50:53]
	v_mfma_f32_16x16x32_bf16 v[38:41], v[174:177], v[204:207], v[38:41]
	v_mfma_f32_16x16x32_bf16 v[34:37], v[182:185], v[204:207], v[34:37]
	v_mfma_f32_16x16x32_bf16 v[22:25], v[174:177], v[212:215], v[22:25]
	v_mfma_f32_16x16x32_bf16 v[18:21], v[182:185], v[212:215], v[18:21]
	v_mfma_f32_16x16x32_bf16 v[6:9], v[174:177], v[220:223], v[6:9]
	v_mfma_f32_16x16x32_bf16 v[2:5], v[182:185], v[220:223], v[2:5]
	v_mfma_f32_16x16x32_bf16 v[54:57], v[178:181], v[194:197], v[54:57]
	v_mfma_f32_16x16x32_bf16 v[50:53], v[186:189], v[194:197], v[50:53]
	v_mfma_f32_16x16x32_bf16 v[38:41], v[178:181], v[208:211], v[38:41]
	v_mfma_f32_16x16x32_bf16 v[34:37], v[186:189], v[208:211], v[34:37]
	v_mfma_f32_16x16x32_bf16 v[22:25], v[178:181], v[216:219], v[22:25]
	v_mfma_f32_16x16x32_bf16 v[18:21], v[186:189], v[216:219], v[18:21]
	v_mfma_f32_16x16x32_bf16 v[6:9], v[178:181], v[224:227], v[6:9]
	v_mfma_f32_16x16x32_bf16 v[2:5], v[186:189], v[224:227], v[2:5]
	s_barrier
	s_setprio 0
	s_add_u32 s48, s48, 0x100
	s_addc_u32 s49, s49, 0
	s_add_u32 s56, s56, 0x100
	s_addc_u32 s57, s57, 0
	s_cmp_ge_i32 s72, s3
	s_mov_b32 s50, s72
	s_cbranch_scc0 .LBB7_1274
	s_branch .Lpeelx_1274
	.p2align	6
.LBB7_1274:
	s_add_i32 s72, s50, 2
	s_add_u32 s29, s48, 0xfffc0080
	s_addc_u32 s37, s49, -1
	s_add_i32 s73, 0, 0x10000
	s_cmp_eq_u32 s33, s50
	s_cselect_b32 s53, s13, s37
	s_cselect_b32 s52, s15, s29
	s_cselect_b32 s51, s54, s57
	s_cselect_b32 s50, s55, s56
	s_add_i32 s29, 0, 0x14000
	v_add_u32_e32 v156, s73, v141
	v_add_u32_e32 v160, s29, v141
	ds_read_b128 v[144:147], v156
	ds_read_b128 v[148:151], v156 offset:1024
	ds_read_b128 v[152:155], v156 offset:2048
	ds_read_b128 v[156:159], v156 offset:3072
	ds_read_b128 v[174:177], v160
	ds_read_b128 v[178:181], v160 offset:1024
	ds_read_b128 v[182:185], v160 offset:2048
	ds_read_b128 v[186:189], v160 offset:3072
	s_add_i32 m0, s5, 0xc000
	ds_read_b128 v[190:193], v143
	ds_read_b128 v[194:197], v143 offset:1024
	ds_read_b128 v[204:207], v143 offset:2048
	ds_read_b128 v[208:211], v143 offset:3072
	ds_read_b128 v[212:215], v143 offset:4096
	ds_read_b128 v[216:219], v143 offset:5120
	ds_read_b128 v[220:223], v143 offset:6144
	ds_read_b128 v[224:227], v143 offset:7168
	global_load_lds_dwordx4 v136, s[48:49]
	s_add_i32 m0, s5, 0xe000
	s_nop 0
	global_load_lds_dwordx4 v138, s[48:49]
	.p2align	3
	s_waitcnt vmcnt(8)
	s_waitcnt lgkmcnt(0)
	s_setprio 1
	s_barrier
	v_mfma_f32_16x16x32_bf16 v[126:129], v[144:147], v[190:193], v[126:129]
	v_mfma_f32_16x16x32_bf16 v[122:125], v[152:155], v[190:193], v[122:125]
	v_mfma_f32_16x16x32_bf16 v[110:113], v[144:147], v[204:207], v[110:113]
	v_mfma_f32_16x16x32_bf16 v[106:109], v[152:155], v[204:207], v[106:109]
	v_mfma_f32_16x16x32_bf16 v[94:97], v[144:147], v[212:215], v[94:97]
	v_mfma_f32_16x16x32_bf16 v[90:93], v[152:155], v[212:215], v[90:93]
	v_mfma_f32_16x16x32_bf16 v[78:81], v[144:147], v[220:223], v[78:81]
	v_mfma_f32_16x16x32_bf16 v[74:77], v[152:155], v[220:223], v[74:77]
	v_mfma_f32_16x16x32_bf16 v[126:129], v[148:151], v[194:197], v[126:129]
	v_mfma_f32_16x16x32_bf16 v[122:125], v[156:159], v[194:197], v[122:125]
	v_mfma_f32_16x16x32_bf16 v[110:113], v[148:151], v[208:211], v[110:113]
	v_mfma_f32_16x16x32_bf16 v[106:109], v[156:159], v[208:211], v[106:109]
	v_mfma_f32_16x16x32_bf16 v[94:97], v[148:151], v[216:219], v[94:97]
	v_mfma_f32_16x16x32_bf16 v[90:93], v[156:159], v[216:219], v[90:93]
	v_mfma_f32_16x16x32_bf16 v[78:81], v[148:151], v[224:227], v[78:81]
	v_mfma_f32_16x16x32_bf16 v[74:77], v[156:159], v[224:227], v[74:77]
	v_mfma_f32_16x16x32_bf16 v[118:121], v[174:177], v[190:193], v[118:121]
	v_mfma_f32_16x16x32_bf16 v[114:117], v[182:185], v[190:193], v[114:117]
	v_mfma_f32_16x16x32_bf16 v[102:105], v[174:177], v[204:207], v[102:105]
	v_mfma_f32_16x16x32_bf16 v[98:101], v[182:185], v[204:207], v[98:101]
	v_mfma_f32_16x16x32_bf16 v[86:89], v[174:177], v[212:215], v[86:89]
	v_mfma_f32_16x16x32_bf16 v[82:85], v[182:185], v[212:215], v[82:85]
	v_mfma_f32_16x16x32_bf16 v[70:73], v[174:177], v[220:223], v[70:73]
	v_mfma_f32_16x16x32_bf16 v[66:69], v[182:185], v[220:223], v[66:69]
	v_mfma_f32_16x16x32_bf16 v[118:121], v[178:181], v[194:197], v[118:121]
	v_mfma_f32_16x16x32_bf16 v[114:117], v[186:189], v[194:197], v[114:117]
	v_mfma_f32_16x16x32_bf16 v[102:105], v[178:181], v[208:211], v[102:105]
	v_mfma_f32_16x16x32_bf16 v[98:101], v[186:189], v[208:211], v[98:101]
	v_mfma_f32_16x16x32_bf16 v[86:89], v[178:181], v[216:219], v[86:89]
	v_mfma_f32_16x16x32_bf16 v[82:85], v[186:189], v[216:219], v[82:85]
	v_mfma_f32_16x16x32_bf16 v[70:73], v[178:181], v[224:227], v[70:73]
	v_mfma_f32_16x16x32_bf16 v[66:69], v[186:189], v[224:227], v[66:69]
	s_barrier
	s_setprio 0
	s_add_i32 s37, s73, s4
	v_lshl_add_u64 v[160:161], s[50:51], 0, v[0:1]
	s_mov_b32 m0, s37
	ds_read_b128 v[190:193], v143 offset:16384
	ds_read_b128 v[194:197], v143 offset:17408
	ds_read_b128 v[204:207], v143 offset:18432
	ds_read_b128 v[208:211], v143 offset:19456
	ds_read_b128 v[212:215], v143 offset:20480
	ds_read_b128 v[216:219], v143 offset:21504
	ds_read_b128 v[220:223], v143 offset:22528
	ds_read_b128 v[224:227], v143 offset:23552
	global_load_lds_dwordx4 v[160:161], off
	s_add_i32 m0, s37, 0x2000
	s_add_u32 s74, s50, 0x100000
	v_lshl_add_u64 v[170:171], s[50:51], 0, v[130:131]
	s_addc_u32 s75, s51, 0
	s_add_i32 s29, s29, s4
	global_load_lds_dwordx4 v[170:171], off
	s_mov_b32 m0, s29
	v_lshl_add_u64 v[198:199], s[52:53], 0, v[132:133]
	global_load_lds_dwordx4 v0, s[74:75]
	s_add_i32 m0, s29, 0x2000
	s_nop 0
	global_load_lds_dwordx4 v130, s[74:75]
	v_lshl_add_u64 v[172:173], s[52:53], 0, v[134:135]
	s_mov_b32 m0, s5
	s_nop 0
	global_load_lds_dwordx4 v[172:173], off
	s_mov_b32 m0, s10
	s_nop 0
	global_load_lds_dwordx4 v[198:199], off
	.p2align	3
	s_waitcnt vmcnt(8)
	s_waitcnt lgkmcnt(0)
	s_setprio 1
	s_barrier
	v_mfma_f32_16x16x32_bf16 v[62:65], v[144:147], v[190:193], v[62:65]
	v_mfma_f32_16x16x32_bf16 v[58:61], v[152:155], v[190:193], v[58:61]
	v_mfma_f32_16x16x32_bf16 v[46:49], v[144:147], v[204:207], v[46:49]
	v_mfma_f32_16x16x32_bf16 v[42:45], v[152:155], v[204:207], v[42:45]
	v_mfma_f32_16x16x32_bf16 v[30:33], v[144:147], v[212:215], v[30:33]
	v_mfma_f32_16x16x32_bf16 v[26:29], v[152:155], v[212:215], v[26:29]
	v_mfma_f32_16x16x32_bf16 v[14:17], v[144:147], v[220:223], v[14:17]
	v_mfma_f32_16x16x32_bf16 v[10:13], v[152:155], v[220:223], v[10:13]
	v_mfma_f32_16x16x32_bf16 v[62:65], v[148:151], v[194:197], v[62:65]
	v_mfma_f32_16x16x32_bf16 v[58:61], v[156:159], v[194:197], v[58:61]
	v_mfma_f32_16x16x32_bf16 v[46:49], v[148:151], v[208:211], v[46:49]
	v_mfma_f32_16x16x32_bf16 v[42:45], v[156:159], v[208:211], v[42:45]
	v_mfma_f32_16x16x32_bf16 v[30:33], v[148:151], v[216:219], v[30:33]
	v_mfma_f32_16x16x32_bf16 v[26:29], v[156:159], v[216:219], v[26:29]
	v_mfma_f32_16x16x32_bf16 v[14:17], v[148:151], v[224:227], v[14:17]
	v_mfma_f32_16x16x32_bf16 v[10:13], v[156:159], v[224:227], v[10:13]
	v_mfma_f32_16x16x32_bf16 v[54:57], v[174:177], v[190:193], v[54:57]
	v_mfma_f32_16x16x32_bf16 v[50:53], v[182:185], v[190:193], v[50:53]
	v_mfma_f32_16x16x32_bf16 v[38:41], v[174:177], v[204:207], v[38:41]
	v_mfma_f32_16x16x32_bf16 v[34:37], v[182:185], v[204:207], v[34:37]
	v_mfma_f32_16x16x32_bf16 v[22:25], v[174:177], v[212:215], v[22:25]
	v_mfma_f32_16x16x32_bf16 v[18:21], v[182:185], v[212:215], v[18:21]
	v_mfma_f32_16x16x32_bf16 v[6:9], v[174:177], v[220:223], v[6:9]
	v_mfma_f32_16x16x32_bf16 v[2:5], v[182:185], v[220:223], v[2:5]
	v_mfma_f32_16x16x32_bf16 v[54:57], v[178:181], v[194:197], v[54:57]
	v_mfma_f32_16x16x32_bf16 v[50:53], v[186:189], v[194:197], v[50:53]
	v_mfma_f32_16x16x32_bf16 v[38:41], v[178:181], v[208:211], v[38:41]
	v_mfma_f32_16x16x32_bf16 v[34:37], v[186:189], v[208:211], v[34:37]
	v_mfma_f32_16x16x32_bf16 v[22:25], v[178:181], v[216:219], v[22:25]
	v_mfma_f32_16x16x32_bf16 v[18:21], v[186:189], v[216:219], v[18:21]
	v_mfma_f32_16x16x32_bf16 v[6:9], v[178:181], v[224:227], v[6:9]
	v_mfma_f32_16x16x32_bf16 v[2:5], v[186:189], v[224:227], v[2:5]
	s_barrier
	s_setprio 0
	s_add_i32 s29, 0, 0x18000
	s_add_i32 s37, 0, 0x1c000
	v_add_u32_e32 v156, s29, v141
	v_add_u32_e32 v186, s37, v141
	ds_read_b128 v[144:147], v156
	ds_read_b128 v[148:151], v156 offset:1024
	ds_read_b128 v[152:155], v156 offset:2048
	ds_read_b128 v[156:159], v156 offset:3072
	ds_read_b128 v[174:177], v186
	ds_read_b128 v[178:181], v186 offset:1024
	ds_read_b128 v[182:185], v186 offset:2048
	ds_read_b128 v[186:189], v186 offset:3072
	s_add_u32 s52, s52, 0x40000
	s_addc_u32 s53, s53, 0
	s_mov_b32 m0, s20
	ds_read_b128 v[190:193], v143 offset:32768
	ds_read_b128 v[194:197], v143 offset:33792
	ds_read_b128 v[204:207], v143 offset:34816
	ds_read_b128 v[208:211], v143 offset:35840
	ds_read_b128 v[212:215], v143 offset:36864
	ds_read_b128 v[216:219], v143 offset:37888
	ds_read_b128 v[220:223], v143 offset:38912
	ds_read_b128 v[224:227], v143 offset:39936
	global_load_lds_dwordx4 v134, s[52:53]
	s_mov_b32 m0, s22
	s_nop 0
	global_load_lds_dwordx4 v132, s[52:53]
	.p2align	3
	s_waitcnt vmcnt(8)
	s_waitcnt lgkmcnt(0)
	s_setprio 1
	s_barrier
	v_mfma_f32_16x16x32_bf16 v[126:129], v[144:147], v[190:193], v[126:129]
	v_mfma_f32_16x16x32_bf16 v[122:125], v[152:155], v[190:193], v[122:125]
	v_mfma_f32_16x16x32_bf16 v[110:113], v[144:147], v[204:207], v[110:113]
	v_mfma_f32_16x16x32_bf16 v[106:109], v[152:155], v[204:207], v[106:109]
	v_mfma_f32_16x16x32_bf16 v[94:97], v[144:147], v[212:215], v[94:97]
	v_mfma_f32_16x16x32_bf16 v[90:93], v[152:155], v[212:215], v[90:93]
	v_mfma_f32_16x16x32_bf16 v[78:81], v[144:147], v[220:223], v[78:81]
	v_mfma_f32_16x16x32_bf16 v[74:77], v[152:155], v[220:223], v[74:77]
	v_mfma_f32_16x16x32_bf16 v[126:129], v[148:151], v[194:197], v[126:129]
	v_mfma_f32_16x16x32_bf16 v[122:125], v[156:159], v[194:197], v[122:125]
	v_mfma_f32_16x16x32_bf16 v[110:113], v[148:151], v[208:211], v[110:113]
	v_mfma_f32_16x16x32_bf16 v[106:109], v[156:159], v[208:211], v[106:109]
	v_mfma_f32_16x16x32_bf16 v[94:97], v[148:151], v[216:219], v[94:97]
	v_mfma_f32_16x16x32_bf16 v[90:93], v[156:159], v[216:219], v[90:93]
	v_mfma_f32_16x16x32_bf16 v[78:81], v[148:151], v[224:227], v[78:81]
	v_mfma_f32_16x16x32_bf16 v[74:77], v[156:159], v[224:227], v[74:77]
	v_mfma_f32_16x16x32_bf16 v[118:121], v[174:177], v[190:193], v[118:121]
	v_mfma_f32_16x16x32_bf16 v[114:117], v[182:185], v[190:193], v[114:117]
	v_mfma_f32_16x16x32_bf16 v[102:105], v[174:177], v[204:207], v[102:105]
	v_mfma_f32_16x16x32_bf16 v[98:101], v[182:185], v[204:207], v[98:101]
	v_mfma_f32_16x16x32_bf16 v[86:89], v[174:177], v[212:215], v[86:89]
	v_mfma_f32_16x16x32_bf16 v[82:85], v[182:185], v[212:215], v[82:85]
	v_mfma_f32_16x16x32_bf16 v[70:73], v[174:177], v[220:223], v[70:73]
	v_mfma_f32_16x16x32_bf16 v[66:69], v[182:185], v[220:223], v[66:69]
	v_mfma_f32_16x16x32_bf16 v[118:121], v[178:181], v[194:197], v[118:121]
	v_mfma_f32_16x16x32_bf16 v[114:117], v[186:189], v[194:197], v[114:117]
	v_mfma_f32_16x16x32_bf16 v[102:105], v[178:181], v[208:211], v[102:105]
	v_mfma_f32_16x16x32_bf16 v[98:101], v[186:189], v[208:211], v[98:101]
	v_mfma_f32_16x16x32_bf16 v[86:89], v[178:181], v[216:219], v[86:89]
	v_mfma_f32_16x16x32_bf16 v[82:85], v[186:189], v[216:219], v[82:85]
	v_mfma_f32_16x16x32_bf16 v[70:73], v[178:181], v[224:227], v[70:73]
	v_mfma_f32_16x16x32_bf16 v[66:69], v[186:189], v[224:227], v[66:69]
	s_barrier
	s_setprio 0
	s_add_i32 s29, s29, s4
	v_lshl_add_u64 v[160:161], v[160:161], 0, s[24:25]
	s_mov_b32 m0, s29
	ds_read_b128 v[190:193], v143 offset:49152
	ds_read_b128 v[194:197], v143 offset:50176
	ds_read_b128 v[204:207], v143 offset:51200
	ds_read_b128 v[208:211], v143 offset:52224
	ds_read_b128 v[212:215], v143 offset:53248
	ds_read_b128 v[216:219], v143 offset:54272
	ds_read_b128 v[220:223], v143 offset:55296
	ds_read_b128 v[224:227], v143 offset:56320
	global_load_lds_dwordx4 v[160:161], off
	s_add_i32 m0, s29, 0x2000
	s_add_u32 s50, s50, 0x100080
	v_lshl_add_u64 v[160:161], v[170:171], 0, s[24:25]
	s_addc_u32 s51, s51, 0
	s_add_i32 s29, s37, s4
	global_load_lds_dwordx4 v[160:161], off
	s_mov_b32 m0, s29
	s_nop 0
	global_load_lds_dwordx4 v0, s[50:51]
	s_add_i32 m0, s29, 0x2000
	s_nop 0
	global_load_lds_dwordx4 v130, s[50:51]
	v_lshl_add_u64 v[160:161], v[172:173], 0, s[24:25]
	s_mov_b32 m0, s23
	s_nop 0
	global_load_lds_dwordx4 v[160:161], off
	v_lshl_add_u64 v[160:161], v[198:199], 0, s[24:25]
	s_mov_b32 m0, s28
	s_nop 0
	global_load_lds_dwordx4 v[160:161], off
	.p2align	3
	s_waitcnt vmcnt(8)
	s_waitcnt lgkmcnt(0)
	s_setprio 1
	s_barrier
	v_mfma_f32_16x16x32_bf16 v[62:65], v[144:147], v[190:193], v[62:65]
	v_mfma_f32_16x16x32_bf16 v[58:61], v[152:155], v[190:193], v[58:61]
	v_mfma_f32_16x16x32_bf16 v[46:49], v[144:147], v[204:207], v[46:49]
	v_mfma_f32_16x16x32_bf16 v[42:45], v[152:155], v[204:207], v[42:45]
	v_mfma_f32_16x16x32_bf16 v[30:33], v[144:147], v[212:215], v[30:33]
	v_mfma_f32_16x16x32_bf16 v[26:29], v[152:155], v[212:215], v[26:29]
	v_mfma_f32_16x16x32_bf16 v[14:17], v[144:147], v[220:223], v[14:17]
	v_mfma_f32_16x16x32_bf16 v[10:13], v[152:155], v[220:223], v[10:13]
	v_mfma_f32_16x16x32_bf16 v[62:65], v[148:151], v[194:197], v[62:65]
	v_mfma_f32_16x16x32_bf16 v[58:61], v[156:159], v[194:197], v[58:61]
	v_mfma_f32_16x16x32_bf16 v[46:49], v[148:151], v[208:211], v[46:49]
	v_mfma_f32_16x16x32_bf16 v[42:45], v[156:159], v[208:211], v[42:45]
	v_mfma_f32_16x16x32_bf16 v[30:33], v[148:151], v[216:219], v[30:33]
	v_mfma_f32_16x16x32_bf16 v[26:29], v[156:159], v[216:219], v[26:29]
	v_mfma_f32_16x16x32_bf16 v[14:17], v[148:151], v[224:227], v[14:17]
	v_mfma_f32_16x16x32_bf16 v[10:13], v[156:159], v[224:227], v[10:13]
	v_mfma_f32_16x16x32_bf16 v[54:57], v[174:177], v[190:193], v[54:57]
	v_mfma_f32_16x16x32_bf16 v[50:53], v[182:185], v[190:193], v[50:53]
	v_mfma_f32_16x16x32_bf16 v[38:41], v[174:177], v[204:207], v[38:41]
	v_mfma_f32_16x16x32_bf16 v[34:37], v[182:185], v[204:207], v[34:37]
	v_mfma_f32_16x16x32_bf16 v[22:25], v[174:177], v[212:215], v[22:25]
	v_mfma_f32_16x16x32_bf16 v[18:21], v[182:185], v[212:215], v[18:21]
	v_mfma_f32_16x16x32_bf16 v[6:9], v[174:177], v[220:223], v[6:9]
	v_mfma_f32_16x16x32_bf16 v[2:5], v[182:185], v[220:223], v[2:5]
	v_mfma_f32_16x16x32_bf16 v[54:57], v[178:181], v[194:197], v[54:57]
	v_mfma_f32_16x16x32_bf16 v[50:53], v[186:189], v[194:197], v[50:53]
	v_mfma_f32_16x16x32_bf16 v[38:41], v[178:181], v[208:211], v[38:41]
	v_mfma_f32_16x16x32_bf16 v[34:37], v[186:189], v[208:211], v[34:37]
	v_mfma_f32_16x16x32_bf16 v[22:25], v[178:181], v[216:219], v[22:25]
	v_mfma_f32_16x16x32_bf16 v[18:21], v[186:189], v[216:219], v[18:21]
	v_mfma_f32_16x16x32_bf16 v[6:9], v[178:181], v[224:227], v[6:9]
	v_mfma_f32_16x16x32_bf16 v[2:5], v[186:189], v[224:227], v[2:5]
	s_barrier
	s_setprio 0
	s_add_u32 s48, s48, 0x100
	s_addc_u32 s49, s49, 0
	s_add_u32 s56, s56, 0x100
	s_addc_u32 s57, s57, 0
	s_cmp_ge_i32 s72, s3
	s_mov_b32 s50, s72
	s_cbranch_scc0 .LBB7_1274
